# GEMM epilogue tile stores marked nt (outputs are next read by other XCDs; lighter L2 write-back at the grid barrier); otherwise v043
# baseline (speedup 1.0000x reference)
.LBB0_859:
	v_mov_b32_e32 v189, v239
	v_mov_b32_e32 v191, v241
	s_cmp_lt_i32 s85, 2
	s_mov_b64 s[0:1], -1
	s_cbranch_scc0 .LBB0_1183
	s_lshl_b32 s0, s75, 6
	s_add_i32 s0, s0, 0
	s_add_i32 s0, s0, 0x21400
	v_mov_b32_e32 v2, s0
	s_waitcnt lgkmcnt(0)
	ds_read_b96 v[134:136], v2
	v_mov_b32_e32 v2, s73
	ds_read_b32 v2, v2
	s_mov_b64 s[6:7], -1
	s_mov_b64 s[0:1], 0
	s_waitcnt lgkmcnt(0)
	v_readfirstlane_b32 s42, v134
	v_readfirstlane_b32 s36, v135
	v_readfirstlane_b32 s12, v2
	v_mov_b32_e32 v2, s77
	ds_read_b32 v2, v2
	v_readfirstlane_b32 s37, v136
	s_cmp_lt_i32 s42, 3
	s_mov_b64 s[14:15], 0
	s_waitcnt lgkmcnt(0)
	v_readfirstlane_b32 s13, v2
	s_cbranch_scc1 .LBB0_993
	s_cmp_gt_i32 s42, 3
	s_cbranch_scc0 .LBB0_966
	s_cmp_gt_i32 s42, 4
	s_cbranch_scc0 .LBB0_892
	s_cmp_eq_u32 s42, 5
	s_mov_b64 s[14:15], -1
	s_cbranch_scc0 .LBB0_891
	s_add_u32 s6, s12, 0x41900000
	s_addc_u32 s7, s13, 0
	s_add_u32 s8, s12, 0x2af00000
	s_addc_u32 s9, s13, 0
	s_lshl_b32 s10, s4, 8
	v_readlane_b32 s11, v255, 18
	s_add_i32 s10, s10, s11
	v_add_u32_e32 v162, s10, v189
	s_lshl_b32 s10, s3, 8
	s_or_b32 s10, s10, s70
	v_lshl_add_u32 v4, v191, 3, s10
	v_ashrrev_i32_e32 v5, 31, v4
	v_lshlrev_b64 v[158:159], 1, v[4:5]
	v_lshl_add_u64 v[134:135], s[12:13], 0, v[158:159]
	s_mov_b64 s[10:11], 0x3f500000
	v_lshl_add_u64 v[160:161], v[134:135], 0, s[10:11]
	v_add_u32_e32 v134, 16, v162
	s_movk_i32 s14, 0x3000
	v_ashrrev_i32_e32 v135, 31, v134
	v_mov_b64_e32 v[136:137], s[8:9]
	v_mad_i64_i32 v[138:139], s[10:11], v134, s14, v[136:137]
	v_lshlrev_b64 v[168:169], 12, v[134:135]
	v_add_u32_e32 v134, 32, v162
	v_lshl_add_u64 v[176:177], v[138:139], 0, v[158:159]
	s_movk_i32 s15, 0x2000
	v_ashrrev_i32_e32 v135, 31, v134
	v_add_co_u32_e32 v138, vcc, s15, v176
	v_lshlrev_b64 v[166:167], 12, v[134:135]
	s_nop 0
	v_addc_co_u32_e32 v139, vcc, 0, v177, vcc
	v_lshl_add_u64 v[180:181], v[160:161], 0, v[166:167]
	global_load_dwordx4 v[150:153], v[138:139], off
	global_load_dwordx4 v[146:149], v[180:181], off
	v_mad_i64_i32 v[138:139], s[10:11], v134, s14, v[136:137]
	v_lshl_add_u64 v[178:179], v[138:139], 0, v[158:159]
	v_add_co_u32_e32 v138, vcc, s15, v178
	v_lshl_add_u64 v[174:175], v[160:161], 0, v[168:169]
	s_nop 0
	v_addc_co_u32_e32 v139, vcc, 0, v179, vcc
	global_load_dwordx4 v[142:145], v[138:139], off
	v_add_u32_e32 v138, 48, v162
	v_mad_i64_i32 v[134:135], s[10:11], v138, s14, v[136:137]
	v_ashrrev_i32_e32 v139, 31, v138
	v_lshl_add_u64 v[182:183], v[134:135], 0, v[158:159]
	v_add_co_u32_e32 v134, vcc, 0x2000, v182
	v_lshlrev_b64 v[164:165], 12, v[138:139]
	s_nop 0
	v_addc_co_u32_e32 v135, vcc, 0, v183, vcc
	v_lshl_add_u64 v[184:185], v[160:161], 0, v[164:165]
	global_load_dwordx4 v[154:157], v[174:175], off
	global_load_dwordx4 v[138:141], v[184:185], off
	v_mad_i64_i32 v[172:173], s[10:11], v162, s14, 0
	global_load_dwordx4 v[134:137], v[134:135], off
	s_and_b32 s14, s84, 1
	v_ashrrev_i32_e32 v163, 31, v162
	s_bitcmp1_b32 s84, 0
	v_lshlrev_b64 v[170:171], 12, v[162:163]
	s_cselect_b64 s[10:11], -1, 0
	s_cmp_eq_u32 s14, 0
	s_cbranch_scc1 .LBB0_866
	v_lshl_add_u64 v[186:187], v[160:161], 0, v[170:171]
	global_load_dwordx4 v[204:207], v[186:187], off
	v_lshl_add_u64 v[186:187], s[8:9], 0, v[172:173]
	v_lshl_add_u64 v[186:187], v[186:187], 0, v[158:159]
	v_add_co_u32_e32 v186, vcc, 0x2000, v186
	s_nop 1
	v_addc_co_u32_e32 v187, vcc, 0, v187, vcc
	global_load_dwordx4 v[208:211], v[186:187], off
	s_waitcnt vmcnt(0)
	v_lshlrev_b32_e32 v186, 16, v204
	v_and_b32_e32 v187, 0xffff0000, v204
	v_lshlrev_b32_e32 v204, 16, v205
	v_and_b32_e32 v205, 0xffff0000, v205
	v_lshlrev_b32_e32 v212, 16, v208
	v_and_b32_e32 v213, 0xffff0000, v208
	v_lshlrev_b32_e32 v208, 16, v209
	v_and_b32_e32 v209, 0xffff0000, v209
	v_pk_fma_f32 v[208:209], v[128:129], v[208:209], v[204:205]
	v_pk_fma_f32 v[186:187], v[126:127], v[212:213], v[186:187]
	v_lshlrev_b32_e32 v204, 16, v206
	v_and_b32_e32 v205, 0xffff0000, v206
	v_lshlrev_b32_e32 v206, 16, v207
	v_and_b32_e32 v207, 0xffff0000, v207
	v_lshlrev_b32_e32 v212, 16, v210
	v_and_b32_e32 v213, 0xffff0000, v210
	v_lshlrev_b32_e32 v210, 16, v211
	v_and_b32_e32 v211, 0xffff0000, v211
	v_pk_fma_f32 v[210:211], v[132:133], v[210:211], v[206:207]
	v_pk_fma_f32 v[206:207], v[130:131], v[212:213], v[204:205]
	v_cvt_pk_bf16_f32 v204, v186, v187
	v_lshl_add_u64 v[186:187], s[6:7], 0, v[170:171]
	v_cvt_pk_bf16_f32 v205, v208, v209
	v_cvt_pk_bf16_f32 v206, v206, v207
	v_cvt_pk_bf16_f32 v207, v210, v211
	v_lshl_add_u64 v[186:187], v[186:187], 0, v[158:159]
	global_store_dwordx4 v[186:187], v[204:207], off nt
.LBB0_866:
	s_and_b32 s16, s84, 2
	s_bitcmp1_b32 s84, 1
	s_cselect_b64 s[14:15], -1, 0
	s_cmp_eq_u32 s16, 0
	s_cbranch_scc1 .LBB0_868
	s_waitcnt vmcnt(0)
	v_lshlrev_b32_e32 v186, 16, v154
	v_and_b32_e32 v187, 0xffff0000, v154
	v_lshlrev_b32_e32 v154, 16, v155
	v_and_b32_e32 v155, 0xffff0000, v155
	v_lshlrev_b32_e32 v204, 16, v150
	v_and_b32_e32 v205, 0xffff0000, v150
	v_lshlrev_b32_e32 v150, 16, v151
	v_and_b32_e32 v151, 0xffff0000, v151
	v_pk_fma_f32 v[154:155], v[120:121], v[150:151], v[154:155]
	v_pk_fma_f32 v[150:151], v[118:119], v[204:205], v[186:187]
	v_lshlrev_b32_e32 v186, 16, v156
	v_and_b32_e32 v187, 0xffff0000, v156
	v_lshlrev_b32_e32 v156, 16, v157
	v_and_b32_e32 v157, 0xffff0000, v157
	v_lshlrev_b32_e32 v204, 16, v152
	v_and_b32_e32 v205, 0xffff0000, v152
	v_lshlrev_b32_e32 v152, 16, v153
	v_and_b32_e32 v153, 0xffff0000, v153
	v_pk_fma_f32 v[156:157], v[124:125], v[152:153], v[156:157]
	v_pk_fma_f32 v[152:153], v[122:123], v[204:205], v[186:187]
	v_cvt_pk_bf16_f32 v150, v150, v151
	v_cvt_pk_bf16_f32 v151, v154, v155
	v_lshl_add_u64 v[154:155], s[6:7], 0, v[168:169]
	v_cvt_pk_bf16_f32 v152, v152, v153
	v_cvt_pk_bf16_f32 v153, v156, v157
	v_lshl_add_u64 v[154:155], v[4:5], 1, v[154:155]
	global_store_dwordx4 v[154:155], v[150:153], off nt
.LBB0_868:
	s_and_b32 s18, s84, 4
	s_bitcmp1_b32 s84, 2
	s_cselect_b64 s[16:17], -1, 0
	s_cmp_eq_u32 s18, 0
	s_cbranch_scc1 .LBB0_870
	s_waitcnt vmcnt(0)
	v_lshlrev_b32_e32 v150, 16, v146
	v_and_b32_e32 v151, 0xffff0000, v146
	v_lshlrev_b32_e32 v146, 16, v147
	v_and_b32_e32 v147, 0xffff0000, v147
	v_lshlrev_b32_e32 v152, 16, v142
	v_and_b32_e32 v153, 0xffff0000, v142
	v_lshlrev_b32_e32 v142, 16, v143
	v_and_b32_e32 v143, 0xffff0000, v143
	v_pk_fma_f32 v[146:147], v[112:113], v[142:143], v[146:147]
	v_pk_fma_f32 v[142:143], v[110:111], v[152:153], v[150:151]
	v_lshlrev_b32_e32 v150, 16, v148
	v_and_b32_e32 v151, 0xffff0000, v148
	v_lshlrev_b32_e32 v148, 16, v149
	v_and_b32_e32 v149, 0xffff0000, v149
	v_lshlrev_b32_e32 v152, 16, v144
	v_and_b32_e32 v153, 0xffff0000, v144
	v_lshlrev_b32_e32 v144, 16, v145
	v_and_b32_e32 v145, 0xffff0000, v145
	v_pk_fma_f32 v[148:149], v[116:117], v[144:145], v[148:149]
	v_pk_fma_f32 v[144:145], v[114:115], v[152:153], v[150:151]
	v_cvt_pk_bf16_f32 v142, v142, v143
	v_cvt_pk_bf16_f32 v143, v146, v147
	v_lshl_add_u64 v[146:147], s[6:7], 0, v[166:167]
	v_cvt_pk_bf16_f32 v144, v144, v145
	v_cvt_pk_bf16_f32 v145, v148, v149
	v_lshl_add_u64 v[146:147], v[4:5], 1, v[146:147]
	global_store_dwordx4 v[146:147], v[142:145], off nt
.LBB0_870:
	s_and_b32 s20, s84, 8
	s_bitcmp1_b32 s84, 3
	s_cselect_b64 s[18:19], -1, 0
	s_cmp_eq_u32 s20, 0
	s_cbranch_scc1 .LBB0_872
	s_waitcnt vmcnt(0)
	v_lshlrev_b32_e32 v142, 16, v138
	v_and_b32_e32 v143, 0xffff0000, v138
	v_lshlrev_b32_e32 v138, 16, v139
	v_and_b32_e32 v139, 0xffff0000, v139
	v_lshlrev_b32_e32 v144, 16, v134
	v_and_b32_e32 v145, 0xffff0000, v134
	v_lshlrev_b32_e32 v134, 16, v135
	v_and_b32_e32 v135, 0xffff0000, v135
	v_pk_fma_f32 v[138:139], v[104:105], v[134:135], v[138:139]
	v_pk_fma_f32 v[134:135], v[102:103], v[144:145], v[142:143]
	v_lshlrev_b32_e32 v142, 16, v140
	v_and_b32_e32 v143, 0xffff0000, v140
	v_lshlrev_b32_e32 v140, 16, v141
	v_and_b32_e32 v141, 0xffff0000, v141
	v_lshlrev_b32_e32 v144, 16, v136
	v_and_b32_e32 v145, 0xffff0000, v136
	v_lshlrev_b32_e32 v136, 16, v137
	v_and_b32_e32 v137, 0xffff0000, v137
	v_pk_fma_f32 v[140:141], v[108:109], v[136:137], v[140:141]
	v_pk_fma_f32 v[136:137], v[106:107], v[144:145], v[142:143]
	v_cvt_pk_bf16_f32 v134, v134, v135
	v_cvt_pk_bf16_f32 v135, v138, v139
	v_lshl_add_u64 v[138:139], s[6:7], 0, v[164:165]
	v_cvt_pk_bf16_f32 v136, v136, v137
	v_cvt_pk_bf16_f32 v137, v140, v141
	v_lshl_add_u64 v[138:139], v[4:5], 1, v[138:139]
	global_store_dwordx4 v[138:139], v[134:137], off nt

.LBB0_876:
	s_waitcnt vmcnt(0)
	v_lshlrev_b32_e32 v142, 16, v138
	v_and_b32_e32 v143, 0xffff0000, v138
	v_lshlrev_b32_e32 v138, 16, v139
	v_and_b32_e32 v139, 0xffff0000, v139
	v_lshlrev_b32_e32 v144, 16, v134
	v_and_b32_e32 v145, 0xffff0000, v134
	v_lshlrev_b32_e32 v134, 16, v135
	v_and_b32_e32 v135, 0xffff0000, v135
	v_pk_fma_f32 v[138:139], v[72:73], v[134:135], v[138:139]
	v_pk_fma_f32 v[134:135], v[70:71], v[144:145], v[142:143]
	v_lshlrev_b32_e32 v142, 16, v140
	v_and_b32_e32 v143, 0xffff0000, v140
	v_lshlrev_b32_e32 v140, 16, v141
	v_and_b32_e32 v141, 0xffff0000, v141
	v_lshlrev_b32_e32 v144, 16, v136
	v_and_b32_e32 v145, 0xffff0000, v136
	v_lshlrev_b32_e32 v136, 16, v137
	v_and_b32_e32 v137, 0xffff0000, v137
	v_pk_fma_f32 v[140:141], v[76:77], v[136:137], v[140:141]
	v_pk_fma_f32 v[136:137], v[74:75], v[144:145], v[142:143]
	v_cvt_pk_bf16_f32 v134, v134, v135
	v_cvt_pk_bf16_f32 v135, v138, v139
	v_lshl_add_u64 v[138:139], s[6:7], 0, v[164:165]
	v_cvt_pk_bf16_f32 v136, v136, v137
	v_cvt_pk_bf16_f32 v137, v140, v141
	v_lshl_add_u64 v[138:139], v[4:5], 1, v[138:139]
	global_store_dwordx4 v[138:139], v[134:137], off offset:256 nt
.LBB0_877:
	s_waitcnt vmcnt(2)
	s_nop 0
	v_add_u32_e32 v134, 0x80, v162
	v_ashrrev_i32_e32 v135, 31, v134
	s_movk_i32 s14, 0x3000
	v_mad_i64_i32 v[170:171], s[10:11], v134, s14, 0
	v_lshlrev_b64 v[168:169], 12, v[134:135]
	v_add_u32_e32 v134, 0x90, v162
	v_ashrrev_i32_e32 v135, 31, v134
	v_mov_b64_e32 v[136:137], s[8:9]
	s_waitcnt vmcnt(0)
	v_mad_i64_i32 v[138:139], s[10:11], v134, s14, v[136:137]
	v_lshlrev_b64 v[166:167], 12, v[134:135]
	v_add_u32_e32 v134, 0xa0, v162
	v_lshl_add_u64 v[174:175], v[138:139], 0, v[158:159]
	v_ashrrev_i32_e32 v135, 31, v134
	v_add_co_u32_e32 v138, vcc, 0x2000, v174
	v_lshlrev_b64 v[164:165], 12, v[134:135]
	s_nop 0
	v_addc_co_u32_e32 v139, vcc, 0, v175, vcc
	v_lshl_add_u64 v[178:179], v[160:161], 0, v[164:165]
	global_load_dwordx4 v[150:153], v[138:139], off
	global_load_dwordx4 v[146:149], v[178:179], off
	v_mad_i64_i32 v[138:139], s[10:11], v134, s14, v[136:137]
	v_lshl_add_u64 v[176:177], v[138:139], 0, v[158:159]
	v_add_co_u32_e32 v138, vcc, 0x2000, v176
	v_lshl_add_u64 v[172:173], v[160:161], 0, v[166:167]
	s_nop 0
	v_addc_co_u32_e32 v139, vcc, 0, v177, vcc
	global_load_dwordx4 v[142:145], v[138:139], off
	v_add_u32_e32 v138, 0xb0, v162
	v_mad_i64_i32 v[134:135], s[10:11], v138, s14, v[136:137]
	v_ashrrev_i32_e32 v139, 31, v138
	v_lshl_add_u64 v[180:181], v[134:135], 0, v[158:159]
	v_add_co_u32_e32 v134, vcc, 0x2000, v180
	v_lshlrev_b64 v[162:163], 12, v[138:139]
	s_nop 0
	v_addc_co_u32_e32 v135, vcc, 0, v181, vcc
	v_lshl_add_u64 v[182:183], v[160:161], 0, v[162:163]
	global_load_dwordx4 v[154:157], v[172:173], off
	global_load_dwordx4 v[138:141], v[182:183], off
	s_and_b32 s14, s84, 16
	global_load_dwordx4 v[134:137], v[134:135], off
	s_bitcmp1_b32 s84, 4
	s_cselect_b64 s[10:11], -1, 0
	s_cmp_eq_u32 s14, 0
	s_cbranch_scc1 .LBB0_879
	v_lshl_add_u64 v[204:205], s[8:9], 0, v[170:171]
	v_lshl_add_u64 v[204:205], v[204:205], 0, v[158:159]
	v_add_co_u32_e32 v204, vcc, 0x2000, v204
	v_lshl_add_u64 v[184:185], v[160:161], 0, v[168:169]
	s_nop 0
	v_addc_co_u32_e32 v205, vcc, 0, v205, vcc
	global_load_dwordx4 v[184:187], v[184:185], off
	s_nop 0
	global_load_dwordx4 v[204:207], v[204:205], off
	s_waitcnt vmcnt(1)
	v_lshlrev_b32_e32 v208, 16, v184
	v_and_b32_e32 v209, 0xffff0000, v184
	v_lshlrev_b32_e32 v184, 16, v185
	v_and_b32_e32 v185, 0xffff0000, v185
	s_waitcnt vmcnt(0)
	v_lshlrev_b32_e32 v210, 16, v204
	v_and_b32_e32 v211, 0xffff0000, v204
	v_lshlrev_b32_e32 v204, 16, v205
	v_and_b32_e32 v205, 0xffff0000, v205
	v_pk_fma_f32 v[204:205], v[48:49], v[204:205], v[184:185]
	v_pk_fma_f32 v[184:185], v[46:47], v[210:211], v[208:209]
	v_lshlrev_b32_e32 v208, 16, v186
	v_and_b32_e32 v209, 0xffff0000, v186
	v_lshlrev_b32_e32 v186, 16, v187
	v_and_b32_e32 v187, 0xffff0000, v187
	v_lshlrev_b32_e32 v210, 16, v206
	v_and_b32_e32 v211, 0xffff0000, v206
	v_lshlrev_b32_e32 v206, 16, v207
	v_and_b32_e32 v207, 0xffff0000, v207
	v_pk_fma_f32 v[206:207], v[52:53], v[206:207], v[186:187]
	v_pk_fma_f32 v[186:187], v[50:51], v[210:211], v[208:209]
	v_cvt_pk_bf16_f32 v184, v184, v185
	v_cvt_pk_bf16_f32 v185, v204, v205
	v_lshl_add_u64 v[204:205], s[6:7], 0, v[168:169]
	v_cvt_pk_bf16_f32 v186, v186, v187
	v_cvt_pk_bf16_f32 v187, v206, v207
	v_lshl_add_u64 v[204:205], v[204:205], 0, v[158:159]
	global_store_dwordx4 v[204:205], v[184:187], off nt
.LBB0_879:
	s_and_b32 s16, s84, 32
	s_bitcmp1_b32 s84, 5
	s_cselect_b64 s[14:15], -1, 0
	s_cmp_eq_u32 s16, 0
	s_cbranch_scc1 .LBB0_881
	s_waitcnt vmcnt(2)
	v_lshlrev_b32_e32 v184, 16, v154
	v_and_b32_e32 v185, 0xffff0000, v154
	v_lshlrev_b32_e32 v154, 16, v155
	v_and_b32_e32 v155, 0xffff0000, v155
	v_lshlrev_b32_e32 v186, 16, v150
	v_and_b32_e32 v187, 0xffff0000, v150
	v_lshlrev_b32_e32 v150, 16, v151
	v_and_b32_e32 v151, 0xffff0000, v151
	v_pk_fma_f32 v[154:155], v[40:41], v[150:151], v[154:155]
	v_pk_fma_f32 v[150:151], v[38:39], v[186:187], v[184:185]
	v_lshlrev_b32_e32 v184, 16, v156
	v_and_b32_e32 v185, 0xffff0000, v156
	v_lshlrev_b32_e32 v156, 16, v157
	v_and_b32_e32 v157, 0xffff0000, v157
	v_lshlrev_b32_e32 v186, 16, v152
	v_and_b32_e32 v187, 0xffff0000, v152
	v_lshlrev_b32_e32 v152, 16, v153
	v_and_b32_e32 v153, 0xffff0000, v153
	v_pk_fma_f32 v[156:157], v[44:45], v[152:153], v[156:157]
	v_pk_fma_f32 v[152:153], v[42:43], v[186:187], v[184:185]
	v_cvt_pk_bf16_f32 v150, v150, v151
	v_cvt_pk_bf16_f32 v151, v154, v155
	v_lshl_add_u64 v[154:155], s[6:7], 0, v[166:167]
	v_cvt_pk_bf16_f32 v152, v152, v153
	v_cvt_pk_bf16_f32 v153, v156, v157
	v_lshl_add_u64 v[154:155], v[4:5], 1, v[154:155]
	global_store_dwordx4 v[154:155], v[150:153], off nt
.LBB0_881:
	s_and_b32 s18, s84, 64
	s_bitcmp1_b32 s84, 6
	s_cselect_b64 s[16:17], -1, 0
	s_cmp_eq_u32 s18, 0
	s_cbranch_scc1 .LBB0_883
	s_waitcnt vmcnt(4)
	v_lshlrev_b32_e32 v150, 16, v146
	v_and_b32_e32 v151, 0xffff0000, v146
	v_lshlrev_b32_e32 v146, 16, v147
	v_and_b32_e32 v147, 0xffff0000, v147
	s_waitcnt vmcnt(3)
	v_lshlrev_b32_e32 v152, 16, v142
	v_and_b32_e32 v153, 0xffff0000, v142
	v_lshlrev_b32_e32 v142, 16, v143
	v_and_b32_e32 v143, 0xffff0000, v143
	v_pk_fma_f32 v[146:147], v[32:33], v[142:143], v[146:147]
	v_pk_fma_f32 v[142:143], v[30:31], v[152:153], v[150:151]
	v_lshlrev_b32_e32 v150, 16, v148
	v_and_b32_e32 v151, 0xffff0000, v148
	v_lshlrev_b32_e32 v148, 16, v149
	v_and_b32_e32 v149, 0xffff0000, v149
	v_lshlrev_b32_e32 v152, 16, v144
	v_and_b32_e32 v153, 0xffff0000, v144
	v_lshlrev_b32_e32 v144, 16, v145
	v_and_b32_e32 v145, 0xffff0000, v145
	v_pk_fma_f32 v[148:149], v[36:37], v[144:145], v[148:149]
	v_pk_fma_f32 v[144:145], v[34:35], v[152:153], v[150:151]
	v_cvt_pk_bf16_f32 v142, v142, v143
	v_cvt_pk_bf16_f32 v143, v146, v147
	v_lshl_add_u64 v[146:147], s[6:7], 0, v[164:165]
	v_cvt_pk_bf16_f32 v144, v144, v145
	v_cvt_pk_bf16_f32 v145, v148, v149
	v_lshl_add_u64 v[146:147], v[4:5], 1, v[146:147]
	global_store_dwordx4 v[146:147], v[142:145], off nt
.LBB0_883:
	s_and_b32 s20, s84, 0x80
	s_bitcmp1_b32 s84, 7
	s_cselect_b64 s[18:19], -1, 0
	s_cmp_eq_u32 s20, 0
	s_cbranch_scc1 .LBB0_885
	s_waitcnt vmcnt(1)
	v_lshlrev_b32_e32 v142, 16, v138
	v_and_b32_e32 v143, 0xffff0000, v138
	v_lshlrev_b32_e32 v138, 16, v139
	v_and_b32_e32 v139, 0xffff0000, v139
	s_waitcnt vmcnt(0)
	v_lshlrev_b32_e32 v144, 16, v134
	v_and_b32_e32 v145, 0xffff0000, v134
	v_lshlrev_b32_e32 v134, 16, v135
	v_and_b32_e32 v135, 0xffff0000, v135
	v_pk_fma_f32 v[138:139], v[24:25], v[134:135], v[138:139]
	v_pk_fma_f32 v[134:135], v[22:23], v[144:145], v[142:143]
	v_lshlrev_b32_e32 v142, 16, v140
	v_and_b32_e32 v143, 0xffff0000, v140
	v_lshlrev_b32_e32 v140, 16, v141
	v_and_b32_e32 v141, 0xffff0000, v141
	v_lshlrev_b32_e32 v144, 16, v136
	v_and_b32_e32 v145, 0xffff0000, v136
	v_lshlrev_b32_e32 v136, 16, v137
	v_and_b32_e32 v137, 0xffff0000, v137
	v_pk_fma_f32 v[140:141], v[28:29], v[136:137], v[140:141]
	v_pk_fma_f32 v[136:137], v[26:27], v[144:145], v[142:143]
	v_cvt_pk_bf16_f32 v134, v134, v135
	v_cvt_pk_bf16_f32 v135, v138, v139
	v_lshl_add_u64 v[138:139], s[6:7], 0, v[162:163]
	v_cvt_pk_bf16_f32 v136, v136, v137
	v_cvt_pk_bf16_f32 v137, v140, v141
	v_lshl_add_u64 v[138:139], v[4:5], 1, v[138:139]
	global_store_dwordx4 v[138:139], v[134:137], off nt

.LBB0_889:
	s_waitcnt vmcnt(0)
	v_lshlrev_b32_e32 v142, 16, v138
	v_and_b32_e32 v143, 0xffff0000, v138
	v_lshlrev_b32_e32 v138, 16, v139
	v_and_b32_e32 v139, 0xffff0000, v139
	v_lshlrev_b32_e32 v144, 16, v134
	v_and_b32_e32 v145, 0xffff0000, v134
	v_lshlrev_b32_e32 v134, 16, v135
	v_and_b32_e32 v135, 0xffff0000, v135
	v_pk_fma_f32 v[138:139], v[60:61], v[134:135], v[138:139]
	v_pk_fma_f32 v[134:135], v[58:59], v[144:145], v[142:143]
	v_lshlrev_b32_e32 v142, 16, v140
	v_and_b32_e32 v143, 0xffff0000, v140
	v_lshlrev_b32_e32 v140, 16, v141
	v_and_b32_e32 v141, 0xffff0000, v141
	v_lshlrev_b32_e32 v144, 16, v136
	v_and_b32_e32 v145, 0xffff0000, v136
	v_lshlrev_b32_e32 v136, 16, v137
	v_and_b32_e32 v137, 0xffff0000, v137
	v_pk_fma_f32 v[140:141], v[68:69], v[136:137], v[140:141]
	v_pk_fma_f32 v[136:137], v[66:67], v[144:145], v[142:143]
	v_cvt_pk_bf16_f32 v134, v134, v135
	v_cvt_pk_bf16_f32 v135, v138, v139
	v_lshl_add_u64 v[138:139], s[6:7], 0, v[162:163]
	v_cvt_pk_bf16_f32 v136, v136, v137
	v_cvt_pk_bf16_f32 v137, v140, v141
	v_lshl_add_u64 v[4:5], v[4:5], 1, v[138:139]
	global_store_dwordx4 v[4:5], v[134:137], off offset:256 nt

.LBB0_892:
	s_and_b64 vcc, exec, s[6:7]
	s_cbranch_vccz .LBB0_965
	v_readlane_b32 s10, v255, 18
	s_add_u32 s6, s12, 0x27900000
	s_addc_u32 s7, s13, 0
	v_add_u32_e32 v5, s10, v189
	v_lshl_add_u32 v2, v5, 3, 0
	v_add_u32_e32 v4, 0x20000, v2
	ds_read2_b64 v[176:179], v4 offset1:16
	s_add_u32 s8, s12, 0x33f00000
	v_lshlrev_b32_e32 v210, 3, v191
	s_addc_u32 s9, s13, 0
	v_add_u32_e32 v180, s70, v210
	s_waitcnt lgkmcnt(0)
	v_mul_f32_e32 v2, 0x3a000000, v176
	s_and_b32 s10, s3, -4
	s_nop 0
	v_mul_f32_e32 v134, v2, v2
	s_cmp_eq_u32 s10, 4
	v_fma_f32 v134, v177, s72, -v134
	ds_read2_b64 v[174:177], v4 offset0:32 offset1:48
	ds_read2_b64 v[170:173], v4 offset0:128 offset1:144
	ds_read2_b64 v[162:165], v4 offset0:160 offset1:176
	v_lshlrev_b32_e32 v4, 2, v180
	v_readlane_b32 s10, v254, 42
	v_readlane_b32 s11, v254, 43
	v_add_f32_e32 v134, 0x3727c5ac, v134
	v_add_u32_e32 v138, s10, v4
	v_add_u32_e32 v142, s11, v4
	v_or_b32_e32 v4, 16, v4
	v_rsq_f32_e32 v208, v134
	v_add_u32_e32 v134, s10, v4
	v_add_u32_e32 v4, s11, v4
	ds_read_b128 v[154:157], v134
	ds_read_b128 v[150:153], v4
	ds_read_b128 v[166:169], v138
	ds_read_b128 v[134:137], v138 offset:512
	ds_read_b128 v[158:161], v142
	ds_read_b128 v[146:149], v138 offset:528
	ds_read_b128 v[138:141], v142 offset:512
	ds_read_b128 v[142:145], v142 offset:528
	v_lshl_add_u32 v4, s3, 8, v180
	s_cselect_b64 vcc, -1, 0
	v_mov_b32_e32 v180, 0x3d800000
	v_readlane_b32 s10, v255, 23
	v_cndmask_b32_e32 v204, 1.0, v180, vcc
	v_cmp_gt_i32_e32 vcc, 2, v191
	v_readlane_b32 s11, v255, 24
	s_and_b64 s[10:11], s[10:11], vcc
	s_and_b32 s18, s84, 1
	v_lshl_add_u32 v206, s4, 8, v5
	v_mov_b32_e32 v205, v204
	v_ashrrev_i32_e32 v211, 31, v210
	s_cmp_eq_u32 s18, 0
	v_ashrrev_i32_e32 v5, 31, v4
	s_cbranch_scc1 .LBB0_900
	s_waitcnt lgkmcnt(5)
	v_pk_fma_f32 v[180:181], v[2:3], v[168:169], v[128:129] op_sel_hi:[0,1,1] neg_lo:[1,0,0] neg_hi:[1,0,0]
	v_pk_fma_f32 v[182:183], v[2:3], v[166:167], v[126:127] op_sel_hi:[0,1,1] neg_lo:[1,0,0] neg_hi:[1,0,0]
	s_waitcnt lgkmcnt(3)
	v_pk_fma_f32 v[180:181], v[208:209], v[180:181], v[160:161] op_sel_hi:[0,1,1]
	v_pk_fma_f32 v[184:185], v[208:209], v[182:183], v[158:159] op_sel_hi:[0,1,1]
	v_mov_b32_e32 v186, v204
	v_mov_b32_e32 v187, v204
	v_pk_mul_f32 v[182:183], v[186:187], v[180:181]
	v_pk_mul_f32 v[180:181], v[204:205], v[184:185]
	v_pk_fma_f32 v[184:185], v[2:3], v[156:157], v[132:133] op_sel_hi:[0,1,1] neg_lo:[1,0,0] neg_hi:[1,0,0]
	v_pk_fma_f32 v[212:213], v[2:3], v[154:155], v[130:131] op_sel_hi:[0,1,1] neg_lo:[1,0,0] neg_hi:[1,0,0]
	v_pk_fma_f32 v[184:185], v[208:209], v[184:185], v[152:153] op_sel_hi:[0,1,1]
	v_pk_fma_f32 v[212:213], v[208:209], v[212:213], v[150:151] op_sel_hi:[0,1,1]
	v_pk_mul_f32 v[186:187], v[186:187], v[184:185]
	v_pk_mul_f32 v[184:185], v[204:205], v[212:213]
	s_cmp_gt_i32 s3, 11
	s_mov_b64 s[16:17], -1
	s_cbranch_scc0 .LBB0_898
	s_and_saveexec_b64 s[16:17], s[10:11]
	s_cbranch_execz .LBB0_897
	v_ashrrev_i32_e32 v207, 31, v206
	v_lshlrev_b64 v[212:213], 6, v[206:207]
	v_lshl_add_u64 v[212:213], s[8:9], 0, v[212:213]
	v_lshl_add_u64 v[212:213], v[210:211], 2, v[212:213]
	global_store_dwordx4 v[212:213], v[180:183], off nt
	global_store_dwordx4 v[212:213], v[184:187], off offset:16 nt

.LBB0_898:
	s_andn2_b64 vcc, exec, s[16:17]
	s_cbranch_vccnz .LBB0_900
	v_cvt_pk_bf16_f32 v180, v180, v181
	v_cvt_pk_bf16_f32 v181, v182, v183
	v_cvt_pk_bf16_f32 v182, v184, v185
	v_mov_b64_e32 v[184:185], s[6:7]
	s_movk_i32 s16, 0x1800
	v_mad_i64_i32 v[184:185], s[16:17], v206, s16, v[184:185]
	v_cvt_pk_bf16_f32 v183, v186, v187
	v_lshl_add_u64 v[184:185], v[4:5], 1, v[184:185]
	global_store_dwordx4 v[184:185], v[180:183], off nt
.LBB0_900:
	v_mul_f32_e32 v186, 0x3a000000, v178
	v_mul_f32_e32 v178, v186, v186
	v_fma_f32 v178, v179, s72, -v178
	v_add_f32_e32 v178, 0x3727c5ac, v178
	v_rsq_f32_e32 v212, v178
	s_and_b32 s19, s84, 2
	s_cmp_eq_u32 s19, 0
	s_cbranch_scc1 .LBB0_907
	s_waitcnt lgkmcnt(5)
	v_pk_fma_f32 v[178:179], v[186:187], v[168:169], v[120:121] op_sel_hi:[0,1,1] neg_lo:[1,0,0] neg_hi:[1,0,0]
	v_pk_fma_f32 v[180:181], v[186:187], v[166:167], v[118:119] op_sel_hi:[0,1,1] neg_lo:[1,0,0] neg_hi:[1,0,0]
	s_waitcnt lgkmcnt(3)
	v_pk_fma_f32 v[178:179], v[212:213], v[178:179], v[160:161] op_sel_hi:[0,1,1]
	v_pk_fma_f32 v[182:183], v[212:213], v[180:181], v[158:159] op_sel_hi:[0,1,1]
	v_mov_b32_e32 v184, v204
	v_mov_b32_e32 v185, v204
	v_pk_mul_f32 v[180:181], v[184:185], v[178:179]
	v_pk_mul_f32 v[178:179], v[204:205], v[182:183]
	v_pk_fma_f32 v[182:183], v[186:187], v[156:157], v[124:125] op_sel_hi:[0,1,1] neg_lo:[1,0,0] neg_hi:[1,0,0]
	v_pk_fma_f32 v[214:215], v[186:187], v[154:155], v[122:123] op_sel_hi:[0,1,1] neg_lo:[1,0,0] neg_hi:[1,0,0]
	v_pk_fma_f32 v[182:183], v[212:213], v[182:183], v[152:153] op_sel_hi:[0,1,1]
	v_pk_fma_f32 v[214:215], v[212:213], v[214:215], v[150:151] op_sel_hi:[0,1,1]
	v_pk_mul_f32 v[184:185], v[184:185], v[182:183]
	v_pk_mul_f32 v[182:183], v[204:205], v[214:215]
	v_add_u32_e32 v214, 16, v206
	s_cmp_lt_i32 s3, 12
	s_mov_b64 s[16:17], -1
	s_cbranch_scc1 .LBB0_905
	s_and_saveexec_b64 s[16:17], s[10:11]
	s_cbranch_execz .LBB0_904
	v_ashrrev_i32_e32 v215, 31, v214
	v_lshlrev_b64 v[216:217], 6, v[214:215]
	v_lshl_add_u64 v[216:217], s[8:9], 0, v[216:217]
	v_lshl_add_u64 v[216:217], v[210:211], 2, v[216:217]
	global_store_dwordx4 v[216:217], v[178:181], off nt
	global_store_dwordx4 v[216:217], v[182:185], off offset:16 nt

.LBB0_905:
	s_andn2_b64 vcc, exec, s[16:17]
	s_cbranch_vccnz .LBB0_907
	v_cvt_pk_bf16_f32 v178, v178, v179
	v_cvt_pk_bf16_f32 v179, v180, v181
	v_cvt_pk_bf16_f32 v180, v182, v183
	v_mov_b64_e32 v[182:183], s[6:7]
	s_movk_i32 s16, 0x1800
	v_mad_i64_i32 v[182:183], s[16:17], v214, s16, v[182:183]
	v_cvt_pk_bf16_f32 v181, v184, v185
	v_lshl_add_u64 v[182:183], v[4:5], 1, v[182:183]
	global_store_dwordx4 v[182:183], v[178:181], off nt
.LBB0_907:
	s_waitcnt lgkmcnt(10)
	v_mul_f32_e32 v214, 0x3a000000, v174
	v_mul_f32_e32 v174, v214, v214
	v_fma_f32 v174, v175, s72, -v174
	v_add_f32_e32 v174, 0x3727c5ac, v174
	v_rsq_f32_e32 v216, v174
	s_and_b32 s20, s84, 4
	s_cmp_eq_u32 s20, 0
	s_cbranch_scc1 .LBB0_914
	s_waitcnt lgkmcnt(5)
	v_pk_fma_f32 v[174:175], v[214:215], v[168:169], v[112:113] op_sel_hi:[0,1,1] neg_lo:[1,0,0] neg_hi:[1,0,0]
	s_waitcnt lgkmcnt(3)
	v_pk_fma_f32 v[174:175], v[216:217], v[174:175], v[160:161] op_sel_hi:[0,1,1]
	v_mov_b32_e32 v182, v204
	v_mov_b32_e32 v183, v204
	v_pk_fma_f32 v[178:179], v[214:215], v[166:167], v[110:111] op_sel_hi:[0,1,1] neg_lo:[1,0,0] neg_hi:[1,0,0]
	v_pk_mul_f32 v[180:181], v[182:183], v[174:175]
	v_pk_fma_f32 v[174:175], v[214:215], v[156:157], v[116:117] op_sel_hi:[0,1,1] neg_lo:[1,0,0] neg_hi:[1,0,0]
	v_pk_fma_f32 v[184:185], v[214:215], v[154:155], v[114:115] op_sel_hi:[0,1,1] neg_lo:[1,0,0] neg_hi:[1,0,0]
	v_pk_fma_f32 v[178:179], v[216:217], v[178:179], v[158:159] op_sel_hi:[0,1,1]
	v_pk_fma_f32 v[174:175], v[216:217], v[174:175], v[152:153] op_sel_hi:[0,1,1]
	v_pk_fma_f32 v[218:219], v[216:217], v[184:185], v[150:151] op_sel_hi:[0,1,1]
	v_pk_mul_f32 v[178:179], v[204:205], v[178:179]
	v_pk_mul_f32 v[184:185], v[182:183], v[174:175]
	v_pk_mul_f32 v[182:183], v[204:205], v[218:219]
	v_add_u32_e32 v174, 32, v206
	s_cmp_lt_i32 s3, 12
	s_mov_b64 s[16:17], -1
	s_cbranch_scc1 .LBB0_912
	s_and_saveexec_b64 s[16:17], s[10:11]
	s_cbranch_execz .LBB0_911
	v_ashrrev_i32_e32 v175, 31, v174
	v_lshlrev_b64 v[218:219], 6, v[174:175]
	v_lshl_add_u64 v[218:219], s[8:9], 0, v[218:219]
	v_lshl_add_u64 v[218:219], v[210:211], 2, v[218:219]
	global_store_dwordx4 v[218:219], v[178:181], off nt
	global_store_dwordx4 v[218:219], v[182:185], off offset:16 nt

.LBB0_912:
	s_andn2_b64 vcc, exec, s[16:17]
	s_cbranch_vccnz .LBB0_914
	v_cvt_pk_bf16_f32 v178, v178, v179
	v_cvt_pk_bf16_f32 v179, v180, v181
	v_cvt_pk_bf16_f32 v180, v182, v183
	v_mov_b64_e32 v[182:183], s[6:7]
	s_movk_i32 s16, 0x1800
	v_mad_i64_i32 v[174:175], s[16:17], v174, s16, v[182:183]
	v_cvt_pk_bf16_f32 v181, v184, v185
	v_lshl_add_u64 v[174:175], v[4:5], 1, v[174:175]
	global_store_dwordx4 v[174:175], v[178:181], off nt
.LBB0_914:
	v_mul_f32_e32 v182, 0x3a000000, v176
	v_mul_f32_e32 v174, v182, v182
	v_fma_f32 v174, v177, s72, -v174
	v_add_f32_e32 v174, 0x3727c5ac, v174
	v_rsq_f32_e32 v184, v174
	s_and_b32 s21, s84, 8
	s_cmp_eq_u32 s21, 0
	s_cbranch_scc1 .LBB0_921
	s_waitcnt lgkmcnt(5)
	v_pk_fma_f32 v[174:175], v[182:183], v[168:169], v[104:105] op_sel_hi:[0,1,1] neg_lo:[1,0,0] neg_hi:[1,0,0]
	v_pk_fma_f32 v[176:177], v[182:183], v[166:167], v[102:103] op_sel_hi:[0,1,1] neg_lo:[1,0,0] neg_hi:[1,0,0]
	s_waitcnt lgkmcnt(3)
	v_pk_fma_f32 v[174:175], v[174:175], v[184:185], v[160:161] op_sel_hi:[1,0,1]
	v_pk_fma_f32 v[178:179], v[176:177], v[184:185], v[158:159] op_sel_hi:[1,0,1]
	v_mov_b32_e32 v180, v204
	v_mov_b32_e32 v181, v204
	v_pk_mul_f32 v[176:177], v[180:181], v[174:175]
	v_pk_mul_f32 v[174:175], v[204:205], v[178:179]
	v_pk_fma_f32 v[178:179], v[182:183], v[156:157], v[108:109] op_sel_hi:[0,1,1] neg_lo:[1,0,0] neg_hi:[1,0,0]
	v_pk_fma_f32 v[218:219], v[182:183], v[154:155], v[106:107] op_sel_hi:[0,1,1] neg_lo:[1,0,0] neg_hi:[1,0,0]
	v_pk_fma_f32 v[178:179], v[184:185], v[178:179], v[152:153] op_sel_hi:[0,1,1]
	v_pk_fma_f32 v[218:219], v[184:185], v[218:219], v[150:151] op_sel_hi:[0,1,1]
	v_pk_mul_f32 v[180:181], v[180:181], v[178:179]
	v_pk_mul_f32 v[178:179], v[204:205], v[218:219]
	v_add_u32_e32 v218, 48, v206
	s_cmp_lt_i32 s3, 12
	s_mov_b64 s[16:17], -1
	s_cbranch_scc1 .LBB0_919
	s_and_saveexec_b64 s[16:17], s[10:11]
	s_cbranch_execz .LBB0_918
	v_ashrrev_i32_e32 v219, 31, v218
	v_lshlrev_b64 v[222:223], 6, v[218:219]
	v_lshl_add_u64 v[222:223], s[8:9], 0, v[222:223]
	v_lshl_add_u64 v[222:223], v[210:211], 2, v[222:223]
	global_store_dwordx4 v[222:223], v[174:177], off nt
	global_store_dwordx4 v[222:223], v[178:181], off offset:16 nt

.LBB0_919:
	s_andn2_b64 vcc, exec, s[16:17]
	s_cbranch_vccnz .LBB0_921
	v_cvt_pk_bf16_f32 v174, v174, v175
	v_cvt_pk_bf16_f32 v175, v176, v177
	v_cvt_pk_bf16_f32 v176, v178, v179
	v_mov_b64_e32 v[178:179], s[6:7]
	s_movk_i32 s16, 0x1800
	v_mad_i64_i32 v[178:179], s[16:17], v218, s16, v[178:179]
	v_cvt_pk_bf16_f32 v177, v180, v181
	v_lshl_add_u64 v[178:179], v[4:5], 1, v[178:179]
	global_store_dwordx4 v[178:179], v[174:177], off nt
.LBB0_921:
	s_waitcnt lgkmcnt(9)
	v_mul_f32_e32 v220, 0x3a000000, v170
	v_mul_f32_e32 v170, v220, v220
	v_fma_f32 v170, v171, s72, -v170
	v_add_f32_e32 v170, 0x3727c5ac, v170
	v_rsq_f32_e32 v222, v170
	s_and_b32 s24, s84, 16
	s_cmp_eq_u32 s24, 0
	v_add_u32_e32 v218, 0x80, v206
	s_cbranch_scc1 .LBB0_928
	s_waitcnt lgkmcnt(5)
	v_pk_fma_f32 v[170:171], v[220:221], v[168:169], v[48:49] op_sel_hi:[0,1,1] neg_lo:[1,0,0] neg_hi:[1,0,0]
	s_waitcnt lgkmcnt(3)
	v_pk_fma_f32 v[170:171], v[170:171], v[222:223], v[160:161] op_sel_hi:[1,0,1]
	v_mov_b32_e32 v178, v204
	v_mov_b32_e32 v179, v204
	v_pk_fma_f32 v[174:175], v[220:221], v[166:167], v[46:47] op_sel_hi:[0,1,1] neg_lo:[1,0,0] neg_hi:[1,0,0]
	v_pk_mul_f32 v[176:177], v[178:179], v[170:171]
	v_pk_fma_f32 v[170:171], v[220:221], v[156:157], v[52:53] op_sel_hi:[0,1,1] neg_lo:[1,0,0] neg_hi:[1,0,0]
	v_pk_fma_f32 v[180:181], v[220:221], v[154:155], v[50:51] op_sel_hi:[0,1,1] neg_lo:[1,0,0] neg_hi:[1,0,0]
	v_pk_fma_f32 v[174:175], v[174:175], v[222:223], v[158:159] op_sel_hi:[1,0,1]
	v_pk_fma_f32 v[170:171], v[222:223], v[170:171], v[152:153] op_sel_hi:[0,1,1]
	v_pk_fma_f32 v[224:225], v[222:223], v[180:181], v[150:151] op_sel_hi:[0,1,1]
	v_pk_mul_f32 v[174:175], v[204:205], v[174:175]
	v_pk_mul_f32 v[180:181], v[178:179], v[170:171]
	v_pk_mul_f32 v[178:179], v[204:205], v[224:225]
	s_cmp_lt_i32 s3, 12
	s_mov_b64 s[16:17], -1
	s_cbranch_scc1 .LBB0_926
	s_and_saveexec_b64 s[16:17], s[10:11]
	s_cbranch_execz .LBB0_925
	v_ashrrev_i32_e32 v219, 31, v218
	v_lshlrev_b64 v[170:171], 6, v[218:219]
	v_lshl_add_u64 v[170:171], s[8:9], 0, v[170:171]
	v_lshl_add_u64 v[170:171], v[210:211], 2, v[170:171]
	global_store_dwordx4 v[170:171], v[174:177], off nt
	global_store_dwordx4 v[170:171], v[178:181], off offset:16 nt

.LBB0_926:
	s_andn2_b64 vcc, exec, s[16:17]
	s_cbranch_vccnz .LBB0_928
	v_mov_b64_e32 v[170:171], s[6:7]
	s_movk_i32 s16, 0x1800
	v_mad_i64_i32 v[170:171], s[16:17], v218, s16, v[170:171]
	v_cvt_pk_bf16_f32 v174, v174, v175
	v_cvt_pk_bf16_f32 v175, v176, v177
	v_cvt_pk_bf16_f32 v176, v178, v179
	v_cvt_pk_bf16_f32 v177, v180, v181
	v_lshl_add_u64 v[170:171], v[4:5], 1, v[170:171]
	global_store_dwordx4 v[170:171], v[174:177], off nt
.LBB0_928:
	v_mul_f32_e32 v178, 0x3a000000, v172
	v_mul_f32_e32 v170, v178, v178
	v_fma_f32 v170, v173, s72, -v170
	v_add_f32_e32 v170, 0x3727c5ac, v170
	v_rsq_f32_e32 v180, v170
	s_and_b32 s25, s84, 32
	s_cmp_eq_u32 s25, 0
	s_cbranch_scc1 .LBB0_935
	s_waitcnt lgkmcnt(5)
	v_xor_b32_e32 v171, 0x80000000, v169
	v_xor_b32_e32 v170, 0x80000000, v168
	v_pk_fma_f32 v[170:171], v[170:171], v[178:179], v[40:41] op_sel_hi:[1,0,1]
	v_pk_fma_f32 v[172:173], v[166:167], v[178:179], v[38:39] op_sel_hi:[1,0,1] neg_lo:[1,0,0] neg_hi:[1,0,0]
	s_waitcnt lgkmcnt(3)
	v_pk_fma_f32 v[174:175], v[170:171], v[180:181], v[160:161] op_sel_hi:[1,0,1]
	v_mov_b32_e32 v176, v204
	v_mov_b32_e32 v177, v204
	v_pk_fma_f32 v[170:171], v[172:173], v[180:181], v[158:159] op_sel_hi:[1,0,1]
	v_pk_mul_f32 v[172:173], v[176:177], v[174:175]
	v_pk_fma_f32 v[174:175], v[178:179], v[156:157], v[44:45] op_sel_hi:[0,1,1] neg_lo:[1,0,0] neg_hi:[1,0,0]
	v_pk_fma_f32 v[224:225], v[178:179], v[154:155], v[42:43] op_sel_hi:[0,1,1] neg_lo:[1,0,0] neg_hi:[1,0,0]
	v_pk_fma_f32 v[174:175], v[174:175], v[180:181], v[152:153] op_sel_hi:[1,0,1]
	v_pk_fma_f32 v[224:225], v[224:225], v[180:181], v[150:151] op_sel_hi:[1,0,1]
	v_pk_mul_f32 v[170:171], v[204:205], v[170:171]
	v_pk_mul_f32 v[176:177], v[176:177], v[174:175]
	v_pk_mul_f32 v[174:175], v[204:205], v[224:225]
	v_add_u32_e32 v224, 0x90, v206
	s_cmp_lt_i32 s3, 12
	s_mov_b64 s[16:17], -1
	s_cbranch_scc1 .LBB0_933
	s_and_saveexec_b64 s[16:17], s[10:11]
	s_cbranch_execz .LBB0_932
	v_ashrrev_i32_e32 v225, 31, v224
	v_lshlrev_b64 v[226:227], 6, v[224:225]
	v_lshl_add_u64 v[226:227], s[8:9], 0, v[226:227]
	v_lshl_add_u64 v[226:227], v[210:211], 2, v[226:227]
	global_store_dwordx4 v[226:227], v[170:173], off nt
	global_store_dwordx4 v[226:227], v[174:177], off offset:16 nt

.LBB0_933:
	s_andn2_b64 vcc, exec, s[16:17]
	s_cbranch_vccnz .LBB0_935
	v_cvt_pk_bf16_f32 v170, v170, v171
	v_cvt_pk_bf16_f32 v171, v172, v173
	v_cvt_pk_bf16_f32 v172, v174, v175
	v_mov_b64_e32 v[174:175], s[6:7]
	s_movk_i32 s16, 0x1800
	v_mad_i64_i32 v[174:175], s[16:17], v224, s16, v[174:175]
	v_cvt_pk_bf16_f32 v173, v176, v177
	v_lshl_add_u64 v[174:175], v[4:5], 1, v[174:175]
	global_store_dwordx4 v[174:175], v[170:173], off nt
.LBB0_935:
	s_waitcnt lgkmcnt(8)
	v_mul_f32_e32 v162, 0x3a000000, v162
	v_mul_f32_e32 v170, v162, v162
	v_fma_f32 v163, v163, s72, -v170
	v_add_f32_e32 v163, 0x3727c5ac, v163
	v_rsq_f32_e32 v224, v163
	s_and_b32 s26, s84, 64
	s_cmp_eq_u32 s26, 0
	s_cbranch_scc1 .LBB0_942
	s_waitcnt lgkmcnt(5)
	v_xor_b32_e32 v171, 0x80000000, v169
	v_xor_b32_e32 v170, 0x80000000, v168
	v_pk_fma_f32 v[170:171], v[170:171], v[162:163], v[32:33] op_sel_hi:[1,0,1]
	v_pk_fma_f32 v[172:173], v[166:167], v[162:163], v[30:31] op_sel_hi:[1,0,1] neg_lo:[1,0,0] neg_hi:[1,0,0]
	s_waitcnt lgkmcnt(3)
	v_pk_fma_f32 v[174:175], v[170:171], v[224:225], v[160:161] op_sel_hi:[1,0,1]
	v_mov_b32_e32 v176, v204
	v_mov_b32_e32 v177, v204
	v_pk_fma_f32 v[170:171], v[172:173], v[224:225], v[158:159] op_sel_hi:[1,0,1]
	v_pk_mul_f32 v[172:173], v[176:177], v[174:175]
	v_pk_fma_f32 v[174:175], v[162:163], v[156:157], v[36:37] op_sel_hi:[0,1,1] neg_lo:[1,0,0] neg_hi:[1,0,0]
	v_pk_fma_f32 v[226:227], v[162:163], v[154:155], v[34:35] op_sel_hi:[0,1,1] neg_lo:[1,0,0] neg_hi:[1,0,0]
	v_pk_fma_f32 v[174:175], v[174:175], v[224:225], v[152:153] op_sel_hi:[1,0,1]
	v_pk_fma_f32 v[226:227], v[226:227], v[224:225], v[150:151] op_sel_hi:[1,0,1]
	v_pk_mul_f32 v[170:171], v[204:205], v[170:171]
	v_pk_mul_f32 v[176:177], v[176:177], v[174:175]
	v_pk_mul_f32 v[174:175], v[204:205], v[226:227]
	v_add_u32_e32 v226, 0xa0, v206
	s_cmp_lt_i32 s3, 12
	s_mov_b64 s[16:17], -1
	s_cbranch_scc1 .LBB0_940
	s_and_saveexec_b64 s[16:17], s[10:11]
	s_cbranch_execz .LBB0_939
	v_ashrrev_i32_e32 v227, 31, v226
	v_lshlrev_b64 v[232:233], 6, v[226:227]
	v_lshl_add_u64 v[232:233], s[8:9], 0, v[232:233]
	v_lshl_add_u64 v[232:233], v[210:211], 2, v[232:233]
	global_store_dwordx4 v[232:233], v[170:173], off nt
	global_store_dwordx4 v[232:233], v[174:177], off offset:16 nt

.LBB0_940:
	s_andn2_b64 vcc, exec, s[16:17]
	s_cbranch_vccnz .LBB0_942
	v_cvt_pk_bf16_f32 v170, v170, v171
	v_cvt_pk_bf16_f32 v171, v172, v173
	v_cvt_pk_bf16_f32 v172, v174, v175
	v_mov_b64_e32 v[174:175], s[6:7]
	s_movk_i32 s16, 0x1800
	v_mad_i64_i32 v[174:175], s[16:17], v226, s16, v[174:175]
	v_cvt_pk_bf16_f32 v173, v176, v177
	v_lshl_add_u64 v[174:175], v[4:5], 1, v[174:175]
	global_store_dwordx4 v[174:175], v[170:173], off nt
.LBB0_942:
	v_mul_f32_e32 v164, 0x3a000000, v164
	v_mul_f32_e32 v163, v164, v164
	v_fma_f32 v163, v165, s72, -v163
	v_add_f32_e32 v163, 0x3727c5ac, v163
	v_rsq_f32_e32 v170, v163
	s_and_b32 s27, s84, 0x80
	s_cmp_eq_u32 s27, 0
	s_cbranch_scc1 .LBB0_949
	s_waitcnt lgkmcnt(5)
	v_xor_b32_e32 v169, 0x80000000, v169
	v_xor_b32_e32 v168, 0x80000000, v168
	v_xor_b32_e32 v157, 0x80000000, v157
	v_xor_b32_e32 v156, 0x80000000, v156
	v_pk_fma_f32 v[168:169], v[168:169], v[164:165], v[24:25] op_sel_hi:[1,0,1]
	v_pk_fma_f32 v[166:167], v[166:167], v[164:165], v[22:23] op_sel_hi:[1,0,1] neg_lo:[1,0,0] neg_hi:[1,0,0]
	v_pk_fma_f32 v[156:157], v[156:157], v[164:165], v[28:29] op_sel_hi:[1,0,1]
	v_pk_fma_f32 v[154:155], v[154:155], v[164:165], v[26:27] op_sel_hi:[1,0,1] neg_lo:[1,0,0] neg_hi:[1,0,0]
	s_waitcnt lgkmcnt(3)
	v_pk_fma_f32 v[160:161], v[168:169], v[170:171], v[160:161] op_sel_hi:[1,0,1]
	v_pk_fma_f32 v[158:159], v[166:167], v[170:171], v[158:159] op_sel_hi:[1,0,1]
	v_mov_b32_e32 v166, v204
	v_mov_b32_e32 v167, v204
	v_pk_fma_f32 v[152:153], v[156:157], v[170:171], v[152:153] op_sel_hi:[1,0,1]
	v_pk_fma_f32 v[150:151], v[154:155], v[170:171], v[150:151] op_sel_hi:[1,0,1]
	v_pk_mul_f32 v[158:159], v[204:205], v[158:159]
	v_pk_mul_f32 v[160:161], v[166:167], v[160:161]
	v_pk_mul_f32 v[150:151], v[204:205], v[150:151]
	v_pk_mul_f32 v[152:153], v[166:167], v[152:153]
	v_add_u32_e32 v154, 0xb0, v206
	s_cmp_lt_i32 s3, 12
	s_mov_b64 s[16:17], -1
	s_cbranch_scc1 .LBB0_947
	s_and_saveexec_b64 s[16:17], s[10:11]
	s_cbranch_execz .LBB0_946
	v_ashrrev_i32_e32 v155, 31, v154
	v_lshlrev_b64 v[156:157], 6, v[154:155]
	v_lshl_add_u64 v[156:157], s[8:9], 0, v[156:157]
	v_lshl_add_u64 v[156:157], v[210:211], 2, v[156:157]
	global_store_dwordx4 v[156:157], v[158:161], off nt
	global_store_dwordx4 v[156:157], v[150:153], off offset:16 nt

.LBB0_947:
	s_andn2_b64 vcc, exec, s[16:17]
	s_cbranch_vccnz .LBB0_949
	v_cvt_pk_bf16_f32 v156, v158, v159
	v_cvt_pk_bf16_f32 v158, v150, v151
	v_mov_b64_e32 v[150:151], s[6:7]
	s_movk_i32 s8, 0x1800
	v_mad_i64_i32 v[150:151], s[8:9], v154, s8, v[150:151]
	v_cvt_pk_bf16_f32 v157, v160, v161
	v_cvt_pk_bf16_f32 v159, v152, v153
	v_lshl_add_u64 v[150:151], v[4:5], 1, v[150:151]
	global_store_dwordx4 v[150:151], v[156:159], off nt
.LBB0_949:
	s_cmp_lg_u32 s18, 0
	s_cselect_b64 s[10:11], -1, 0
	s_cmp_lt_i32 s3, 12
	s_cselect_b64 s[8:9], -1, 0
	s_and_b64 s[10:11], s[10:11], s[8:9]
	s_andn2_b64 vcc, exec, s[10:11]
	s_cbranch_vccnz .LBB0_951
	s_waitcnt lgkmcnt(2)
	v_pk_fma_f32 v[150:151], v[2:3], v[148:149], v[100:101] op_sel_hi:[0,1,1] neg_lo:[1,0,0] neg_hi:[1,0,0]
	s_waitcnt lgkmcnt(0)
	v_pk_fma_f32 v[150:151], v[208:209], v[150:151], v[144:145] op_sel_hi:[0,1,1]
	v_mov_b32_e32 v154, v204
	v_mov_b32_e32 v155, v204
	v_pk_mul_f32 v[156:157], v[154:155], v[150:151]
	v_pk_fma_f32 v[150:151], v[2:3], v[136:137], v[96:97] op_sel_hi:[0,1,1] neg_lo:[1,0,0] neg_hi:[1,0,0]
	v_pk_fma_f32 v[158:159], v[2:3], v[134:135], v[94:95] op_sel_hi:[0,1,1] neg_lo:[1,0,0] neg_hi:[1,0,0]
	v_pk_fma_f32 v[150:151], v[208:209], v[150:151], v[140:141] op_sel_hi:[0,1,1]
	v_pk_fma_f32 v[158:159], v[208:209], v[158:159], v[138:139] op_sel_hi:[0,1,1]
	v_pk_fma_f32 v[152:153], v[2:3], v[146:147], v[98:99] op_sel_hi:[0,1,1] neg_lo:[1,0,0] neg_hi:[1,0,0]
	v_pk_mul_f32 v[154:155], v[154:155], v[150:151]
	v_pk_mul_f32 v[150:151], v[204:205], v[158:159]
	v_pk_fma_f32 v[152:153], v[208:209], v[152:153], v[142:143] op_sel_hi:[0,1,1]
	v_cvt_pk_bf16_f32 v150, v150, v151
	v_cvt_pk_bf16_f32 v151, v154, v155
	v_mov_b64_e32 v[154:155], s[6:7]
	s_movk_i32 s10, 0x1800
	v_pk_mul_f32 v[152:153], v[204:205], v[152:153]
	v_mad_i64_i32 v[154:155], s[10:11], v206, s10, v[154:155]
	v_cvt_pk_bf16_f32 v152, v152, v153
	v_cvt_pk_bf16_f32 v153, v156, v157
	v_lshl_add_u64 v[154:155], v[4:5], 1, v[154:155]
	global_store_dwordx4 v[154:155], v[150:153], off offset:256 nt
.LBB0_951:
	s_cmp_lg_u32 s19, 0
	s_cselect_b64 s[10:11], -1, 0
	s_and_b64 s[10:11], s[10:11], s[8:9]
	s_andn2_b64 vcc, exec, s[10:11]
	s_cbranch_vccnz .LBB0_953
	s_waitcnt lgkmcnt(2)
	v_pk_fma_f32 v[150:151], v[186:187], v[148:149], v[92:93] op_sel_hi:[0,1,1] neg_lo:[1,0,0] neg_hi:[1,0,0]
	s_waitcnt lgkmcnt(0)
	v_pk_fma_f32 v[150:151], v[212:213], v[150:151], v[144:145] op_sel_hi:[0,1,1]
	v_mov_b32_e32 v154, v204
	v_mov_b32_e32 v155, v204
	v_pk_mul_f32 v[156:157], v[154:155], v[150:151]
	v_pk_fma_f32 v[150:151], v[186:187], v[136:137], v[88:89] op_sel_hi:[0,1,1] neg_lo:[1,0,0] neg_hi:[1,0,0]
	v_pk_fma_f32 v[158:159], v[186:187], v[134:135], v[86:87] op_sel_hi:[0,1,1] neg_lo:[1,0,0] neg_hi:[1,0,0]
	v_pk_fma_f32 v[150:151], v[212:213], v[150:151], v[140:141] op_sel_hi:[0,1,1]
	v_pk_fma_f32 v[158:159], v[212:213], v[158:159], v[138:139] op_sel_hi:[0,1,1]
	v_pk_fma_f32 v[152:153], v[186:187], v[146:147], v[90:91] op_sel_hi:[0,1,1] neg_lo:[1,0,0] neg_hi:[1,0,0]
	v_pk_mul_f32 v[154:155], v[154:155], v[150:151]
	v_pk_mul_f32 v[150:151], v[204:205], v[158:159]
	v_pk_fma_f32 v[152:153], v[212:213], v[152:153], v[142:143] op_sel_hi:[0,1,1]
	v_add_u32_e32 v2, 16, v206
	v_cvt_pk_bf16_f32 v150, v150, v151
	v_cvt_pk_bf16_f32 v151, v154, v155
	v_mov_b64_e32 v[154:155], s[6:7]
	s_movk_i32 s10, 0x1800
	v_pk_mul_f32 v[152:153], v[204:205], v[152:153]
	v_mad_i64_i32 v[154:155], s[10:11], v2, s10, v[154:155]
	v_cvt_pk_bf16_f32 v152, v152, v153
	v_cvt_pk_bf16_f32 v153, v156, v157
	v_lshl_add_u64 v[154:155], v[4:5], 1, v[154:155]
	global_store_dwordx4 v[154:155], v[150:153], off offset:256 nt
.LBB0_953:
	s_cmp_lg_u32 s20, 0
	s_cselect_b64 s[10:11], -1, 0
	s_and_b64 s[10:11], s[10:11], s[8:9]
	s_andn2_b64 vcc, exec, s[10:11]
	s_cbranch_vccnz .LBB0_955
	s_waitcnt lgkmcnt(2)
	v_pk_fma_f32 v[150:151], v[214:215], v[148:149], v[84:85] op_sel_hi:[0,1,1] neg_lo:[1,0,0] neg_hi:[1,0,0]
	s_waitcnt lgkmcnt(0)
	v_pk_fma_f32 v[150:151], v[216:217], v[150:151], v[144:145] op_sel_hi:[0,1,1]
	v_mov_b32_e32 v154, v204
	v_mov_b32_e32 v155, v204
	v_pk_mul_f32 v[156:157], v[154:155], v[150:151]
	v_pk_fma_f32 v[150:151], v[214:215], v[136:137], v[80:81] op_sel_hi:[0,1,1] neg_lo:[1,0,0] neg_hi:[1,0,0]
	v_pk_fma_f32 v[158:159], v[214:215], v[134:135], v[78:79] op_sel_hi:[0,1,1] neg_lo:[1,0,0] neg_hi:[1,0,0]
	v_pk_fma_f32 v[150:151], v[216:217], v[150:151], v[140:141] op_sel_hi:[0,1,1]
	v_pk_fma_f32 v[158:159], v[216:217], v[158:159], v[138:139] op_sel_hi:[0,1,1]
	v_pk_fma_f32 v[152:153], v[214:215], v[146:147], v[82:83] op_sel_hi:[0,1,1] neg_lo:[1,0,0] neg_hi:[1,0,0]
	v_pk_mul_f32 v[154:155], v[154:155], v[150:151]
	v_pk_mul_f32 v[150:151], v[204:205], v[158:159]
	v_pk_fma_f32 v[152:153], v[216:217], v[152:153], v[142:143] op_sel_hi:[0,1,1]
	v_add_u32_e32 v2, 32, v206
	v_cvt_pk_bf16_f32 v150, v150, v151
	v_cvt_pk_bf16_f32 v151, v154, v155
	v_mov_b64_e32 v[154:155], s[6:7]
	s_movk_i32 s10, 0x1800
	v_pk_mul_f32 v[152:153], v[204:205], v[152:153]
	v_mad_i64_i32 v[154:155], s[10:11], v2, s10, v[154:155]
	v_cvt_pk_bf16_f32 v152, v152, v153
	v_cvt_pk_bf16_f32 v153, v156, v157
	v_lshl_add_u64 v[154:155], v[4:5], 1, v[154:155]
	global_store_dwordx4 v[154:155], v[150:153], off offset:256 nt
.LBB0_955:
	s_cmp_lg_u32 s21, 0
	s_cselect_b64 s[10:11], -1, 0
	s_and_b64 s[10:11], s[10:11], s[8:9]
	s_andn2_b64 vcc, exec, s[10:11]
	s_cbranch_vccnz .LBB0_957
	s_waitcnt lgkmcnt(2)
	v_pk_fma_f32 v[150:151], v[182:183], v[148:149], v[76:77] op_sel_hi:[0,1,1] neg_lo:[1,0,0] neg_hi:[1,0,0]
	s_waitcnt lgkmcnt(0)
	v_pk_fma_f32 v[150:151], v[184:185], v[150:151], v[144:145] op_sel_hi:[0,1,1]
	v_mov_b32_e32 v154, v204
	v_mov_b32_e32 v155, v204
	v_pk_mul_f32 v[156:157], v[154:155], v[150:151]
	v_pk_fma_f32 v[150:151], v[182:183], v[136:137], v[72:73] op_sel_hi:[0,1,1] neg_lo:[1,0,0] neg_hi:[1,0,0]
	v_pk_fma_f32 v[158:159], v[182:183], v[134:135], v[70:71] op_sel_hi:[0,1,1] neg_lo:[1,0,0] neg_hi:[1,0,0]
	v_pk_fma_f32 v[150:151], v[184:185], v[150:151], v[140:141] op_sel_hi:[0,1,1]
	v_pk_fma_f32 v[158:159], v[184:185], v[158:159], v[138:139] op_sel_hi:[0,1,1]
	v_pk_fma_f32 v[152:153], v[182:183], v[146:147], v[74:75] op_sel_hi:[0,1,1] neg_lo:[1,0,0] neg_hi:[1,0,0]
	v_pk_mul_f32 v[154:155], v[154:155], v[150:151]
	v_pk_mul_f32 v[150:151], v[204:205], v[158:159]
	v_pk_fma_f32 v[152:153], v[184:185], v[152:153], v[142:143] op_sel_hi:[0,1,1]
	v_add_u32_e32 v2, 48, v206
	v_cvt_pk_bf16_f32 v150, v150, v151
	v_cvt_pk_bf16_f32 v151, v154, v155
	v_mov_b64_e32 v[154:155], s[6:7]
	s_movk_i32 s10, 0x1800
	v_pk_mul_f32 v[152:153], v[204:205], v[152:153]
	v_mad_i64_i32 v[154:155], s[10:11], v2, s10, v[154:155]
	v_cvt_pk_bf16_f32 v152, v152, v153
	v_cvt_pk_bf16_f32 v153, v156, v157
	v_lshl_add_u64 v[154:155], v[4:5], 1, v[154:155]
	global_store_dwordx4 v[154:155], v[150:153], off offset:256 nt
.LBB0_957:
	s_cmp_lg_u32 s24, 0
	s_cselect_b64 s[10:11], -1, 0
	s_and_b64 s[10:11], s[10:11], s[8:9]
	s_andn2_b64 vcc, exec, s[10:11]
	s_cbranch_vccnz .LBB0_959
	s_waitcnt lgkmcnt(2)
	v_pk_fma_f32 v[150:151], v[220:221], v[148:149], v[20:21] op_sel_hi:[0,1,1] neg_lo:[1,0,0] neg_hi:[1,0,0]
	s_waitcnt lgkmcnt(0)
	v_pk_fma_f32 v[150:151], v[222:223], v[150:151], v[144:145] op_sel_hi:[0,1,1]
	v_mov_b32_e32 v154, v204
	v_mov_b32_e32 v155, v204
	v_pk_mul_f32 v[156:157], v[154:155], v[150:151]
	v_pk_fma_f32 v[150:151], v[220:221], v[136:137], v[16:17] op_sel_hi:[0,1,1] neg_lo:[1,0,0] neg_hi:[1,0,0]
	v_pk_fma_f32 v[158:159], v[220:221], v[134:135], v[14:15] op_sel_hi:[0,1,1] neg_lo:[1,0,0] neg_hi:[1,0,0]
	v_pk_fma_f32 v[150:151], v[222:223], v[150:151], v[140:141] op_sel_hi:[0,1,1]
	v_pk_fma_f32 v[158:159], v[222:223], v[158:159], v[138:139] op_sel_hi:[0,1,1]
	v_pk_fma_f32 v[152:153], v[220:221], v[146:147], v[18:19] op_sel_hi:[0,1,1] neg_lo:[1,0,0] neg_hi:[1,0,0]
	v_pk_mul_f32 v[154:155], v[154:155], v[150:151]
	v_pk_mul_f32 v[150:151], v[204:205], v[158:159]
	v_pk_fma_f32 v[152:153], v[222:223], v[152:153], v[142:143] op_sel_hi:[0,1,1]
	v_cvt_pk_bf16_f32 v150, v150, v151
	v_cvt_pk_bf16_f32 v151, v154, v155
	v_mov_b64_e32 v[154:155], s[6:7]
	s_movk_i32 s10, 0x1800
	v_pk_mul_f32 v[152:153], v[204:205], v[152:153]
	v_mad_i64_i32 v[154:155], s[10:11], v218, s10, v[154:155]
	v_cvt_pk_bf16_f32 v152, v152, v153
	v_cvt_pk_bf16_f32 v153, v156, v157
	v_lshl_add_u64 v[154:155], v[4:5], 1, v[154:155]
	global_store_dwordx4 v[154:155], v[150:153], off offset:256 nt
.LBB0_959:
	s_cmp_lg_u32 s25, 0
	s_cselect_b64 s[10:11], -1, 0
	s_and_b64 s[10:11], s[10:11], s[8:9]
	s_andn2_b64 vcc, exec, s[10:11]
	s_cbranch_vccnz .LBB0_961
	s_waitcnt lgkmcnt(2)
	v_pk_fma_f32 v[150:151], v[178:179], v[148:149], v[12:13] op_sel_hi:[0,1,1] neg_lo:[1,0,0] neg_hi:[1,0,0]
	s_waitcnt lgkmcnt(0)
	v_pk_fma_f32 v[150:151], v[180:181], v[150:151], v[144:145] op_sel_hi:[0,1,1]
	v_mov_b32_e32 v154, v204
	v_mov_b32_e32 v155, v204
	v_pk_mul_f32 v[156:157], v[154:155], v[150:151]
	v_pk_fma_f32 v[150:151], v[178:179], v[136:137], v[8:9] op_sel_hi:[0,1,1] neg_lo:[1,0,0] neg_hi:[1,0,0]
	v_pk_fma_f32 v[158:159], v[178:179], v[134:135], v[6:7] op_sel_hi:[0,1,1] neg_lo:[1,0,0] neg_hi:[1,0,0]
	v_pk_fma_f32 v[150:151], v[180:181], v[150:151], v[140:141] op_sel_hi:[0,1,1]
	v_pk_fma_f32 v[158:159], v[180:181], v[158:159], v[138:139] op_sel_hi:[0,1,1]
	v_pk_fma_f32 v[152:153], v[178:179], v[146:147], v[10:11] op_sel_hi:[0,1,1] neg_lo:[1,0,0] neg_hi:[1,0,0]
	v_pk_mul_f32 v[154:155], v[154:155], v[150:151]
	v_pk_mul_f32 v[150:151], v[204:205], v[158:159]
	v_pk_fma_f32 v[152:153], v[180:181], v[152:153], v[142:143] op_sel_hi:[0,1,1]
	v_add_u32_e32 v2, 0x90, v206
	v_cvt_pk_bf16_f32 v150, v150, v151
	v_cvt_pk_bf16_f32 v151, v154, v155
	v_mov_b64_e32 v[154:155], s[6:7]
	s_movk_i32 s10, 0x1800
	v_pk_mul_f32 v[152:153], v[204:205], v[152:153]
	v_mad_i64_i32 v[154:155], s[10:11], v2, s10, v[154:155]
	v_cvt_pk_bf16_f32 v152, v152, v153
	v_cvt_pk_bf16_f32 v153, v156, v157
	v_lshl_add_u64 v[154:155], v[4:5], 1, v[154:155]
	global_store_dwordx4 v[154:155], v[150:153], off offset:256 nt
.LBB0_961:
	s_cmp_lg_u32 s26, 0
	s_cselect_b64 s[10:11], -1, 0
	s_and_b64 s[10:11], s[10:11], s[8:9]
	s_andn2_b64 vcc, exec, s[10:11]
	s_cbranch_vccnz .LBB0_963
	s_waitcnt lgkmcnt(2)
	v_pk_fma_f32 v[150:151], v[162:163], v[148:149], v[64:65] op_sel_hi:[0,1,1] neg_lo:[1,0,0] neg_hi:[1,0,0]
	s_waitcnt lgkmcnt(0)
	v_pk_fma_f32 v[150:151], v[224:225], v[150:151], v[144:145] op_sel_hi:[0,1,1]
	v_mov_b32_e32 v154, v204
	v_mov_b32_e32 v155, v204
	v_pk_mul_f32 v[156:157], v[154:155], v[150:151]
	v_pk_fma_f32 v[150:151], v[162:163], v[136:137], v[56:57] op_sel_hi:[0,1,1] neg_lo:[1,0,0] neg_hi:[1,0,0]
	v_pk_fma_f32 v[158:159], v[162:163], v[134:135], v[54:55] op_sel_hi:[0,1,1] neg_lo:[1,0,0] neg_hi:[1,0,0]
	v_pk_fma_f32 v[150:151], v[224:225], v[150:151], v[140:141] op_sel_hi:[0,1,1]
	v_pk_fma_f32 v[158:159], v[224:225], v[158:159], v[138:139] op_sel_hi:[0,1,1]
	v_pk_fma_f32 v[152:153], v[162:163], v[146:147], v[62:63] op_sel_hi:[0,1,1] neg_lo:[1,0,0] neg_hi:[1,0,0]
	v_pk_mul_f32 v[154:155], v[154:155], v[150:151]
	v_pk_mul_f32 v[150:151], v[204:205], v[158:159]
	v_pk_fma_f32 v[152:153], v[224:225], v[152:153], v[142:143] op_sel_hi:[0,1,1]
	v_add_u32_e32 v2, 0xa0, v206
	v_cvt_pk_bf16_f32 v150, v150, v151
	v_cvt_pk_bf16_f32 v151, v154, v155
	v_mov_b64_e32 v[154:155], s[6:7]
	s_movk_i32 s10, 0x1800
	v_pk_mul_f32 v[152:153], v[204:205], v[152:153]
	v_mad_i64_i32 v[154:155], s[10:11], v2, s10, v[154:155]
	v_cvt_pk_bf16_f32 v152, v152, v153
	v_cvt_pk_bf16_f32 v153, v156, v157
	v_lshl_add_u64 v[154:155], v[4:5], 1, v[154:155]
	global_store_dwordx4 v[154:155], v[150:153], off offset:256 nt
.LBB0_963:
	s_cmp_lg_u32 s27, 0
	s_cselect_b64 s[10:11], -1, 0
	s_and_b64 s[8:9], s[10:11], s[8:9]
	s_andn2_b64 vcc, exec, s[8:9]
	s_cbranch_vccnz .LBB0_965
	s_waitcnt lgkmcnt(2)
	v_pk_fma_f32 v[148:149], v[164:165], v[148:149], v[68:69] op_sel_hi:[0,1,1] neg_lo:[1,0,0] neg_hi:[1,0,0]
	v_pk_fma_f32 v[146:147], v[164:165], v[146:147], v[66:67] op_sel_hi:[0,1,1] neg_lo:[1,0,0] neg_hi:[1,0,0]
	v_pk_fma_f32 v[136:137], v[164:165], v[136:137], v[60:61] op_sel_hi:[0,1,1] neg_lo:[1,0,0] neg_hi:[1,0,0]
	v_pk_fma_f32 v[134:135], v[164:165], v[134:135], v[58:59] op_sel_hi:[0,1,1] neg_lo:[1,0,0] neg_hi:[1,0,0]
	v_add_u32_e32 v2, 0xb0, v206
	s_waitcnt lgkmcnt(0)
	v_pk_fma_f32 v[144:145], v[170:171], v[148:149], v[144:145] op_sel_hi:[0,1,1]
	v_pk_fma_f32 v[142:143], v[170:171], v[146:147], v[142:143] op_sel_hi:[0,1,1]
	v_mov_b32_e32 v146, v204
	v_mov_b32_e32 v147, v204
	v_pk_fma_f32 v[136:137], v[136:137], v[170:171], v[140:141] op_sel_hi:[1,0,1]
	v_pk_fma_f32 v[134:135], v[134:135], v[170:171], v[138:139] op_sel_hi:[1,0,1]
	v_mov_b64_e32 v[138:139], s[6:7]
	s_movk_i32 s6, 0x1800
	v_pk_mul_f32 v[144:145], v[146:147], v[144:145]
	v_pk_mul_f32 v[142:143], v[204:205], v[142:143]
	v_pk_mul_f32 v[136:137], v[146:147], v[136:137]
	v_pk_mul_f32 v[134:135], v[204:205], v[134:135]
	v_mad_i64_i32 v[138:139], s[6:7], v2, s6, v[138:139]
	v_cvt_pk_bf16_f32 v134, v134, v135
	v_cvt_pk_bf16_f32 v135, v136, v137
	v_cvt_pk_bf16_f32 v136, v142, v143
	v_cvt_pk_bf16_f32 v137, v144, v145
	v_lshl_add_u64 v[4:5], v[4:5], 1, v[138:139]
	global_store_dwordx4 v[4:5], v[134:137], off offset:256 nt

.LBB0_966:
	s_and_b64 vcc, exec, s[6:7]
	s_cbranch_vccz .LBB0_992
	v_readlane_b32 s8, v255, 18
	v_lshl_add_u32 v2, v191, 3, s70
	v_lshlrev_b32_e32 v173, 3, v2
	v_add_u32_e32 v5, s8, v189
	v_lshl_add_u32 v4, v5, 2, 0
	s_waitcnt lgkmcnt(0)
	v_add_u32_e32 v134, 0x20800, v4
	v_add_u32_e32 v4, 0x20c00, v4
	ds_read2_b32 v[148:149], v134 offset1:16
	ds_read2_b32 v[146:147], v4 offset1:16
	ds_read2_b32 v[144:145], v134 offset0:32 offset1:48
	ds_read2_b32 v[142:143], v4 offset0:32 offset1:48
	ds_read2_b32 v[140:141], v134 offset0:128 offset1:144
	ds_read2_b32 v[138:139], v4 offset0:128 offset1:144
	ds_read2_b32 v[136:137], v134 offset0:160 offset1:176
	ds_read2_b32 v[134:135], v4 offset0:160 offset1:176
	v_lshl_add_u32 v4, s3, 8, v2
	v_add_u32_e32 v2, 0, v173
	v_add_u32_e32 v150, 0x20000, v2
	ds_read_b128 v[152:155], v150
	ds_read_b128 v[160:163], v150 offset:16
	ds_read_b128 v[164:167], v150 offset:32
	ds_read_b128 v[168:171], v150 offset:48
	v_lshl_add_u32 v2, s4, 8, v5
	s_add_u32 s6, s12, 0x31b00000
	s_addc_u32 s7, s13, 0
	s_waitcnt lgkmcnt(3)
	v_mov_b32_e32 v150, v152
	v_mov_b32_e32 v151, v154
	v_pk_mul_f32 v[150:151], v[150:151], s[72:73] op_sel_hi:[1,0]
	s_waitcnt lgkmcnt(2)
	v_mov_b32_e32 v154, v160
	v_pk_mul_f32 v[156:157], v[150:151], v[150:151]
	s_and_b32 s10, s84, 1
	v_fma_f32 v5, v153, s72, -v156
	v_add_f32_e32 v5, 0x3727c5ac, v5
	v_rsq_f32_e32 v152, v5
	v_fma_f32 v5, v155, s72, -v157
	v_mov_b32_e32 v155, v162
	v_pk_mul_f32 v[158:159], v[154:155], s[72:73] op_sel_hi:[1,0]
	v_add_f32_e32 v5, 0x3727c5ac, v5
	v_pk_mul_f32 v[154:155], v[158:159], v[158:159]
	v_rsq_f32_e32 v153, v5
	v_fma_f32 v5, v161, s72, -v154
	v_add_f32_e32 v5, 0x3727c5ac, v5
	s_waitcnt lgkmcnt(1)
	v_mov_b32_e32 v156, v164
	v_mov_b32_e32 v157, v166
	v_rsq_f32_e32 v154, v5
	v_fma_f32 v5, v163, s72, -v155
	v_pk_mul_f32 v[156:157], v[156:157], s[72:73] op_sel_hi:[1,0]
	v_add_f32_e32 v5, 0x3727c5ac, v5
	v_pk_mul_f32 v[160:161], v[156:157], v[156:157]
	v_rsq_f32_e32 v155, v5
	v_fma_f32 v5, v165, s72, -v160
	v_add_f32_e32 v5, 0x3727c5ac, v5
	s_waitcnt lgkmcnt(0)
	v_mov_b32_e32 v162, v168
	v_mov_b32_e32 v163, v170
	v_rsq_f32_e32 v160, v5
	v_fma_f32 v5, v167, s72, -v161
	v_pk_mul_f32 v[164:165], v[162:163], s[72:73] op_sel_hi:[1,0]
	v_add_f32_e32 v5, 0x3727c5ac, v5
	v_pk_mul_f32 v[162:163], v[164:165], v[164:165]
	v_rsq_f32_e32 v161, v5
	v_fma_f32 v5, v169, s72, -v162
	v_add_f32_e32 v5, 0x3727c5ac, v5
	v_rsq_f32_e32 v162, v5
	v_fma_f32 v5, v171, s72, -v163
	v_add_f32_e32 v5, 0x3727c5ac, v5
	v_rsq_f32_e32 v163, v5
	s_bitcmp1_b32 s84, 0
	s_cselect_b64 s[8:9], -1, 0
	s_cmp_eq_u32 s10, 0
	v_ashrrev_i32_e32 v5, 31, v4
	s_cbranch_scc1 .LBB0_969
	v_pk_fma_f32 v[166:167], v[148:149], v[158:159], v[128:129] op_sel_hi:[0,1,1] neg_lo:[1,0,0] neg_hi:[1,0,0]
	v_pk_fma_f32 v[170:171], v[154:155], v[166:167], v[146:147] op_sel_hi:[1,1,0]
	v_pk_fma_f32 v[166:167], v[148:149], v[164:165], v[132:133] op_sel_hi:[0,1,1] neg_lo:[1,0,0] neg_hi:[1,0,0]
	v_pk_fma_f32 v[168:169], v[148:149], v[150:151], v[126:127] op_sel_hi:[0,1,1] neg_lo:[1,0,0] neg_hi:[1,0,0]
	v_pk_fma_f32 v[174:175], v[148:149], v[156:157], v[130:131] op_sel_hi:[0,1,1] neg_lo:[1,0,0] neg_hi:[1,0,0]
	v_pk_fma_f32 v[176:177], v[162:163], v[166:167], v[146:147] op_sel_hi:[1,1,0]
	v_cvt_pk_bf16_f32 v167, v170, v171
	v_mov_b64_e32 v[170:171], s[6:7]
	s_movk_i32 s10, 0x4800
	v_pk_fma_f32 v[168:169], v[152:153], v[168:169], v[146:147] op_sel_hi:[1,1,0]
	v_pk_fma_f32 v[174:175], v[160:161], v[174:175], v[146:147] op_sel_hi:[1,1,0]
	v_mad_i64_i32 v[170:171], s[10:11], v2, s10, v[170:171]
	v_cvt_pk_bf16_f32 v166, v168, v169
	v_cvt_pk_bf16_f32 v168, v174, v175
	v_cvt_pk_bf16_f32 v169, v176, v177
	v_lshl_add_u64 v[170:171], v[4:5], 1, v[170:171]
	global_store_dwordx4 v[170:171], v[166:169], off nt
.LBB0_969:
	s_and_b32 s16, s84, 2
	s_bitcmp1_b32 s84, 1
	s_cselect_b64 s[10:11], -1, 0
	s_cmp_eq_u32 s16, 0
	v_add_u32_e32 v166, 16, v2
	s_cbranch_scc1 .LBB0_971
	v_mov_b32_e32 v168, v149
	v_pk_fma_f32 v[174:175], v[168:169], v[150:151], v[118:119] op_sel_hi:[0,1,1] neg_lo:[1,0,0] neg_hi:[1,0,0]
	v_mov_b32_e32 v172, v147
	v_pk_fma_f32 v[170:171], v[168:169], v[158:159], v[120:121] op_sel_hi:[0,1,1] neg_lo:[1,0,0] neg_hi:[1,0,0]
	v_pk_fma_f32 v[174:175], v[152:153], v[174:175], v[172:173] op_sel_hi:[1,1,0]
	v_pk_fma_f32 v[176:177], v[168:169], v[164:165], v[124:125] op_sel_hi:[0,1,1] neg_lo:[1,0,0] neg_hi:[1,0,0]
	v_pk_fma_f32 v[168:169], v[168:169], v[156:157], v[122:123] op_sel_hi:[0,1,1] neg_lo:[1,0,0] neg_hi:[1,0,0]
	v_pk_fma_f32 v[178:179], v[160:161], v[168:169], v[172:173] op_sel_hi:[1,1,0]
	v_cvt_pk_bf16_f32 v168, v174, v175
	v_mov_b64_e32 v[174:175], s[6:7]
	s_movk_i32 s16, 0x4800
	v_pk_fma_f32 v[170:171], v[154:155], v[170:171], v[172:173] op_sel_hi:[1,1,0]
	v_pk_fma_f32 v[176:177], v[162:163], v[176:177], v[172:173] op_sel_hi:[1,1,0]
	v_mad_i64_i32 v[174:175], s[16:17], v166, s16, v[174:175]
	v_cvt_pk_bf16_f32 v169, v170, v171
	v_cvt_pk_bf16_f32 v170, v178, v179
	v_cvt_pk_bf16_f32 v171, v176, v177
	v_lshl_add_u64 v[174:175], v[4:5], 1, v[174:175]
	global_store_dwordx4 v[174:175], v[168:171], off nt
.LBB0_971:
	s_and_b32 s18, s84, 4
	s_bitcmp1_b32 s84, 2
	s_cselect_b64 s[16:17], -1, 0
	s_cmp_eq_u32 s18, 0
	v_add_u32_e32 v167, 32, v2
	s_cbranch_scc1 .LBB0_973
	v_pk_fma_f32 v[168:169], v[144:145], v[158:159], v[112:113] op_sel_hi:[0,1,1] neg_lo:[1,0,0] neg_hi:[1,0,0]
	v_pk_fma_f32 v[174:175], v[154:155], v[168:169], v[142:143] op_sel_hi:[1,1,0]
	v_pk_fma_f32 v[168:169], v[144:145], v[164:165], v[116:117] op_sel_hi:[0,1,1] neg_lo:[1,0,0] neg_hi:[1,0,0]
	v_pk_fma_f32 v[170:171], v[144:145], v[150:151], v[110:111] op_sel_hi:[0,1,1] neg_lo:[1,0,0] neg_hi:[1,0,0]
	v_pk_fma_f32 v[176:177], v[144:145], v[156:157], v[114:115] op_sel_hi:[0,1,1] neg_lo:[1,0,0] neg_hi:[1,0,0]
	v_pk_fma_f32 v[178:179], v[162:163], v[168:169], v[142:143] op_sel_hi:[1,1,0]
	v_cvt_pk_bf16_f32 v169, v174, v175
	v_mov_b64_e32 v[174:175], s[6:7]
	s_movk_i32 s18, 0x4800
	v_pk_fma_f32 v[170:171], v[152:153], v[170:171], v[142:143] op_sel_hi:[1,1,0]
	v_pk_fma_f32 v[176:177], v[160:161], v[176:177], v[142:143] op_sel_hi:[1,1,0]
	v_mad_i64_i32 v[174:175], s[18:19], v167, s18, v[174:175]
	v_cvt_pk_bf16_f32 v168, v170, v171
	v_cvt_pk_bf16_f32 v170, v176, v177
	v_cvt_pk_bf16_f32 v171, v178, v179
	v_lshl_add_u64 v[174:175], v[4:5], 1, v[174:175]
	global_store_dwordx4 v[174:175], v[168:171], off nt
.LBB0_973:
	s_and_b32 s20, s84, 8
	s_bitcmp1_b32 s84, 3
	s_cselect_b64 s[18:19], -1, 0
	s_cmp_eq_u32 s20, 0
	v_add_u32_e32 v168, 48, v2
	s_cbranch_scc1 .LBB0_975
	v_mov_b32_e32 v170, v145
	v_pk_fma_f32 v[174:175], v[170:171], v[158:159], v[104:105] op_sel_hi:[0,1,1] neg_lo:[1,0,0] neg_hi:[1,0,0]
	v_mov_b32_e32 v172, v143
	v_pk_fma_f32 v[176:177], v[170:171], v[150:151], v[102:103] op_sel_hi:[0,1,1] neg_lo:[1,0,0] neg_hi:[1,0,0]
	v_pk_fma_f32 v[178:179], v[154:155], v[174:175], v[172:173] op_sel_hi:[1,1,0]
	v_pk_fma_f32 v[174:175], v[170:171], v[164:165], v[108:109] op_sel_hi:[0,1,1] neg_lo:[1,0,0] neg_hi:[1,0,0]
	v_pk_fma_f32 v[170:171], v[170:171], v[156:157], v[106:107] op_sel_hi:[0,1,1] neg_lo:[1,0,0] neg_hi:[1,0,0]
	v_pk_fma_f32 v[176:177], v[152:153], v[176:177], v[172:173] op_sel_hi:[1,1,0]
	v_pk_fma_f32 v[170:171], v[160:161], v[170:171], v[172:173] op_sel_hi:[1,1,0]
	v_pk_fma_f32 v[180:181], v[162:163], v[174:175], v[172:173] op_sel_hi:[1,1,0]
	v_cvt_pk_bf16_f32 v174, v176, v177
	v_cvt_pk_bf16_f32 v176, v170, v171
	v_mov_b64_e32 v[170:171], s[6:7]
	s_movk_i32 s20, 0x4800
	v_mad_i64_i32 v[170:171], s[20:21], v168, s20, v[170:171]
	v_cvt_pk_bf16_f32 v175, v178, v179
	v_cvt_pk_bf16_f32 v177, v180, v181
	v_lshl_add_u64 v[170:171], v[4:5], 1, v[170:171]
	global_store_dwordx4 v[170:171], v[174:177], off nt
.LBB0_975:
	s_and_b32 s24, s84, 16
	s_bitcmp1_b32 s84, 4
	s_cselect_b64 s[20:21], -1, 0
	s_cmp_eq_u32 s24, 0
	v_add_u32_e32 v169, 0x80, v2
	s_cbranch_scc1 .LBB0_977
	v_pk_fma_f32 v[170:171], v[140:141], v[158:159], v[48:49] op_sel_hi:[0,1,1] neg_lo:[1,0,0] neg_hi:[1,0,0]
	v_pk_fma_f32 v[174:175], v[140:141], v[150:151], v[46:47] op_sel_hi:[0,1,1] neg_lo:[1,0,0] neg_hi:[1,0,0]
	v_pk_fma_f32 v[174:175], v[152:153], v[174:175], v[138:139] op_sel_hi:[1,1,0]
	v_pk_fma_f32 v[170:171], v[154:155], v[170:171], v[138:139] op_sel_hi:[1,1,0]
	v_pk_fma_f32 v[176:177], v[140:141], v[164:165], v[52:53] op_sel_hi:[0,1,1] neg_lo:[1,0,0] neg_hi:[1,0,0]
	v_pk_fma_f32 v[178:179], v[140:141], v[156:157], v[50:51] op_sel_hi:[0,1,1] neg_lo:[1,0,0] neg_hi:[1,0,0]
	v_cvt_pk_bf16_f32 v174, v174, v175
	v_cvt_pk_bf16_f32 v175, v170, v171
	v_mov_b64_e32 v[170:171], s[6:7]
	s_movk_i32 s24, 0x4800
	v_pk_fma_f32 v[178:179], v[160:161], v[178:179], v[138:139] op_sel_hi:[1,1,0]
	v_pk_fma_f32 v[180:181], v[162:163], v[176:177], v[138:139] op_sel_hi:[1,1,0]
	v_mad_i64_i32 v[170:171], s[24:25], v169, s24, v[170:171]
	v_cvt_pk_bf16_f32 v176, v178, v179
	v_cvt_pk_bf16_f32 v177, v180, v181
	v_lshl_add_u64 v[170:171], v[4:5], 1, v[170:171]
	global_store_dwordx4 v[170:171], v[174:177], off nt
.LBB0_977:
	s_and_b32 s26, s84, 32
	s_bitcmp1_b32 s84, 5
	s_cselect_b64 s[24:25], -1, 0
	s_cmp_eq_u32 s26, 0
	v_add_u32_e32 v170, 0x90, v2
	s_cbranch_scc1 .LBB0_979
	v_mov_b32_e32 v172, v141
	v_pk_fma_f32 v[174:175], v[172:173], v[158:159], v[40:41] op_sel_hi:[0,1,1] neg_lo:[1,0,0] neg_hi:[1,0,0]
	v_mov_b32_e32 v178, v139
	v_pk_fma_f32 v[176:177], v[172:173], v[150:151], v[38:39] op_sel_hi:[0,1,1] neg_lo:[1,0,0] neg_hi:[1,0,0]
	v_pk_fma_f32 v[180:181], v[154:155], v[174:175], v[178:179] op_sel_hi:[1,1,0]
	v_pk_fma_f32 v[174:175], v[172:173], v[164:165], v[44:45] op_sel_hi:[0,1,1] neg_lo:[1,0,0] neg_hi:[1,0,0]
	v_pk_fma_f32 v[182:183], v[172:173], v[156:157], v[42:43] op_sel_hi:[0,1,1] neg_lo:[1,0,0] neg_hi:[1,0,0]
	v_pk_fma_f32 v[176:177], v[152:153], v[176:177], v[178:179] op_sel_hi:[1,1,0]
	v_pk_fma_f32 v[182:183], v[160:161], v[182:183], v[178:179] op_sel_hi:[1,1,0]
	v_pk_fma_f32 v[178:179], v[162:163], v[174:175], v[178:179] op_sel_hi:[1,1,0]
	v_cvt_pk_bf16_f32 v174, v176, v177
	v_cvt_pk_bf16_f32 v177, v178, v179
	v_mov_b64_e32 v[178:179], s[6:7]
	s_movk_i32 s26, 0x4800
	v_mad_i64_i32 v[178:179], s[26:27], v170, s26, v[178:179]
	v_cvt_pk_bf16_f32 v175, v180, v181
	v_cvt_pk_bf16_f32 v176, v182, v183
	v_lshl_add_u64 v[178:179], v[4:5], 1, v[178:179]
	global_store_dwordx4 v[178:179], v[174:177], off nt
.LBB0_979:
	s_and_b32 s28, s84, 64
	s_bitcmp1_b32 s84, 6
	s_cselect_b64 s[26:27], -1, 0
	s_cmp_eq_u32 s28, 0
	v_add_u32_e32 v171, 0xa0, v2
	s_cbranch_scc1 .LBB0_981
	v_pk_fma_f32 v[174:175], v[136:137], v[158:159], v[32:33] op_sel_hi:[0,1,1] neg_lo:[1,0,0] neg_hi:[1,0,0]
	v_pk_fma_f32 v[178:179], v[154:155], v[174:175], v[134:135] op_sel_hi:[1,1,0]
	v_pk_fma_f32 v[174:175], v[136:137], v[164:165], v[36:37] op_sel_hi:[0,1,1] neg_lo:[1,0,0] neg_hi:[1,0,0]
	v_pk_fma_f32 v[176:177], v[136:137], v[150:151], v[30:31] op_sel_hi:[0,1,1] neg_lo:[1,0,0] neg_hi:[1,0,0]
	v_pk_fma_f32 v[180:181], v[136:137], v[156:157], v[34:35] op_sel_hi:[0,1,1] neg_lo:[1,0,0] neg_hi:[1,0,0]
	v_pk_fma_f32 v[182:183], v[162:163], v[174:175], v[134:135] op_sel_hi:[1,1,0]
	v_cvt_pk_bf16_f32 v175, v178, v179
	v_mov_b64_e32 v[178:179], s[6:7]
	s_movk_i32 s28, 0x4800
	v_pk_fma_f32 v[176:177], v[152:153], v[176:177], v[134:135] op_sel_hi:[1,1,0]
	v_pk_fma_f32 v[180:181], v[160:161], v[180:181], v[134:135] op_sel_hi:[1,1,0]
	v_mad_i64_i32 v[178:179], s[28:29], v171, s28, v[178:179]
	v_cvt_pk_bf16_f32 v174, v176, v177
	v_cvt_pk_bf16_f32 v176, v180, v181
	v_cvt_pk_bf16_f32 v177, v182, v183
	v_lshl_add_u64 v[178:179], v[4:5], 1, v[178:179]
	global_store_dwordx4 v[178:179], v[174:177], off nt
.LBB0_981:
	s_and_b32 s43, s84, 0x80
	s_bitcmp1_b32 s84, 7
	s_cselect_b64 s[28:29], -1, 0
	s_cmp_eq_u32 s43, 0
	v_add_u32_e32 v172, 0xb0, v2
	s_cbranch_scc1 .LBB0_983
	v_mov_b32_e32 v174, v137
	v_pk_fma_f32 v[158:159], v[174:175], v[158:159], v[24:25] op_sel_hi:[0,1,1] neg_lo:[1,0,0] neg_hi:[1,0,0]
	v_pk_fma_f32 v[150:151], v[174:175], v[150:151], v[22:23] op_sel_hi:[0,1,1] neg_lo:[1,0,0] neg_hi:[1,0,0]
	v_mov_b32_e32 v176, v135
	v_pk_fma_f32 v[150:151], v[152:153], v[150:151], v[176:177] op_sel_hi:[1,1,0]
	v_pk_fma_f32 v[152:153], v[154:155], v[158:159], v[176:177] op_sel_hi:[1,1,0]
	v_pk_fma_f32 v[154:155], v[174:175], v[164:165], v[28:29] op_sel_hi:[0,1,1] neg_lo:[1,0,0] neg_hi:[1,0,0]
	v_pk_fma_f32 v[154:155], v[162:163], v[154:155], v[176:177] op_sel_hi:[1,1,0]
	v_pk_fma_f32 v[156:157], v[174:175], v[156:157], v[26:27] op_sel_hi:[0,1,1] neg_lo:[1,0,0] neg_hi:[1,0,0]
	v_cvt_pk_bf16_f32 v150, v150, v151
	v_cvt_pk_bf16_f32 v151, v152, v153
	v_cvt_pk_bf16_f32 v153, v154, v155
	v_mov_b64_e32 v[154:155], s[6:7]
	s_movk_i32 s43, 0x4800
	v_pk_fma_f32 v[156:157], v[160:161], v[156:157], v[176:177] op_sel_hi:[1,1,0]
	v_mad_i64_i32 v[154:155], s[56:57], v172, s43, v[154:155]
	v_cvt_pk_bf16_f32 v152, v156, v157
	v_lshl_add_u64 v[154:155], v[4:5], 1, v[154:155]
	global_store_dwordx4 v[154:155], v[150:153], off nt

.LBB0_991:
	v_mov_b32_e32 v2, v137
	v_pk_fma_f32 v[138:139], v[2:3], v[150:151], v[58:59] op_sel_hi:[0,1,1] neg_lo:[1,0,0] neg_hi:[1,0,0]
	v_mov_b32_e32 v134, v135
	v_pk_fma_f32 v[136:137], v[2:3], v[158:159], v[60:61] op_sel_hi:[0,1,1] neg_lo:[1,0,0] neg_hi:[1,0,0]
	v_pk_fma_f32 v[138:139], v[152:153], v[138:139], v[134:135] op_sel_hi:[1,1,0]
	v_pk_fma_f32 v[140:141], v[2:3], v[164:165], v[68:69] op_sel_hi:[0,1,1] neg_lo:[1,0,0] neg_hi:[1,0,0]
	v_pk_fma_f32 v[142:143], v[2:3], v[156:157], v[66:67] op_sel_hi:[0,1,1] neg_lo:[1,0,0] neg_hi:[1,0,0]
	v_pk_fma_f32 v[136:137], v[154:155], v[136:137], v[134:135] op_sel_hi:[1,1,0]
	v_pk_fma_f32 v[142:143], v[160:161], v[142:143], v[134:135] op_sel_hi:[1,1,0]
	v_pk_fma_f32 v[140:141], v[162:163], v[140:141], v[134:135] op_sel_hi:[1,1,0]
	v_cvt_pk_bf16_f32 v134, v138, v139
	v_mov_b64_e32 v[138:139], s[6:7]
	s_movk_i32 s6, 0x4800
	v_mad_i64_i32 v[138:139], s[6:7], v172, s6, v[138:139]
	v_cvt_pk_bf16_f32 v135, v136, v137
	v_cvt_pk_bf16_f32 v136, v142, v143
	v_cvt_pk_bf16_f32 v137, v140, v141
	v_lshl_add_u64 v[4:5], v[4:5], 1, v[138:139]
	global_store_dwordx4 v[4:5], v[134:137], off offset:256 nt

.LBB0_993:
	s_and_b64 vcc, exec, s[6:7]
	s_cbranch_vccz .LBB0_1109
	s_cmp_gt_i32 s42, 0
	s_mov_b64 s[0:1], -1
	s_cbranch_scc0 .LBB0_1107
	s_cmp_gt_i32 s42, 1
	s_cbranch_scc0 .LBB0_1021
	v_readlane_b32 s0, v255, 18
	s_waitcnt lgkmcnt(0)
	v_lshl_add_u32 v135, v191, 3, s70
	v_readlane_b32 s1, v254, 43
	v_add_u32_e32 v5, s0, v189
	v_lshl_add_u32 v2, v5, 3, 0
	v_add_u32_e32 v134, 0x20000, v2
	ds_read2_b64 v[176:179], v134 offset1:16
	v_readlane_b32 s0, v254, 42
	v_lshl_add_u32 v4, s3, 8, v135
	s_add_u32 s6, s12, 0x2af00000
	s_addc_u32 s7, s13, 0
	s_waitcnt lgkmcnt(0)
	v_mul_f32_e32 v2, 0x3a000000, v176
	v_mul_f32_e32 v136, v2, v2
	v_fma_f32 v136, v177, s72, -v136
	v_add_f32_e32 v136, 0x3727c5ac, v136
	ds_read2_b64 v[174:177], v134 offset0:32 offset1:48
	ds_read2_b64 v[170:173], v134 offset0:128 offset1:144
	ds_read2_b64 v[166:169], v134 offset0:160 offset1:176
	v_lshlrev_b32_e32 v134, 2, v135
	v_rsq_f32_e32 v180, v136
	v_add_u32_e32 v135, s0, v134
	v_add_u32_e32 v136, s1, v134
	v_or_b32_e32 v134, 16, v134
	v_add_u32_e32 v137, s0, v134
	v_add_u32_e32 v134, s1, v134
	ds_read_b128 v[154:157], v137
	ds_read_b128 v[150:153], v134
	ds_read_b128 v[162:165], v135
	ds_read_b128 v[146:149], v135 offset:512
	ds_read_b128 v[158:161], v136
	ds_read_b128 v[138:141], v135 offset:528
	ds_read_b128 v[142:145], v136 offset:512
	ds_read_b128 v[134:137], v136 offset:528
	s_cmp_lt_i32 s3, 8
	s_cselect_b64 s[0:1], -1, 0
	s_and_b32 s10, s84, 1
	s_bitcmp1_b32 s84, 0
	v_lshl_add_u32 v181, s4, 8, v5
	s_cselect_b64 s[8:9], -1, 0
	s_cmp_eq_u32 s10, 0
	v_ashrrev_i32_e32 v5, 31, v4
	s_cbranch_scc1 .LBB0_998
	s_waitcnt lgkmcnt(5)
	v_pk_fma_f32 v[182:183], v[2:3], v[164:165], v[128:129] op_sel_hi:[0,1,1] neg_lo:[1,0,0] neg_hi:[1,0,0]
	v_pk_fma_f32 v[184:185], v[2:3], v[162:163], v[126:127] op_sel_hi:[0,1,1] neg_lo:[1,0,0] neg_hi:[1,0,0]
	s_waitcnt lgkmcnt(3)
	v_pk_fma_f32 v[182:183], v[180:181], v[182:183], v[160:161] op_sel_hi:[0,1,1]
	v_pk_fma_f32 v[184:185], v[180:181], v[184:185], v[158:159] op_sel_hi:[0,1,1]
	v_mul_f32_e32 v186, 0xbfb8aa3b, v184
	v_mul_f32_e32 v187, 0xbfb8aa3b, v185
	v_mul_f32_e32 v197, 0xbfb8aa3b, v182
	v_exp_f32_e32 v186, v186
	v_exp_f32_e32 v187, v187
	v_exp_f32_e32 v204, v197
	v_mul_f32_e32 v197, 0xbfb8aa3b, v183
	v_exp_f32_e32 v205, v197
	v_pk_add_f32 v[186:187], v[186:187], 1.0 op_sel_hi:[1,0]
	s_movk_i32 s10, 0x3000
	v_rcp_f32_e32 v186, v186
	v_pk_add_f32 v[204:205], v[204:205], 1.0 op_sel_hi:[1,0]
	v_rcp_f32_e32 v187, v187
	v_rcp_f32_e32 v204, v204
	v_rcp_f32_e32 v205, v205
	v_pk_mul_f32 v[184:185], v[184:185], v[186:187]
	s_nop 0
	v_cndmask_b32_e64 v201, v187, v185, s[0:1]
	v_pk_mul_f32 v[182:183], v[182:183], v[204:205]
	v_cndmask_b32_e64 v203, v186, v184, s[0:1]
	v_pk_fma_f32 v[184:185], v[2:3], v[154:155], v[130:131] op_sel_hi:[0,1,1] neg_lo:[1,0,0] neg_hi:[1,0,0]
	v_cndmask_b32_e64 v197, v205, v183, s[0:1]
	v_cndmask_b32_e64 v199, v204, v182, s[0:1]
	v_pk_fma_f32 v[182:183], v[2:3], v[156:157], v[132:133] op_sel_hi:[0,1,1] neg_lo:[1,0,0] neg_hi:[1,0,0]
	v_pk_fma_f32 v[184:185], v[180:181], v[184:185], v[150:151] op_sel_hi:[0,1,1]
	v_pk_fma_f32 v[182:183], v[180:181], v[182:183], v[152:153] op_sel_hi:[0,1,1]
	v_mul_f32_e32 v186, 0xbfb8aa3b, v184
	v_mul_f32_e32 v187, 0xbfb8aa3b, v185
	v_exp_f32_e32 v186, v186
	v_exp_f32_e32 v187, v187
	v_mul_f32_e32 v204, 0xbfb8aa3b, v182
	v_mul_f32_e32 v205, 0xbfb8aa3b, v183
	v_exp_f32_e32 v204, v204
	v_exp_f32_e32 v205, v205
	v_pk_add_f32 v[186:187], v[186:187], 1.0 op_sel_hi:[1,0]
	v_pk_add_f32 v[204:205], v[204:205], 1.0 op_sel_hi:[1,0]
	v_rcp_f32_e32 v186, v186
	v_rcp_f32_e32 v187, v187
	v_rcp_f32_e32 v204, v204
	v_rcp_f32_e32 v205, v205
	v_pk_mul_f32 v[184:185], v[184:185], v[186:187]
	s_nop 0
	v_cndmask_b32_e64 v185, v187, v185, s[0:1]
	v_pk_mul_f32 v[182:183], v[182:183], v[204:205]
	v_cndmask_b32_e64 v184, v186, v184, s[0:1]
	v_mov_b64_e32 v[186:187], s[6:7]
	v_cndmask_b32_e64 v205, v205, v183, s[0:1]
	v_cndmask_b32_e64 v204, v204, v182, s[0:1]
	v_mad_i64_i32 v[186:187], s[10:11], v181, s10, v[186:187]
	v_cvt_pk_bf16_f32 v182, v203, v201
	v_cvt_pk_bf16_f32 v183, v199, v197
	v_cvt_pk_bf16_f32 v184, v184, v185
	v_cvt_pk_bf16_f32 v185, v204, v205
	v_lshl_add_u64 v[186:187], v[4:5], 1, v[186:187]
	global_store_dwordx4 v[186:187], v[182:185], off nt
.LBB0_998:
	v_mul_f32_e32 v178, 0x3a000000, v178
	s_nop 0
	v_mul_f32_e32 v182, v178, v178
	v_fma_f32 v179, v179, s72, -v182
	v_add_f32_e32 v179, 0x3727c5ac, v179
	v_rsq_f32_e32 v182, v179
	s_and_b32 s16, s84, 2
	s_bitcmp1_b32 s84, 1
	s_cselect_b64 s[10:11], -1, 0
	s_cmp_eq_u32 s16, 0
	s_cbranch_scc1 .LBB0_1000
	s_waitcnt lgkmcnt(5)
	v_pk_fma_f32 v[186:187], v[178:179], v[162:163], v[118:119] op_sel_hi:[0,1,1] neg_lo:[1,0,0] neg_hi:[1,0,0]
	s_waitcnt lgkmcnt(3)
	v_pk_fma_f32 v[186:187], v[182:183], v[186:187], v[158:159] op_sel_hi:[0,1,1]
	v_pk_fma_f32 v[184:185], v[178:179], v[164:165], v[120:121] op_sel_hi:[0,1,1] neg_lo:[1,0,0] neg_hi:[1,0,0]
	v_mul_f32_e32 v179, 0xbfb8aa3b, v186
	v_pk_fma_f32 v[184:185], v[182:183], v[184:185], v[160:161] op_sel_hi:[0,1,1]
	v_exp_f32_e32 v204, v179
	v_mul_f32_e32 v179, 0xbfb8aa3b, v187
	v_exp_f32_e32 v205, v179
	v_mul_f32_e32 v179, 0xbfb8aa3b, v184
	v_exp_f32_e32 v206, v179
	v_mul_f32_e32 v179, 0xbfb8aa3b, v185
	v_exp_f32_e32 v207, v179
	v_pk_add_f32 v[204:205], v[204:205], 1.0 op_sel_hi:[1,0]
	s_movk_i32 s16, 0x3000
	v_rcp_f32_e32 v204, v204
	v_pk_add_f32 v[206:207], v[206:207], 1.0 op_sel_hi:[1,0]
	v_rcp_f32_e32 v205, v205
	v_rcp_f32_e32 v206, v206
	v_rcp_f32_e32 v207, v207
	v_pk_mul_f32 v[186:187], v[186:187], v[204:205]
	s_nop 0
	v_cndmask_b32_e64 v197, v205, v187, s[0:1]
	v_pk_mul_f32 v[184:185], v[184:185], v[206:207]
	v_cndmask_b32_e64 v199, v204, v186, s[0:1]
	v_cndmask_b32_e64 v179, v207, v185, s[0:1]
	v_cndmask_b32_e64 v183, v206, v184, s[0:1]
	v_pk_fma_f32 v[186:187], v[178:179], v[154:155], v[122:123] op_sel_hi:[0,1,1] neg_lo:[1,0,0] neg_hi:[1,0,0]
	v_pk_fma_f32 v[186:187], v[182:183], v[186:187], v[150:151] op_sel_hi:[0,1,1]
	v_pk_fma_f32 v[184:185], v[178:179], v[156:157], v[124:125] op_sel_hi:[0,1,1] neg_lo:[1,0,0] neg_hi:[1,0,0]
	v_mul_f32_e32 v201, 0xbfb8aa3b, v186
	v_pk_fma_f32 v[184:185], v[182:183], v[184:185], v[152:153] op_sel_hi:[0,1,1]
	v_exp_f32_e32 v204, v201
	v_mul_f32_e32 v201, 0xbfb8aa3b, v187
	v_exp_f32_e32 v205, v201
	v_mul_f32_e32 v201, 0xbfb8aa3b, v184
	v_exp_f32_e32 v206, v201
	v_mul_f32_e32 v201, 0xbfb8aa3b, v185
	v_exp_f32_e32 v207, v201
	v_pk_add_f32 v[204:205], v[204:205], 1.0 op_sel_hi:[1,0]
	v_pk_add_f32 v[206:207], v[206:207], 1.0 op_sel_hi:[1,0]
	v_rcp_f32_e32 v204, v204
	v_rcp_f32_e32 v205, v205
	v_rcp_f32_e32 v206, v206
	v_rcp_f32_e32 v207, v207
	v_pk_mul_f32 v[186:187], v[186:187], v[204:205]
	s_nop 0
	v_cndmask_b32_e64 v187, v205, v187, s[0:1]
	v_pk_mul_f32 v[184:185], v[184:185], v[206:207]
	v_cndmask_b32_e64 v186, v204, v186, s[0:1]
	v_cndmask_b32_e64 v203, v206, v184, s[0:1]
	v_add_u32_e32 v206, 16, v181
	v_mov_b64_e32 v[204:205], s[6:7]
	v_cndmask_b32_e64 v201, v207, v185, s[0:1]
	v_mad_i64_i32 v[204:205], s[16:17], v206, s16, v[204:205]
	v_cvt_pk_bf16_f32 v184, v199, v197
	v_cvt_pk_bf16_f32 v185, v183, v179
	v_cvt_pk_bf16_f32 v186, v186, v187
	v_cvt_pk_bf16_f32 v187, v203, v201
	v_lshl_add_u64 v[204:205], v[4:5], 1, v[204:205]
	global_store_dwordx4 v[204:205], v[184:187], off nt
.LBB0_1000:
	s_waitcnt lgkmcnt(10)
	v_mul_f32_e32 v174, 0x3a000000, v174
	v_mul_f32_e32 v179, v174, v174
	v_fma_f32 v175, v175, s72, -v179
	v_add_f32_e32 v175, 0x3727c5ac, v175
	v_rsq_f32_e32 v184, v175
	s_and_b32 s18, s84, 4
	s_bitcmp1_b32 s84, 2
	s_cselect_b64 s[16:17], -1, 0
	s_cmp_eq_u32 s18, 0
	s_cbranch_scc1 .LBB0_1002
	s_waitcnt lgkmcnt(5)
	v_pk_fma_f32 v[204:205], v[174:175], v[162:163], v[110:111] op_sel_hi:[0,1,1] neg_lo:[1,0,0] neg_hi:[1,0,0]
	s_waitcnt lgkmcnt(3)
	v_pk_fma_f32 v[204:205], v[184:185], v[204:205], v[158:159] op_sel_hi:[0,1,1]
	v_pk_fma_f32 v[186:187], v[174:175], v[164:165], v[112:113] op_sel_hi:[0,1,1] neg_lo:[1,0,0] neg_hi:[1,0,0]
	v_mul_f32_e32 v175, 0xbfb8aa3b, v204
	v_pk_fma_f32 v[186:187], v[184:185], v[186:187], v[160:161] op_sel_hi:[0,1,1]
	v_exp_f32_e32 v206, v175
	v_mul_f32_e32 v175, 0xbfb8aa3b, v205
	v_exp_f32_e32 v207, v175
	v_mul_f32_e32 v175, 0xbfb8aa3b, v186
	v_exp_f32_e32 v208, v175
	v_mul_f32_e32 v175, 0xbfb8aa3b, v187
	v_exp_f32_e32 v209, v175
	v_pk_add_f32 v[206:207], v[206:207], 1.0 op_sel_hi:[1,0]
	v_add_u32_e32 v201, 32, v181
	v_rcp_f32_e32 v206, v206
	v_pk_add_f32 v[208:209], v[208:209], 1.0 op_sel_hi:[1,0]
	v_rcp_f32_e32 v207, v207
	v_rcp_f32_e32 v208, v208
	v_rcp_f32_e32 v209, v209
	s_movk_i32 s18, 0x3000
	v_pk_mul_f32 v[204:205], v[204:205], v[206:207]
	v_pk_mul_f32 v[186:187], v[186:187], v[208:209]
	s_nop 0
	v_cndmask_b32_e64 v175, v209, v187, s[0:1]
	v_cndmask_b32_e64 v183, v207, v205, s[0:1]
	v_cndmask_b32_e64 v185, v206, v204, s[0:1]
	v_pk_fma_f32 v[204:205], v[174:175], v[154:155], v[114:115] op_sel_hi:[0,1,1] neg_lo:[1,0,0] neg_hi:[1,0,0]
	v_pk_fma_f32 v[204:205], v[184:185], v[204:205], v[150:151] op_sel_hi:[0,1,1]
	v_cndmask_b32_e64 v179, v208, v186, s[0:1]
	v_pk_fma_f32 v[186:187], v[174:175], v[156:157], v[116:117] op_sel_hi:[0,1,1] neg_lo:[1,0,0] neg_hi:[1,0,0]
	v_mul_f32_e32 v197, 0xbfb8aa3b, v204
	v_pk_fma_f32 v[186:187], v[184:185], v[186:187], v[152:153] op_sel_hi:[0,1,1]
	v_exp_f32_e32 v206, v197
	v_mul_f32_e32 v197, 0xbfb8aa3b, v205
	v_exp_f32_e32 v207, v197
	v_mul_f32_e32 v197, 0xbfb8aa3b, v186
	v_exp_f32_e32 v208, v197
	v_mul_f32_e32 v197, 0xbfb8aa3b, v187
	v_exp_f32_e32 v209, v197
	v_pk_add_f32 v[206:207], v[206:207], 1.0 op_sel_hi:[1,0]
	v_pk_add_f32 v[208:209], v[208:209], 1.0 op_sel_hi:[1,0]
	s_nop 0
	v_rcp_f32_e32 v208, v208
	v_rcp_f32_e32 v209, v209
	v_rcp_f32_e32 v206, v206
	v_rcp_f32_e32 v207, v207
	v_pk_mul_f32 v[186:187], v[186:187], v[208:209]
	s_nop 0
	v_cndmask_b32_e64 v187, v209, v187, s[0:1]
	v_pk_mul_f32 v[204:205], v[204:205], v[206:207]
	v_cndmask_b32_e64 v186, v208, v186, s[0:1]
	v_cndmask_b32_e64 v197, v207, v205, s[0:1]
	v_cvt_pk_bf16_f32 v207, v186, v187
	v_mov_b64_e32 v[186:187], s[6:7]
	v_cndmask_b32_e64 v199, v206, v204, s[0:1]
	v_mad_i64_i32 v[186:187], s[18:19], v201, s18, v[186:187]
	v_cvt_pk_bf16_f32 v204, v185, v183
	v_cvt_pk_bf16_f32 v205, v179, v175
	v_cvt_pk_bf16_f32 v206, v199, v197
	v_lshl_add_u64 v[186:187], v[4:5], 1, v[186:187]
	global_store_dwordx4 v[186:187], v[204:207], off nt
.LBB0_1002:
	v_mul_f32_e32 v176, 0x3a000000, v176
	v_mul_f32_e32 v175, v176, v176
	v_fma_f32 v175, v177, s72, -v175
	v_add_f32_e32 v175, 0x3727c5ac, v175
	v_rsq_f32_e32 v186, v175
	s_and_b32 s20, s84, 8
	s_bitcmp1_b32 s84, 3
	s_cselect_b64 s[18:19], -1, 0
	s_cmp_eq_u32 s20, 0
	s_cbranch_scc1 .LBB0_1004
	s_waitcnt lgkmcnt(5)
	v_pk_fma_f32 v[206:207], v[176:177], v[162:163], v[102:103] op_sel_hi:[0,1,1] neg_lo:[1,0,0] neg_hi:[1,0,0]
	s_waitcnt lgkmcnt(3)
	v_pk_fma_f32 v[206:207], v[206:207], v[186:187], v[158:159] op_sel_hi:[1,0,1]
	v_pk_fma_f32 v[204:205], v[176:177], v[164:165], v[104:105] op_sel_hi:[0,1,1] neg_lo:[1,0,0] neg_hi:[1,0,0]
	v_mul_f32_e32 v175, 0xbfb8aa3b, v206
	v_pk_fma_f32 v[204:205], v[204:205], v[186:187], v[160:161] op_sel_hi:[1,0,1]
	v_exp_f32_e32 v208, v175
	v_mul_f32_e32 v175, 0xbfb8aa3b, v207
	v_exp_f32_e32 v209, v175
	v_mul_f32_e32 v175, 0xbfb8aa3b, v204
	v_exp_f32_e32 v210, v175
	v_mul_f32_e32 v175, 0xbfb8aa3b, v205
	v_exp_f32_e32 v211, v175
	v_pk_add_f32 v[208:209], v[208:209], 1.0 op_sel_hi:[1,0]
	v_add_u32_e32 v201, 48, v181
	v_rcp_f32_e32 v208, v208
	v_pk_add_f32 v[210:211], v[210:211], 1.0 op_sel_hi:[1,0]
	v_rcp_f32_e32 v209, v209
	v_rcp_f32_e32 v210, v210
	v_rcp_f32_e32 v211, v211
	s_movk_i32 s20, 0x3000
	v_pk_mul_f32 v[206:207], v[206:207], v[208:209]
	v_pk_mul_f32 v[204:205], v[204:205], v[210:211]
	s_nop 0
	v_cndmask_b32_e64 v177, v210, v204, s[0:1]
	v_cndmask_b32_e64 v179, v209, v207, s[0:1]
	v_cndmask_b32_e64 v183, v208, v206, s[0:1]
	v_pk_fma_f32 v[206:207], v[176:177], v[154:155], v[106:107] op_sel_hi:[0,1,1] neg_lo:[1,0,0] neg_hi:[1,0,0]
	v_pk_fma_f32 v[206:207], v[186:187], v[206:207], v[150:151] op_sel_hi:[0,1,1]
	v_cndmask_b32_e64 v175, v211, v205, s[0:1]
	v_pk_fma_f32 v[204:205], v[176:177], v[156:157], v[108:109] op_sel_hi:[0,1,1] neg_lo:[1,0,0] neg_hi:[1,0,0]
	v_mul_f32_e32 v185, 0xbfb8aa3b, v206
	v_pk_fma_f32 v[204:205], v[186:187], v[204:205], v[152:153] op_sel_hi:[0,1,1]
	v_exp_f32_e32 v208, v185
	v_mul_f32_e32 v185, 0xbfb8aa3b, v207
	v_exp_f32_e32 v209, v185
	v_mul_f32_e32 v185, 0xbfb8aa3b, v204
	v_exp_f32_e32 v210, v185
	v_mul_f32_e32 v185, 0xbfb8aa3b, v205
	v_exp_f32_e32 v211, v185
	v_pk_add_f32 v[208:209], v[208:209], 1.0 op_sel_hi:[1,0]
	v_pk_add_f32 v[210:211], v[210:211], 1.0 op_sel_hi:[1,0]
	v_rcp_f32_e32 v208, v208
	v_rcp_f32_e32 v209, v209
	v_rcp_f32_e32 v210, v210
	v_rcp_f32_e32 v211, v211
	v_pk_mul_f32 v[206:207], v[206:207], v[208:209]
	s_nop 0
	v_cndmask_b32_e64 v197, v209, v207, s[0:1]
	v_pk_mul_f32 v[204:205], v[204:205], v[210:211]
	v_cndmask_b32_e64 v199, v208, v206, s[0:1]
	v_mov_b64_e32 v[208:209], s[6:7]
	v_cndmask_b32_e64 v185, v211, v205, s[0:1]
	v_cndmask_b32_e64 v187, v210, v204, s[0:1]
	v_mad_i64_i32 v[208:209], s[20:21], v201, s20, v[208:209]
	v_cvt_pk_bf16_f32 v204, v183, v179
	v_cvt_pk_bf16_f32 v205, v177, v175
	v_cvt_pk_bf16_f32 v206, v199, v197
	v_cvt_pk_bf16_f32 v207, v187, v185
	v_lshl_add_u64 v[208:209], v[4:5], 1, v[208:209]
	global_store_dwordx4 v[208:209], v[204:207], off nt
.LBB0_1004:
	s_waitcnt lgkmcnt(9)
	v_mul_f32_e32 v170, 0x3a000000, v170
	v_mul_f32_e32 v175, v170, v170
	v_fma_f32 v171, v171, s72, -v175
	v_add_f32_e32 v171, 0x3727c5ac, v171
	v_rsq_f32_e32 v204, v171
	s_and_b32 s24, s84, 16
	s_bitcmp1_b32 s84, 4
	s_cselect_b64 s[20:21], -1, 0
	s_cmp_eq_u32 s24, 0
	v_add_u32_e32 v171, 0x80, v181
	s_cbranch_scc1 .LBB0_1006
	s_waitcnt lgkmcnt(5)
	v_pk_fma_f32 v[208:209], v[170:171], v[162:163], v[46:47] op_sel_hi:[0,1,1] neg_lo:[1,0,0] neg_hi:[1,0,0]
	s_waitcnt lgkmcnt(3)
	v_pk_fma_f32 v[208:209], v[208:209], v[204:205], v[158:159] op_sel_hi:[1,0,1]
	v_pk_fma_f32 v[206:207], v[170:171], v[164:165], v[48:49] op_sel_hi:[0,1,1] neg_lo:[1,0,0] neg_hi:[1,0,0]
	v_mul_f32_e32 v175, 0xbfb8aa3b, v208
	v_pk_fma_f32 v[206:207], v[206:207], v[204:205], v[160:161] op_sel_hi:[1,0,1]
	v_exp_f32_e32 v210, v175
	v_mul_f32_e32 v175, 0xbfb8aa3b, v209
	v_exp_f32_e32 v211, v175
	v_mul_f32_e32 v175, 0xbfb8aa3b, v206
	v_exp_f32_e32 v212, v175
	v_mul_f32_e32 v175, 0xbfb8aa3b, v207
	v_exp_f32_e32 v213, v175
	v_pk_add_f32 v[210:211], v[210:211], 1.0 op_sel_hi:[1,0]
	s_movk_i32 s24, 0x3000
	v_rcp_f32_e32 v210, v210
	v_rcp_f32_e32 v211, v211
	v_pk_add_f32 v[212:213], v[212:213], 1.0 op_sel_hi:[1,0]
	v_pk_mul_f32 v[208:209], v[208:209], v[210:211]
	v_rcp_f32_e32 v212, v212
	v_rcp_f32_e32 v213, v213
	v_cndmask_b32_e64 v179, v211, v209, s[0:1]
	v_cndmask_b32_e64 v183, v210, v208, s[0:1]
	v_pk_fma_f32 v[208:209], v[170:171], v[154:155], v[50:51] op_sel_hi:[0,1,1] neg_lo:[1,0,0] neg_hi:[1,0,0]
	v_pk_mul_f32 v[206:207], v[206:207], v[212:213]
	v_pk_fma_f32 v[208:209], v[204:205], v[208:209], v[150:151] op_sel_hi:[0,1,1]
	v_cndmask_b32_e64 v175, v213, v207, s[0:1]
	v_cndmask_b32_e64 v177, v212, v206, s[0:1]
	v_pk_fma_f32 v[206:207], v[170:171], v[156:157], v[52:53] op_sel_hi:[0,1,1] neg_lo:[1,0,0] neg_hi:[1,0,0]
	v_mul_f32_e32 v185, 0xbfb8aa3b, v208
	v_pk_fma_f32 v[206:207], v[204:205], v[206:207], v[152:153] op_sel_hi:[0,1,1]
	v_exp_f32_e32 v210, v185
	v_mul_f32_e32 v185, 0xbfb8aa3b, v209
	v_exp_f32_e32 v211, v185
	v_mul_f32_e32 v185, 0xbfb8aa3b, v206
	v_exp_f32_e32 v212, v185
	v_mul_f32_e32 v185, 0xbfb8aa3b, v207
	v_exp_f32_e32 v213, v185
	v_pk_add_f32 v[210:211], v[210:211], 1.0 op_sel_hi:[1,0]
	v_pk_add_f32 v[212:213], v[212:213], 1.0 op_sel_hi:[1,0]
	v_rcp_f32_e32 v210, v210
	v_rcp_f32_e32 v211, v211
	v_rcp_f32_e32 v212, v212
	v_rcp_f32_e32 v213, v213
	v_pk_mul_f32 v[208:209], v[208:209], v[210:211]
	s_nop 0
	v_cndmask_b32_e64 v197, v211, v209, s[0:1]
	v_pk_mul_f32 v[206:207], v[206:207], v[212:213]
	v_cndmask_b32_e64 v199, v210, v208, s[0:1]
	v_mov_b64_e32 v[210:211], s[6:7]
	v_cndmask_b32_e64 v185, v213, v207, s[0:1]
	v_cndmask_b32_e64 v187, v212, v206, s[0:1]
	v_mad_i64_i32 v[210:211], s[24:25], v171, s24, v[210:211]
	v_cvt_pk_bf16_f32 v206, v183, v179
	v_cvt_pk_bf16_f32 v207, v177, v175
	v_cvt_pk_bf16_f32 v208, v199, v197
	v_cvt_pk_bf16_f32 v209, v187, v185
	v_lshl_add_u64 v[210:211], v[4:5], 1, v[210:211]
	global_store_dwordx4 v[210:211], v[206:209], off nt
.LBB0_1006:
	v_mul_f32_e32 v172, 0x3a000000, v172
	v_mul_f32_e32 v175, v172, v172
	v_fma_f32 v173, v173, s72, -v175
	v_add_f32_e32 v173, 0x3727c5ac, v173
	v_rsq_f32_e32 v206, v173
	s_and_b32 s26, s84, 32
	s_bitcmp1_b32 s84, 5
	s_cselect_b64 s[24:25], -1, 0
	s_cmp_eq_u32 s26, 0
	s_cbranch_scc1 .LBB0_1008
	s_waitcnt lgkmcnt(5)
	v_pk_fma_f32 v[210:211], v[162:163], v[172:173], v[38:39] op_sel_hi:[1,0,1] neg_lo:[1,0,0] neg_hi:[1,0,0]
	v_xor_b32_e32 v209, 0x80000000, v165
	v_xor_b32_e32 v208, 0x80000000, v164
	s_waitcnt lgkmcnt(3)
	v_pk_fma_f32 v[210:211], v[210:211], v[206:207], v[158:159] op_sel_hi:[1,0,1]
	v_pk_fma_f32 v[208:209], v[208:209], v[172:173], v[40:41] op_sel_hi:[1,0,1]
	v_mul_f32_e32 v173, 0xbfb8aa3b, v210
	v_pk_fma_f32 v[208:209], v[208:209], v[206:207], v[160:161] op_sel_hi:[1,0,1]
	v_exp_f32_e32 v212, v173
	v_mul_f32_e32 v173, 0xbfb8aa3b, v211
	v_exp_f32_e32 v213, v173
	v_mul_f32_e32 v173, 0xbfb8aa3b, v208
	v_exp_f32_e32 v214, v173
	v_mul_f32_e32 v173, 0xbfb8aa3b, v209
	v_exp_f32_e32 v215, v173
	v_pk_add_f32 v[212:213], v[212:213], 1.0 op_sel_hi:[1,0]
	v_add_u32_e32 v199, 0x90, v181
	v_rcp_f32_e32 v212, v212
	v_pk_add_f32 v[214:215], v[214:215], 1.0 op_sel_hi:[1,0]
	v_rcp_f32_e32 v213, v213
	v_rcp_f32_e32 v214, v214
	v_rcp_f32_e32 v215, v215
	s_movk_i32 s26, 0x3000
	v_pk_mul_f32 v[210:211], v[210:211], v[212:213]
	v_pk_mul_f32 v[208:209], v[208:209], v[214:215]
	s_nop 0
	v_cndmask_b32_e64 v173, v215, v209, s[0:1]
	v_cndmask_b32_e64 v177, v213, v211, s[0:1]
	v_cndmask_b32_e64 v179, v212, v210, s[0:1]
	v_pk_fma_f32 v[210:211], v[172:173], v[154:155], v[42:43] op_sel_hi:[0,1,1] neg_lo:[1,0,0] neg_hi:[1,0,0]
	v_pk_fma_f32 v[210:211], v[210:211], v[206:207], v[150:151] op_sel_hi:[1,0,1]
	v_cndmask_b32_e64 v175, v214, v208, s[0:1]
	v_pk_fma_f32 v[208:209], v[172:173], v[156:157], v[44:45] op_sel_hi:[0,1,1] neg_lo:[1,0,0] neg_hi:[1,0,0]
	v_mul_f32_e32 v183, 0xbfb8aa3b, v210
	v_pk_fma_f32 v[208:209], v[208:209], v[206:207], v[152:153] op_sel_hi:[1,0,1]
	v_exp_f32_e32 v212, v183
	v_mul_f32_e32 v183, 0xbfb8aa3b, v211
	v_exp_f32_e32 v213, v183
	v_mul_f32_e32 v183, 0xbfb8aa3b, v208
	v_exp_f32_e32 v214, v183
	v_mul_f32_e32 v183, 0xbfb8aa3b, v209
	v_exp_f32_e32 v215, v183
	v_pk_add_f32 v[212:213], v[212:213], 1.0 op_sel_hi:[1,0]
	v_pk_add_f32 v[214:215], v[214:215], 1.0 op_sel_hi:[1,0]
	v_rcp_f32_e32 v212, v212
	v_rcp_f32_e32 v213, v213
	v_rcp_f32_e32 v214, v214
	v_rcp_f32_e32 v215, v215
	v_pk_mul_f32 v[210:211], v[210:211], v[212:213]
	s_nop 0
	v_cndmask_b32_e64 v187, v213, v211, s[0:1]
	v_pk_mul_f32 v[208:209], v[208:209], v[214:215]
	v_cndmask_b32_e64 v197, v212, v210, s[0:1]
	v_mov_b64_e32 v[212:213], s[6:7]
	v_cndmask_b32_e64 v183, v215, v209, s[0:1]
	v_cndmask_b32_e64 v185, v214, v208, s[0:1]
	v_mad_i64_i32 v[212:213], s[26:27], v199, s26, v[212:213]
	v_cvt_pk_bf16_f32 v208, v179, v177
	v_cvt_pk_bf16_f32 v209, v175, v173
	v_cvt_pk_bf16_f32 v210, v197, v187
	v_cvt_pk_bf16_f32 v211, v185, v183
	v_lshl_add_u64 v[212:213], v[4:5], 1, v[212:213]
	global_store_dwordx4 v[212:213], v[208:211], off nt
.LBB0_1008:
	s_waitcnt lgkmcnt(8)
	v_mul_f32_e32 v166, 0x3a000000, v166
	v_mul_f32_e32 v173, v166, v166
	v_fma_f32 v167, v167, s72, -v173
	v_add_f32_e32 v167, 0x3727c5ac, v167
	v_rsq_f32_e32 v208, v167
	s_and_b32 s28, s84, 64
	s_bitcmp1_b32 s84, 6
	s_cselect_b64 s[26:27], -1, 0
	s_cmp_eq_u32 s28, 0
	s_cbranch_scc1 .LBB0_1010
	s_waitcnt lgkmcnt(5)
	v_pk_fma_f32 v[212:213], v[162:163], v[166:167], v[30:31] op_sel_hi:[1,0,1] neg_lo:[1,0,0] neg_hi:[1,0,0]
	v_xor_b32_e32 v211, 0x80000000, v165
	v_xor_b32_e32 v210, 0x80000000, v164
	s_waitcnt lgkmcnt(3)
	v_pk_fma_f32 v[212:213], v[212:213], v[208:209], v[158:159] op_sel_hi:[1,0,1]
	v_pk_fma_f32 v[210:211], v[210:211], v[166:167], v[32:33] op_sel_hi:[1,0,1]
	v_mul_f32_e32 v167, 0xbfb8aa3b, v212
	v_pk_fma_f32 v[210:211], v[210:211], v[208:209], v[160:161] op_sel_hi:[1,0,1]
	v_exp_f32_e32 v214, v167
	v_mul_f32_e32 v167, 0xbfb8aa3b, v213
	v_exp_f32_e32 v215, v167
	v_mul_f32_e32 v167, 0xbfb8aa3b, v210
	v_exp_f32_e32 v216, v167
	v_mul_f32_e32 v167, 0xbfb8aa3b, v211
	v_exp_f32_e32 v217, v167
	v_pk_add_f32 v[214:215], v[214:215], 1.0 op_sel_hi:[1,0]
	v_add_u32_e32 v197, 0xa0, v181
	v_rcp_f32_e32 v214, v214
	v_pk_add_f32 v[216:217], v[216:217], 1.0 op_sel_hi:[1,0]
	v_rcp_f32_e32 v215, v215
	v_rcp_f32_e32 v216, v216
	v_rcp_f32_e32 v217, v217
	s_movk_i32 s28, 0x3000
	v_pk_mul_f32 v[212:213], v[212:213], v[214:215]
	v_pk_mul_f32 v[210:211], v[210:211], v[216:217]
	s_nop 0
	v_cndmask_b32_e64 v167, v217, v211, s[0:1]
	v_cndmask_b32_e64 v175, v215, v213, s[0:1]
	v_cndmask_b32_e64 v177, v214, v212, s[0:1]
	v_pk_fma_f32 v[212:213], v[166:167], v[154:155], v[34:35] op_sel_hi:[0,1,1] neg_lo:[1,0,0] neg_hi:[1,0,0]
	v_pk_fma_f32 v[212:213], v[212:213], v[208:209], v[150:151] op_sel_hi:[1,0,1]
	v_cndmask_b32_e64 v173, v216, v210, s[0:1]
	v_pk_fma_f32 v[210:211], v[166:167], v[156:157], v[36:37] op_sel_hi:[0,1,1] neg_lo:[1,0,0] neg_hi:[1,0,0]
	v_mul_f32_e32 v179, 0xbfb8aa3b, v212
	v_pk_fma_f32 v[210:211], v[210:211], v[208:209], v[152:153] op_sel_hi:[1,0,1]
	v_exp_f32_e32 v214, v179
	v_mul_f32_e32 v179, 0xbfb8aa3b, v213
	v_exp_f32_e32 v215, v179
	v_mul_f32_e32 v179, 0xbfb8aa3b, v210
	v_exp_f32_e32 v216, v179
	v_mul_f32_e32 v179, 0xbfb8aa3b, v211
	v_exp_f32_e32 v217, v179
	v_pk_add_f32 v[214:215], v[214:215], 1.0 op_sel_hi:[1,0]
	v_pk_add_f32 v[216:217], v[216:217], 1.0 op_sel_hi:[1,0]
	v_rcp_f32_e32 v214, v214
	v_rcp_f32_e32 v215, v215
	v_rcp_f32_e32 v216, v216
	v_rcp_f32_e32 v217, v217
	v_pk_mul_f32 v[212:213], v[212:213], v[214:215]
	s_nop 0
	v_cndmask_b32_e64 v185, v215, v213, s[0:1]
	v_pk_mul_f32 v[210:211], v[210:211], v[216:217]
	v_cndmask_b32_e64 v187, v214, v212, s[0:1]
	v_mov_b64_e32 v[214:215], s[6:7]
	v_cndmask_b32_e64 v179, v217, v211, s[0:1]
	v_cndmask_b32_e64 v183, v216, v210, s[0:1]
	v_mad_i64_i32 v[214:215], s[28:29], v197, s28, v[214:215]
	v_cvt_pk_bf16_f32 v210, v177, v175
	v_cvt_pk_bf16_f32 v211, v173, v167
	v_cvt_pk_bf16_f32 v212, v187, v185
	v_cvt_pk_bf16_f32 v213, v183, v179
	v_lshl_add_u64 v[214:215], v[4:5], 1, v[214:215]
	global_store_dwordx4 v[214:215], v[210:213], off nt

.LBB0_1019:
	s_waitcnt lgkmcnt(4)
	v_pk_fma_f32 v[148:149], v[168:169], v[148:149], v[60:61] op_sel_hi:[0,1,1] neg_lo:[1,0,0] neg_hi:[1,0,0]
	v_pk_fma_f32 v[146:147], v[168:169], v[146:147], v[58:59] op_sel_hi:[0,1,1] neg_lo:[1,0,0] neg_hi:[1,0,0]
	s_waitcnt lgkmcnt(1)
	v_pk_fma_f32 v[144:145], v[148:149], v[210:211], v[144:145] op_sel_hi:[1,0,1]
	v_pk_fma_f32 v[142:143], v[146:147], v[210:211], v[142:143] op_sel_hi:[1,0,1]
	v_mul_f32_e32 v147, 0xbfb8aa3b, v144
	v_mul_f32_e32 v2, 0xbfb8aa3b, v142
	v_pk_fma_f32 v[140:141], v[168:169], v[140:141], v[68:69] op_sel_hi:[0,1,1] neg_lo:[1,0,0] neg_hi:[1,0,0]
	v_pk_fma_f32 v[138:139], v[168:169], v[138:139], v[66:67] op_sel_hi:[0,1,1] neg_lo:[1,0,0] neg_hi:[1,0,0]
	v_exp_f32_e32 v146, v2
	v_mul_f32_e32 v2, 0xbfb8aa3b, v143
	v_exp_f32_e32 v148, v147
	v_mul_f32_e32 v147, 0xbfb8aa3b, v145
	s_waitcnt lgkmcnt(0)
	v_pk_fma_f32 v[136:137], v[210:211], v[140:141], v[136:137] op_sel_hi:[0,1,1]
	v_pk_fma_f32 v[134:135], v[210:211], v[138:139], v[134:135] op_sel_hi:[0,1,1]
	v_exp_f32_e32 v149, v147
	v_exp_f32_e32 v147, v2
	v_mul_f32_e32 v2, 0xbfb8aa3b, v134
	v_mul_f32_e32 v139, 0xbfb8aa3b, v136
	v_exp_f32_e32 v138, v2
	v_mul_f32_e32 v2, 0xbfb8aa3b, v135
	v_exp_f32_e32 v140, v139
	v_mul_f32_e32 v139, 0xbfb8aa3b, v137
	v_exp_f32_e32 v141, v139
	v_exp_f32_e32 v139, v2
	v_pk_add_f32 v[148:149], v[148:149], 1.0 op_sel_hi:[1,0]
	v_pk_add_f32 v[146:147], v[146:147], 1.0 op_sel_hi:[1,0]
	v_pk_add_f32 v[140:141], v[140:141], 1.0 op_sel_hi:[1,0]
	v_pk_add_f32 v[138:139], v[138:139], 1.0 op_sel_hi:[1,0]
	v_rcp_f32_e32 v140, v140
	v_rcp_f32_e32 v138, v138
	v_rcp_f32_e32 v141, v141
	v_rcp_f32_e32 v139, v139
	v_rcp_f32_e32 v146, v146
	v_rcp_f32_e32 v148, v148
	v_rcp_f32_e32 v149, v149
	v_rcp_f32_e32 v147, v147
	v_pk_mul_f32 v[136:137], v[136:137], v[140:141]
	v_pk_mul_f32 v[134:135], v[134:135], v[138:139]
	v_pk_mul_f32 v[144:145], v[144:145], v[148:149]
	v_pk_mul_f32 v[142:143], v[142:143], v[146:147]
	v_cndmask_b32_e64 v140, v140, v136, s[0:1]
	v_cndmask_b32_e64 v136, v139, v135, s[0:1]
	v_cndmask_b32_e64 v138, v138, v134, s[0:1]
	v_cndmask_b32_e64 v2, v149, v145, s[0:1]
	v_cndmask_b32_e64 v144, v148, v144, s[0:1]
	v_cndmask_b32_e64 v143, v147, v143, s[0:1]
	v_cndmask_b32_e64 v142, v146, v142, s[0:1]
	v_cndmask_b32_e64 v137, v141, v137, s[0:1]
	v_add_u32_e32 v141, 0xb0, v181
	v_cvt_pk_bf16_f32 v136, v138, v136
	v_mov_b64_e32 v[138:139], s[6:7]
	s_movk_i32 s0, 0x3000
	v_mad_i64_i32 v[138:139], s[0:1], v141, s0, v[138:139]
	v_cvt_pk_bf16_f32 v134, v142, v143
	v_cvt_pk_bf16_f32 v135, v144, v2
	v_cvt_pk_bf16_f32 v137, v140, v137
	v_lshl_add_u64 v[4:5], v[4:5], 1, v[138:139]
	global_store_dwordx4 v[4:5], v[134:137], off offset:256 nt

.Lrf_notouch:
	s_mul_hi_i32 s9, s8, 0x12000
	s_mul_i32 s8, s8, 0x12000
	s_add_u32 s8, s12, s8
	s_addc_u32 s9, s13, s9
	s_add_u32 s16, s8, 0x20000
	v_readlane_b32 s8, v254, 38
	s_addc_u32 s17, s9, 0
	s_and_b64 vcc, exec, s[6:7]
	v_mov_b32_e32 v2, s8
	ds_read_b32 v2, v2
	v_readlane_b32 s8, v254, 39
	s_waitcnt lgkmcnt(0)
	s_nop 0
	v_mov_b32_e32 v2, s8
	ds_read_b32 v2, v2
	v_readlane_b32 s8, v254, 40
	s_waitcnt lgkmcnt(0)
	s_nop 0
	v_mov_b32_e32 v2, s8
	ds_read_b32 v2, v2
	v_readlane_b32 s8, v254, 41
	s_waitcnt lgkmcnt(0)
	s_nop 0
	v_mov_b32_e32 v2, s8
	ds_read_b32 v2, v2
	v_readlane_b32 s8, v255, 18
	s_waitcnt lgkmcnt(0)
	v_lshl_add_u32 v2, v191, 3, s70
	v_lshl_add_u32 v178, s3, 8, v2
	v_add_u32_e32 v4, s8, v189
	v_lshl_add_u32 v180, s4, 8, v4
	s_cbranch_vccnz .LBB0_1082
	s_cmp_eq_u32 s84, 0xff
	s_cbranch_scc1 .Lrfast_ffo
	v_ashrrev_i32_e32 v181, 31, v180
	v_lshlrev_b64 v[206:207], 12, v[180:181]
	s_mov_b64 s[0:1], 0x10000
	v_lshl_add_u64 v[212:213], v[206:207], 0, s[0:1]
	s_mov_b64 s[0:1], 0x20000
	v_ashrrev_i32_e32 v179, 31, v178
	v_lshl_add_u64 v[210:211], v[206:207], 0, s[0:1]
	s_mov_b64 s[0:1], 0x30000
	v_lshl_add_u64 v[182:183], v[178:179], 1, s[18:19]
	v_lshl_add_u64 v[208:209], v[206:207], 0, s[0:1]
	v_lshl_add_u64 v[204:205], v[182:183], 0, v[212:213]
	v_lshl_add_u64 v[184:185], v[182:183], 0, v[208:209]
	v_lshl_add_u64 v[186:187], v[182:183], 0, v[210:211]
	global_load_dwordx4 v[170:173], v[204:205], off
	global_load_dwordx4 v[166:169], v[186:187], off
	global_load_dwordx4 v[158:161], v[184:185], off
	v_lshlrev_b32_e32 v4, 3, v4
	v_add_u32_e32 v214, 0, v4
	v_add_u32_e32 v4, 0x20000, v214
	ds_read2_b64 v[174:177], v4 offset1:16
	v_lshl_add_u32 v2, v2, 2, 0
	v_add_u32_e32 v197, 0x20800, v2
	v_add_u32_e32 v199, 0x20c00, v2
	ds_read2_b64 v[162:165], v4 offset0:32 offset1:48
	s_waitcnt lgkmcnt(0)
	v_mul_f32_e32 v201, 0x3a000000, v174
	v_mul_f32_e32 v5, v201, v201
	v_fma_f32 v5, v175, s72, -v5
	v_add_f32_e32 v5, 0x3727c5ac, v5
	s_waitcnt vmcnt(0)
	ds_read_b128 v[150:153], v197
	ds_read_b128 v[142:145], v197 offset:16
	ds_read_b128 v[154:157], v199
	ds_read_b128 v[146:149], v199 offset:16
	v_rsq_f32_e32 v174, v5
	s_and_b32 s6, s84, 1
	s_bitcmp1_b32 s84, 0
	s_cselect_b64 s[0:1], -1, 0
	s_cmp_eq_u32 s6, 0
	s_cbranch_scc1 .LBB0_1048
	v_lshl_add_u64 v[4:5], v[182:183], 0, v[206:207]
	global_load_dwordx4 v[134:137], v[4:5], off
	s_waitcnt vmcnt(0)
	v_lshlrev_b32_e32 v2, 16, v134
	v_and_b32_e32 v4, 0xffff0000, v134
	v_lshlrev_b32_e32 v134, 16, v135
	v_and_b32_e32 v135, 0xffff0000, v135
	v_lshlrev_b32_e32 v175, 16, v136
	v_sub_f32_e32 v5, v4, v201
	v_sub_f32_e32 v4, v2, v201
	v_sub_f32_e32 v135, v135, v201
	v_sub_f32_e32 v134, v134, v201
	v_pk_mul_f32 v[134:135], v[174:175], v[134:135] op_sel_hi:[0,1]
	v_pk_mul_f32 v[4:5], v[174:175], v[4:5] op_sel_hi:[0,1]
	s_waitcnt lgkmcnt(1)
	v_pk_fma_f32 v[4:5], v[150:151], v[4:5], v[154:155]
	v_pk_fma_f32 v[134:135], v[152:153], v[134:135], v[156:157]
	v_and_b32_e32 v136, 0xffff0000, v136
	v_lshlrev_b32_e32 v203, 16, v137
	v_and_b32_e32 v137, 0xffff0000, v137
	v_pk_mul_f32 v[134:135], v[134:135], s[76:77] op_sel_hi:[1,0]
	v_pk_mul_f32 v[4:5], v[4:5], s[76:77] op_sel_hi:[1,0]
	v_pk_fma_f32 v[140:141], v[128:129], 0.5, v[134:135] op_sel_hi:[1,0,1]
	v_pk_fma_f32 v[138:139], v[126:127], 0.5, v[4:5] op_sel_hi:[1,0,1]
	v_sub_f32_e32 v5, v136, v201
	v_sub_f32_e32 v4, v175, v201
	v_sub_f32_e32 v135, v137, v201
	v_sub_f32_e32 v134, v203, v201
	v_pk_mul_f32 v[134:135], v[174:175], v[134:135] op_sel_hi:[0,1]
	v_pk_mul_f32 v[4:5], v[174:175], v[4:5] op_sel_hi:[0,1]
	s_waitcnt lgkmcnt(0)
	v_pk_fma_f32 v[4:5], v[142:143], v[4:5], v[146:147]
	v_pk_fma_f32 v[134:135], v[144:145], v[134:135], v[148:149]
	v_pk_mul_f32 v[4:5], v[4:5], s[76:77] op_sel_hi:[1,0]
	v_pk_mul_f32 v[134:135], v[134:135], s[76:77] op_sel_hi:[1,0]
	v_pk_fma_f32 v[216:217], v[130:131], 0.5, v[4:5] op_sel_hi:[1,0,1]
	v_pk_fma_f32 v[218:219], v[132:133], 0.5, v[134:135] op_sel_hi:[1,0,1]
	v_pk_add_f32 v[134:135], v[138:139], v[216:217]
	v_pk_add_f32 v[4:5], v[140:141], v[218:219]
	v_pk_mul_f32 v[136:137], v[216:217], v[216:217]
	v_pk_mul_f32 v[222:223], v[218:219], v[218:219]
	v_pk_fma_f32 v[136:137], v[138:139], v[138:139], v[136:137]
	v_pk_fma_f32 v[222:223], v[140:141], v[140:141], v[222:223]
	v_pk_mov_b32 v[224:225], v[134:135], v[4:5] op_sel:[1,0]
	v_mov_b32_e32 v135, v5
	v_pk_add_f32 v[4:5], v[224:225], v[134:135]
	v_pk_mov_b32 v[134:135], v[136:137], v[222:223] op_sel:[1,0]
	v_mov_b32_e32 v137, v223
	v_pk_add_f32 v[134:135], v[134:135], v[136:137]
	v_add_f32_e32 v2, v4, v5
	v_pk_add_f32 v[134:135], v[134:135], v[134:135] op_sel:[0,1] op_sel_hi:[1,0]
	v_cvt_pk_bf16_f32 v138, v138, v139
	v_cvt_pk_bf16_f32 v139, v140, v141
	v_cvt_pk_bf16_f32 v140, v216, v217
	v_lshl_add_u64 v[216:217], s[18:19], 0, v[206:207]
	v_add_f32_e32 v2, 0, v2
	v_mov_b32_e32 v4, v3
	v_mov_b32_e32 v5, v3
	v_mov_b32_e32 v135, v3
	v_mov_b32_e32 v136, v3
	v_mov_b32_e32 v137, v3
	v_cvt_pk_bf16_f32 v141, v218, v219
	v_lshl_add_u64 v[216:217], v[178:179], 1, v[216:217]
	global_store_dwordx4 v[216:217], v[138:141], off nt
	s_branch .LBB0_1049
.Lrfast_ffo:
	v_lshlrev_b32_e32 v134, 12, v180
	v_lshl_add_u32 v134, v178, 1, v134
	v_add_u32_e32 v135, 0x80000, v134
	v_lshl_add_u32 v138, v191, 4, v180
	v_lshlrev_b32_e32 v138, 3, v138
	s_add_u32 s6, s18, 0x10000
	s_addc_u32 s7, s19, 0
	s_add_u32 s8, s18, 0x20000
	s_addc_u32 s9, s19, 0
	s_add_u32 s10, s18, 0x30000
	s_addc_u32 s11, s19, 0
	v_lshlrev_b32_e32 v136, 3, v4
	v_add_u32_e32 v136, 0x20000, v136
	v_lshlrev_b32_e32 v137, 2, v2
	v_add_u32_e32 v137, 0x20800, v137
	global_load_dwordx4 v[204:207], v134, s[18:19]
	global_load_dwordx4 v[208:211], v134, s[6:7]
	global_load_dwordx4 v[212:215], v134, s[8:9]
	global_load_dwordx4 v[216:219], v134, s[10:11]
	global_load_dwordx4 v[222:225], v134, s[18:19] offset:256
	global_load_dwordx4 v[182:185], v134, s[6:7] offset:256
	global_load_dwordx4 v[166:169], v134, s[8:9] offset:256
	global_load_dwordx4 v[170:173], v134, s[10:11] offset:256
	ds_read2_b64 v[142:145], v136 offset0:0 offset1:16
	ds_read2_b64 v[146:149], v136 offset0:32 offset1:48
	ds_read_b128 v[150:153], v137
	ds_read_b128 v[154:157], v137 offset:16
	ds_read_b128 v[158:161], v137 offset:1024
	ds_read_b128 v[162:165], v137 offset:1040
	v_cmp_lt_i32_e32 vcc, v234, v230
	s_nop 1
	v_cndmask_b32_e32 v201, v228, v234, vcc
	v_cmp_lt_i32_e32 vcc, v195, v230
	s_nop 1
	v_cndmask_b32_e32 v203, v228, v195, vcc
	v_lshlrev_b32_e32 v201, 2, v201
	v_lshlrev_b32_e32 v203, 2, v203
	s_waitcnt lgkmcnt(0)
	v_mul_f32_e32 v142, 0x3a000000, v142
	v_mul_f32_e32 v174, v142, v142
	v_fma_f32 v174, v143, s72, -v174
	v_add_f32_e32 v174, 0x3727c5ac, v174
	v_mul_f32_e32 v144, 0x3a000000, v144
	v_mul_f32_e32 v175, v144, v144
	v_fma_f32 v175, v145, s72, -v175
	v_add_f32_e32 v175, 0x3727c5ac, v175
	v_mul_f32_e32 v146, 0x3a000000, v146
	v_mul_f32_e32 v176, v146, v146
	v_fma_f32 v176, v147, s72, -v176
	v_add_f32_e32 v176, 0x3727c5ac, v176
	v_mul_f32_e32 v148, 0x3a000000, v148
	v_mul_f32_e32 v177, v148, v148
	v_fma_f32 v177, v149, s72, -v177
	v_add_f32_e32 v177, 0x3727c5ac, v177
	v_rsq_f32_e32 v143, v174
	v_rsq_f32_e32 v145, v175
	v_rsq_f32_e32 v147, v176
	v_rsq_f32_e32 v149, v177
	s_nop 0
	s_waitcnt vmcnt(4)
	v_lshlrev_b32_e32 v174, 16, v204
	v_and_b32_e32 v175, 0xffff0000, v204
	v_lshlrev_b32_e32 v176, 16, v205
	v_and_b32_e32 v177, 0xffff0000, v205
	v_lshlrev_b32_e32 v178, 16, v206
	v_and_b32_e32 v179, 0xffff0000, v206
	v_lshlrev_b32_e32 v180, 16, v207
	v_and_b32_e32 v181, 0xffff0000, v207
	v_pk_add_f32 v[174:175], v[174:175], v[142:143] op_sel_hi:[1,0] neg_lo:[0,1] neg_hi:[0,1]
	v_pk_add_f32 v[176:177], v[176:177], v[142:143] op_sel_hi:[1,0] neg_lo:[0,1] neg_hi:[0,1]
	v_pk_add_f32 v[178:179], v[178:179], v[142:143] op_sel_hi:[1,0] neg_lo:[0,1] neg_hi:[0,1]
	v_pk_add_f32 v[180:181], v[180:181], v[142:143] op_sel_hi:[1,0] neg_lo:[0,1] neg_hi:[0,1]
	v_pk_mul_f32 v[174:175], v[142:143], v[174:175] op_sel:[1,0] op_sel_hi:[1,1]
	v_pk_mul_f32 v[176:177], v[142:143], v[176:177] op_sel:[1,0] op_sel_hi:[1,1]
	v_pk_mul_f32 v[178:179], v[142:143], v[178:179] op_sel:[1,0] op_sel_hi:[1,1]
	v_pk_mul_f32 v[180:181], v[142:143], v[180:181] op_sel:[1,0] op_sel_hi:[1,1]
	v_pk_fma_f32 v[174:175], v[150:151], v[174:175], v[158:159]
	v_pk_fma_f32 v[176:177], v[152:153], v[176:177], v[160:161]
	v_pk_fma_f32 v[178:179], v[154:155], v[178:179], v[162:163]
	v_pk_fma_f32 v[180:181], v[156:157], v[180:181], v[164:165]
	v_pk_mul_f32 v[174:175], v[174:175], s[76:77] op_sel_hi:[1,0]
	v_pk_mul_f32 v[176:177], v[176:177], s[76:77] op_sel_hi:[1,0]
	v_pk_mul_f32 v[178:179], v[178:179], s[76:77] op_sel_hi:[1,0]
	v_pk_mul_f32 v[180:181], v[180:181], s[76:77] op_sel_hi:[1,0]
	v_pk_fma_f32 v[126:127], v[126:127], 0.5, v[174:175] op_sel_hi:[1,0,1]
	v_pk_fma_f32 v[128:129], v[128:129], 0.5, v[176:177] op_sel_hi:[1,0,1]
	v_pk_fma_f32 v[130:131], v[130:131], 0.5, v[178:179] op_sel_hi:[1,0,1]
	v_pk_fma_f32 v[132:133], v[132:133], 0.5, v[180:181] op_sel_hi:[1,0,1]
	v_pk_add_f32 v[174:175], v[126:127], v[130:131]
	v_pk_add_f32 v[176:177], v[128:129], v[132:133]
	v_pk_mul_f32 v[178:179], v[126:127], v[126:127]
	v_pk_mul_f32 v[180:181], v[128:129], v[128:129]
	v_pk_fma_f32 v[178:179], v[130:131], v[130:131], v[178:179]
	v_pk_fma_f32 v[180:181], v[132:133], v[132:133], v[180:181]
	v_pk_add_f32 v[174:175], v[174:175], v[176:177]
	v_pk_add_f32 v[178:179], v[178:179], v[180:181]
	v_cvt_pk_bf16_f32 v204, v126, v127
	v_cvt_pk_bf16_f32 v205, v128, v129
	v_cvt_pk_bf16_f32 v206, v130, v131
	v_cvt_pk_bf16_f32 v207, v132, v133
	v_add_f32_e32 v2, v174, v175
	v_add_f32_e32 v140, v178, v179
	v_lshlrev_b32_e32 v174, 16, v208
	v_and_b32_e32 v175, 0xffff0000, v208
	v_lshlrev_b32_e32 v176, 16, v209
	v_and_b32_e32 v177, 0xffff0000, v209
	v_lshlrev_b32_e32 v178, 16, v210
	v_and_b32_e32 v179, 0xffff0000, v210
	v_lshlrev_b32_e32 v180, 16, v211
	v_and_b32_e32 v181, 0xffff0000, v211
	v_pk_add_f32 v[174:175], v[174:175], v[144:145] op_sel_hi:[1,0] neg_lo:[0,1] neg_hi:[0,1]
	v_pk_add_f32 v[176:177], v[176:177], v[144:145] op_sel_hi:[1,0] neg_lo:[0,1] neg_hi:[0,1]
	v_pk_add_f32 v[178:179], v[178:179], v[144:145] op_sel_hi:[1,0] neg_lo:[0,1] neg_hi:[0,1]
	v_pk_add_f32 v[180:181], v[180:181], v[144:145] op_sel_hi:[1,0] neg_lo:[0,1] neg_hi:[0,1]
	v_pk_mul_f32 v[174:175], v[144:145], v[174:175] op_sel:[1,0] op_sel_hi:[1,1]
	v_pk_mul_f32 v[176:177], v[144:145], v[176:177] op_sel:[1,0] op_sel_hi:[1,1]
	v_pk_mul_f32 v[178:179], v[144:145], v[178:179] op_sel:[1,0] op_sel_hi:[1,1]
	v_pk_mul_f32 v[180:181], v[144:145], v[180:181] op_sel:[1,0] op_sel_hi:[1,1]
	v_pk_fma_f32 v[174:175], v[150:151], v[174:175], v[158:159]
	v_pk_fma_f32 v[176:177], v[152:153], v[176:177], v[160:161]
	v_pk_fma_f32 v[178:179], v[154:155], v[178:179], v[162:163]
	v_pk_fma_f32 v[180:181], v[156:157], v[180:181], v[164:165]
	v_pk_mul_f32 v[174:175], v[174:175], s[76:77] op_sel_hi:[1,0]
	v_pk_mul_f32 v[176:177], v[176:177], s[76:77] op_sel_hi:[1,0]
	v_pk_mul_f32 v[178:179], v[178:179], s[76:77] op_sel_hi:[1,0]
	v_pk_mul_f32 v[180:181], v[180:181], s[76:77] op_sel_hi:[1,0]
	v_pk_fma_f32 v[118:119], v[118:119], 0.5, v[174:175] op_sel_hi:[1,0,1]
	v_pk_fma_f32 v[120:121], v[120:121], 0.5, v[176:177] op_sel_hi:[1,0,1]
	v_pk_fma_f32 v[122:123], v[122:123], 0.5, v[178:179] op_sel_hi:[1,0,1]
	v_pk_fma_f32 v[124:125], v[124:125], 0.5, v[180:181] op_sel_hi:[1,0,1]
	v_pk_add_f32 v[174:175], v[118:119], v[122:123]
	v_pk_add_f32 v[176:177], v[120:121], v[124:125]
	v_pk_mul_f32 v[178:179], v[118:119], v[118:119]
	v_pk_mul_f32 v[180:181], v[120:121], v[120:121]
	v_pk_fma_f32 v[178:179], v[122:123], v[122:123], v[178:179]
	v_pk_fma_f32 v[180:181], v[124:125], v[124:125], v[180:181]
	v_pk_add_f32 v[174:175], v[174:175], v[176:177]
	v_pk_add_f32 v[178:179], v[178:179], v[180:181]
	v_cvt_pk_bf16_f32 v208, v118, v119
	v_cvt_pk_bf16_f32 v209, v120, v121
	v_cvt_pk_bf16_f32 v210, v122, v123
	v_cvt_pk_bf16_f32 v211, v124, v125
	v_add_f32_e32 v4, v174, v175
	v_add_f32_e32 v186, v178, v179
	v_lshlrev_b32_e32 v174, 16, v212
	v_and_b32_e32 v175, 0xffff0000, v212
	v_lshlrev_b32_e32 v176, 16, v213
	v_and_b32_e32 v177, 0xffff0000, v213
	v_lshlrev_b32_e32 v178, 16, v214
	v_and_b32_e32 v179, 0xffff0000, v214
	v_lshlrev_b32_e32 v180, 16, v215
	v_and_b32_e32 v181, 0xffff0000, v215
	v_pk_add_f32 v[174:175], v[174:175], v[146:147] op_sel_hi:[1,0] neg_lo:[0,1] neg_hi:[0,1]
	v_pk_add_f32 v[176:177], v[176:177], v[146:147] op_sel_hi:[1,0] neg_lo:[0,1] neg_hi:[0,1]
	v_pk_add_f32 v[178:179], v[178:179], v[146:147] op_sel_hi:[1,0] neg_lo:[0,1] neg_hi:[0,1]
	v_pk_add_f32 v[180:181], v[180:181], v[146:147] op_sel_hi:[1,0] neg_lo:[0,1] neg_hi:[0,1]
	v_pk_mul_f32 v[174:175], v[146:147], v[174:175] op_sel:[1,0] op_sel_hi:[1,1]
	v_pk_mul_f32 v[176:177], v[146:147], v[176:177] op_sel:[1,0] op_sel_hi:[1,1]
	v_pk_mul_f32 v[178:179], v[146:147], v[178:179] op_sel:[1,0] op_sel_hi:[1,1]
	v_pk_mul_f32 v[180:181], v[146:147], v[180:181] op_sel:[1,0] op_sel_hi:[1,1]
	v_pk_fma_f32 v[174:175], v[150:151], v[174:175], v[158:159]
	v_pk_fma_f32 v[176:177], v[152:153], v[176:177], v[160:161]
	v_pk_fma_f32 v[178:179], v[154:155], v[178:179], v[162:163]
	v_pk_fma_f32 v[180:181], v[156:157], v[180:181], v[164:165]
	v_pk_mul_f32 v[174:175], v[174:175], s[76:77] op_sel_hi:[1,0]
	v_pk_mul_f32 v[176:177], v[176:177], s[76:77] op_sel_hi:[1,0]
	v_pk_mul_f32 v[178:179], v[178:179], s[76:77] op_sel_hi:[1,0]
	v_pk_mul_f32 v[180:181], v[180:181], s[76:77] op_sel_hi:[1,0]
	v_pk_fma_f32 v[110:111], v[110:111], 0.5, v[174:175] op_sel_hi:[1,0,1]
	v_pk_fma_f32 v[112:113], v[112:113], 0.5, v[176:177] op_sel_hi:[1,0,1]
	v_pk_fma_f32 v[114:115], v[114:115], 0.5, v[178:179] op_sel_hi:[1,0,1]
	v_pk_fma_f32 v[116:117], v[116:117], 0.5, v[180:181] op_sel_hi:[1,0,1]
	v_pk_add_f32 v[174:175], v[110:111], v[114:115]
	v_pk_add_f32 v[176:177], v[112:113], v[116:117]
	v_pk_mul_f32 v[178:179], v[110:111], v[110:111]
	v_pk_mul_f32 v[180:181], v[112:113], v[112:113]
	v_pk_fma_f32 v[178:179], v[114:115], v[114:115], v[178:179]
	v_pk_fma_f32 v[180:181], v[116:117], v[116:117], v[180:181]
	v_pk_add_f32 v[174:175], v[174:175], v[176:177]
	v_pk_add_f32 v[178:179], v[178:179], v[180:181]
	v_cvt_pk_bf16_f32 v212, v110, v111
	v_cvt_pk_bf16_f32 v213, v112, v113
	v_cvt_pk_bf16_f32 v214, v114, v115
	v_cvt_pk_bf16_f32 v215, v116, v117
	v_add_f32_e32 v5, v174, v175
	v_add_f32_e32 v187, v178, v179
	v_lshlrev_b32_e32 v174, 16, v216
	v_and_b32_e32 v175, 0xffff0000, v216
	v_lshlrev_b32_e32 v176, 16, v217
	v_and_b32_e32 v177, 0xffff0000, v217
	v_lshlrev_b32_e32 v178, 16, v218
	v_and_b32_e32 v179, 0xffff0000, v218
	v_lshlrev_b32_e32 v180, 16, v219
	v_and_b32_e32 v181, 0xffff0000, v219
	v_pk_add_f32 v[174:175], v[174:175], v[148:149] op_sel_hi:[1,0] neg_lo:[0,1] neg_hi:[0,1]
	v_pk_add_f32 v[176:177], v[176:177], v[148:149] op_sel_hi:[1,0] neg_lo:[0,1] neg_hi:[0,1]
	v_pk_add_f32 v[178:179], v[178:179], v[148:149] op_sel_hi:[1,0] neg_lo:[0,1] neg_hi:[0,1]
	v_pk_add_f32 v[180:181], v[180:181], v[148:149] op_sel_hi:[1,0] neg_lo:[0,1] neg_hi:[0,1]
	v_pk_mul_f32 v[174:175], v[148:149], v[174:175] op_sel:[1,0] op_sel_hi:[1,1]
	v_pk_mul_f32 v[176:177], v[148:149], v[176:177] op_sel:[1,0] op_sel_hi:[1,1]
	v_pk_mul_f32 v[178:179], v[148:149], v[178:179] op_sel:[1,0] op_sel_hi:[1,1]
	v_pk_mul_f32 v[180:181], v[148:149], v[180:181] op_sel:[1,0] op_sel_hi:[1,1]
	v_pk_fma_f32 v[174:175], v[150:151], v[174:175], v[158:159]
	v_pk_fma_f32 v[176:177], v[152:153], v[176:177], v[160:161]
	v_pk_fma_f32 v[178:179], v[154:155], v[178:179], v[162:163]
	v_pk_fma_f32 v[180:181], v[156:157], v[180:181], v[164:165]
	v_pk_mul_f32 v[174:175], v[174:175], s[76:77] op_sel_hi:[1,0]
	v_pk_mul_f32 v[176:177], v[176:177], s[76:77] op_sel_hi:[1,0]
	v_pk_mul_f32 v[178:179], v[178:179], s[76:77] op_sel_hi:[1,0]
	v_pk_mul_f32 v[180:181], v[180:181], s[76:77] op_sel_hi:[1,0]
	v_pk_fma_f32 v[102:103], v[102:103], 0.5, v[174:175] op_sel_hi:[1,0,1]
	v_pk_fma_f32 v[104:105], v[104:105], 0.5, v[176:177] op_sel_hi:[1,0,1]
	v_pk_fma_f32 v[106:107], v[106:107], 0.5, v[178:179] op_sel_hi:[1,0,1]
	v_pk_fma_f32 v[108:109], v[108:109], 0.5, v[180:181] op_sel_hi:[1,0,1]
	v_pk_add_f32 v[174:175], v[102:103], v[106:107]
	v_pk_add_f32 v[176:177], v[104:105], v[108:109]
	v_pk_mul_f32 v[178:179], v[102:103], v[102:103]
	v_pk_mul_f32 v[180:181], v[104:105], v[104:105]
	v_pk_fma_f32 v[178:179], v[106:107], v[106:107], v[178:179]
	v_pk_fma_f32 v[180:181], v[108:109], v[108:109], v[180:181]
	v_pk_add_f32 v[174:175], v[174:175], v[176:177]
	v_pk_add_f32 v[178:179], v[178:179], v[180:181]
	v_cvt_pk_bf16_f32 v216, v102, v103
	v_cvt_pk_bf16_f32 v217, v104, v105
	v_cvt_pk_bf16_f32 v218, v106, v107
	v_cvt_pk_bf16_f32 v219, v108, v109
	v_add_f32_e32 v139, v174, v175
	v_add_f32_e32 v197, v178, v179
	global_load_dwordx4 v[102:105], v135, s[18:19]
	global_load_dwordx4 v[106:109], v135, s[6:7]
	global_load_dwordx4 v[110:113], v135, s[8:9]
	global_load_dwordx4 v[114:117], v135, s[10:11]
	global_load_dwordx4 v[118:121], v135, s[18:19] offset:256
	global_load_dwordx4 v[122:125], v135, s[6:7] offset:256
	global_load_dwordx4 v[126:129], v135, s[8:9] offset:256
	global_load_dwordx4 v[130:133], v135, s[10:11] offset:256
	global_store_dwordx4 v134, v[204:207], s[18:19] nt
	global_store_dwordx4 v134, v[208:211], s[6:7] nt
	global_store_dwordx4 v134, v[212:215], s[8:9] nt
	global_store_dwordx4 v134, v[216:219], s[10:11] nt
	ds_read_b128 v[150:153], v137 offset:512
	ds_read_b128 v[154:157], v137 offset:528
	ds_read_b128 v[158:161], v137 offset:1536
	ds_read_b128 v[162:165], v137 offset:1552
	s_waitcnt lgkmcnt(0)
	s_waitcnt vmcnt(12)
	v_lshlrev_b32_e32 v174, 16, v222
	v_and_b32_e32 v175, 0xffff0000, v222
	v_lshlrev_b32_e32 v176, 16, v223
	v_and_b32_e32 v177, 0xffff0000, v223
	v_lshlrev_b32_e32 v178, 16, v224
	v_and_b32_e32 v179, 0xffff0000, v224
	v_lshlrev_b32_e32 v180, 16, v225
	v_and_b32_e32 v181, 0xffff0000, v225
	v_pk_add_f32 v[174:175], v[174:175], v[142:143] op_sel_hi:[1,0] neg_lo:[0,1] neg_hi:[0,1]
	v_pk_add_f32 v[176:177], v[176:177], v[142:143] op_sel_hi:[1,0] neg_lo:[0,1] neg_hi:[0,1]
	v_pk_add_f32 v[178:179], v[178:179], v[142:143] op_sel_hi:[1,0] neg_lo:[0,1] neg_hi:[0,1]
	v_pk_add_f32 v[180:181], v[180:181], v[142:143] op_sel_hi:[1,0] neg_lo:[0,1] neg_hi:[0,1]
	v_pk_mul_f32 v[174:175], v[142:143], v[174:175] op_sel:[1,0] op_sel_hi:[1,1]
	v_pk_mul_f32 v[176:177], v[142:143], v[176:177] op_sel:[1,0] op_sel_hi:[1,1]
	v_pk_mul_f32 v[178:179], v[142:143], v[178:179] op_sel:[1,0] op_sel_hi:[1,1]
	v_pk_mul_f32 v[180:181], v[142:143], v[180:181] op_sel:[1,0] op_sel_hi:[1,1]
	v_pk_fma_f32 v[174:175], v[150:151], v[174:175], v[158:159]
	v_pk_fma_f32 v[176:177], v[152:153], v[176:177], v[160:161]
	v_pk_fma_f32 v[178:179], v[154:155], v[178:179], v[162:163]
	v_pk_fma_f32 v[180:181], v[156:157], v[180:181], v[164:165]
	v_pk_mul_f32 v[174:175], v[174:175], s[76:77] op_sel_hi:[1,0]
	v_pk_mul_f32 v[176:177], v[176:177], s[76:77] op_sel_hi:[1,0]
	v_pk_mul_f32 v[178:179], v[178:179], s[76:77] op_sel_hi:[1,0]
	v_pk_mul_f32 v[180:181], v[180:181], s[76:77] op_sel_hi:[1,0]
	v_pk_fma_f32 v[94:95], v[94:95], 0.5, v[174:175] op_sel_hi:[1,0,1]
	v_pk_fma_f32 v[96:97], v[96:97], 0.5, v[176:177] op_sel_hi:[1,0,1]
	v_pk_fma_f32 v[98:99], v[98:99], 0.5, v[178:179] op_sel_hi:[1,0,1]
	v_pk_fma_f32 v[100:101], v[100:101], 0.5, v[180:181] op_sel_hi:[1,0,1]
	v_pk_add_f32 v[174:175], v[94:95], v[98:99]
	v_pk_add_f32 v[176:177], v[96:97], v[100:101]
	v_pk_mul_f32 v[178:179], v[94:95], v[94:95]
	v_pk_mul_f32 v[180:181], v[96:97], v[96:97]
	v_pk_fma_f32 v[178:179], v[98:99], v[98:99], v[178:179]
	v_pk_fma_f32 v[180:181], v[100:101], v[100:101], v[180:181]
	v_pk_add_f32 v[174:175], v[174:175], v[176:177]
	v_pk_add_f32 v[178:179], v[178:179], v[180:181]
	v_cvt_pk_bf16_f32 v222, v94, v95
	v_cvt_pk_bf16_f32 v223, v96, v97
	v_cvt_pk_bf16_f32 v224, v98, v99
	v_cvt_pk_bf16_f32 v225, v100, v101
	v_add_f32_e32 v174, v174, v175
	v_add_f32_e32 v178, v178, v179
	v_add_f32_e32 v2, v2, v174
	v_add_f32_e32 v140, v140, v178
	v_lshlrev_b32_e32 v174, 16, v182
	v_and_b32_e32 v175, 0xffff0000, v182
	v_lshlrev_b32_e32 v176, 16, v183
	v_and_b32_e32 v177, 0xffff0000, v183
	v_lshlrev_b32_e32 v178, 16, v184
	v_and_b32_e32 v179, 0xffff0000, v184
	v_lshlrev_b32_e32 v180, 16, v185
	v_and_b32_e32 v181, 0xffff0000, v185
	v_pk_add_f32 v[174:175], v[174:175], v[144:145] op_sel_hi:[1,0] neg_lo:[0,1] neg_hi:[0,1]
	v_pk_add_f32 v[176:177], v[176:177], v[144:145] op_sel_hi:[1,0] neg_lo:[0,1] neg_hi:[0,1]
	v_pk_add_f32 v[178:179], v[178:179], v[144:145] op_sel_hi:[1,0] neg_lo:[0,1] neg_hi:[0,1]
	v_pk_add_f32 v[180:181], v[180:181], v[144:145] op_sel_hi:[1,0] neg_lo:[0,1] neg_hi:[0,1]
	v_pk_mul_f32 v[174:175], v[144:145], v[174:175] op_sel:[1,0] op_sel_hi:[1,1]
	v_pk_mul_f32 v[176:177], v[144:145], v[176:177] op_sel:[1,0] op_sel_hi:[1,1]
	v_pk_mul_f32 v[178:179], v[144:145], v[178:179] op_sel:[1,0] op_sel_hi:[1,1]
	v_pk_mul_f32 v[180:181], v[144:145], v[180:181] op_sel:[1,0] op_sel_hi:[1,1]
	v_pk_fma_f32 v[174:175], v[150:151], v[174:175], v[158:159]
	v_pk_fma_f32 v[176:177], v[152:153], v[176:177], v[160:161]
	v_pk_fma_f32 v[178:179], v[154:155], v[178:179], v[162:163]
	v_pk_fma_f32 v[180:181], v[156:157], v[180:181], v[164:165]
	v_pk_mul_f32 v[174:175], v[174:175], s[76:77] op_sel_hi:[1,0]
	v_pk_mul_f32 v[176:177], v[176:177], s[76:77] op_sel_hi:[1,0]
	v_pk_mul_f32 v[178:179], v[178:179], s[76:77] op_sel_hi:[1,0]
	v_pk_mul_f32 v[180:181], v[180:181], s[76:77] op_sel_hi:[1,0]
	v_pk_fma_f32 v[86:87], v[86:87], 0.5, v[174:175] op_sel_hi:[1,0,1]
	v_pk_fma_f32 v[88:89], v[88:89], 0.5, v[176:177] op_sel_hi:[1,0,1]
	v_pk_fma_f32 v[90:91], v[90:91], 0.5, v[178:179] op_sel_hi:[1,0,1]
	v_pk_fma_f32 v[92:93], v[92:93], 0.5, v[180:181] op_sel_hi:[1,0,1]
	v_pk_add_f32 v[174:175], v[86:87], v[90:91]
	v_pk_add_f32 v[176:177], v[88:89], v[92:93]
	v_pk_mul_f32 v[178:179], v[86:87], v[86:87]
	v_pk_mul_f32 v[180:181], v[88:89], v[88:89]
	v_pk_fma_f32 v[178:179], v[90:91], v[90:91], v[178:179]
	v_pk_fma_f32 v[180:181], v[92:93], v[92:93], v[180:181]
	v_pk_add_f32 v[174:175], v[174:175], v[176:177]
	v_pk_add_f32 v[178:179], v[178:179], v[180:181]
	v_cvt_pk_bf16_f32 v182, v86, v87
	v_cvt_pk_bf16_f32 v183, v88, v89
	v_cvt_pk_bf16_f32 v184, v90, v91
	v_cvt_pk_bf16_f32 v185, v92, v93
	v_add_f32_e32 v174, v174, v175
	v_add_f32_e32 v178, v178, v179
	v_add_f32_e32 v4, v4, v174
	v_add_f32_e32 v186, v186, v178
	v_lshlrev_b32_e32 v174, 16, v166
	v_and_b32_e32 v175, 0xffff0000, v166
	v_lshlrev_b32_e32 v176, 16, v167
	v_and_b32_e32 v177, 0xffff0000, v167
	v_lshlrev_b32_e32 v178, 16, v168
	v_and_b32_e32 v179, 0xffff0000, v168
	v_lshlrev_b32_e32 v180, 16, v169
	v_and_b32_e32 v181, 0xffff0000, v169
	v_pk_add_f32 v[174:175], v[174:175], v[146:147] op_sel_hi:[1,0] neg_lo:[0,1] neg_hi:[0,1]
	v_pk_add_f32 v[176:177], v[176:177], v[146:147] op_sel_hi:[1,0] neg_lo:[0,1] neg_hi:[0,1]
	v_pk_add_f32 v[178:179], v[178:179], v[146:147] op_sel_hi:[1,0] neg_lo:[0,1] neg_hi:[0,1]
	v_pk_add_f32 v[180:181], v[180:181], v[146:147] op_sel_hi:[1,0] neg_lo:[0,1] neg_hi:[0,1]
	v_pk_mul_f32 v[174:175], v[146:147], v[174:175] op_sel:[1,0] op_sel_hi:[1,1]
	v_pk_mul_f32 v[176:177], v[146:147], v[176:177] op_sel:[1,0] op_sel_hi:[1,1]
	v_pk_mul_f32 v[178:179], v[146:147], v[178:179] op_sel:[1,0] op_sel_hi:[1,1]
	v_pk_mul_f32 v[180:181], v[146:147], v[180:181] op_sel:[1,0] op_sel_hi:[1,1]
	v_pk_fma_f32 v[174:175], v[150:151], v[174:175], v[158:159]
	v_pk_fma_f32 v[176:177], v[152:153], v[176:177], v[160:161]
	v_pk_fma_f32 v[178:179], v[154:155], v[178:179], v[162:163]
	v_pk_fma_f32 v[180:181], v[156:157], v[180:181], v[164:165]
	v_pk_mul_f32 v[174:175], v[174:175], s[76:77] op_sel_hi:[1,0]
	v_pk_mul_f32 v[176:177], v[176:177], s[76:77] op_sel_hi:[1,0]
	v_pk_mul_f32 v[178:179], v[178:179], s[76:77] op_sel_hi:[1,0]
	v_pk_mul_f32 v[180:181], v[180:181], s[76:77] op_sel_hi:[1,0]
	v_pk_fma_f32 v[78:79], v[78:79], 0.5, v[174:175] op_sel_hi:[1,0,1]
	v_pk_fma_f32 v[80:81], v[80:81], 0.5, v[176:177] op_sel_hi:[1,0,1]
	v_pk_fma_f32 v[82:83], v[82:83], 0.5, v[178:179] op_sel_hi:[1,0,1]
	v_pk_fma_f32 v[84:85], v[84:85], 0.5, v[180:181] op_sel_hi:[1,0,1]
	v_pk_add_f32 v[174:175], v[78:79], v[82:83]
	v_pk_add_f32 v[176:177], v[80:81], v[84:85]
	v_pk_mul_f32 v[178:179], v[78:79], v[78:79]
	v_pk_mul_f32 v[180:181], v[80:81], v[80:81]
	v_pk_fma_f32 v[178:179], v[82:83], v[82:83], v[178:179]
	v_pk_fma_f32 v[180:181], v[84:85], v[84:85], v[180:181]
	v_pk_add_f32 v[174:175], v[174:175], v[176:177]
	v_pk_add_f32 v[178:179], v[178:179], v[180:181]
	v_cvt_pk_bf16_f32 v166, v78, v79
	v_cvt_pk_bf16_f32 v167, v80, v81
	v_cvt_pk_bf16_f32 v168, v82, v83
	v_cvt_pk_bf16_f32 v169, v84, v85
	v_add_f32_e32 v174, v174, v175
	v_add_f32_e32 v178, v178, v179
	v_add_f32_e32 v5, v5, v174
	v_add_f32_e32 v187, v187, v178
	v_lshlrev_b32_e32 v174, 16, v170
	v_and_b32_e32 v175, 0xffff0000, v170
	v_lshlrev_b32_e32 v176, 16, v171
	v_and_b32_e32 v177, 0xffff0000, v171
	v_lshlrev_b32_e32 v178, 16, v172
	v_and_b32_e32 v179, 0xffff0000, v172
	v_lshlrev_b32_e32 v180, 16, v173
	v_and_b32_e32 v181, 0xffff0000, v173
	v_pk_add_f32 v[174:175], v[174:175], v[148:149] op_sel_hi:[1,0] neg_lo:[0,1] neg_hi:[0,1]
	v_pk_add_f32 v[176:177], v[176:177], v[148:149] op_sel_hi:[1,0] neg_lo:[0,1] neg_hi:[0,1]
	v_pk_add_f32 v[178:179], v[178:179], v[148:149] op_sel_hi:[1,0] neg_lo:[0,1] neg_hi:[0,1]
	v_pk_add_f32 v[180:181], v[180:181], v[148:149] op_sel_hi:[1,0] neg_lo:[0,1] neg_hi:[0,1]
	v_pk_mul_f32 v[174:175], v[148:149], v[174:175] op_sel:[1,0] op_sel_hi:[1,1]
	v_pk_mul_f32 v[176:177], v[148:149], v[176:177] op_sel:[1,0] op_sel_hi:[1,1]
	v_pk_mul_f32 v[178:179], v[148:149], v[178:179] op_sel:[1,0] op_sel_hi:[1,1]
	v_pk_mul_f32 v[180:181], v[148:149], v[180:181] op_sel:[1,0] op_sel_hi:[1,1]
	v_pk_fma_f32 v[174:175], v[150:151], v[174:175], v[158:159]
	v_pk_fma_f32 v[176:177], v[152:153], v[176:177], v[160:161]
	v_pk_fma_f32 v[178:179], v[154:155], v[178:179], v[162:163]
	v_pk_fma_f32 v[180:181], v[156:157], v[180:181], v[164:165]
	v_pk_mul_f32 v[174:175], v[174:175], s[76:77] op_sel_hi:[1,0]
	v_pk_mul_f32 v[176:177], v[176:177], s[76:77] op_sel_hi:[1,0]
	v_pk_mul_f32 v[178:179], v[178:179], s[76:77] op_sel_hi:[1,0]
	v_pk_mul_f32 v[180:181], v[180:181], s[76:77] op_sel_hi:[1,0]
	v_pk_fma_f32 v[70:71], v[70:71], 0.5, v[174:175] op_sel_hi:[1,0,1]
	v_pk_fma_f32 v[72:73], v[72:73], 0.5, v[176:177] op_sel_hi:[1,0,1]
	v_pk_fma_f32 v[74:75], v[74:75], 0.5, v[178:179] op_sel_hi:[1,0,1]
	v_pk_fma_f32 v[76:77], v[76:77], 0.5, v[180:181] op_sel_hi:[1,0,1]
	v_pk_add_f32 v[174:175], v[70:71], v[74:75]
	v_pk_add_f32 v[176:177], v[72:73], v[76:77]
	v_pk_mul_f32 v[178:179], v[70:71], v[70:71]
	v_pk_mul_f32 v[180:181], v[72:73], v[72:73]
	v_pk_fma_f32 v[178:179], v[74:75], v[74:75], v[178:179]
	v_pk_fma_f32 v[180:181], v[76:77], v[76:77], v[180:181]
	v_pk_add_f32 v[174:175], v[174:175], v[176:177]
	v_pk_add_f32 v[178:179], v[178:179], v[180:181]
	v_cvt_pk_bf16_f32 v170, v70, v71
	v_cvt_pk_bf16_f32 v171, v72, v73
	v_cvt_pk_bf16_f32 v172, v74, v75
	v_cvt_pk_bf16_f32 v173, v76, v77
	v_add_f32_e32 v174, v174, v175
	v_add_f32_e32 v178, v178, v179
	v_add_f32_e32 v139, v139, v174
	v_add_f32_e32 v197, v197, v178
	global_store_dwordx4 v134, v[222:225], s[18:19] offset:256 nt
	global_store_dwordx4 v134, v[182:185], s[6:7] offset:256 nt
	global_store_dwordx4 v134, v[166:169], s[8:9] offset:256 nt
	global_store_dwordx4 v134, v[170:173], s[10:11] offset:256 nt
	ds_bpermute_b32 v174, v201, v2
	ds_bpermute_b32 v175, v201, v4
	ds_bpermute_b32 v176, v201, v5
	ds_bpermute_b32 v177, v201, v139
	ds_bpermute_b32 v178, v201, v140
	ds_bpermute_b32 v179, v201, v186
	ds_bpermute_b32 v180, v201, v187
	ds_bpermute_b32 v181, v201, v197
	s_waitcnt lgkmcnt(0)
	v_add_f32_e32 v2, v2, v174
	v_add_f32_e32 v4, v4, v175
	v_add_f32_e32 v5, v5, v176
	v_add_f32_e32 v139, v139, v177
	v_add_f32_e32 v140, v140, v178
	v_add_f32_e32 v186, v186, v179
	v_add_f32_e32 v187, v187, v180
	v_add_f32_e32 v197, v197, v181
	ds_bpermute_b32 v174, v203, v2
	ds_bpermute_b32 v175, v203, v4
	ds_bpermute_b32 v176, v203, v5
	ds_bpermute_b32 v177, v203, v139
	ds_bpermute_b32 v178, v203, v140
	ds_bpermute_b32 v179, v203, v186
	ds_bpermute_b32 v180, v203, v187
	ds_bpermute_b32 v181, v203, v197
	s_waitcnt lgkmcnt(0)
	v_add_f32_e32 v2, v2, v174
	v_add_f32_e32 v4, v4, v175
	v_add_f32_e32 v5, v5, v176
	v_add_f32_e32 v139, v139, v177
	v_add_f32_e32 v140, v140, v178
	v_add_f32_e32 v186, v186, v179
	v_add_f32_e32 v187, v187, v180
	v_add_f32_e32 v197, v197, v181
	v_cmp_eq_u32_e32 vcc, 1, v191
	s_nop 1
	v_cndmask_b32_e32 v2, v2, v4, vcc
	v_cndmask_b32_e32 v140, v140, v186, vcc
	v_cmp_eq_u32_e32 vcc, 2, v191
	s_nop 1
	v_cndmask_b32_e32 v2, v2, v5, vcc
	v_cndmask_b32_e32 v140, v140, v187, vcc
	v_cmp_eq_u32_e32 vcc, 3, v191
	s_nop 1
	v_cndmask_b32_e32 v2, v2, v139, vcc
	v_cndmask_b32_e32 v140, v140, v197, vcc
	global_atomic_add_f32 v138, v2, s[16:17]
	global_atomic_add_f32 v138, v140, s[16:17] offset:4
	ds_read2_b64 v[142:145], v136 offset0:128 offset1:144
	ds_read2_b64 v[146:149], v136 offset0:160 offset1:176
	ds_read_b128 v[150:153], v137
	ds_read_b128 v[154:157], v137 offset:16
	ds_read_b128 v[158:161], v137 offset:1024
	ds_read_b128 v[162:165], v137 offset:1040
	s_waitcnt lgkmcnt(0)
	v_mul_f32_e32 v142, 0x3a000000, v142
	v_mul_f32_e32 v174, v142, v142
	v_fma_f32 v174, v143, s72, -v174
	v_add_f32_e32 v174, 0x3727c5ac, v174
	v_mul_f32_e32 v144, 0x3a000000, v144
	v_mul_f32_e32 v175, v144, v144
	v_fma_f32 v175, v145, s72, -v175
	v_add_f32_e32 v175, 0x3727c5ac, v175
	v_mul_f32_e32 v146, 0x3a000000, v146
	v_mul_f32_e32 v176, v146, v146
	v_fma_f32 v176, v147, s72, -v176
	v_add_f32_e32 v176, 0x3727c5ac, v176
	v_mul_f32_e32 v148, 0x3a000000, v148
	v_mul_f32_e32 v177, v148, v148
	v_fma_f32 v177, v149, s72, -v177
	v_add_f32_e32 v177, 0x3727c5ac, v177
	v_rsq_f32_e32 v143, v174
	v_rsq_f32_e32 v145, v175
	v_rsq_f32_e32 v147, v176
	v_rsq_f32_e32 v149, v177
	s_nop 0
	s_waitcnt vmcnt(14)
	v_lshlrev_b32_e32 v174, 16, v102
	v_and_b32_e32 v175, 0xffff0000, v102
	v_lshlrev_b32_e32 v176, 16, v103
	v_and_b32_e32 v177, 0xffff0000, v103
	v_lshlrev_b32_e32 v178, 16, v104
	v_and_b32_e32 v179, 0xffff0000, v104
	v_lshlrev_b32_e32 v180, 16, v105
	v_and_b32_e32 v181, 0xffff0000, v105
	v_pk_add_f32 v[174:175], v[174:175], v[142:143] op_sel_hi:[1,0] neg_lo:[0,1] neg_hi:[0,1]
	v_pk_add_f32 v[176:177], v[176:177], v[142:143] op_sel_hi:[1,0] neg_lo:[0,1] neg_hi:[0,1]
	v_pk_add_f32 v[178:179], v[178:179], v[142:143] op_sel_hi:[1,0] neg_lo:[0,1] neg_hi:[0,1]
	v_pk_add_f32 v[180:181], v[180:181], v[142:143] op_sel_hi:[1,0] neg_lo:[0,1] neg_hi:[0,1]
	v_pk_mul_f32 v[174:175], v[142:143], v[174:175] op_sel:[1,0] op_sel_hi:[1,1]
	v_pk_mul_f32 v[176:177], v[142:143], v[176:177] op_sel:[1,0] op_sel_hi:[1,1]
	v_pk_mul_f32 v[178:179], v[142:143], v[178:179] op_sel:[1,0] op_sel_hi:[1,1]
	v_pk_mul_f32 v[180:181], v[142:143], v[180:181] op_sel:[1,0] op_sel_hi:[1,1]
	v_pk_fma_f32 v[174:175], v[150:151], v[174:175], v[158:159]
	v_pk_fma_f32 v[176:177], v[152:153], v[176:177], v[160:161]
	v_pk_fma_f32 v[178:179], v[154:155], v[178:179], v[162:163]
	v_pk_fma_f32 v[180:181], v[156:157], v[180:181], v[164:165]
	v_pk_mul_f32 v[174:175], v[174:175], s[76:77] op_sel_hi:[1,0]
	v_pk_mul_f32 v[176:177], v[176:177], s[76:77] op_sel_hi:[1,0]
	v_pk_mul_f32 v[178:179], v[178:179], s[76:77] op_sel_hi:[1,0]
	v_pk_mul_f32 v[180:181], v[180:181], s[76:77] op_sel_hi:[1,0]
	v_pk_fma_f32 v[46:47], v[46:47], 0.5, v[174:175] op_sel_hi:[1,0,1]
	v_pk_fma_f32 v[48:49], v[48:49], 0.5, v[176:177] op_sel_hi:[1,0,1]
	v_pk_fma_f32 v[50:51], v[50:51], 0.5, v[178:179] op_sel_hi:[1,0,1]
	v_pk_fma_f32 v[52:53], v[52:53], 0.5, v[180:181] op_sel_hi:[1,0,1]
	v_pk_add_f32 v[174:175], v[46:47], v[50:51]
	v_pk_add_f32 v[176:177], v[48:49], v[52:53]
	v_pk_mul_f32 v[178:179], v[46:47], v[46:47]
	v_pk_mul_f32 v[180:181], v[48:49], v[48:49]
	v_pk_fma_f32 v[178:179], v[50:51], v[50:51], v[178:179]
	v_pk_fma_f32 v[180:181], v[52:53], v[52:53], v[180:181]
	v_pk_add_f32 v[174:175], v[174:175], v[176:177]
	v_pk_add_f32 v[178:179], v[178:179], v[180:181]
	v_cvt_pk_bf16_f32 v102, v46, v47
	v_cvt_pk_bf16_f32 v103, v48, v49
	v_cvt_pk_bf16_f32 v104, v50, v51
	v_cvt_pk_bf16_f32 v105, v52, v53
	v_add_f32_e32 v2, v174, v175
	v_add_f32_e32 v140, v178, v179
	v_lshlrev_b32_e32 v174, 16, v106
	v_and_b32_e32 v175, 0xffff0000, v106
	v_lshlrev_b32_e32 v176, 16, v107
	v_and_b32_e32 v177, 0xffff0000, v107
	v_lshlrev_b32_e32 v178, 16, v108
	v_and_b32_e32 v179, 0xffff0000, v108
	v_lshlrev_b32_e32 v180, 16, v109
	v_and_b32_e32 v181, 0xffff0000, v109
	v_pk_add_f32 v[174:175], v[174:175], v[144:145] op_sel_hi:[1,0] neg_lo:[0,1] neg_hi:[0,1]
	v_pk_add_f32 v[176:177], v[176:177], v[144:145] op_sel_hi:[1,0] neg_lo:[0,1] neg_hi:[0,1]
	v_pk_add_f32 v[178:179], v[178:179], v[144:145] op_sel_hi:[1,0] neg_lo:[0,1] neg_hi:[0,1]
	v_pk_add_f32 v[180:181], v[180:181], v[144:145] op_sel_hi:[1,0] neg_lo:[0,1] neg_hi:[0,1]
	v_pk_mul_f32 v[174:175], v[144:145], v[174:175] op_sel:[1,0] op_sel_hi:[1,1]
	v_pk_mul_f32 v[176:177], v[144:145], v[176:177] op_sel:[1,0] op_sel_hi:[1,1]
	v_pk_mul_f32 v[178:179], v[144:145], v[178:179] op_sel:[1,0] op_sel_hi:[1,1]
	v_pk_mul_f32 v[180:181], v[144:145], v[180:181] op_sel:[1,0] op_sel_hi:[1,1]
	v_pk_fma_f32 v[174:175], v[150:151], v[174:175], v[158:159]
	v_pk_fma_f32 v[176:177], v[152:153], v[176:177], v[160:161]
	v_pk_fma_f32 v[178:179], v[154:155], v[178:179], v[162:163]
	v_pk_fma_f32 v[180:181], v[156:157], v[180:181], v[164:165]
	v_pk_mul_f32 v[174:175], v[174:175], s[76:77] op_sel_hi:[1,0]
	v_pk_mul_f32 v[176:177], v[176:177], s[76:77] op_sel_hi:[1,0]
	v_pk_mul_f32 v[178:179], v[178:179], s[76:77] op_sel_hi:[1,0]
	v_pk_mul_f32 v[180:181], v[180:181], s[76:77] op_sel_hi:[1,0]
	v_pk_fma_f32 v[38:39], v[38:39], 0.5, v[174:175] op_sel_hi:[1,0,1]
	v_pk_fma_f32 v[40:41], v[40:41], 0.5, v[176:177] op_sel_hi:[1,0,1]
	v_pk_fma_f32 v[42:43], v[42:43], 0.5, v[178:179] op_sel_hi:[1,0,1]
	v_pk_fma_f32 v[44:45], v[44:45], 0.5, v[180:181] op_sel_hi:[1,0,1]
	v_pk_add_f32 v[174:175], v[38:39], v[42:43]
	v_pk_add_f32 v[176:177], v[40:41], v[44:45]
	v_pk_mul_f32 v[178:179], v[38:39], v[38:39]
	v_pk_mul_f32 v[180:181], v[40:41], v[40:41]
	v_pk_fma_f32 v[178:179], v[42:43], v[42:43], v[178:179]
	v_pk_fma_f32 v[180:181], v[44:45], v[44:45], v[180:181]
	v_pk_add_f32 v[174:175], v[174:175], v[176:177]
	v_pk_add_f32 v[178:179], v[178:179], v[180:181]
	v_cvt_pk_bf16_f32 v106, v38, v39
	v_cvt_pk_bf16_f32 v107, v40, v41
	v_cvt_pk_bf16_f32 v108, v42, v43
	v_cvt_pk_bf16_f32 v109, v44, v45
	v_add_f32_e32 v4, v174, v175
	v_add_f32_e32 v186, v178, v179
	v_lshlrev_b32_e32 v174, 16, v110
	v_and_b32_e32 v175, 0xffff0000, v110
	v_lshlrev_b32_e32 v176, 16, v111
	v_and_b32_e32 v177, 0xffff0000, v111
	v_lshlrev_b32_e32 v178, 16, v112
	v_and_b32_e32 v179, 0xffff0000, v112
	v_lshlrev_b32_e32 v180, 16, v113
	v_and_b32_e32 v181, 0xffff0000, v113
	v_pk_add_f32 v[174:175], v[174:175], v[146:147] op_sel_hi:[1,0] neg_lo:[0,1] neg_hi:[0,1]
	v_pk_add_f32 v[176:177], v[176:177], v[146:147] op_sel_hi:[1,0] neg_lo:[0,1] neg_hi:[0,1]
	v_pk_add_f32 v[178:179], v[178:179], v[146:147] op_sel_hi:[1,0] neg_lo:[0,1] neg_hi:[0,1]
	v_pk_add_f32 v[180:181], v[180:181], v[146:147] op_sel_hi:[1,0] neg_lo:[0,1] neg_hi:[0,1]
	v_pk_mul_f32 v[174:175], v[146:147], v[174:175] op_sel:[1,0] op_sel_hi:[1,1]
	v_pk_mul_f32 v[176:177], v[146:147], v[176:177] op_sel:[1,0] op_sel_hi:[1,1]
	v_pk_mul_f32 v[178:179], v[146:147], v[178:179] op_sel:[1,0] op_sel_hi:[1,1]
	v_pk_mul_f32 v[180:181], v[146:147], v[180:181] op_sel:[1,0] op_sel_hi:[1,1]
	v_pk_fma_f32 v[174:175], v[150:151], v[174:175], v[158:159]
	v_pk_fma_f32 v[176:177], v[152:153], v[176:177], v[160:161]
	v_pk_fma_f32 v[178:179], v[154:155], v[178:179], v[162:163]
	v_pk_fma_f32 v[180:181], v[156:157], v[180:181], v[164:165]
	v_pk_mul_f32 v[174:175], v[174:175], s[76:77] op_sel_hi:[1,0]
	v_pk_mul_f32 v[176:177], v[176:177], s[76:77] op_sel_hi:[1,0]
	v_pk_mul_f32 v[178:179], v[178:179], s[76:77] op_sel_hi:[1,0]
	v_pk_mul_f32 v[180:181], v[180:181], s[76:77] op_sel_hi:[1,0]
	v_pk_fma_f32 v[30:31], v[30:31], 0.5, v[174:175] op_sel_hi:[1,0,1]
	v_pk_fma_f32 v[32:33], v[32:33], 0.5, v[176:177] op_sel_hi:[1,0,1]
	v_pk_fma_f32 v[34:35], v[34:35], 0.5, v[178:179] op_sel_hi:[1,0,1]
	v_pk_fma_f32 v[36:37], v[36:37], 0.5, v[180:181] op_sel_hi:[1,0,1]
	v_pk_add_f32 v[174:175], v[30:31], v[34:35]
	v_pk_add_f32 v[176:177], v[32:33], v[36:37]
	v_pk_mul_f32 v[178:179], v[30:31], v[30:31]
	v_pk_mul_f32 v[180:181], v[32:33], v[32:33]
	v_pk_fma_f32 v[178:179], v[34:35], v[34:35], v[178:179]
	v_pk_fma_f32 v[180:181], v[36:37], v[36:37], v[180:181]
	v_pk_add_f32 v[174:175], v[174:175], v[176:177]
	v_pk_add_f32 v[178:179], v[178:179], v[180:181]
	v_cvt_pk_bf16_f32 v110, v30, v31
	v_cvt_pk_bf16_f32 v111, v32, v33
	v_cvt_pk_bf16_f32 v112, v34, v35
	v_cvt_pk_bf16_f32 v113, v36, v37
	v_add_f32_e32 v5, v174, v175
	v_add_f32_e32 v187, v178, v179
	v_lshlrev_b32_e32 v174, 16, v114
	v_and_b32_e32 v175, 0xffff0000, v114
	v_lshlrev_b32_e32 v176, 16, v115
	v_and_b32_e32 v177, 0xffff0000, v115
	v_lshlrev_b32_e32 v178, 16, v116
	v_and_b32_e32 v179, 0xffff0000, v116
	v_lshlrev_b32_e32 v180, 16, v117
	v_and_b32_e32 v181, 0xffff0000, v117
	v_pk_add_f32 v[174:175], v[174:175], v[148:149] op_sel_hi:[1,0] neg_lo:[0,1] neg_hi:[0,1]
	v_pk_add_f32 v[176:177], v[176:177], v[148:149] op_sel_hi:[1,0] neg_lo:[0,1] neg_hi:[0,1]
	v_pk_add_f32 v[178:179], v[178:179], v[148:149] op_sel_hi:[1,0] neg_lo:[0,1] neg_hi:[0,1]
	v_pk_add_f32 v[180:181], v[180:181], v[148:149] op_sel_hi:[1,0] neg_lo:[0,1] neg_hi:[0,1]
	v_pk_mul_f32 v[174:175], v[148:149], v[174:175] op_sel:[1,0] op_sel_hi:[1,1]
	v_pk_mul_f32 v[176:177], v[148:149], v[176:177] op_sel:[1,0] op_sel_hi:[1,1]
	v_pk_mul_f32 v[178:179], v[148:149], v[178:179] op_sel:[1,0] op_sel_hi:[1,1]
	v_pk_mul_f32 v[180:181], v[148:149], v[180:181] op_sel:[1,0] op_sel_hi:[1,1]
	v_pk_fma_f32 v[174:175], v[150:151], v[174:175], v[158:159]
	v_pk_fma_f32 v[176:177], v[152:153], v[176:177], v[160:161]
	v_pk_fma_f32 v[178:179], v[154:155], v[178:179], v[162:163]
	v_pk_fma_f32 v[180:181], v[156:157], v[180:181], v[164:165]
	v_pk_mul_f32 v[174:175], v[174:175], s[76:77] op_sel_hi:[1,0]
	v_pk_mul_f32 v[176:177], v[176:177], s[76:77] op_sel_hi:[1,0]
	v_pk_mul_f32 v[178:179], v[178:179], s[76:77] op_sel_hi:[1,0]
	v_pk_mul_f32 v[180:181], v[180:181], s[76:77] op_sel_hi:[1,0]
	v_pk_fma_f32 v[22:23], v[22:23], 0.5, v[174:175] op_sel_hi:[1,0,1]
	v_pk_fma_f32 v[24:25], v[24:25], 0.5, v[176:177] op_sel_hi:[1,0,1]
	v_pk_fma_f32 v[26:27], v[26:27], 0.5, v[178:179] op_sel_hi:[1,0,1]
	v_pk_fma_f32 v[28:29], v[28:29], 0.5, v[180:181] op_sel_hi:[1,0,1]
	v_pk_add_f32 v[174:175], v[22:23], v[26:27]
	v_pk_add_f32 v[176:177], v[24:25], v[28:29]
	v_pk_mul_f32 v[178:179], v[22:23], v[22:23]
	v_pk_mul_f32 v[180:181], v[24:25], v[24:25]
	v_pk_fma_f32 v[178:179], v[26:27], v[26:27], v[178:179]
	v_pk_fma_f32 v[180:181], v[28:29], v[28:29], v[180:181]
	v_pk_add_f32 v[174:175], v[174:175], v[176:177]
	v_pk_add_f32 v[178:179], v[178:179], v[180:181]
	v_cvt_pk_bf16_f32 v114, v22, v23
	v_cvt_pk_bf16_f32 v115, v24, v25
	v_cvt_pk_bf16_f32 v116, v26, v27
	v_cvt_pk_bf16_f32 v117, v28, v29
	v_add_f32_e32 v139, v174, v175
	v_add_f32_e32 v197, v178, v179
	global_store_dwordx4 v135, v[102:105], s[18:19] nt
	global_store_dwordx4 v135, v[106:109], s[6:7] nt
	global_store_dwordx4 v135, v[110:113], s[8:9] nt
	global_store_dwordx4 v135, v[114:117], s[10:11] nt
	ds_read_b128 v[150:153], v137 offset:512
	ds_read_b128 v[154:157], v137 offset:528
	ds_read_b128 v[158:161], v137 offset:1536
	ds_read_b128 v[162:165], v137 offset:1552
	s_waitcnt lgkmcnt(0)
	s_waitcnt vmcnt(14)
	v_lshlrev_b32_e32 v174, 16, v118
	v_and_b32_e32 v175, 0xffff0000, v118
	v_lshlrev_b32_e32 v176, 16, v119
	v_and_b32_e32 v177, 0xffff0000, v119
	v_lshlrev_b32_e32 v178, 16, v120
	v_and_b32_e32 v179, 0xffff0000, v120
	v_lshlrev_b32_e32 v180, 16, v121
	v_and_b32_e32 v181, 0xffff0000, v121
	v_pk_add_f32 v[174:175], v[174:175], v[142:143] op_sel_hi:[1,0] neg_lo:[0,1] neg_hi:[0,1]
	v_pk_add_f32 v[176:177], v[176:177], v[142:143] op_sel_hi:[1,0] neg_lo:[0,1] neg_hi:[0,1]
	v_pk_add_f32 v[178:179], v[178:179], v[142:143] op_sel_hi:[1,0] neg_lo:[0,1] neg_hi:[0,1]
	v_pk_add_f32 v[180:181], v[180:181], v[142:143] op_sel_hi:[1,0] neg_lo:[0,1] neg_hi:[0,1]
	v_pk_mul_f32 v[174:175], v[142:143], v[174:175] op_sel:[1,0] op_sel_hi:[1,1]
	v_pk_mul_f32 v[176:177], v[142:143], v[176:177] op_sel:[1,0] op_sel_hi:[1,1]
	v_pk_mul_f32 v[178:179], v[142:143], v[178:179] op_sel:[1,0] op_sel_hi:[1,1]
	v_pk_mul_f32 v[180:181], v[142:143], v[180:181] op_sel:[1,0] op_sel_hi:[1,1]
	v_pk_fma_f32 v[174:175], v[150:151], v[174:175], v[158:159]
	v_pk_fma_f32 v[176:177], v[152:153], v[176:177], v[160:161]
	v_pk_fma_f32 v[178:179], v[154:155], v[178:179], v[162:163]
	v_pk_fma_f32 v[180:181], v[156:157], v[180:181], v[164:165]
	v_pk_mul_f32 v[174:175], v[174:175], s[76:77] op_sel_hi:[1,0]
	v_pk_mul_f32 v[176:177], v[176:177], s[76:77] op_sel_hi:[1,0]
	v_pk_mul_f32 v[178:179], v[178:179], s[76:77] op_sel_hi:[1,0]
	v_pk_mul_f32 v[180:181], v[180:181], s[76:77] op_sel_hi:[1,0]
	v_pk_fma_f32 v[14:15], v[14:15], 0.5, v[174:175] op_sel_hi:[1,0,1]
	v_pk_fma_f32 v[16:17], v[16:17], 0.5, v[176:177] op_sel_hi:[1,0,1]
	v_pk_fma_f32 v[18:19], v[18:19], 0.5, v[178:179] op_sel_hi:[1,0,1]
	v_pk_fma_f32 v[20:21], v[20:21], 0.5, v[180:181] op_sel_hi:[1,0,1]
	v_pk_add_f32 v[174:175], v[14:15], v[18:19]
	v_pk_add_f32 v[176:177], v[16:17], v[20:21]
	v_pk_mul_f32 v[178:179], v[14:15], v[14:15]
	v_pk_mul_f32 v[180:181], v[16:17], v[16:17]
	v_pk_fma_f32 v[178:179], v[18:19], v[18:19], v[178:179]
	v_pk_fma_f32 v[180:181], v[20:21], v[20:21], v[180:181]
	v_pk_add_f32 v[174:175], v[174:175], v[176:177]
	v_pk_add_f32 v[178:179], v[178:179], v[180:181]
	v_cvt_pk_bf16_f32 v118, v14, v15
	v_cvt_pk_bf16_f32 v119, v16, v17
	v_cvt_pk_bf16_f32 v120, v18, v19
	v_cvt_pk_bf16_f32 v121, v20, v21
	v_add_f32_e32 v174, v174, v175
	v_add_f32_e32 v178, v178, v179
	v_add_f32_e32 v2, v2, v174
	v_add_f32_e32 v140, v140, v178
	v_lshlrev_b32_e32 v174, 16, v122
	v_and_b32_e32 v175, 0xffff0000, v122
	v_lshlrev_b32_e32 v176, 16, v123
	v_and_b32_e32 v177, 0xffff0000, v123
	v_lshlrev_b32_e32 v178, 16, v124
	v_and_b32_e32 v179, 0xffff0000, v124
	v_lshlrev_b32_e32 v180, 16, v125
	v_and_b32_e32 v181, 0xffff0000, v125
	v_pk_add_f32 v[174:175], v[174:175], v[144:145] op_sel_hi:[1,0] neg_lo:[0,1] neg_hi:[0,1]
	v_pk_add_f32 v[176:177], v[176:177], v[144:145] op_sel_hi:[1,0] neg_lo:[0,1] neg_hi:[0,1]
	v_pk_add_f32 v[178:179], v[178:179], v[144:145] op_sel_hi:[1,0] neg_lo:[0,1] neg_hi:[0,1]
	v_pk_add_f32 v[180:181], v[180:181], v[144:145] op_sel_hi:[1,0] neg_lo:[0,1] neg_hi:[0,1]
	v_pk_mul_f32 v[174:175], v[144:145], v[174:175] op_sel:[1,0] op_sel_hi:[1,1]
	v_pk_mul_f32 v[176:177], v[144:145], v[176:177] op_sel:[1,0] op_sel_hi:[1,1]
	v_pk_mul_f32 v[178:179], v[144:145], v[178:179] op_sel:[1,0] op_sel_hi:[1,1]
	v_pk_mul_f32 v[180:181], v[144:145], v[180:181] op_sel:[1,0] op_sel_hi:[1,1]
	v_pk_fma_f32 v[174:175], v[150:151], v[174:175], v[158:159]
	v_pk_fma_f32 v[176:177], v[152:153], v[176:177], v[160:161]
	v_pk_fma_f32 v[178:179], v[154:155], v[178:179], v[162:163]
	v_pk_fma_f32 v[180:181], v[156:157], v[180:181], v[164:165]
	v_pk_mul_f32 v[174:175], v[174:175], s[76:77] op_sel_hi:[1,0]
	v_pk_mul_f32 v[176:177], v[176:177], s[76:77] op_sel_hi:[1,0]
	v_pk_mul_f32 v[178:179], v[178:179], s[76:77] op_sel_hi:[1,0]
	v_pk_mul_f32 v[180:181], v[180:181], s[76:77] op_sel_hi:[1,0]
	v_pk_fma_f32 v[6:7], v[6:7], 0.5, v[174:175] op_sel_hi:[1,0,1]
	v_pk_fma_f32 v[8:9], v[8:9], 0.5, v[176:177] op_sel_hi:[1,0,1]
	v_pk_fma_f32 v[10:11], v[10:11], 0.5, v[178:179] op_sel_hi:[1,0,1]
	v_pk_fma_f32 v[12:13], v[12:13], 0.5, v[180:181] op_sel_hi:[1,0,1]
	v_pk_add_f32 v[174:175], v[6:7], v[10:11]
	v_pk_add_f32 v[176:177], v[8:9], v[12:13]
	v_pk_mul_f32 v[178:179], v[6:7], v[6:7]
	v_pk_mul_f32 v[180:181], v[8:9], v[8:9]
	v_pk_fma_f32 v[178:179], v[10:11], v[10:11], v[178:179]
	v_pk_fma_f32 v[180:181], v[12:13], v[12:13], v[180:181]
	v_pk_add_f32 v[174:175], v[174:175], v[176:177]
	v_pk_add_f32 v[178:179], v[178:179], v[180:181]
	v_cvt_pk_bf16_f32 v122, v6, v7
	v_cvt_pk_bf16_f32 v123, v8, v9
	v_cvt_pk_bf16_f32 v124, v10, v11
	v_cvt_pk_bf16_f32 v125, v12, v13
	v_add_f32_e32 v174, v174, v175
	v_add_f32_e32 v178, v178, v179
	v_add_f32_e32 v4, v4, v174
	v_add_f32_e32 v186, v186, v178
	v_lshlrev_b32_e32 v174, 16, v126
	v_and_b32_e32 v175, 0xffff0000, v126
	v_lshlrev_b32_e32 v176, 16, v127
	v_and_b32_e32 v177, 0xffff0000, v127
	v_lshlrev_b32_e32 v178, 16, v128
	v_and_b32_e32 v179, 0xffff0000, v128
	v_lshlrev_b32_e32 v180, 16, v129
	v_and_b32_e32 v181, 0xffff0000, v129
	v_pk_add_f32 v[174:175], v[174:175], v[146:147] op_sel_hi:[1,0] neg_lo:[0,1] neg_hi:[0,1]
	v_pk_add_f32 v[176:177], v[176:177], v[146:147] op_sel_hi:[1,0] neg_lo:[0,1] neg_hi:[0,1]
	v_pk_add_f32 v[178:179], v[178:179], v[146:147] op_sel_hi:[1,0] neg_lo:[0,1] neg_hi:[0,1]
	v_pk_add_f32 v[180:181], v[180:181], v[146:147] op_sel_hi:[1,0] neg_lo:[0,1] neg_hi:[0,1]
	v_pk_mul_f32 v[174:175], v[146:147], v[174:175] op_sel:[1,0] op_sel_hi:[1,1]
	v_pk_mul_f32 v[176:177], v[146:147], v[176:177] op_sel:[1,0] op_sel_hi:[1,1]
	v_pk_mul_f32 v[178:179], v[146:147], v[178:179] op_sel:[1,0] op_sel_hi:[1,1]
	v_pk_mul_f32 v[180:181], v[146:147], v[180:181] op_sel:[1,0] op_sel_hi:[1,1]
	v_pk_fma_f32 v[174:175], v[150:151], v[174:175], v[158:159]
	v_pk_fma_f32 v[176:177], v[152:153], v[176:177], v[160:161]
	v_pk_fma_f32 v[178:179], v[154:155], v[178:179], v[162:163]
	v_pk_fma_f32 v[180:181], v[156:157], v[180:181], v[164:165]
	v_pk_mul_f32 v[174:175], v[174:175], s[76:77] op_sel_hi:[1,0]
	v_pk_mul_f32 v[176:177], v[176:177], s[76:77] op_sel_hi:[1,0]
	v_pk_mul_f32 v[178:179], v[178:179], s[76:77] op_sel_hi:[1,0]
	v_pk_mul_f32 v[180:181], v[180:181], s[76:77] op_sel_hi:[1,0]
	v_pk_fma_f32 v[54:55], v[54:55], 0.5, v[174:175] op_sel_hi:[1,0,1]
	v_pk_fma_f32 v[56:57], v[56:57], 0.5, v[176:177] op_sel_hi:[1,0,1]
	v_pk_fma_f32 v[62:63], v[62:63], 0.5, v[178:179] op_sel_hi:[1,0,1]
	v_pk_fma_f32 v[64:65], v[64:65], 0.5, v[180:181] op_sel_hi:[1,0,1]
	v_pk_add_f32 v[174:175], v[54:55], v[62:63]
	v_pk_add_f32 v[176:177], v[56:57], v[64:65]
	v_pk_mul_f32 v[178:179], v[54:55], v[54:55]
	v_pk_mul_f32 v[180:181], v[56:57], v[56:57]
	v_pk_fma_f32 v[178:179], v[62:63], v[62:63], v[178:179]
	v_pk_fma_f32 v[180:181], v[64:65], v[64:65], v[180:181]
	v_pk_add_f32 v[174:175], v[174:175], v[176:177]
	v_pk_add_f32 v[178:179], v[178:179], v[180:181]
	v_cvt_pk_bf16_f32 v126, v54, v55
	v_cvt_pk_bf16_f32 v127, v56, v57
	v_cvt_pk_bf16_f32 v128, v62, v63
	v_cvt_pk_bf16_f32 v129, v64, v65
	v_add_f32_e32 v174, v174, v175
	v_add_f32_e32 v178, v178, v179
	v_add_f32_e32 v5, v5, v174
	v_add_f32_e32 v187, v187, v178
	v_lshlrev_b32_e32 v174, 16, v130
	v_and_b32_e32 v175, 0xffff0000, v130
	v_lshlrev_b32_e32 v176, 16, v131
	v_and_b32_e32 v177, 0xffff0000, v131
	v_lshlrev_b32_e32 v178, 16, v132
	v_and_b32_e32 v179, 0xffff0000, v132
	v_lshlrev_b32_e32 v180, 16, v133
	v_and_b32_e32 v181, 0xffff0000, v133
	v_pk_add_f32 v[174:175], v[174:175], v[148:149] op_sel_hi:[1,0] neg_lo:[0,1] neg_hi:[0,1]
	v_pk_add_f32 v[176:177], v[176:177], v[148:149] op_sel_hi:[1,0] neg_lo:[0,1] neg_hi:[0,1]
	v_pk_add_f32 v[178:179], v[178:179], v[148:149] op_sel_hi:[1,0] neg_lo:[0,1] neg_hi:[0,1]
	v_pk_add_f32 v[180:181], v[180:181], v[148:149] op_sel_hi:[1,0] neg_lo:[0,1] neg_hi:[0,1]
	v_pk_mul_f32 v[174:175], v[148:149], v[174:175] op_sel:[1,0] op_sel_hi:[1,1]
	v_pk_mul_f32 v[176:177], v[148:149], v[176:177] op_sel:[1,0] op_sel_hi:[1,1]
	v_pk_mul_f32 v[178:179], v[148:149], v[178:179] op_sel:[1,0] op_sel_hi:[1,1]
	v_pk_mul_f32 v[180:181], v[148:149], v[180:181] op_sel:[1,0] op_sel_hi:[1,1]
	v_pk_fma_f32 v[174:175], v[150:151], v[174:175], v[158:159]
	v_pk_fma_f32 v[176:177], v[152:153], v[176:177], v[160:161]
	v_pk_fma_f32 v[178:179], v[154:155], v[178:179], v[162:163]
	v_pk_fma_f32 v[180:181], v[156:157], v[180:181], v[164:165]
	v_pk_mul_f32 v[174:175], v[174:175], s[76:77] op_sel_hi:[1,0]
	v_pk_mul_f32 v[176:177], v[176:177], s[76:77] op_sel_hi:[1,0]
	v_pk_mul_f32 v[178:179], v[178:179], s[76:77] op_sel_hi:[1,0]
	v_pk_mul_f32 v[180:181], v[180:181], s[76:77] op_sel_hi:[1,0]
	v_pk_fma_f32 v[58:59], v[58:59], 0.5, v[174:175] op_sel_hi:[1,0,1]
	v_pk_fma_f32 v[60:61], v[60:61], 0.5, v[176:177] op_sel_hi:[1,0,1]
	v_pk_fma_f32 v[66:67], v[66:67], 0.5, v[178:179] op_sel_hi:[1,0,1]
	v_pk_fma_f32 v[68:69], v[68:69], 0.5, v[180:181] op_sel_hi:[1,0,1]
	v_pk_add_f32 v[174:175], v[58:59], v[66:67]
	v_pk_add_f32 v[176:177], v[60:61], v[68:69]
	v_pk_mul_f32 v[178:179], v[58:59], v[58:59]
	v_pk_mul_f32 v[180:181], v[60:61], v[60:61]
	v_pk_fma_f32 v[178:179], v[66:67], v[66:67], v[178:179]
	v_pk_fma_f32 v[180:181], v[68:69], v[68:69], v[180:181]
	v_pk_add_f32 v[174:175], v[174:175], v[176:177]
	v_pk_add_f32 v[178:179], v[178:179], v[180:181]
	v_cvt_pk_bf16_f32 v130, v58, v59
	v_cvt_pk_bf16_f32 v131, v60, v61
	v_cvt_pk_bf16_f32 v132, v66, v67
	v_cvt_pk_bf16_f32 v133, v68, v69
	v_add_f32_e32 v174, v174, v175
	v_add_f32_e32 v178, v178, v179
	v_add_f32_e32 v139, v139, v174
	v_add_f32_e32 v197, v197, v178
	global_store_dwordx4 v135, v[118:121], s[18:19] offset:256 nt
	global_store_dwordx4 v135, v[122:125], s[6:7] offset:256 nt
	global_store_dwordx4 v135, v[126:129], s[8:9] offset:256 nt
	global_store_dwordx4 v135, v[130:133], s[10:11] offset:256 nt
	ds_bpermute_b32 v174, v201, v2
	ds_bpermute_b32 v175, v201, v4
	ds_bpermute_b32 v176, v201, v5
	ds_bpermute_b32 v177, v201, v139
	ds_bpermute_b32 v178, v201, v140
	ds_bpermute_b32 v179, v201, v186
	ds_bpermute_b32 v180, v201, v187
	ds_bpermute_b32 v181, v201, v197
	s_waitcnt lgkmcnt(0)
	v_add_f32_e32 v2, v2, v174
	v_add_f32_e32 v4, v4, v175
	v_add_f32_e32 v5, v5, v176
	v_add_f32_e32 v139, v139, v177
	v_add_f32_e32 v140, v140, v178
	v_add_f32_e32 v186, v186, v179
	v_add_f32_e32 v187, v187, v180
	v_add_f32_e32 v197, v197, v181
	ds_bpermute_b32 v174, v203, v2
	ds_bpermute_b32 v175, v203, v4
	ds_bpermute_b32 v176, v203, v5
	ds_bpermute_b32 v177, v203, v139
	ds_bpermute_b32 v178, v203, v140
	ds_bpermute_b32 v179, v203, v186
	ds_bpermute_b32 v180, v203, v187
	ds_bpermute_b32 v181, v203, v197
	s_waitcnt lgkmcnt(0)
	v_add_f32_e32 v2, v2, v174
	v_add_f32_e32 v4, v4, v175
	v_add_f32_e32 v5, v5, v176
	v_add_f32_e32 v139, v139, v177
	v_add_f32_e32 v140, v140, v178
	v_add_f32_e32 v186, v186, v179
	v_add_f32_e32 v187, v187, v180
	v_add_f32_e32 v197, v197, v181
	v_cmp_eq_u32_e32 vcc, 1, v191
	s_nop 1
	v_cndmask_b32_e32 v2, v2, v4, vcc
	v_cndmask_b32_e32 v140, v140, v186, vcc
	v_cmp_eq_u32_e32 vcc, 2, v191
	s_nop 1
	v_cndmask_b32_e32 v2, v2, v5, vcc
	v_cndmask_b32_e32 v140, v140, v187, vcc
	v_cmp_eq_u32_e32 vcc, 3, v191
	s_nop 1
	v_cndmask_b32_e32 v2, v2, v139, vcc
	v_cndmask_b32_e32 v140, v140, v197, vcc
	global_atomic_add_f32 v138, v2, s[16:17] offset:1024
	global_atomic_add_f32 v138, v140, s[16:17] offset:1028
	s_branch .LBB0_1106

.LBB0_1027:
	v_pk_fma_f32 v[174:175], v[148:149], v[158:159], v[96:97] op_sel_hi:[0,1,1] neg_lo:[1,0,0] neg_hi:[1,0,0]
	v_pk_fma_f32 v[178:179], v[154:155], v[174:175], v[146:147] op_sel_hi:[1,1,0]
	v_pk_fma_f32 v[174:175], v[148:149], v[164:165], v[100:101] op_sel_hi:[0,1,1] neg_lo:[1,0,0] neg_hi:[1,0,0]
	v_pk_fma_f32 v[176:177], v[148:149], v[150:151], v[94:95] op_sel_hi:[0,1,1] neg_lo:[1,0,0] neg_hi:[1,0,0]
	v_pk_fma_f32 v[180:181], v[148:149], v[156:157], v[98:99] op_sel_hi:[0,1,1] neg_lo:[1,0,0] neg_hi:[1,0,0]
	v_pk_fma_f32 v[182:183], v[162:163], v[174:175], v[146:147] op_sel_hi:[1,1,0]
	v_cvt_pk_bf16_f32 v175, v178, v179
	v_mov_b64_e32 v[178:179], s[6:7]
	s_movk_i32 s8, 0x4800
	v_pk_fma_f32 v[176:177], v[152:153], v[176:177], v[146:147] op_sel_hi:[1,1,0]
	v_pk_fma_f32 v[180:181], v[160:161], v[180:181], v[146:147] op_sel_hi:[1,1,0]
	v_mad_i64_i32 v[178:179], s[8:9], v2, s8, v[178:179]
	v_cvt_pk_bf16_f32 v174, v176, v177
	v_cvt_pk_bf16_f32 v176, v180, v181
	v_cvt_pk_bf16_f32 v177, v182, v183
	v_lshl_add_u64 v[178:179], v[4:5], 1, v[178:179]
	global_store_dwordx4 v[178:179], v[174:177], off offset:256 nt
	s_andn2_b64 vcc, exec, s[10:11]
	s_cbranch_vccnz .LBB0_985
.LBB0_1028:
	v_mov_b32_e32 v2, v149
	v_pk_fma_f32 v[174:175], v[2:3], v[150:151], v[86:87] op_sel_hi:[0,1,1] neg_lo:[1,0,0] neg_hi:[1,0,0]
	v_mov_b32_e32 v146, v147
	v_pk_fma_f32 v[148:149], v[2:3], v[158:159], v[88:89] op_sel_hi:[0,1,1] neg_lo:[1,0,0] neg_hi:[1,0,0]
	v_pk_fma_f32 v[174:175], v[152:153], v[174:175], v[146:147] op_sel_hi:[1,1,0]
	v_pk_fma_f32 v[176:177], v[2:3], v[164:165], v[92:93] op_sel_hi:[0,1,1] neg_lo:[1,0,0] neg_hi:[1,0,0]
	v_pk_fma_f32 v[178:179], v[2:3], v[156:157], v[90:91] op_sel_hi:[0,1,1] neg_lo:[1,0,0] neg_hi:[1,0,0]
	v_pk_fma_f32 v[148:149], v[154:155], v[148:149], v[146:147] op_sel_hi:[1,1,0]
	v_pk_fma_f32 v[178:179], v[160:161], v[178:179], v[146:147] op_sel_hi:[1,1,0]
	v_pk_fma_f32 v[176:177], v[162:163], v[176:177], v[146:147] op_sel_hi:[1,1,0]
	v_cvt_pk_bf16_f32 v146, v174, v175
	v_mov_b64_e32 v[174:175], s[6:7]
	s_movk_i32 s8, 0x4800
	v_mad_i64_i32 v[174:175], s[8:9], v166, s8, v[174:175]
	v_cvt_pk_bf16_f32 v147, v148, v149
	v_cvt_pk_bf16_f32 v148, v178, v179
	v_cvt_pk_bf16_f32 v149, v176, v177
	v_lshl_add_u64 v[174:175], v[4:5], 1, v[174:175]
	global_store_dwordx4 v[174:175], v[146:149], off offset:256 nt
	s_andn2_b64 vcc, exec, s[16:17]
	s_cbranch_vccnz .LBB0_986
.LBB0_1029:
	v_pk_fma_f32 v[146:147], v[144:145], v[158:159], v[80:81] op_sel_hi:[0,1,1] neg_lo:[1,0,0] neg_hi:[1,0,0]
	v_pk_fma_f32 v[174:175], v[154:155], v[146:147], v[142:143] op_sel_hi:[1,1,0]
	v_pk_fma_f32 v[146:147], v[144:145], v[164:165], v[84:85] op_sel_hi:[0,1,1] neg_lo:[1,0,0] neg_hi:[1,0,0]
	v_pk_fma_f32 v[148:149], v[144:145], v[150:151], v[78:79] op_sel_hi:[0,1,1] neg_lo:[1,0,0] neg_hi:[1,0,0]
	v_pk_fma_f32 v[176:177], v[144:145], v[156:157], v[82:83] op_sel_hi:[0,1,1] neg_lo:[1,0,0] neg_hi:[1,0,0]
	v_pk_fma_f32 v[178:179], v[162:163], v[146:147], v[142:143] op_sel_hi:[1,1,0]
	v_cvt_pk_bf16_f32 v147, v174, v175
	v_mov_b64_e32 v[174:175], s[6:7]
	s_movk_i32 s8, 0x4800
	v_pk_fma_f32 v[148:149], v[152:153], v[148:149], v[142:143] op_sel_hi:[1,1,0]
	v_pk_fma_f32 v[176:177], v[160:161], v[176:177], v[142:143] op_sel_hi:[1,1,0]
	v_mad_i64_i32 v[166:167], s[8:9], v167, s8, v[174:175]
	v_cvt_pk_bf16_f32 v146, v148, v149
	v_cvt_pk_bf16_f32 v148, v176, v177
	v_cvt_pk_bf16_f32 v149, v178, v179
	v_lshl_add_u64 v[166:167], v[4:5], 1, v[166:167]
	global_store_dwordx4 v[166:167], v[146:149], off offset:256 nt
	s_andn2_b64 vcc, exec, s[18:19]
	s_cbranch_vccnz .LBB0_987
.LBB0_1030:
	v_mov_b32_e32 v2, v145
	v_pk_fma_f32 v[146:147], v[2:3], v[150:151], v[70:71] op_sel_hi:[0,1,1] neg_lo:[1,0,0] neg_hi:[1,0,0]
	v_mov_b32_e32 v142, v143
	v_pk_fma_f32 v[144:145], v[2:3], v[158:159], v[72:73] op_sel_hi:[0,1,1] neg_lo:[1,0,0] neg_hi:[1,0,0]
	v_pk_fma_f32 v[146:147], v[152:153], v[146:147], v[142:143] op_sel_hi:[1,1,0]
	v_pk_fma_f32 v[148:149], v[2:3], v[164:165], v[76:77] op_sel_hi:[0,1,1] neg_lo:[1,0,0] neg_hi:[1,0,0]
	v_pk_fma_f32 v[166:167], v[2:3], v[156:157], v[74:75] op_sel_hi:[0,1,1] neg_lo:[1,0,0] neg_hi:[1,0,0]
	v_pk_fma_f32 v[144:145], v[154:155], v[144:145], v[142:143] op_sel_hi:[1,1,0]
	v_pk_fma_f32 v[166:167], v[160:161], v[166:167], v[142:143] op_sel_hi:[1,1,0]
	v_pk_fma_f32 v[148:149], v[162:163], v[148:149], v[142:143] op_sel_hi:[1,1,0]
	v_cvt_pk_bf16_f32 v142, v146, v147
	v_mov_b64_e32 v[146:147], s[6:7]
	s_movk_i32 s8, 0x4800
	v_mad_i64_i32 v[146:147], s[8:9], v168, s8, v[146:147]
	v_cvt_pk_bf16_f32 v143, v144, v145
	v_cvt_pk_bf16_f32 v144, v166, v167
	v_cvt_pk_bf16_f32 v145, v148, v149
	v_lshl_add_u64 v[146:147], v[4:5], 1, v[146:147]
	global_store_dwordx4 v[146:147], v[142:145], off offset:256 nt
	s_andn2_b64 vcc, exec, s[20:21]
	s_cbranch_vccnz .LBB0_988
.LBB0_1031:
	v_pk_fma_f32 v[142:143], v[140:141], v[158:159], v[16:17] op_sel_hi:[0,1,1] neg_lo:[1,0,0] neg_hi:[1,0,0]
	v_pk_fma_f32 v[146:147], v[154:155], v[142:143], v[138:139] op_sel_hi:[1,1,0]
	v_pk_fma_f32 v[142:143], v[140:141], v[164:165], v[20:21] op_sel_hi:[0,1,1] neg_lo:[1,0,0] neg_hi:[1,0,0]
	v_pk_fma_f32 v[144:145], v[140:141], v[150:151], v[14:15] op_sel_hi:[0,1,1] neg_lo:[1,0,0] neg_hi:[1,0,0]
	v_pk_fma_f32 v[148:149], v[140:141], v[156:157], v[18:19] op_sel_hi:[0,1,1] neg_lo:[1,0,0] neg_hi:[1,0,0]
	v_pk_fma_f32 v[166:167], v[162:163], v[142:143], v[138:139] op_sel_hi:[1,1,0]
	v_cvt_pk_bf16_f32 v143, v146, v147
	v_mov_b64_e32 v[146:147], s[6:7]
	s_movk_i32 s8, 0x4800
	v_pk_fma_f32 v[144:145], v[152:153], v[144:145], v[138:139] op_sel_hi:[1,1,0]
	v_pk_fma_f32 v[148:149], v[160:161], v[148:149], v[138:139] op_sel_hi:[1,1,0]
	v_mad_i64_i32 v[146:147], s[8:9], v169, s8, v[146:147]
	v_cvt_pk_bf16_f32 v142, v144, v145
	v_cvt_pk_bf16_f32 v144, v148, v149
	v_cvt_pk_bf16_f32 v145, v166, v167
	v_lshl_add_u64 v[146:147], v[4:5], 1, v[146:147]
	global_store_dwordx4 v[146:147], v[142:145], off offset:256 nt
	s_andn2_b64 vcc, exec, s[24:25]
	s_cbranch_vccnz .LBB0_989
.LBB0_1032:
	v_mov_b32_e32 v2, v141
	v_pk_fma_f32 v[142:143], v[2:3], v[150:151], v[6:7] op_sel_hi:[0,1,1] neg_lo:[1,0,0] neg_hi:[1,0,0]
	v_mov_b32_e32 v138, v139
	v_pk_fma_f32 v[140:141], v[2:3], v[158:159], v[8:9] op_sel_hi:[0,1,1] neg_lo:[1,0,0] neg_hi:[1,0,0]
	v_pk_fma_f32 v[142:143], v[152:153], v[142:143], v[138:139] op_sel_hi:[1,1,0]
	v_pk_fma_f32 v[144:145], v[2:3], v[164:165], v[12:13] op_sel_hi:[0,1,1] neg_lo:[1,0,0] neg_hi:[1,0,0]
	v_pk_fma_f32 v[146:147], v[2:3], v[156:157], v[10:11] op_sel_hi:[0,1,1] neg_lo:[1,0,0] neg_hi:[1,0,0]
	v_pk_fma_f32 v[140:141], v[154:155], v[140:141], v[138:139] op_sel_hi:[1,1,0]
	v_pk_fma_f32 v[146:147], v[160:161], v[146:147], v[138:139] op_sel_hi:[1,1,0]
	v_pk_fma_f32 v[144:145], v[162:163], v[144:145], v[138:139] op_sel_hi:[1,1,0]
	v_cvt_pk_bf16_f32 v138, v142, v143
	v_mov_b64_e32 v[142:143], s[6:7]
	s_movk_i32 s8, 0x4800
	v_mad_i64_i32 v[142:143], s[8:9], v170, s8, v[142:143]
	v_cvt_pk_bf16_f32 v139, v140, v141
	v_cvt_pk_bf16_f32 v140, v146, v147
	v_cvt_pk_bf16_f32 v141, v144, v145
	v_lshl_add_u64 v[142:143], v[4:5], 1, v[142:143]
	global_store_dwordx4 v[142:143], v[138:141], off offset:256 nt
	s_andn2_b64 vcc, exec, s[26:27]
	s_cbranch_vccnz .LBB0_990
.LBB0_1033:
	v_pk_fma_f32 v[138:139], v[136:137], v[158:159], v[56:57] op_sel_hi:[0,1,1] neg_lo:[1,0,0] neg_hi:[1,0,0]
	v_pk_fma_f32 v[142:143], v[154:155], v[138:139], v[134:135] op_sel_hi:[1,1,0]
	v_pk_fma_f32 v[138:139], v[136:137], v[164:165], v[64:65] op_sel_hi:[0,1,1] neg_lo:[1,0,0] neg_hi:[1,0,0]
	v_pk_fma_f32 v[140:141], v[136:137], v[150:151], v[54:55] op_sel_hi:[0,1,1] neg_lo:[1,0,0] neg_hi:[1,0,0]
	v_pk_fma_f32 v[144:145], v[136:137], v[156:157], v[62:63] op_sel_hi:[0,1,1] neg_lo:[1,0,0] neg_hi:[1,0,0]
	v_pk_fma_f32 v[146:147], v[162:163], v[138:139], v[134:135] op_sel_hi:[1,1,0]
	v_cvt_pk_bf16_f32 v139, v142, v143
	v_mov_b64_e32 v[142:143], s[6:7]
	s_movk_i32 s8, 0x4800
	v_pk_fma_f32 v[140:141], v[152:153], v[140:141], v[134:135] op_sel_hi:[1,1,0]
	v_pk_fma_f32 v[144:145], v[160:161], v[144:145], v[134:135] op_sel_hi:[1,1,0]
	v_mad_i64_i32 v[142:143], s[8:9], v171, s8, v[142:143]
	v_cvt_pk_bf16_f32 v138, v140, v141
	v_cvt_pk_bf16_f32 v140, v144, v145
	v_cvt_pk_bf16_f32 v141, v146, v147
	v_lshl_add_u64 v[142:143], v[4:5], 1, v[142:143]
	global_store_dwordx4 v[142:143], v[138:141], off offset:256 nt
	s_andn2_b64 vcc, exec, s[28:29]
	s_cbranch_vccz .LBB0_991
	s_branch .LBB0_992
.LBB0_1034:
	s_waitcnt lgkmcnt(7)
	v_xor_b32_e32 v157, 0x80000000, v157
	v_xor_b32_e32 v156, 0x80000000, v156
	v_pk_fma_f32 v[156:157], v[156:157], v[168:169], v[28:29] op_sel_hi:[1,0,1]
	v_pk_fma_f32 v[154:155], v[154:155], v[168:169], v[26:27] op_sel_hi:[1,0,1] neg_lo:[1,0,0] neg_hi:[1,0,0]
	s_waitcnt lgkmcnt(5)
	v_xor_b32_e32 v165, 0x80000000, v165
	v_xor_b32_e32 v164, 0x80000000, v164
	v_pk_fma_f32 v[152:153], v[156:157], v[210:211], v[152:153] op_sel_hi:[1,0,1]
	v_pk_fma_f32 v[150:151], v[154:155], v[210:211], v[150:151] op_sel_hi:[1,0,1]
	v_pk_fma_f32 v[164:165], v[164:165], v[168:169], v[24:25] op_sel_hi:[1,0,1]
	v_pk_fma_f32 v[162:163], v[162:163], v[168:169], v[22:23] op_sel_hi:[1,0,1] neg_lo:[1,0,0] neg_hi:[1,0,0]
	v_mul_f32_e32 v154, 0xbfb8aa3b, v150
	v_mul_f32_e32 v155, 0xbfb8aa3b, v151
	v_mul_f32_e32 v156, 0xbfb8aa3b, v152
	v_mul_f32_e32 v157, 0xbfb8aa3b, v153
	s_waitcnt lgkmcnt(3)
	v_pk_fma_f32 v[160:161], v[164:165], v[210:211], v[160:161] op_sel_hi:[1,0,1]
	v_pk_fma_f32 v[158:159], v[162:163], v[210:211], v[158:159] op_sel_hi:[1,0,1]
	v_exp_f32_e32 v154, v154
	v_exp_f32_e32 v156, v156
	v_exp_f32_e32 v157, v157
	v_exp_f32_e32 v155, v155
	v_mul_f32_e32 v162, 0xbfb8aa3b, v158
	v_mul_f32_e32 v163, 0xbfb8aa3b, v159
	v_mul_f32_e32 v164, 0xbfb8aa3b, v160
	v_mul_f32_e32 v165, 0xbfb8aa3b, v161
	v_exp_f32_e32 v162, v162
	v_exp_f32_e32 v164, v164
	v_exp_f32_e32 v165, v165
	v_exp_f32_e32 v163, v163
	v_pk_add_f32 v[156:157], v[156:157], 1.0 op_sel_hi:[1,0]
	v_pk_add_f32 v[154:155], v[154:155], 1.0 op_sel_hi:[1,0]
	v_rcp_f32_e32 v156, v156
	v_rcp_f32_e32 v154, v154
	v_rcp_f32_e32 v155, v155
	v_rcp_f32_e32 v157, v157
	v_pk_add_f32 v[164:165], v[164:165], 1.0 op_sel_hi:[1,0]
	v_pk_add_f32 v[162:163], v[162:163], 1.0 op_sel_hi:[1,0]
	v_rcp_f32_e32 v164, v164
	v_rcp_f32_e32 v162, v162
	v_rcp_f32_e32 v163, v163
	v_rcp_f32_e32 v165, v165
	v_pk_mul_f32 v[150:151], v[150:151], v[154:155]
	v_pk_mul_f32 v[152:153], v[152:153], v[156:157]
	v_cndmask_b32_e64 v154, v154, v150, s[0:1]
	v_cndmask_b32_e64 v156, v156, v152, s[0:1]
	v_cndmask_b32_e64 v152, v155, v151, s[0:1]
	v_pk_mul_f32 v[158:159], v[158:159], v[162:163]
	v_pk_mul_f32 v[160:161], v[160:161], v[164:165]
	v_cndmask_b32_e64 v153, v157, v153, s[0:1]
	v_add_u32_e32 v157, 0xb0, v181
	v_cvt_pk_bf16_f32 v152, v154, v152
	v_mov_b64_e32 v[154:155], s[6:7]
	s_movk_i32 s43, 0x3000
	v_cndmask_b32_e64 v161, v165, v161, s[0:1]
	v_cndmask_b32_e64 v160, v164, v160, s[0:1]
	v_cndmask_b32_e64 v159, v163, v159, s[0:1]
	v_cndmask_b32_e64 v158, v162, v158, s[0:1]
	v_mad_i64_i32 v[154:155], s[56:57], v157, s43, v[154:155]
	v_cvt_pk_bf16_f32 v150, v158, v159
	v_cvt_pk_bf16_f32 v151, v160, v161
	v_cvt_pk_bf16_f32 v153, v156, v153
	v_lshl_add_u64 v[154:155], v[4:5], 1, v[154:155]
	global_store_dwordx4 v[154:155], v[150:153], off nt
	s_andn2_b64 vcc, exec, s[8:9]
	s_cbranch_vccnz .LBB0_1012
.LBB0_1035:
	s_waitcnt lgkmcnt(4)
	v_pk_fma_f32 v[152:153], v[2:3], v[146:147], v[94:95] op_sel_hi:[0,1,1] neg_lo:[1,0,0] neg_hi:[1,0,0]
	s_waitcnt lgkmcnt(1)
	v_pk_fma_f32 v[152:153], v[180:181], v[152:153], v[142:143] op_sel_hi:[0,1,1]
	v_pk_fma_f32 v[150:151], v[2:3], v[148:149], v[96:97] op_sel_hi:[0,1,1] neg_lo:[1,0,0] neg_hi:[1,0,0]
	v_mul_f32_e32 v154, 0xbfb8aa3b, v152
	v_mul_f32_e32 v155, 0xbfb8aa3b, v153
	v_pk_fma_f32 v[150:151], v[180:181], v[150:151], v[144:145] op_sel_hi:[0,1,1]
	v_exp_f32_e32 v154, v154
	v_exp_f32_e32 v155, v155
	v_mul_f32_e32 v156, 0xbfb8aa3b, v150
	v_mul_f32_e32 v157, 0xbfb8aa3b, v151
	v_exp_f32_e32 v156, v156
	v_exp_f32_e32 v157, v157
	v_pk_add_f32 v[154:155], v[154:155], 1.0 op_sel_hi:[1,0]
	s_movk_i32 s8, 0x3000
	v_rcp_f32_e32 v154, v154
	v_rcp_f32_e32 v155, v155
	v_pk_add_f32 v[156:157], v[156:157], 1.0 op_sel_hi:[1,0]
	v_pk_mul_f32 v[152:153], v[152:153], v[154:155]
	v_rcp_f32_e32 v156, v156
	v_rcp_f32_e32 v157, v157
	v_cndmask_b32_e64 v160, v155, v153, s[0:1]
	v_cndmask_b32_e64 v161, v154, v152, s[0:1]
	v_pk_fma_f32 v[152:153], v[2:3], v[138:139], v[98:99] op_sel_hi:[0,1,1] neg_lo:[1,0,0] neg_hi:[1,0,0]
	v_pk_mul_f32 v[150:151], v[150:151], v[156:157]
	s_waitcnt lgkmcnt(0)
	v_pk_fma_f32 v[152:153], v[180:181], v[152:153], v[134:135] op_sel_hi:[0,1,1]
	v_cndmask_b32_e64 v158, v157, v151, s[0:1]
	v_cndmask_b32_e64 v159, v156, v150, s[0:1]
	v_pk_fma_f32 v[150:151], v[2:3], v[140:141], v[100:101] op_sel_hi:[0,1,1] neg_lo:[1,0,0] neg_hi:[1,0,0]
	v_mul_f32_e32 v2, 0xbfb8aa3b, v152
	v_pk_fma_f32 v[150:151], v[180:181], v[150:151], v[136:137] op_sel_hi:[0,1,1]
	v_exp_f32_e32 v154, v2
	v_mul_f32_e32 v2, 0xbfb8aa3b, v153
	v_exp_f32_e32 v155, v2
	v_mul_f32_e32 v2, 0xbfb8aa3b, v150
	v_exp_f32_e32 v156, v2
	v_mul_f32_e32 v2, 0xbfb8aa3b, v151
	v_exp_f32_e32 v157, v2
	v_pk_add_f32 v[154:155], v[154:155], 1.0 op_sel_hi:[1,0]
	v_pk_add_f32 v[156:157], v[156:157], 1.0 op_sel_hi:[1,0]
	v_rcp_f32_e32 v154, v154
	v_rcp_f32_e32 v155, v155
	v_rcp_f32_e32 v156, v156
	v_rcp_f32_e32 v157, v157
	v_pk_mul_f32 v[152:153], v[152:153], v[154:155]
	s_nop 0
	v_cndmask_b32_e64 v153, v155, v153, s[0:1]
	v_pk_mul_f32 v[150:151], v[150:151], v[156:157]
	v_cndmask_b32_e64 v152, v154, v152, s[0:1]
	v_mov_b64_e32 v[154:155], s[6:7]
	v_cndmask_b32_e64 v2, v157, v151, s[0:1]
	v_cndmask_b32_e64 v156, v156, v150, s[0:1]
	v_mad_i64_i32 v[154:155], s[8:9], v181, s8, v[154:155]
	v_cvt_pk_bf16_f32 v150, v161, v160
	v_cvt_pk_bf16_f32 v151, v159, v158
	v_cvt_pk_bf16_f32 v152, v152, v153
	v_cvt_pk_bf16_f32 v153, v156, v2
	v_lshl_add_u64 v[154:155], v[4:5], 1, v[154:155]
	global_store_dwordx4 v[154:155], v[150:153], off offset:256 nt
	s_andn2_b64 vcc, exec, s[10:11]
	s_cbranch_vccnz .LBB0_1013
.LBB0_1036:
	s_waitcnt lgkmcnt(4)
	v_pk_fma_f32 v[152:153], v[178:179], v[146:147], v[86:87] op_sel_hi:[0,1,1] neg_lo:[1,0,0] neg_hi:[1,0,0]
	s_waitcnt lgkmcnt(1)
	v_pk_fma_f32 v[152:153], v[182:183], v[152:153], v[142:143] op_sel_hi:[0,1,1]
	v_pk_fma_f32 v[150:151], v[178:179], v[148:149], v[88:89] op_sel_hi:[0,1,1] neg_lo:[1,0,0] neg_hi:[1,0,0]
	v_mul_f32_e32 v2, 0xbfb8aa3b, v152
	v_pk_fma_f32 v[150:151], v[182:183], v[150:151], v[144:145] op_sel_hi:[0,1,1]
	v_exp_f32_e32 v154, v2
	v_mul_f32_e32 v2, 0xbfb8aa3b, v153
	v_exp_f32_e32 v155, v2
	v_mul_f32_e32 v2, 0xbfb8aa3b, v150
	v_exp_f32_e32 v156, v2
	v_mul_f32_e32 v2, 0xbfb8aa3b, v151
	v_exp_f32_e32 v157, v2
	v_pk_add_f32 v[154:155], v[154:155], 1.0 op_sel_hi:[1,0]
	v_add_u32_e32 v161, 16, v181
	v_rcp_f32_e32 v154, v154
	v_pk_add_f32 v[156:157], v[156:157], 1.0 op_sel_hi:[1,0]
	v_rcp_f32_e32 v155, v155
	v_rcp_f32_e32 v156, v156
	v_rcp_f32_e32 v157, v157
	s_movk_i32 s8, 0x3000
	v_pk_mul_f32 v[152:153], v[152:153], v[154:155]
	v_pk_mul_f32 v[150:151], v[150:151], v[156:157]
	v_cndmask_b32_e64 v159, v155, v153, s[0:1]
	v_cndmask_b32_e64 v160, v154, v152, s[0:1]
	v_pk_fma_f32 v[152:153], v[178:179], v[138:139], v[90:91] op_sel_hi:[0,1,1] neg_lo:[1,0,0] neg_hi:[1,0,0]
	v_cndmask_b32_e64 v2, v157, v151, s[0:1]
	v_cndmask_b32_e64 v158, v156, v150, s[0:1]
	v_pk_fma_f32 v[150:151], v[178:179], v[140:141], v[92:93] op_sel_hi:[0,1,1] neg_lo:[1,0,0] neg_hi:[1,0,0]
	s_waitcnt lgkmcnt(0)
	v_pk_fma_f32 v[152:153], v[182:183], v[152:153], v[134:135] op_sel_hi:[0,1,1]
	v_pk_fma_f32 v[150:151], v[182:183], v[150:151], v[136:137] op_sel_hi:[0,1,1]
	v_mul_f32_e32 v154, 0xbfb8aa3b, v152
	v_mul_f32_e32 v155, 0xbfb8aa3b, v153
	v_exp_f32_e32 v154, v154
	v_exp_f32_e32 v155, v155
	v_mul_f32_e32 v156, 0xbfb8aa3b, v150
	v_mul_f32_e32 v157, 0xbfb8aa3b, v151
	v_exp_f32_e32 v156, v156
	v_exp_f32_e32 v157, v157
	v_pk_add_f32 v[154:155], v[154:155], 1.0 op_sel_hi:[1,0]
	v_pk_add_f32 v[156:157], v[156:157], 1.0 op_sel_hi:[1,0]
	v_rcp_f32_e32 v154, v154
	v_rcp_f32_e32 v155, v155
	v_rcp_f32_e32 v156, v156
	v_rcp_f32_e32 v157, v157
	v_pk_mul_f32 v[152:153], v[152:153], v[154:155]
	s_nop 0
	v_cndmask_b32_e64 v153, v155, v153, s[0:1]
	v_pk_mul_f32 v[150:151], v[150:151], v[156:157]
	v_cndmask_b32_e64 v152, v154, v152, s[0:1]
	v_mov_b64_e32 v[154:155], s[6:7]
	v_cndmask_b32_e64 v157, v157, v151, s[0:1]
	v_cndmask_b32_e64 v156, v156, v150, s[0:1]
	v_mad_i64_i32 v[154:155], s[8:9], v161, s8, v[154:155]
	v_cvt_pk_bf16_f32 v150, v160, v159
	v_cvt_pk_bf16_f32 v151, v158, v2
	v_cvt_pk_bf16_f32 v152, v152, v153
	v_cvt_pk_bf16_f32 v153, v156, v157
	v_lshl_add_u64 v[154:155], v[4:5], 1, v[154:155]
	global_store_dwordx4 v[154:155], v[150:153], off offset:256 nt
	s_andn2_b64 vcc, exec, s[16:17]
	s_cbranch_vccnz .LBB0_1014
.LBB0_1037:
	s_waitcnt lgkmcnt(4)
	v_pk_fma_f32 v[152:153], v[174:175], v[146:147], v[78:79] op_sel_hi:[0,1,1] neg_lo:[1,0,0] neg_hi:[1,0,0]
	s_waitcnt lgkmcnt(1)
	v_pk_fma_f32 v[152:153], v[184:185], v[152:153], v[142:143] op_sel_hi:[0,1,1]
	v_pk_fma_f32 v[150:151], v[174:175], v[148:149], v[80:81] op_sel_hi:[0,1,1] neg_lo:[1,0,0] neg_hi:[1,0,0]
	v_mul_f32_e32 v2, 0xbfb8aa3b, v152
	v_pk_fma_f32 v[150:151], v[184:185], v[150:151], v[144:145] op_sel_hi:[0,1,1]
	v_exp_f32_e32 v154, v2
	v_mul_f32_e32 v2, 0xbfb8aa3b, v153
	v_exp_f32_e32 v155, v2
	v_mul_f32_e32 v2, 0xbfb8aa3b, v150
	v_exp_f32_e32 v156, v2
	v_mul_f32_e32 v2, 0xbfb8aa3b, v151
	v_exp_f32_e32 v157, v2
	v_pk_add_f32 v[154:155], v[154:155], 1.0 op_sel_hi:[1,0]
	v_add_u32_e32 v161, 32, v181
	v_rcp_f32_e32 v154, v154
	v_pk_add_f32 v[156:157], v[156:157], 1.0 op_sel_hi:[1,0]
	v_rcp_f32_e32 v155, v155
	v_rcp_f32_e32 v156, v156
	v_rcp_f32_e32 v157, v157
	s_movk_i32 s8, 0x3000
	v_pk_mul_f32 v[152:153], v[152:153], v[154:155]
	v_pk_mul_f32 v[150:151], v[150:151], v[156:157]
	v_cndmask_b32_e64 v159, v155, v153, s[0:1]
	v_cndmask_b32_e64 v160, v154, v152, s[0:1]
	v_pk_fma_f32 v[152:153], v[174:175], v[138:139], v[82:83] op_sel_hi:[0,1,1] neg_lo:[1,0,0] neg_hi:[1,0,0]
	v_cndmask_b32_e64 v2, v157, v151, s[0:1]
	v_cndmask_b32_e64 v158, v156, v150, s[0:1]
	v_pk_fma_f32 v[150:151], v[174:175], v[140:141], v[84:85] op_sel_hi:[0,1,1] neg_lo:[1,0,0] neg_hi:[1,0,0]
	s_waitcnt lgkmcnt(0)
	v_pk_fma_f32 v[152:153], v[184:185], v[152:153], v[134:135] op_sel_hi:[0,1,1]
	v_pk_fma_f32 v[150:151], v[184:185], v[150:151], v[136:137] op_sel_hi:[0,1,1]
	v_mul_f32_e32 v154, 0xbfb8aa3b, v152
	v_mul_f32_e32 v155, 0xbfb8aa3b, v153
	v_exp_f32_e32 v154, v154
	v_exp_f32_e32 v155, v155
	v_mul_f32_e32 v156, 0xbfb8aa3b, v150
	v_mul_f32_e32 v157, 0xbfb8aa3b, v151
	v_exp_f32_e32 v156, v156
	v_exp_f32_e32 v157, v157
	v_pk_add_f32 v[154:155], v[154:155], 1.0 op_sel_hi:[1,0]
	v_pk_add_f32 v[156:157], v[156:157], 1.0 op_sel_hi:[1,0]
	v_rcp_f32_e32 v154, v154
	v_rcp_f32_e32 v155, v155
	v_rcp_f32_e32 v156, v156
	v_rcp_f32_e32 v157, v157
	v_pk_mul_f32 v[152:153], v[152:153], v[154:155]
	s_nop 0
	v_cndmask_b32_e64 v153, v155, v153, s[0:1]
	v_pk_mul_f32 v[150:151], v[150:151], v[156:157]
	v_cndmask_b32_e64 v152, v154, v152, s[0:1]
	v_mov_b64_e32 v[154:155], s[6:7]
	v_cndmask_b32_e64 v157, v157, v151, s[0:1]
	v_cndmask_b32_e64 v156, v156, v150, s[0:1]
	v_mad_i64_i32 v[154:155], s[8:9], v161, s8, v[154:155]
	v_cvt_pk_bf16_f32 v150, v160, v159
	v_cvt_pk_bf16_f32 v151, v158, v2
	v_cvt_pk_bf16_f32 v152, v152, v153
	v_cvt_pk_bf16_f32 v153, v156, v157
	v_lshl_add_u64 v[154:155], v[4:5], 1, v[154:155]
	global_store_dwordx4 v[154:155], v[150:153], off offset:256 nt
	s_andn2_b64 vcc, exec, s[18:19]
	s_cbranch_vccnz .LBB0_1015
.LBB0_1038:
	s_waitcnt lgkmcnt(4)
	v_pk_fma_f32 v[152:153], v[176:177], v[146:147], v[70:71] op_sel_hi:[0,1,1] neg_lo:[1,0,0] neg_hi:[1,0,0]
	s_waitcnt lgkmcnt(1)
	v_pk_fma_f32 v[152:153], v[186:187], v[152:153], v[142:143] op_sel_hi:[0,1,1]
	v_pk_fma_f32 v[150:151], v[176:177], v[148:149], v[72:73] op_sel_hi:[0,1,1] neg_lo:[1,0,0] neg_hi:[1,0,0]
	v_mul_f32_e32 v2, 0xbfb8aa3b, v152
	v_pk_fma_f32 v[150:151], v[186:187], v[150:151], v[144:145] op_sel_hi:[0,1,1]
	v_exp_f32_e32 v154, v2
	v_mul_f32_e32 v2, 0xbfb8aa3b, v153
	v_exp_f32_e32 v155, v2
	v_mul_f32_e32 v2, 0xbfb8aa3b, v150
	v_exp_f32_e32 v156, v2
	v_mul_f32_e32 v2, 0xbfb8aa3b, v151
	v_exp_f32_e32 v157, v2
	v_pk_add_f32 v[154:155], v[154:155], 1.0 op_sel_hi:[1,0]
	v_add_u32_e32 v161, 48, v181
	v_rcp_f32_e32 v154, v154
	v_pk_add_f32 v[156:157], v[156:157], 1.0 op_sel_hi:[1,0]
	v_rcp_f32_e32 v155, v155
	v_rcp_f32_e32 v156, v156
	v_rcp_f32_e32 v157, v157
	s_movk_i32 s8, 0x3000
	v_pk_mul_f32 v[152:153], v[152:153], v[154:155]
	v_pk_mul_f32 v[150:151], v[150:151], v[156:157]
	v_cndmask_b32_e64 v159, v155, v153, s[0:1]
	v_cndmask_b32_e64 v160, v154, v152, s[0:1]
	v_pk_fma_f32 v[152:153], v[176:177], v[138:139], v[74:75] op_sel_hi:[0,1,1] neg_lo:[1,0,0] neg_hi:[1,0,0]
	v_cndmask_b32_e64 v2, v157, v151, s[0:1]
	v_cndmask_b32_e64 v158, v156, v150, s[0:1]
	v_pk_fma_f32 v[150:151], v[176:177], v[140:141], v[76:77] op_sel_hi:[0,1,1] neg_lo:[1,0,0] neg_hi:[1,0,0]
	s_waitcnt lgkmcnt(0)
	v_pk_fma_f32 v[152:153], v[186:187], v[152:153], v[134:135] op_sel_hi:[0,1,1]
	v_pk_fma_f32 v[150:151], v[186:187], v[150:151], v[136:137] op_sel_hi:[0,1,1]
	v_mul_f32_e32 v154, 0xbfb8aa3b, v152
	v_mul_f32_e32 v155, 0xbfb8aa3b, v153
	v_exp_f32_e32 v154, v154
	v_exp_f32_e32 v155, v155
	v_mul_f32_e32 v156, 0xbfb8aa3b, v150
	v_mul_f32_e32 v157, 0xbfb8aa3b, v151
	v_exp_f32_e32 v156, v156
	v_exp_f32_e32 v157, v157
	v_pk_add_f32 v[154:155], v[154:155], 1.0 op_sel_hi:[1,0]
	v_pk_add_f32 v[156:157], v[156:157], 1.0 op_sel_hi:[1,0]
	v_rcp_f32_e32 v154, v154
	v_rcp_f32_e32 v155, v155
	v_rcp_f32_e32 v156, v156
	v_rcp_f32_e32 v157, v157
	v_pk_mul_f32 v[152:153], v[152:153], v[154:155]
	s_nop 0
	v_cndmask_b32_e64 v153, v155, v153, s[0:1]
	v_pk_mul_f32 v[150:151], v[150:151], v[156:157]
	v_cndmask_b32_e64 v152, v154, v152, s[0:1]
	v_mov_b64_e32 v[154:155], s[6:7]
	v_cndmask_b32_e64 v157, v157, v151, s[0:1]
	v_cndmask_b32_e64 v156, v156, v150, s[0:1]
	v_mad_i64_i32 v[154:155], s[8:9], v161, s8, v[154:155]
	v_cvt_pk_bf16_f32 v150, v160, v159
	v_cvt_pk_bf16_f32 v151, v158, v2
	v_cvt_pk_bf16_f32 v152, v152, v153
	v_cvt_pk_bf16_f32 v153, v156, v157
	v_lshl_add_u64 v[154:155], v[4:5], 1, v[154:155]
	global_store_dwordx4 v[154:155], v[150:153], off offset:256 nt
	s_andn2_b64 vcc, exec, s[20:21]
	s_cbranch_vccnz .LBB0_1016
.LBB0_1039:
	s_waitcnt lgkmcnt(4)
	v_pk_fma_f32 v[152:153], v[170:171], v[146:147], v[14:15] op_sel_hi:[0,1,1] neg_lo:[1,0,0] neg_hi:[1,0,0]
	s_waitcnt lgkmcnt(1)
	v_pk_fma_f32 v[152:153], v[204:205], v[152:153], v[142:143] op_sel_hi:[0,1,1]
	v_pk_fma_f32 v[150:151], v[170:171], v[148:149], v[16:17] op_sel_hi:[0,1,1] neg_lo:[1,0,0] neg_hi:[1,0,0]
	v_mul_f32_e32 v2, 0xbfb8aa3b, v152
	v_pk_fma_f32 v[150:151], v[204:205], v[150:151], v[144:145] op_sel_hi:[0,1,1]
	v_exp_f32_e32 v154, v2
	v_mul_f32_e32 v2, 0xbfb8aa3b, v153
	v_exp_f32_e32 v155, v2
	v_mul_f32_e32 v2, 0xbfb8aa3b, v150
	v_exp_f32_e32 v156, v2
	v_mul_f32_e32 v2, 0xbfb8aa3b, v151
	v_exp_f32_e32 v157, v2
	v_pk_add_f32 v[154:155], v[154:155], 1.0 op_sel_hi:[1,0]
	s_movk_i32 s8, 0x3000
	v_rcp_f32_e32 v154, v154
	v_pk_add_f32 v[156:157], v[156:157], 1.0 op_sel_hi:[1,0]
	v_rcp_f32_e32 v155, v155
	v_rcp_f32_e32 v156, v156
	v_rcp_f32_e32 v157, v157
	v_pk_mul_f32 v[152:153], v[152:153], v[154:155]
	s_nop 0
	v_cndmask_b32_e64 v159, v155, v153, s[0:1]
	v_pk_mul_f32 v[150:151], v[150:151], v[156:157]
	v_cndmask_b32_e64 v160, v154, v152, s[0:1]
	v_pk_fma_f32 v[152:153], v[170:171], v[138:139], v[18:19] op_sel_hi:[0,1,1] neg_lo:[1,0,0] neg_hi:[1,0,0]
	v_cndmask_b32_e64 v2, v157, v151, s[0:1]
	v_cndmask_b32_e64 v158, v156, v150, s[0:1]
	v_pk_fma_f32 v[150:151], v[170:171], v[140:141], v[20:21] op_sel_hi:[0,1,1] neg_lo:[1,0,0] neg_hi:[1,0,0]
	s_waitcnt lgkmcnt(0)
	v_pk_fma_f32 v[152:153], v[204:205], v[152:153], v[134:135] op_sel_hi:[0,1,1]
	v_pk_fma_f32 v[150:151], v[204:205], v[150:151], v[136:137] op_sel_hi:[0,1,1]
	v_mul_f32_e32 v154, 0xbfb8aa3b, v152
	v_mul_f32_e32 v155, 0xbfb8aa3b, v153
	v_exp_f32_e32 v154, v154
	v_exp_f32_e32 v155, v155
	v_mul_f32_e32 v156, 0xbfb8aa3b, v150
	v_mul_f32_e32 v157, 0xbfb8aa3b, v151
	v_exp_f32_e32 v156, v156
	v_exp_f32_e32 v157, v157
	v_pk_add_f32 v[154:155], v[154:155], 1.0 op_sel_hi:[1,0]
	v_pk_add_f32 v[156:157], v[156:157], 1.0 op_sel_hi:[1,0]
	v_rcp_f32_e32 v154, v154
	v_rcp_f32_e32 v155, v155
	v_rcp_f32_e32 v156, v156
	v_rcp_f32_e32 v157, v157
	v_pk_mul_f32 v[152:153], v[152:153], v[154:155]
	s_nop 0
	v_cndmask_b32_e64 v153, v155, v153, s[0:1]
	v_pk_mul_f32 v[150:151], v[150:151], v[156:157]
	v_cndmask_b32_e64 v152, v154, v152, s[0:1]
	v_mov_b64_e32 v[154:155], s[6:7]
	v_cndmask_b32_e64 v157, v157, v151, s[0:1]
	v_cndmask_b32_e64 v156, v156, v150, s[0:1]
	v_mad_i64_i32 v[154:155], s[8:9], v171, s8, v[154:155]
	v_cvt_pk_bf16_f32 v150, v160, v159
	v_cvt_pk_bf16_f32 v151, v158, v2
	v_cvt_pk_bf16_f32 v152, v152, v153
	v_cvt_pk_bf16_f32 v153, v156, v157
	v_lshl_add_u64 v[154:155], v[4:5], 1, v[154:155]
	global_store_dwordx4 v[154:155], v[150:153], off offset:256 nt
	s_andn2_b64 vcc, exec, s[24:25]
	s_cbranch_vccnz .LBB0_1017
.LBB0_1040:
	s_waitcnt lgkmcnt(4)
	v_pk_fma_f32 v[152:153], v[172:173], v[146:147], v[6:7] op_sel_hi:[0,1,1] neg_lo:[1,0,0] neg_hi:[1,0,0]
	s_waitcnt lgkmcnt(1)
	v_pk_fma_f32 v[152:153], v[206:207], v[152:153], v[142:143] op_sel_hi:[0,1,1]
	v_pk_fma_f32 v[150:151], v[172:173], v[148:149], v[8:9] op_sel_hi:[0,1,1] neg_lo:[1,0,0] neg_hi:[1,0,0]
	v_mul_f32_e32 v2, 0xbfb8aa3b, v152
	v_pk_fma_f32 v[150:151], v[206:207], v[150:151], v[144:145] op_sel_hi:[0,1,1]
	v_exp_f32_e32 v154, v2
	v_mul_f32_e32 v2, 0xbfb8aa3b, v153
	v_exp_f32_e32 v155, v2
	v_mul_f32_e32 v2, 0xbfb8aa3b, v150
	v_exp_f32_e32 v156, v2
	v_mul_f32_e32 v2, 0xbfb8aa3b, v151
	v_exp_f32_e32 v157, v2
	v_pk_add_f32 v[154:155], v[154:155], 1.0 op_sel_hi:[1,0]
	v_add_u32_e32 v161, 0x90, v181
	v_rcp_f32_e32 v154, v154
	v_pk_add_f32 v[156:157], v[156:157], 1.0 op_sel_hi:[1,0]
	v_rcp_f32_e32 v155, v155
	v_rcp_f32_e32 v156, v156
	v_rcp_f32_e32 v157, v157
	s_movk_i32 s8, 0x3000
	v_pk_mul_f32 v[152:153], v[152:153], v[154:155]
	v_pk_mul_f32 v[150:151], v[150:151], v[156:157]
	v_cndmask_b32_e64 v159, v155, v153, s[0:1]
	v_cndmask_b32_e64 v160, v154, v152, s[0:1]
	v_pk_fma_f32 v[152:153], v[172:173], v[138:139], v[10:11] op_sel_hi:[0,1,1] neg_lo:[1,0,0] neg_hi:[1,0,0]
	v_cndmask_b32_e64 v2, v157, v151, s[0:1]
	v_cndmask_b32_e64 v158, v156, v150, s[0:1]
	v_pk_fma_f32 v[150:151], v[172:173], v[140:141], v[12:13] op_sel_hi:[0,1,1] neg_lo:[1,0,0] neg_hi:[1,0,0]
	s_waitcnt lgkmcnt(0)
	v_pk_fma_f32 v[152:153], v[206:207], v[152:153], v[134:135] op_sel_hi:[0,1,1]
	v_pk_fma_f32 v[150:151], v[206:207], v[150:151], v[136:137] op_sel_hi:[0,1,1]
	v_mul_f32_e32 v154, 0xbfb8aa3b, v152
	v_mul_f32_e32 v155, 0xbfb8aa3b, v153
	v_exp_f32_e32 v154, v154
	v_exp_f32_e32 v155, v155
	v_mul_f32_e32 v156, 0xbfb8aa3b, v150
	v_mul_f32_e32 v157, 0xbfb8aa3b, v151
	v_exp_f32_e32 v156, v156
	v_exp_f32_e32 v157, v157
	v_pk_add_f32 v[154:155], v[154:155], 1.0 op_sel_hi:[1,0]
	v_pk_add_f32 v[156:157], v[156:157], 1.0 op_sel_hi:[1,0]
	v_rcp_f32_e32 v154, v154
	v_rcp_f32_e32 v155, v155
	v_rcp_f32_e32 v156, v156
	v_rcp_f32_e32 v157, v157
	v_pk_mul_f32 v[152:153], v[152:153], v[154:155]
	s_nop 0
	v_cndmask_b32_e64 v153, v155, v153, s[0:1]
	v_pk_mul_f32 v[150:151], v[150:151], v[156:157]
	v_cndmask_b32_e64 v152, v154, v152, s[0:1]
	v_mov_b64_e32 v[154:155], s[6:7]
	v_cndmask_b32_e64 v157, v157, v151, s[0:1]
	v_cndmask_b32_e64 v156, v156, v150, s[0:1]
	v_mad_i64_i32 v[154:155], s[8:9], v161, s8, v[154:155]
	v_cvt_pk_bf16_f32 v150, v160, v159
	v_cvt_pk_bf16_f32 v151, v158, v2
	v_cvt_pk_bf16_f32 v152, v152, v153
	v_cvt_pk_bf16_f32 v153, v156, v157
	v_lshl_add_u64 v[154:155], v[4:5], 1, v[154:155]
	global_store_dwordx4 v[154:155], v[150:153], off offset:256 nt
	s_andn2_b64 vcc, exec, s[26:27]
	s_cbranch_vccnz .LBB0_1018
.LBB0_1041:
	s_waitcnt lgkmcnt(4)
	v_pk_fma_f32 v[152:153], v[166:167], v[146:147], v[54:55] op_sel_hi:[0,1,1] neg_lo:[1,0,0] neg_hi:[1,0,0]
	s_waitcnt lgkmcnt(1)
	v_pk_fma_f32 v[152:153], v[208:209], v[152:153], v[142:143] op_sel_hi:[0,1,1]
	v_pk_fma_f32 v[150:151], v[166:167], v[148:149], v[56:57] op_sel_hi:[0,1,1] neg_lo:[1,0,0] neg_hi:[1,0,0]
	v_mul_f32_e32 v2, 0xbfb8aa3b, v152
	v_pk_fma_f32 v[150:151], v[208:209], v[150:151], v[144:145] op_sel_hi:[0,1,1]
	v_exp_f32_e32 v154, v2
	v_mul_f32_e32 v2, 0xbfb8aa3b, v153
	v_exp_f32_e32 v155, v2
	v_mul_f32_e32 v2, 0xbfb8aa3b, v150
	v_exp_f32_e32 v156, v2
	v_mul_f32_e32 v2, 0xbfb8aa3b, v151
	v_exp_f32_e32 v157, v2
	v_pk_add_f32 v[154:155], v[154:155], 1.0 op_sel_hi:[1,0]
	v_add_u32_e32 v161, 0xa0, v181
	v_rcp_f32_e32 v154, v154
	v_pk_add_f32 v[156:157], v[156:157], 1.0 op_sel_hi:[1,0]
	v_rcp_f32_e32 v155, v155
	v_rcp_f32_e32 v156, v156
	v_rcp_f32_e32 v157, v157
	s_movk_i32 s8, 0x3000
	v_pk_mul_f32 v[152:153], v[152:153], v[154:155]
	v_pk_mul_f32 v[150:151], v[150:151], v[156:157]
	v_cndmask_b32_e64 v159, v155, v153, s[0:1]
	v_cndmask_b32_e64 v160, v154, v152, s[0:1]
	v_pk_fma_f32 v[152:153], v[166:167], v[138:139], v[62:63] op_sel_hi:[0,1,1] neg_lo:[1,0,0] neg_hi:[1,0,0]
	v_cndmask_b32_e64 v2, v157, v151, s[0:1]
	v_cndmask_b32_e64 v158, v156, v150, s[0:1]
	v_pk_fma_f32 v[150:151], v[166:167], v[140:141], v[64:65] op_sel_hi:[0,1,1] neg_lo:[1,0,0] neg_hi:[1,0,0]
	s_waitcnt lgkmcnt(0)
	v_pk_fma_f32 v[152:153], v[208:209], v[152:153], v[134:135] op_sel_hi:[0,1,1]
	v_pk_fma_f32 v[150:151], v[208:209], v[150:151], v[136:137] op_sel_hi:[0,1,1]
	v_mul_f32_e32 v154, 0xbfb8aa3b, v152
	v_mul_f32_e32 v155, 0xbfb8aa3b, v153
	v_exp_f32_e32 v154, v154
	v_exp_f32_e32 v155, v155
	v_mul_f32_e32 v156, 0xbfb8aa3b, v150
	v_mul_f32_e32 v157, 0xbfb8aa3b, v151
	v_exp_f32_e32 v156, v156
	v_exp_f32_e32 v157, v157
	v_pk_add_f32 v[154:155], v[154:155], 1.0 op_sel_hi:[1,0]
	v_pk_add_f32 v[156:157], v[156:157], 1.0 op_sel_hi:[1,0]
	v_rcp_f32_e32 v154, v154
	v_rcp_f32_e32 v155, v155
	v_rcp_f32_e32 v156, v156
	v_rcp_f32_e32 v157, v157
	v_pk_mul_f32 v[152:153], v[152:153], v[154:155]
	s_nop 0
	v_cndmask_b32_e64 v153, v155, v153, s[0:1]
	v_pk_mul_f32 v[150:151], v[150:151], v[156:157]
	v_cndmask_b32_e64 v152, v154, v152, s[0:1]
	v_mov_b64_e32 v[154:155], s[6:7]
	v_cndmask_b32_e64 v157, v157, v151, s[0:1]
	v_cndmask_b32_e64 v156, v156, v150, s[0:1]
	v_mad_i64_i32 v[154:155], s[8:9], v161, s8, v[154:155]
	v_cvt_pk_bf16_f32 v150, v160, v159
	v_cvt_pk_bf16_f32 v151, v158, v2
	v_cvt_pk_bf16_f32 v152, v152, v153
	v_cvt_pk_bf16_f32 v153, v156, v157
	v_lshl_add_u64 v[154:155], v[4:5], 1, v[154:155]
	global_store_dwordx4 v[154:155], v[150:153], off offset:256 nt
	s_andn2_b64 vcc, exec, s[28:29]
	s_cbranch_vccz .LBB0_1019
	s_branch .LBB0_1020
.LBB0_1042:
	v_lshl_add_u64 v[172:173], s[8:9], 0, v[172:173]
	v_lshl_add_u64 v[172:173], v[172:173], 0, v[158:159]
	v_add_co_u32_e32 v172, vcc, 0x2000, v172
	v_lshl_add_u64 v[174:175], v[160:161], 0, v[170:171]
	s_nop 0
	v_addc_co_u32_e32 v173, vcc, 0, v173, vcc
	global_load_dwordx4 v[174:177], v[174:175], off offset:256
	v_lshl_add_u64 v[170:171], s[6:7], 0, v[170:171]
	global_load_dwordx4 v[178:181], v[172:173], off offset:256
	v_lshl_add_u64 v[170:171], v[170:171], 0, v[158:159]
	s_waitcnt vmcnt(1)
	v_lshlrev_b32_e32 v172, 16, v174
	v_and_b32_e32 v173, 0xffff0000, v174
	v_lshlrev_b32_e32 v174, 16, v175
	v_and_b32_e32 v175, 0xffff0000, v175
	s_waitcnt vmcnt(0)
	v_lshlrev_b32_e32 v182, 16, v178
	v_and_b32_e32 v183, 0xffff0000, v178
	v_lshlrev_b32_e32 v178, 16, v179
	v_and_b32_e32 v179, 0xffff0000, v179
	v_pk_fma_f32 v[174:175], v[96:97], v[178:179], v[174:175]
	v_pk_fma_f32 v[172:173], v[94:95], v[182:183], v[172:173]
	v_lshlrev_b32_e32 v178, 16, v176
	v_and_b32_e32 v179, 0xffff0000, v176
	v_lshlrev_b32_e32 v176, 16, v177
	v_and_b32_e32 v177, 0xffff0000, v177
	v_lshlrev_b32_e32 v182, 16, v180
	v_and_b32_e32 v183, 0xffff0000, v180
	v_lshlrev_b32_e32 v180, 16, v181
	v_and_b32_e32 v181, 0xffff0000, v181
	v_pk_fma_f32 v[176:177], v[100:101], v[180:181], v[176:177]
	v_pk_fma_f32 v[178:179], v[98:99], v[182:183], v[178:179]
	v_cvt_pk_bf16_f32 v172, v172, v173
	v_cvt_pk_bf16_f32 v173, v174, v175
	v_cvt_pk_bf16_f32 v174, v178, v179
	v_cvt_pk_bf16_f32 v175, v176, v177
	global_store_dwordx4 v[170:171], v[172:175], off offset:256 nt
	s_andn2_b64 vcc, exec, s[14:15]
	s_cbranch_vccnz .LBB0_874
.LBB0_1043:
	s_waitcnt vmcnt(5)
	v_lshlrev_b32_e32 v170, 16, v150
	v_and_b32_e32 v171, 0xffff0000, v150
	v_lshlrev_b32_e32 v150, 16, v151
	v_and_b32_e32 v151, 0xffff0000, v151
	s_waitcnt vmcnt(1)
	v_lshlrev_b32_e32 v172, 16, v154
	v_and_b32_e32 v173, 0xffff0000, v154
	v_lshlrev_b32_e32 v154, 16, v155
	v_and_b32_e32 v155, 0xffff0000, v155
	v_pk_fma_f32 v[154:155], v[88:89], v[154:155], v[150:151]
	v_pk_fma_f32 v[150:151], v[86:87], v[172:173], v[170:171]
	v_lshlrev_b32_e32 v170, 16, v152
	v_and_b32_e32 v171, 0xffff0000, v152
	v_lshlrev_b32_e32 v152, 16, v153
	v_and_b32_e32 v153, 0xffff0000, v153
	v_lshlrev_b32_e32 v172, 16, v156
	v_and_b32_e32 v173, 0xffff0000, v156
	v_lshlrev_b32_e32 v156, 16, v157
	v_and_b32_e32 v157, 0xffff0000, v157
	v_pk_fma_f32 v[156:157], v[92:93], v[156:157], v[152:153]
	v_pk_fma_f32 v[152:153], v[90:91], v[172:173], v[170:171]
	v_cvt_pk_bf16_f32 v150, v150, v151
	v_cvt_pk_bf16_f32 v151, v154, v155
	v_lshl_add_u64 v[154:155], s[6:7], 0, v[168:169]
	v_cvt_pk_bf16_f32 v152, v152, v153
	v_cvt_pk_bf16_f32 v153, v156, v157
	v_lshl_add_u64 v[154:155], v[4:5], 1, v[154:155]
	global_store_dwordx4 v[154:155], v[150:153], off offset:256 nt
	s_andn2_b64 vcc, exec, s[16:17]
	s_cbranch_vccnz .LBB0_875
.LBB0_1044:
	s_waitcnt vmcnt(4)
	v_lshlrev_b32_e32 v150, 16, v142
	v_and_b32_e32 v151, 0xffff0000, v142
	v_lshlrev_b32_e32 v142, 16, v143
	v_and_b32_e32 v143, 0xffff0000, v143
	s_waitcnt vmcnt(3)
	v_lshlrev_b32_e32 v152, 16, v146
	v_and_b32_e32 v153, 0xffff0000, v146
	v_lshlrev_b32_e32 v146, 16, v147
	v_and_b32_e32 v147, 0xffff0000, v147
	v_pk_fma_f32 v[146:147], v[80:81], v[146:147], v[142:143]
	v_pk_fma_f32 v[142:143], v[78:79], v[152:153], v[150:151]
	v_lshlrev_b32_e32 v150, 16, v144
	v_and_b32_e32 v151, 0xffff0000, v144
	v_lshlrev_b32_e32 v144, 16, v145
	v_and_b32_e32 v145, 0xffff0000, v145
	v_lshlrev_b32_e32 v152, 16, v148
	v_and_b32_e32 v153, 0xffff0000, v148
	v_lshlrev_b32_e32 v148, 16, v149
	v_and_b32_e32 v149, 0xffff0000, v149
	v_pk_fma_f32 v[148:149], v[84:85], v[148:149], v[144:145]
	v_pk_fma_f32 v[144:145], v[82:83], v[152:153], v[150:151]
	v_cvt_pk_bf16_f32 v142, v142, v143
	v_cvt_pk_bf16_f32 v143, v146, v147
	v_lshl_add_u64 v[146:147], s[6:7], 0, v[166:167]
	v_cvt_pk_bf16_f32 v144, v144, v145
	v_cvt_pk_bf16_f32 v145, v148, v149
	v_lshl_add_u64 v[146:147], v[4:5], 1, v[146:147]
	global_store_dwordx4 v[146:147], v[142:145], off offset:256 nt
	s_andn2_b64 vcc, exec, s[18:19]
	s_cbranch_vccz .LBB0_876
	s_branch .LBB0_877
.LBB0_1045:
	v_lshl_add_u64 v[160:161], v[160:161], 0, v[168:169]
	global_load_dwordx4 v[172:175], v[160:161], off offset:256
	v_lshl_add_u64 v[160:161], s[8:9], 0, v[170:171]
	v_lshl_add_u64 v[160:161], v[160:161], 0, v[158:159]
	v_add_co_u32_e32 v160, vcc, 0x2000, v160
	s_waitcnt vmcnt(0)
	v_lshlrev_b32_e32 v170, 16, v173
	v_addc_co_u32_e32 v161, vcc, 0, v161, vcc
	global_load_dwordx4 v[176:179], v[160:161], off offset:256
	v_lshlrev_b32_e32 v160, 16, v172
	v_and_b32_e32 v161, 0xffff0000, v172
	v_and_b32_e32 v171, 0xffff0000, v173
	s_waitcnt vmcnt(0)
	v_lshlrev_b32_e32 v172, 16, v176
	v_and_b32_e32 v173, 0xffff0000, v176
	v_lshlrev_b32_e32 v176, 16, v177
	v_and_b32_e32 v177, 0xffff0000, v177
	v_pk_fma_f32 v[176:177], v[16:17], v[176:177], v[170:171]
	v_pk_fma_f32 v[160:161], v[14:15], v[172:173], v[160:161]
	v_lshlrev_b32_e32 v170, 16, v174
	v_and_b32_e32 v171, 0xffff0000, v174
	v_lshlrev_b32_e32 v172, 16, v175
	v_and_b32_e32 v173, 0xffff0000, v175
	v_lshlrev_b32_e32 v174, 16, v178
	v_and_b32_e32 v175, 0xffff0000, v178
	v_lshlrev_b32_e32 v178, 16, v179
	v_and_b32_e32 v179, 0xffff0000, v179
	v_pk_fma_f32 v[178:179], v[20:21], v[178:179], v[172:173]
	v_pk_fma_f32 v[172:173], v[18:19], v[174:175], v[170:171]
	v_cvt_pk_bf16_f32 v170, v160, v161
	v_lshl_add_u64 v[160:161], s[6:7], 0, v[168:169]
	v_cvt_pk_bf16_f32 v171, v176, v177
	v_cvt_pk_bf16_f32 v172, v172, v173
	v_cvt_pk_bf16_f32 v173, v178, v179
	v_lshl_add_u64 v[158:159], v[160:161], 0, v[158:159]
	global_store_dwordx4 v[158:159], v[170:173], off offset:256 nt
	s_andn2_b64 vcc, exec, s[14:15]
	s_cbranch_vccnz .LBB0_887
.LBB0_1046:
	s_waitcnt vmcnt(5)
	v_lshlrev_b32_e32 v158, 16, v150
	v_and_b32_e32 v159, 0xffff0000, v150
	v_lshlrev_b32_e32 v150, 16, v151
	v_and_b32_e32 v151, 0xffff0000, v151
	s_waitcnt vmcnt(1)
	v_lshlrev_b32_e32 v160, 16, v154
	v_and_b32_e32 v161, 0xffff0000, v154
	v_lshlrev_b32_e32 v154, 16, v155
	v_and_b32_e32 v155, 0xffff0000, v155
	v_pk_fma_f32 v[154:155], v[8:9], v[154:155], v[150:151]
	v_pk_fma_f32 v[150:151], v[6:7], v[160:161], v[158:159]
	v_lshlrev_b32_e32 v158, 16, v152
	v_and_b32_e32 v159, 0xffff0000, v152
	v_lshlrev_b32_e32 v152, 16, v153
	v_and_b32_e32 v153, 0xffff0000, v153
	v_lshlrev_b32_e32 v160, 16, v156
	v_and_b32_e32 v161, 0xffff0000, v156
	v_lshlrev_b32_e32 v156, 16, v157
	v_and_b32_e32 v157, 0xffff0000, v157
	v_pk_fma_f32 v[156:157], v[12:13], v[156:157], v[152:153]
	v_pk_fma_f32 v[152:153], v[10:11], v[160:161], v[158:159]
	v_cvt_pk_bf16_f32 v150, v150, v151
	v_cvt_pk_bf16_f32 v151, v154, v155
	v_lshl_add_u64 v[154:155], s[6:7], 0, v[166:167]
	v_cvt_pk_bf16_f32 v152, v152, v153
	v_cvt_pk_bf16_f32 v153, v156, v157
	v_lshl_add_u64 v[154:155], v[4:5], 1, v[154:155]
	global_store_dwordx4 v[154:155], v[150:153], off offset:256 nt
	s_andn2_b64 vcc, exec, s[16:17]
	s_cbranch_vccnz .LBB0_888
.LBB0_1047:
	s_waitcnt vmcnt(4)
	v_lshlrev_b32_e32 v150, 16, v142
	v_and_b32_e32 v151, 0xffff0000, v142
	v_lshlrev_b32_e32 v142, 16, v143
	v_and_b32_e32 v143, 0xffff0000, v143
	s_waitcnt vmcnt(3)
	v_lshlrev_b32_e32 v152, 16, v146
	v_and_b32_e32 v153, 0xffff0000, v146
	v_lshlrev_b32_e32 v146, 16, v147
	v_and_b32_e32 v147, 0xffff0000, v147
	v_pk_fma_f32 v[146:147], v[56:57], v[146:147], v[142:143]
	v_pk_fma_f32 v[142:143], v[54:55], v[152:153], v[150:151]
	v_lshlrev_b32_e32 v150, 16, v144
	v_and_b32_e32 v151, 0xffff0000, v144
	v_lshlrev_b32_e32 v144, 16, v145
	v_and_b32_e32 v145, 0xffff0000, v145
	v_lshlrev_b32_e32 v152, 16, v148
	v_and_b32_e32 v153, 0xffff0000, v148
	v_lshlrev_b32_e32 v148, 16, v149
	v_and_b32_e32 v149, 0xffff0000, v149
	v_pk_fma_f32 v[148:149], v[64:65], v[148:149], v[144:145]
	v_pk_fma_f32 v[144:145], v[62:63], v[152:153], v[150:151]
	v_cvt_pk_bf16_f32 v142, v142, v143
	v_cvt_pk_bf16_f32 v143, v146, v147
	v_lshl_add_u64 v[146:147], s[6:7], 0, v[164:165]
	v_cvt_pk_bf16_f32 v144, v144, v145
	v_cvt_pk_bf16_f32 v145, v148, v149
	v_lshl_add_u64 v[146:147], v[4:5], 1, v[146:147]
	global_store_dwordx4 v[146:147], v[142:145], off offset:256 nt
	s_andn2_b64 vcc, exec, s[18:19]
	s_cbranch_vccz .LBB0_889
	s_branch .LBB0_890

.LBB0_1049:
	s_nop 0
	v_mov_b64_e32 v[140:141], v[4:5]
	v_mov_b64_e32 v[138:139], v[2:3]
	v_mul_f32_e32 v5, 0x3a000000, v176
	v_mul_f32_e32 v2, v5, v5
	v_fma_f32 v2, v177, s72, -v2
	v_add_f32_e32 v2, 0x3727c5ac, v2
	v_rsq_f32_e32 v2, v2
	s_and_b32 s8, s84, 2
	s_bitcmp1_b32 s84, 1
	s_cselect_b64 s[6:7], -1, 0
	s_cmp_eq_u32 s8, 0
	s_cbranch_scc1 .LBB0_1051
	v_lshlrev_b32_e32 v4, 16, v170
	v_and_b32_e32 v170, 0xffff0000, v170
	v_lshlrev_b32_e32 v175, 16, v171
	v_and_b32_e32 v176, 0xffff0000, v171
	v_lshlrev_b32_e32 v203, 16, v172
	v_and_b32_e32 v177, 0xffff0000, v172
	v_lshlrev_b32_e32 v215, 16, v173
	v_and_b32_e32 v216, 0xffff0000, v173
	v_sub_f32_e32 v171, v170, v5
	v_sub_f32_e32 v170, v4, v5
	v_sub_f32_e32 v173, v176, v5
	v_sub_f32_e32 v172, v175, v5
	v_sub_f32_e32 v177, v177, v5
	v_sub_f32_e32 v176, v203, v5
	v_sub_f32_e32 v217, v216, v5
	v_sub_f32_e32 v216, v215, v5
	v_pk_mul_f32 v[172:173], v[2:3], v[172:173] op_sel_hi:[0,1]
	v_pk_mul_f32 v[170:171], v[2:3], v[170:171] op_sel_hi:[0,1]
	v_pk_mul_f32 v[216:217], v[2:3], v[216:217] op_sel_hi:[0,1]
	v_pk_mul_f32 v[176:177], v[2:3], v[176:177] op_sel_hi:[0,1]
	s_waitcnt lgkmcnt(1)
	v_pk_fma_f32 v[170:171], v[150:151], v[170:171], v[154:155]
	v_pk_fma_f32 v[172:173], v[152:153], v[172:173], v[156:157]
	s_waitcnt lgkmcnt(0)
	v_pk_fma_f32 v[176:177], v[142:143], v[176:177], v[146:147]
	v_pk_fma_f32 v[216:217], v[144:145], v[216:217], v[148:149]
	v_pk_mul_f32 v[172:173], v[172:173], s[76:77] op_sel_hi:[1,0]
	v_pk_mul_f32 v[170:171], v[170:171], s[76:77] op_sel_hi:[1,0]
	v_pk_mul_f32 v[216:217], v[216:217], s[76:77] op_sel_hi:[1,0]
	v_pk_mul_f32 v[176:177], v[176:177], s[76:77] op_sel_hi:[1,0]
	v_pk_fma_f32 v[170:171], v[118:119], 0.5, v[170:171] op_sel_hi:[1,0,1]
	v_pk_fma_f32 v[172:173], v[120:121], 0.5, v[172:173] op_sel_hi:[1,0,1]
	v_pk_fma_f32 v[176:177], v[122:123], 0.5, v[176:177] op_sel_hi:[1,0,1]
	v_pk_fma_f32 v[216:217], v[124:125], 0.5, v[216:217] op_sel_hi:[1,0,1]
	v_pk_add_f32 v[222:223], v[170:171], v[176:177]
	v_pk_add_f32 v[218:219], v[172:173], v[216:217]
	v_pk_mul_f32 v[224:225], v[176:177], v[176:177]
	v_pk_mul_f32 v[226:227], v[216:217], v[216:217]
	v_pk_mov_b32 v[232:233], v[222:223], v[218:219] op_sel:[1,0]
	v_mov_b32_e32 v223, v219
	v_pk_fma_f32 v[226:227], v[172:173], v[172:173], v[226:227]
	v_pk_fma_f32 v[224:225], v[170:171], v[170:171], v[224:225]
	v_pk_add_f32 v[218:219], v[232:233], v[222:223]
	v_cvt_pk_bf16_f32 v170, v170, v171
	v_add_f32_e32 v4, v218, v219
	v_pk_mov_b32 v[218:219], v[224:225], v[226:227] op_sel:[1,0]
	v_mov_b32_e32 v225, v227
	v_pk_add_f32 v[218:219], v[218:219], v[224:225]
	v_add_f32_e32 v139, v4, v139
	v_add_f32_e32 v4, v218, v219
	v_cvt_pk_bf16_f32 v171, v172, v173
	v_cvt_pk_bf16_f32 v172, v176, v177
	v_lshl_add_u64 v[176:177], s[18:19], 0, v[212:213]
	v_add_f32_e32 v135, v4, v135
	v_cvt_pk_bf16_f32 v173, v216, v217
	v_lshl_add_u64 v[176:177], v[178:179], 1, v[176:177]
	global_store_dwordx4 v[176:177], v[170:173], off nt
.LBB0_1051:
	s_nop 1
	v_mul_f32_e32 v171, 0x3a000000, v162
	v_mul_f32_e32 v4, v171, v171
	v_fma_f32 v4, v163, s72, -v4
	v_add_f32_e32 v4, 0x3727c5ac, v4
	v_rsq_f32_e32 v4, v4
	s_and_b32 s10, s84, 4
	s_bitcmp1_b32 s84, 2
	s_cselect_b64 s[8:9], -1, 0
	s_cmp_eq_u32 s10, 0
	s_cbranch_scc1 .LBB0_1053
	v_lshlrev_b32_e32 v162, 16, v166
	v_and_b32_e32 v163, 0xffff0000, v166
	v_lshlrev_b32_e32 v166, 16, v167
	v_and_b32_e32 v167, 0xffff0000, v167
	v_sub_f32_e32 v167, v167, v171
	v_sub_f32_e32 v166, v166, v171
	v_pk_mul_f32 v[166:167], v[4:5], v[166:167] op_sel_hi:[0,1]
	s_waitcnt lgkmcnt(1)
	v_pk_fma_f32 v[166:167], v[152:153], v[166:167], v[156:157]
	v_lshlrev_b32_e32 v170, 16, v168
	v_and_b32_e32 v172, 0xffff0000, v168
	v_lshlrev_b32_e32 v175, 16, v169
	v_and_b32_e32 v173, 0xffff0000, v169
	v_pk_mul_f32 v[166:167], v[166:167], s[76:77] op_sel_hi:[1,0]
	v_sub_f32_e32 v163, v163, v171
	v_sub_f32_e32 v162, v162, v171
	v_pk_fma_f32 v[168:169], v[112:113], 0.5, v[166:167] op_sel_hi:[1,0,1]
	v_sub_f32_e32 v167, v172, v171
	v_sub_f32_e32 v166, v170, v171
	v_sub_f32_e32 v173, v173, v171
	v_sub_f32_e32 v172, v175, v171
	v_pk_mul_f32 v[162:163], v[4:5], v[162:163] op_sel_hi:[0,1]
	v_pk_mul_f32 v[172:173], v[4:5], v[172:173] op_sel_hi:[0,1]
	v_pk_mul_f32 v[166:167], v[4:5], v[166:167] op_sel_hi:[0,1]
	v_pk_fma_f32 v[162:163], v[150:151], v[162:163], v[154:155]
	s_waitcnt lgkmcnt(0)
	v_pk_fma_f32 v[166:167], v[142:143], v[166:167], v[146:147]
	v_pk_fma_f32 v[172:173], v[144:145], v[172:173], v[148:149]
	v_pk_mul_f32 v[162:163], v[162:163], s[76:77] op_sel_hi:[1,0]
	v_pk_mul_f32 v[172:173], v[172:173], s[76:77] op_sel_hi:[1,0]
	v_pk_mul_f32 v[166:167], v[166:167], s[76:77] op_sel_hi:[1,0]
	v_pk_fma_f32 v[162:163], v[110:111], 0.5, v[162:163] op_sel_hi:[1,0,1]
	v_pk_fma_f32 v[176:177], v[114:115], 0.5, v[166:167] op_sel_hi:[1,0,1]
	v_pk_fma_f32 v[172:173], v[116:117], 0.5, v[172:173] op_sel_hi:[1,0,1]
	v_pk_add_f32 v[212:213], v[162:163], v[176:177]
	v_pk_add_f32 v[166:167], v[168:169], v[172:173]
	v_pk_mul_f32 v[216:217], v[176:177], v[176:177]
	v_pk_mov_b32 v[222:223], v[212:213], v[166:167] op_sel:[1,0]
	v_mov_b32_e32 v213, v167
	v_pk_mul_f32 v[218:219], v[172:173], v[172:173]
	v_pk_add_f32 v[166:167], v[222:223], v[212:213]
	v_pk_fma_f32 v[218:219], v[168:169], v[168:169], v[218:219]
	v_pk_fma_f32 v[216:217], v[162:163], v[162:163], v[216:217]
	v_add_f32_e32 v166, v166, v167
	v_add_f32_e32 v140, v166, v140
	v_pk_mov_b32 v[166:167], v[216:217], v[218:219] op_sel:[1,0]
	v_mov_b32_e32 v217, v219
	v_pk_add_f32 v[166:167], v[166:167], v[216:217]
	s_nop 0
	v_add_f32_e32 v166, v166, v167
	v_add_f32_e32 v136, v166, v136
	v_cvt_pk_bf16_f32 v166, v162, v163
	v_lshl_add_u64 v[162:163], s[18:19], 0, v[210:211]
	v_cvt_pk_bf16_f32 v167, v168, v169
	v_cvt_pk_bf16_f32 v168, v176, v177
	v_cvt_pk_bf16_f32 v169, v172, v173
	v_lshl_add_u64 v[162:163], v[178:179], 1, v[162:163]
	global_store_dwordx4 v[162:163], v[166:169], off nt
.LBB0_1053:
	v_mul_f32_e32 v172, 0x3a000000, v164
	v_mul_f32_e32 v162, v172, v172
	v_fma_f32 v162, v165, s72, -v162
	v_add_f32_e32 v162, 0x3727c5ac, v162
	v_rsq_f32_e32 v170, v162
	s_and_b32 s20, s84, 8
	s_bitcmp1_b32 s84, 3
	s_cselect_b64 s[10:11], -1, 0
	s_cmp_eq_u32 s20, 0
	s_cbranch_scc1 .LBB0_1055
	v_lshlrev_b32_e32 v162, 16, v158
	v_and_b32_e32 v158, 0xffff0000, v158
	v_lshlrev_b32_e32 v163, 16, v159
	v_and_b32_e32 v164, 0xffff0000, v159
	v_lshlrev_b32_e32 v165, 16, v160
	v_and_b32_e32 v166, 0xffff0000, v160
	v_lshlrev_b32_e32 v167, 16, v161
	v_and_b32_e32 v168, 0xffff0000, v161
	v_sub_f32_e32 v159, v158, v172
	v_sub_f32_e32 v158, v162, v172
	v_sub_f32_e32 v161, v164, v172
	v_sub_f32_e32 v160, v163, v172
	v_pk_mul_f32 v[160:161], v[170:171], v[160:161] op_sel_hi:[0,1]
	v_pk_mul_f32 v[158:159], v[170:171], v[158:159] op_sel_hi:[0,1]
	s_waitcnt lgkmcnt(1)
	v_pk_fma_f32 v[150:151], v[150:151], v[158:159], v[154:155]
	v_pk_fma_f32 v[152:153], v[152:153], v[160:161], v[156:157]
	v_sub_f32_e32 v155, v166, v172
	v_sub_f32_e32 v154, v165, v172
	v_sub_f32_e32 v157, v168, v172
	v_sub_f32_e32 v156, v167, v172
	v_pk_mul_f32 v[156:157], v[170:171], v[156:157] op_sel_hi:[0,1]
	v_pk_mul_f32 v[154:155], v[170:171], v[154:155] op_sel_hi:[0,1]
	s_waitcnt lgkmcnt(0)
	v_pk_fma_f32 v[142:143], v[142:143], v[154:155], v[146:147]
	v_pk_fma_f32 v[144:145], v[144:145], v[156:157], v[148:149]
	v_pk_mul_f32 v[152:153], v[152:153], s[76:77] op_sel_hi:[1,0]
	v_pk_mul_f32 v[150:151], v[150:151], s[76:77] op_sel_hi:[1,0]
	v_pk_mul_f32 v[144:145], v[144:145], s[76:77] op_sel_hi:[1,0]
	v_pk_mul_f32 v[142:143], v[142:143], s[76:77] op_sel_hi:[1,0]
	v_pk_fma_f32 v[150:151], v[102:103], 0.5, v[150:151] op_sel_hi:[1,0,1]
	v_pk_fma_f32 v[152:153], v[104:105], 0.5, v[152:153] op_sel_hi:[1,0,1]
	v_pk_fma_f32 v[146:147], v[106:107], 0.5, v[142:143] op_sel_hi:[1,0,1]
	v_pk_fma_f32 v[148:149], v[108:109], 0.5, v[144:145] op_sel_hi:[1,0,1]
	v_pk_add_f32 v[144:145], v[150:151], v[146:147]
	v_pk_add_f32 v[142:143], v[152:153], v[148:149]
	v_pk_mul_f32 v[154:155], v[146:147], v[146:147]
	v_pk_mov_b32 v[158:159], v[144:145], v[142:143] op_sel:[1,0]
	v_mov_b32_e32 v145, v143
	v_pk_mul_f32 v[156:157], v[148:149], v[148:149]
	v_pk_add_f32 v[142:143], v[158:159], v[144:145]
	v_pk_fma_f32 v[156:157], v[152:153], v[152:153], v[156:157]
	v_pk_fma_f32 v[154:155], v[150:151], v[150:151], v[154:155]
	v_add_f32_e32 v142, v142, v143
	v_add_f32_e32 v141, v142, v141
	v_pk_mov_b32 v[142:143], v[154:155], v[156:157] op_sel:[1,0]
	v_mov_b32_e32 v155, v157
	v_pk_add_f32 v[142:143], v[142:143], v[154:155]
	v_cvt_pk_bf16_f32 v144, v146, v147
	v_add_f32_e32 v142, v142, v143
	v_lshl_add_u64 v[146:147], s[18:19], 0, v[208:209]
	v_add_f32_e32 v137, v142, v137
	v_cvt_pk_bf16_f32 v142, v150, v151
	v_cvt_pk_bf16_f32 v143, v152, v153
	v_cvt_pk_bf16_f32 v145, v148, v149
	v_lshl_add_u64 v[146:147], v[178:179], 1, v[146:147]
	global_store_dwordx4 v[146:147], v[142:145], off nt

.LBB0_1059:
	s_waitcnt vmcnt(0)
	v_lshlrev_b32_e32 v2, 16, v158
	v_and_b32_e32 v4, 0xffff0000, v158
	v_lshlrev_b32_e32 v158, 16, v159
	v_and_b32_e32 v159, 0xffff0000, v159
	v_sub_f32_e32 v5, v4, v172
	v_sub_f32_e32 v4, v2, v172
	v_sub_f32_e32 v159, v159, v172
	v_sub_f32_e32 v158, v158, v172
	v_lshlrev_b32_e32 v162, 16, v160
	v_and_b32_e32 v160, 0xffff0000, v160
	v_lshlrev_b32_e32 v163, 16, v161
	v_and_b32_e32 v161, 0xffff0000, v161
	v_pk_mul_f32 v[158:159], v[170:171], v[158:159] op_sel_hi:[0,1]
	v_pk_mul_f32 v[4:5], v[170:171], v[4:5] op_sel_hi:[0,1]
	s_waitcnt lgkmcnt(1)
	v_pk_fma_f32 v[4:5], v[150:151], v[4:5], v[154:155]
	v_pk_fma_f32 v[150:151], v[152:153], v[158:159], v[156:157]
	v_sub_f32_e32 v153, v160, v172
	v_sub_f32_e32 v152, v162, v172
	v_sub_f32_e32 v155, v161, v172
	v_sub_f32_e32 v154, v163, v172
	v_pk_mul_f32 v[154:155], v[170:171], v[154:155] op_sel_hi:[0,1]
	v_pk_mul_f32 v[152:153], v[170:171], v[152:153] op_sel_hi:[0,1]
	s_waitcnt lgkmcnt(0)
	v_pk_fma_f32 v[142:143], v[142:143], v[152:153], v[146:147]
	v_pk_fma_f32 v[144:145], v[144:145], v[154:155], v[148:149]
	v_pk_mul_f32 v[150:151], v[150:151], s[76:77] op_sel_hi:[1,0]
	v_pk_mul_f32 v[4:5], v[4:5], s[76:77] op_sel_hi:[1,0]
	v_pk_mul_f32 v[144:145], v[144:145], s[76:77] op_sel_hi:[1,0]
	v_pk_mul_f32 v[142:143], v[142:143], s[76:77] op_sel_hi:[1,0]
	v_pk_fma_f32 v[4:5], v[70:71], 0.5, v[4:5] op_sel_hi:[1,0,1]
	v_pk_fma_f32 v[150:151], v[72:73], 0.5, v[150:151] op_sel_hi:[1,0,1]
	v_pk_fma_f32 v[146:147], v[74:75], 0.5, v[142:143] op_sel_hi:[1,0,1]
	v_pk_fma_f32 v[148:149], v[76:77], 0.5, v[144:145] op_sel_hi:[1,0,1]
	v_pk_add_f32 v[144:145], v[4:5], v[146:147]
	v_pk_add_f32 v[142:143], v[150:151], v[148:149]
	v_pk_mul_f32 v[152:153], v[146:147], v[146:147]
	v_pk_mul_f32 v[154:155], v[148:149], v[148:149]
	v_pk_mov_b32 v[156:157], v[144:145], v[142:143] op_sel:[1,0]
	v_mov_b32_e32 v145, v143
	v_pk_fma_f32 v[154:155], v[150:151], v[150:151], v[154:155]
	v_pk_fma_f32 v[152:153], v[4:5], v[4:5], v[152:153]
	v_pk_add_f32 v[142:143], v[156:157], v[144:145]
	v_cvt_pk_bf16_f32 v144, v146, v147
	v_add_f32_e32 v2, v142, v143
	v_pk_mov_b32 v[142:143], v[152:153], v[154:155] op_sel:[1,0]
	v_mov_b32_e32 v153, v155
	v_pk_add_f32 v[142:143], v[142:143], v[152:153]
	v_add_f32_e32 v141, v2, v141
	v_add_f32_e32 v2, v142, v143
	v_add_f32_e32 v137, v2, v137
	v_cvt_pk_bf16_f32 v142, v4, v5
	v_cvt_pk_bf16_f32 v143, v150, v151
	v_cvt_pk_bf16_f32 v145, v148, v149
	global_store_dwordx4 v[184:185], v[142:145], off offset:256 nt

.LBB0_1062:
	s_or_b64 exec, exec, s[20:21]
	v_add_u32_e32 v2, 0x20400, v214
	s_waitcnt vmcnt(2)
	ds_read2_b64 v[168:171], v2 offset1:16
	s_mov_b64 s[20:21], 0x80000
	s_waitcnt lgkmcnt(3)
	ds_read2_b64 v[142:145], v2 offset0:32 offset1:48
	s_and_b32 s24, s84, 16
	s_bitcmp1_b32 s84, 4
	s_waitcnt lgkmcnt(1)
	v_mul_f32_e32 v177, 0x3a000000, v168
	v_mul_f32_e32 v4, v177, v177
	v_fma_f32 v4, v169, s72, -v4
	v_add_f32_e32 v4, 0x3727c5ac, v4
	v_rsq_f32_e32 v206, v4
	v_lshlrev_b64 v[4:5], 12, v[180:181]
	v_lshl_add_u64 v[208:209], v[4:5], 0, s[20:21]
	s_mov_b64 s[20:21], 0x90000
	v_lshl_add_u64 v[214:215], v[4:5], 0, s[20:21]
	s_mov_b64 s[20:21], 0xa0000
	v_lshl_add_u64 v[212:213], v[4:5], 0, s[20:21]
	s_mov_b64 s[20:21], 0xb0000
	v_lshl_add_u64 v[210:211], v[4:5], 0, s[20:21]
	v_lshl_add_u64 v[204:205], v[182:183], 0, v[214:215]
	v_lshl_add_u64 v[186:187], v[182:183], 0, v[212:213]
	v_lshl_add_u64 v[184:185], v[182:183], 0, v[210:211]
	global_load_dwordx4 v[172:175], v[204:205], off
	global_load_dwordx4 v[166:169], v[186:187], off
	global_load_dwordx4 v[154:157], v[184:185], off
	s_waitcnt vmcnt(3)
	ds_read_b128 v[158:161], v197
	ds_read_b128 v[146:149], v197 offset:16
	ds_read_b128 v[162:165], v199
	ds_read_b128 v[150:153], v199 offset:16
	s_cselect_b64 s[20:21], -1, 0
	s_cmp_eq_u32 s24, 0
	s_cbranch_scc1 .LBB0_1067
	v_lshl_add_u64 v[4:5], v[182:183], 0, v[208:209]
	global_load_dwordx4 v[134:137], v[4:5], off
	s_waitcnt vmcnt(0)
	v_lshlrev_b32_e32 v2, 16, v134
	v_and_b32_e32 v4, 0xffff0000, v134
	v_lshlrev_b32_e32 v134, 16, v135
	v_and_b32_e32 v135, 0xffff0000, v135
	v_lshlrev_b32_e32 v207, 16, v137
	v_sub_f32_e32 v5, v4, v177
	v_sub_f32_e32 v4, v2, v177
	v_sub_f32_e32 v135, v135, v177
	v_sub_f32_e32 v134, v134, v177
	v_pk_mul_f32 v[134:135], v[206:207], v[134:135] op_sel_hi:[0,1]
	v_pk_mul_f32 v[4:5], v[206:207], v[4:5] op_sel_hi:[0,1]
	s_waitcnt lgkmcnt(1)
	v_pk_fma_f32 v[4:5], v[158:159], v[4:5], v[162:163]
	v_pk_fma_f32 v[134:135], v[160:161], v[134:135], v[164:165]
	v_lshlrev_b32_e32 v181, 16, v136
	v_and_b32_e32 v136, 0xffff0000, v136
	v_and_b32_e32 v137, 0xffff0000, v137
	v_pk_mul_f32 v[134:135], v[134:135], s[76:77] op_sel_hi:[1,0]
	v_pk_mul_f32 v[4:5], v[4:5], s[76:77] op_sel_hi:[1,0]
	v_pk_fma_f32 v[140:141], v[48:49], 0.5, v[134:135] op_sel_hi:[1,0,1]
	v_pk_fma_f32 v[138:139], v[46:47], 0.5, v[4:5] op_sel_hi:[1,0,1]
	v_sub_f32_e32 v5, v136, v177
	v_sub_f32_e32 v4, v181, v177
	v_sub_f32_e32 v135, v137, v177
	v_sub_f32_e32 v134, v207, v177
	v_pk_mul_f32 v[134:135], v[206:207], v[134:135] op_sel_hi:[0,1]
	v_pk_mul_f32 v[4:5], v[206:207], v[4:5] op_sel_hi:[0,1]
	s_waitcnt lgkmcnt(0)
	v_pk_fma_f32 v[4:5], v[146:147], v[4:5], v[150:151]
	v_pk_fma_f32 v[134:135], v[148:149], v[134:135], v[152:153]
	v_pk_mul_f32 v[4:5], v[4:5], s[76:77] op_sel_hi:[1,0]
	v_pk_mul_f32 v[134:135], v[134:135], s[76:77] op_sel_hi:[1,0]
	v_pk_fma_f32 v[216:217], v[50:51], 0.5, v[4:5] op_sel_hi:[1,0,1]
	v_pk_fma_f32 v[218:219], v[52:53], 0.5, v[134:135] op_sel_hi:[1,0,1]
	v_pk_add_f32 v[134:135], v[138:139], v[216:217]
	v_pk_add_f32 v[4:5], v[140:141], v[218:219]
	v_pk_mul_f32 v[136:137], v[216:217], v[216:217]
	v_pk_mul_f32 v[222:223], v[218:219], v[218:219]
	v_pk_fma_f32 v[136:137], v[138:139], v[138:139], v[136:137]
	v_pk_fma_f32 v[222:223], v[140:141], v[140:141], v[222:223]
	v_pk_mov_b32 v[224:225], v[134:135], v[4:5] op_sel:[1,0]
	v_mov_b32_e32 v135, v5
	v_pk_add_f32 v[4:5], v[224:225], v[134:135]
	v_pk_mov_b32 v[134:135], v[136:137], v[222:223] op_sel:[1,0]
	v_mov_b32_e32 v137, v223
	v_pk_add_f32 v[134:135], v[134:135], v[136:137]
	v_add_f32_e32 v2, v4, v5
	v_pk_add_f32 v[134:135], v[134:135], v[134:135] op_sel:[0,1] op_sel_hi:[1,0]
	v_cvt_pk_bf16_f32 v138, v138, v139
	v_cvt_pk_bf16_f32 v139, v140, v141
	v_cvt_pk_bf16_f32 v140, v216, v217
	v_lshl_add_u64 v[216:217], s[18:19], 0, v[208:209]
	v_add_f32_e32 v2, 0, v2
	v_mov_b32_e32 v4, v3
	v_mov_b32_e32 v5, v3
	v_mov_b32_e32 v135, v3
	v_mov_b32_e32 v136, v3
	v_mov_b32_e32 v137, v3
	v_cvt_pk_bf16_f32 v141, v218, v219
	v_lshl_add_u64 v[216:217], v[178:179], 1, v[216:217]
	global_store_dwordx4 v[216:217], v[138:141], off nt
	s_branch .LBB0_1068
.LBB0_1064:
	v_lshl_add_u64 v[210:211], v[182:183], 0, v[206:207]
	global_load_dwordx4 v[206:209], v[210:211], off offset:256
	s_waitcnt vmcnt(0)
	v_lshlrev_b32_e32 v173, 16, v206
	v_and_b32_e32 v175, 0xffff0000, v206
	v_lshlrev_b32_e32 v203, 16, v207
	v_and_b32_e32 v206, 0xffff0000, v207
	v_lshlrev_b32_e32 v212, 16, v208
	v_and_b32_e32 v208, 0xffff0000, v208
	v_lshlrev_b32_e32 v215, 16, v209
	v_and_b32_e32 v213, 0xffff0000, v209
	v_sub_f32_e32 v177, v175, v201
	v_sub_f32_e32 v176, v173, v201
	v_sub_f32_e32 v207, v206, v201
	v_sub_f32_e32 v206, v203, v201
	v_sub_f32_e32 v209, v208, v201
	v_sub_f32_e32 v208, v212, v201
	v_sub_f32_e32 v213, v213, v201
	v_sub_f32_e32 v212, v215, v201
	v_pk_mul_f32 v[206:207], v[174:175], v[206:207] op_sel_hi:[0,1]
	v_pk_mul_f32 v[176:177], v[174:175], v[176:177] op_sel_hi:[0,1]
	v_pk_mul_f32 v[212:213], v[174:175], v[212:213] op_sel_hi:[0,1]
	v_pk_mul_f32 v[174:175], v[174:175], v[208:209] op_sel_hi:[0,1]
	s_waitcnt lgkmcnt(1)
	v_pk_fma_f32 v[176:177], v[150:151], v[176:177], v[154:155]
	v_pk_fma_f32 v[206:207], v[152:153], v[206:207], v[156:157]
	s_waitcnt lgkmcnt(0)
	v_pk_fma_f32 v[174:175], v[142:143], v[174:175], v[146:147]
	v_pk_fma_f32 v[208:209], v[144:145], v[212:213], v[148:149]
	v_pk_mul_f32 v[206:207], v[206:207], s[76:77] op_sel_hi:[1,0]
	v_pk_mul_f32 v[176:177], v[176:177], s[76:77] op_sel_hi:[1,0]
	v_pk_mul_f32 v[208:209], v[208:209], s[76:77] op_sel_hi:[1,0]
	v_pk_mul_f32 v[174:175], v[174:175], s[76:77] op_sel_hi:[1,0]
	v_pk_fma_f32 v[176:177], v[94:95], 0.5, v[176:177] op_sel_hi:[1,0,1]
	v_pk_fma_f32 v[206:207], v[96:97], 0.5, v[206:207] op_sel_hi:[1,0,1]
	v_pk_fma_f32 v[212:213], v[98:99], 0.5, v[174:175] op_sel_hi:[1,0,1]
	v_pk_fma_f32 v[208:209], v[100:101], 0.5, v[208:209] op_sel_hi:[1,0,1]
	v_pk_add_f32 v[216:217], v[176:177], v[212:213]
	v_pk_add_f32 v[174:175], v[206:207], v[208:209]
	v_pk_mul_f32 v[218:219], v[212:213], v[212:213]
	v_pk_mul_f32 v[222:223], v[208:209], v[208:209]
	v_pk_mov_b32 v[224:225], v[216:217], v[174:175] op_sel:[1,0]
	v_mov_b32_e32 v217, v175
	v_pk_fma_f32 v[222:223], v[206:207], v[206:207], v[222:223]
	v_pk_fma_f32 v[218:219], v[176:177], v[176:177], v[218:219]
	v_pk_add_f32 v[174:175], v[224:225], v[216:217]
	s_nop 0
	v_add_f32_e32 v173, v174, v175
	v_pk_mov_b32 v[174:175], v[218:219], v[222:223] op_sel:[1,0]
	v_mov_b32_e32 v219, v223
	v_pk_add_f32 v[174:175], v[174:175], v[218:219]
	v_add_f32_e32 v138, v138, v173
	v_add_f32_e32 v173, v174, v175
	v_add_f32_e32 v134, v134, v173
	v_cvt_pk_bf16_f32 v174, v176, v177
	v_cvt_pk_bf16_f32 v175, v206, v207
	v_cvt_pk_bf16_f32 v176, v212, v213
	v_cvt_pk_bf16_f32 v177, v208, v209
	global_store_dwordx4 v[210:211], v[174:177], off offset:256 nt
	s_andn2_b64 vcc, exec, s[6:7]
	s_cbranch_vccnz .LBB0_1057
.LBB0_1065:
	s_waitcnt vmcnt(2)
	v_lshlrev_b32_e32 v173, 16, v166
	v_and_b32_e32 v166, 0xffff0000, v166
	v_lshlrev_b32_e32 v174, 16, v167
	v_and_b32_e32 v175, 0xffff0000, v167
	v_lshlrev_b32_e32 v176, 16, v168
	v_and_b32_e32 v177, 0xffff0000, v168
	v_lshlrev_b32_e32 v201, 16, v169
	v_and_b32_e32 v203, 0xffff0000, v169
	v_sub_f32_e32 v167, v166, v5
	v_sub_f32_e32 v166, v173, v5
	v_sub_f32_e32 v169, v175, v5
	v_sub_f32_e32 v168, v174, v5
	v_sub_f32_e32 v175, v177, v5
	v_sub_f32_e32 v174, v176, v5
	v_sub_f32_e32 v177, v203, v5
	v_sub_f32_e32 v176, v201, v5
	v_pk_mul_f32 v[168:169], v[2:3], v[168:169] op_sel_hi:[0,1]
	v_pk_mul_f32 v[166:167], v[2:3], v[166:167] op_sel_hi:[0,1]
	v_pk_mul_f32 v[176:177], v[2:3], v[176:177] op_sel_hi:[0,1]
	v_pk_mul_f32 v[174:175], v[2:3], v[174:175] op_sel_hi:[0,1]
	s_waitcnt lgkmcnt(1)
	v_pk_fma_f32 v[166:167], v[150:151], v[166:167], v[154:155]
	v_pk_fma_f32 v[168:169], v[152:153], v[168:169], v[156:157]
	s_waitcnt lgkmcnt(0)
	v_pk_fma_f32 v[174:175], v[142:143], v[174:175], v[146:147]
	v_pk_fma_f32 v[176:177], v[144:145], v[176:177], v[148:149]
	v_pk_mul_f32 v[168:169], v[168:169], s[76:77] op_sel_hi:[1,0]
	v_pk_mul_f32 v[166:167], v[166:167], s[76:77] op_sel_hi:[1,0]
	v_pk_mul_f32 v[176:177], v[176:177], s[76:77] op_sel_hi:[1,0]
	v_pk_mul_f32 v[174:175], v[174:175], s[76:77] op_sel_hi:[1,0]
	v_pk_fma_f32 v[166:167], v[86:87], 0.5, v[166:167] op_sel_hi:[1,0,1]
	v_pk_fma_f32 v[168:169], v[88:89], 0.5, v[168:169] op_sel_hi:[1,0,1]
	v_pk_fma_f32 v[174:175], v[90:91], 0.5, v[174:175] op_sel_hi:[1,0,1]
	v_pk_fma_f32 v[176:177], v[92:93], 0.5, v[176:177] op_sel_hi:[1,0,1]
	v_pk_add_f32 v[208:209], v[166:167], v[174:175]
	v_pk_add_f32 v[206:207], v[168:169], v[176:177]
	v_pk_mul_f32 v[210:211], v[174:175], v[174:175]
	v_pk_mul_f32 v[212:213], v[176:177], v[176:177]
	v_pk_mov_b32 v[216:217], v[208:209], v[206:207] op_sel:[1,0]
	v_mov_b32_e32 v209, v207
	v_pk_fma_f32 v[212:213], v[168:169], v[168:169], v[212:213]
	v_pk_fma_f32 v[210:211], v[166:167], v[166:167], v[210:211]
	v_pk_add_f32 v[206:207], v[216:217], v[208:209]
	v_cvt_pk_bf16_f32 v166, v166, v167
	v_add_f32_e32 v2, v206, v207
	v_pk_mov_b32 v[206:207], v[210:211], v[212:213] op_sel:[1,0]
	v_mov_b32_e32 v211, v213
	v_pk_add_f32 v[206:207], v[206:207], v[210:211]
	v_add_f32_e32 v139, v2, v139
	v_add_f32_e32 v2, v206, v207
	v_add_f32_e32 v135, v2, v135
	v_cvt_pk_bf16_f32 v167, v168, v169
	v_cvt_pk_bf16_f32 v168, v174, v175
	v_cvt_pk_bf16_f32 v169, v176, v177
	global_store_dwordx4 v[204:205], v[166:169], off offset:256 nt
	s_andn2_b64 vcc, exec, s[8:9]
	s_cbranch_vccnz .LBB0_1058
.LBB0_1066:
	s_waitcnt vmcnt(1)
	v_lshlrev_b32_e32 v2, 16, v162
	v_and_b32_e32 v5, 0xffff0000, v162
	v_lshlrev_b32_e32 v166, 16, v163
	v_and_b32_e32 v167, 0xffff0000, v163
	v_lshlrev_b32_e32 v168, 16, v164
	v_and_b32_e32 v169, 0xffff0000, v164
	v_lshlrev_b32_e32 v173, 16, v165
	v_and_b32_e32 v174, 0xffff0000, v165
	v_sub_f32_e32 v163, v5, v171
	v_sub_f32_e32 v162, v2, v171
	v_sub_f32_e32 v165, v167, v171
	v_sub_f32_e32 v164, v166, v171
	v_sub_f32_e32 v167, v169, v171
	v_sub_f32_e32 v166, v168, v171
	v_sub_f32_e32 v169, v174, v171
	v_sub_f32_e32 v168, v173, v171
	v_pk_mul_f32 v[164:165], v[4:5], v[164:165] op_sel_hi:[0,1]
	v_pk_mul_f32 v[162:163], v[4:5], v[162:163] op_sel_hi:[0,1]
	v_pk_mul_f32 v[168:169], v[4:5], v[168:169] op_sel_hi:[0,1]
	v_pk_mul_f32 v[4:5], v[4:5], v[166:167] op_sel_hi:[0,1]
	s_waitcnt lgkmcnt(1)
	v_pk_fma_f32 v[162:163], v[150:151], v[162:163], v[154:155]
	v_pk_fma_f32 v[164:165], v[152:153], v[164:165], v[156:157]
	s_waitcnt lgkmcnt(0)
	v_pk_fma_f32 v[4:5], v[142:143], v[4:5], v[146:147]
	v_pk_fma_f32 v[166:167], v[144:145], v[168:169], v[148:149]
	v_pk_mul_f32 v[164:165], v[164:165], s[76:77] op_sel_hi:[1,0]
	v_pk_mul_f32 v[162:163], v[162:163], s[76:77] op_sel_hi:[1,0]
	v_pk_mul_f32 v[166:167], v[166:167], s[76:77] op_sel_hi:[1,0]
	v_pk_mul_f32 v[4:5], v[4:5], s[76:77] op_sel_hi:[1,0]
	v_pk_fma_f32 v[162:163], v[78:79], 0.5, v[162:163] op_sel_hi:[1,0,1]
	v_pk_fma_f32 v[164:165], v[80:81], 0.5, v[164:165] op_sel_hi:[1,0,1]
	v_pk_fma_f32 v[4:5], v[82:83], 0.5, v[4:5] op_sel_hi:[1,0,1]
	v_pk_fma_f32 v[166:167], v[84:85], 0.5, v[166:167] op_sel_hi:[1,0,1]
	v_pk_add_f32 v[174:175], v[162:163], v[4:5]
	v_pk_add_f32 v[168:169], v[164:165], v[166:167]
	v_pk_mul_f32 v[176:177], v[4:5], v[4:5]
	v_pk_mul_f32 v[204:205], v[166:167], v[166:167]
	v_pk_mov_b32 v[206:207], v[174:175], v[168:169] op_sel:[1,0]
	v_mov_b32_e32 v175, v169
	v_pk_fma_f32 v[204:205], v[164:165], v[164:165], v[204:205]
	v_pk_fma_f32 v[176:177], v[162:163], v[162:163], v[176:177]
	v_pk_add_f32 v[168:169], v[206:207], v[174:175]
	v_cvt_pk_bf16_f32 v162, v162, v163
	v_add_f32_e32 v2, v168, v169
	v_pk_mov_b32 v[168:169], v[176:177], v[204:205] op_sel:[1,0]
	v_mov_b32_e32 v177, v205
	v_pk_add_f32 v[168:169], v[168:169], v[176:177]
	v_add_f32_e32 v140, v2, v140
	v_add_f32_e32 v2, v168, v169
	v_add_f32_e32 v136, v2, v136
	v_cvt_pk_bf16_f32 v163, v164, v165
	v_cvt_pk_bf16_f32 v164, v4, v5
	v_cvt_pk_bf16_f32 v165, v166, v167
	global_store_dwordx4 v[186:187], v[162:165], off offset:256 nt
	s_andn2_b64 vcc, exec, s[10:11]
	s_cbranch_vccz .LBB0_1059
	s_branch .LBB0_1060

.LBB0_1068:
	s_nop 0
	v_mov_b64_e32 v[140:141], v[4:5]
	v_mov_b64_e32 v[138:139], v[2:3]
	v_mul_f32_e32 v5, 0x3a000000, v170
	v_mul_f32_e32 v2, v5, v5
	v_fma_f32 v2, v171, s72, -v2
	v_add_f32_e32 v2, 0x3727c5ac, v2
	v_rsq_f32_e32 v2, v2
	s_and_b32 s26, s84, 32
	s_bitcmp1_b32 s84, 5
	s_cselect_b64 s[24:25], -1, 0
	s_cmp_eq_u32 s26, 0
	s_cbranch_scc1 .LBB0_1070
	s_waitcnt vmcnt(2)
	v_lshlrev_b32_e32 v4, 16, v172
	v_and_b32_e32 v170, 0xffff0000, v172
	v_lshlrev_b32_e32 v172, 16, v173
	v_and_b32_e32 v173, 0xffff0000, v173
	v_lshlrev_b32_e32 v181, 16, v174
	v_and_b32_e32 v174, 0xffff0000, v174
	v_lshlrev_b32_e32 v207, 16, v175
	v_and_b32_e32 v216, 0xffff0000, v175
	v_sub_f32_e32 v171, v170, v5
	v_sub_f32_e32 v170, v4, v5
	v_sub_f32_e32 v173, v173, v5
	v_sub_f32_e32 v172, v172, v5
	v_sub_f32_e32 v175, v174, v5
	v_sub_f32_e32 v174, v181, v5
	v_sub_f32_e32 v217, v216, v5
	v_sub_f32_e32 v216, v207, v5
	v_pk_mul_f32 v[172:173], v[2:3], v[172:173] op_sel_hi:[0,1]
	v_pk_mul_f32 v[170:171], v[2:3], v[170:171] op_sel_hi:[0,1]
	v_pk_mul_f32 v[216:217], v[2:3], v[216:217] op_sel_hi:[0,1]
	v_pk_mul_f32 v[174:175], v[2:3], v[174:175] op_sel_hi:[0,1]
	s_waitcnt lgkmcnt(1)
	v_pk_fma_f32 v[170:171], v[158:159], v[170:171], v[162:163]
	v_pk_fma_f32 v[172:173], v[160:161], v[172:173], v[164:165]
	s_waitcnt lgkmcnt(0)
	v_pk_fma_f32 v[174:175], v[146:147], v[174:175], v[150:151]
	v_pk_fma_f32 v[216:217], v[148:149], v[216:217], v[152:153]
	v_pk_mul_f32 v[172:173], v[172:173], s[76:77] op_sel_hi:[1,0]
	v_pk_mul_f32 v[170:171], v[170:171], s[76:77] op_sel_hi:[1,0]
	v_pk_mul_f32 v[216:217], v[216:217], s[76:77] op_sel_hi:[1,0]
	v_pk_mul_f32 v[174:175], v[174:175], s[76:77] op_sel_hi:[1,0]
	v_pk_fma_f32 v[170:171], v[38:39], 0.5, v[170:171] op_sel_hi:[1,0,1]
	v_pk_fma_f32 v[172:173], v[40:41], 0.5, v[172:173] op_sel_hi:[1,0,1]
	v_pk_fma_f32 v[174:175], v[42:43], 0.5, v[174:175] op_sel_hi:[1,0,1]
	v_pk_fma_f32 v[216:217], v[44:45], 0.5, v[216:217] op_sel_hi:[1,0,1]
	v_pk_add_f32 v[222:223], v[170:171], v[174:175]
	v_pk_add_f32 v[218:219], v[172:173], v[216:217]
	v_pk_mul_f32 v[224:225], v[174:175], v[174:175]
	v_pk_mul_f32 v[226:227], v[216:217], v[216:217]
	v_pk_mov_b32 v[232:233], v[222:223], v[218:219] op_sel:[1,0]
	v_mov_b32_e32 v223, v219
	v_pk_fma_f32 v[226:227], v[172:173], v[172:173], v[226:227]
	v_pk_fma_f32 v[224:225], v[170:171], v[170:171], v[224:225]
	v_pk_add_f32 v[218:219], v[232:233], v[222:223]
	v_cvt_pk_bf16_f32 v170, v170, v171
	v_add_f32_e32 v4, v218, v219
	v_pk_mov_b32 v[218:219], v[224:225], v[226:227] op_sel:[1,0]
	v_mov_b32_e32 v225, v227
	v_pk_add_f32 v[218:219], v[218:219], v[224:225]
	v_add_f32_e32 v139, v4, v139
	v_add_f32_e32 v4, v218, v219
	v_cvt_pk_bf16_f32 v171, v172, v173
	v_cvt_pk_bf16_f32 v172, v174, v175
	v_lshl_add_u64 v[174:175], s[18:19], 0, v[214:215]
	v_add_f32_e32 v135, v4, v135
	v_cvt_pk_bf16_f32 v173, v216, v217
	v_lshl_add_u64 v[174:175], v[178:179], 1, v[174:175]
	global_store_dwordx4 v[174:175], v[170:173], off nt
.LBB0_1070:
	s_waitcnt lgkmcnt(4)
	s_nop 0
	v_mul_f32_e32 v171, 0x3a000000, v142
	v_mul_f32_e32 v4, v171, v171
	v_fma_f32 v4, v143, s72, -v4
	v_add_f32_e32 v4, 0x3727c5ac, v4
	v_rsq_f32_e32 v4, v4
	s_and_b32 s28, s84, 64
	s_bitcmp1_b32 s84, 6
	s_cselect_b64 s[26:27], -1, 0
	s_cmp_eq_u32 s28, 0
	s_cbranch_scc1 .LBB0_1072
	s_waitcnt vmcnt(1)
	v_lshlrev_b32_e32 v142, 16, v166
	v_and_b32_e32 v143, 0xffff0000, v166
	v_lshlrev_b32_e32 v166, 16, v167
	v_and_b32_e32 v167, 0xffff0000, v167
	v_sub_f32_e32 v167, v167, v171
	v_sub_f32_e32 v166, v166, v171
	v_pk_mul_f32 v[166:167], v[4:5], v[166:167] op_sel_hi:[0,1]
	s_waitcnt lgkmcnt(1)
	v_pk_fma_f32 v[166:167], v[160:161], v[166:167], v[164:165]
	v_lshlrev_b32_e32 v170, 16, v168
	v_and_b32_e32 v172, 0xffff0000, v168
	v_lshlrev_b32_e32 v174, 16, v169
	v_and_b32_e32 v173, 0xffff0000, v169
	v_pk_mul_f32 v[166:167], v[166:167], s[76:77] op_sel_hi:[1,0]
	v_sub_f32_e32 v143, v143, v171
	v_sub_f32_e32 v142, v142, v171
	v_pk_fma_f32 v[168:169], v[32:33], 0.5, v[166:167] op_sel_hi:[1,0,1]
	v_sub_f32_e32 v167, v172, v171
	v_sub_f32_e32 v166, v170, v171
	v_sub_f32_e32 v173, v173, v171
	v_sub_f32_e32 v172, v174, v171
	v_pk_mul_f32 v[142:143], v[4:5], v[142:143] op_sel_hi:[0,1]
	v_pk_mul_f32 v[172:173], v[4:5], v[172:173] op_sel_hi:[0,1]
	v_pk_mul_f32 v[166:167], v[4:5], v[166:167] op_sel_hi:[0,1]
	v_pk_fma_f32 v[142:143], v[158:159], v[142:143], v[162:163]
	s_waitcnt lgkmcnt(0)
	v_pk_fma_f32 v[166:167], v[146:147], v[166:167], v[150:151]
	v_pk_fma_f32 v[172:173], v[148:149], v[172:173], v[152:153]
	v_pk_mul_f32 v[142:143], v[142:143], s[76:77] op_sel_hi:[1,0]
	v_pk_mul_f32 v[172:173], v[172:173], s[76:77] op_sel_hi:[1,0]
	v_pk_mul_f32 v[166:167], v[166:167], s[76:77] op_sel_hi:[1,0]
	v_pk_fma_f32 v[142:143], v[30:31], 0.5, v[142:143] op_sel_hi:[1,0,1]
	v_pk_fma_f32 v[174:175], v[34:35], 0.5, v[166:167] op_sel_hi:[1,0,1]
	v_pk_fma_f32 v[172:173], v[36:37], 0.5, v[172:173] op_sel_hi:[1,0,1]
	v_pk_add_f32 v[214:215], v[142:143], v[174:175]
	v_pk_add_f32 v[166:167], v[168:169], v[172:173]
	v_pk_mul_f32 v[216:217], v[174:175], v[174:175]
	v_pk_mov_b32 v[222:223], v[214:215], v[166:167] op_sel:[1,0]
	v_mov_b32_e32 v215, v167
	v_pk_mul_f32 v[218:219], v[172:173], v[172:173]
	v_pk_add_f32 v[166:167], v[222:223], v[214:215]
	v_pk_fma_f32 v[218:219], v[168:169], v[168:169], v[218:219]
	v_pk_fma_f32 v[216:217], v[142:143], v[142:143], v[216:217]
	v_add_f32_e32 v166, v166, v167
	v_add_f32_e32 v140, v166, v140
	v_pk_mov_b32 v[166:167], v[216:217], v[218:219] op_sel:[1,0]
	v_mov_b32_e32 v217, v219
	v_pk_add_f32 v[166:167], v[166:167], v[216:217]
	s_nop 0
	v_add_f32_e32 v166, v166, v167
	v_add_f32_e32 v136, v166, v136
	v_cvt_pk_bf16_f32 v166, v142, v143
	v_lshl_add_u64 v[142:143], s[18:19], 0, v[212:213]
	v_cvt_pk_bf16_f32 v167, v168, v169
	v_cvt_pk_bf16_f32 v168, v174, v175
	v_cvt_pk_bf16_f32 v169, v172, v173
	v_lshl_add_u64 v[142:143], v[178:179], 1, v[142:143]
	global_store_dwordx4 v[142:143], v[166:169], off nt
.LBB0_1072:
	s_waitcnt vmcnt(2)
	v_mul_f32_e32 v172, 0x3a000000, v144
	v_mul_f32_e32 v142, v172, v172
	v_fma_f32 v142, v145, s72, -v142
	v_add_f32_e32 v142, 0x3727c5ac, v142
	v_rsq_f32_e32 v170, v142
	s_and_b32 s59, s84, 0x80
	s_bitcmp1_b32 s84, 7
	s_cselect_b64 s[28:29], -1, 0
	s_cmp_eq_u32 s59, 0
	s_cbranch_scc1 .LBB0_1074
	s_waitcnt vmcnt(0)
	v_lshlrev_b32_e32 v142, 16, v154
	v_and_b32_e32 v143, 0xffff0000, v154
	v_lshlrev_b32_e32 v144, 16, v155
	v_and_b32_e32 v145, 0xffff0000, v155
	v_lshlrev_b32_e32 v154, 16, v156
	v_and_b32_e32 v155, 0xffff0000, v156
	v_lshlrev_b32_e32 v156, 16, v157
	v_and_b32_e32 v157, 0xffff0000, v157
	v_sub_f32_e32 v143, v143, v172
	v_sub_f32_e32 v142, v142, v172
	v_sub_f32_e32 v145, v145, v172
	v_sub_f32_e32 v144, v144, v172
	v_sub_f32_e32 v155, v155, v172
	v_sub_f32_e32 v154, v154, v172
	v_sub_f32_e32 v157, v157, v172
	v_sub_f32_e32 v156, v156, v172
	v_pk_mul_f32 v[144:145], v[170:171], v[144:145] op_sel_hi:[0,1]
	v_pk_mul_f32 v[142:143], v[170:171], v[142:143] op_sel_hi:[0,1]
	v_pk_mul_f32 v[156:157], v[170:171], v[156:157] op_sel_hi:[0,1]
	v_pk_mul_f32 v[154:155], v[170:171], v[154:155] op_sel_hi:[0,1]
	s_waitcnt lgkmcnt(1)
	v_pk_fma_f32 v[142:143], v[158:159], v[142:143], v[162:163]
	v_pk_fma_f32 v[144:145], v[160:161], v[144:145], v[164:165]
	s_waitcnt lgkmcnt(0)
	v_pk_fma_f32 v[146:147], v[146:147], v[154:155], v[150:151]
	v_pk_fma_f32 v[148:149], v[148:149], v[156:157], v[152:153]
	v_pk_mul_f32 v[144:145], v[144:145], s[76:77] op_sel_hi:[1,0]
	v_pk_mul_f32 v[142:143], v[142:143], s[76:77] op_sel_hi:[1,0]
	v_pk_mul_f32 v[148:149], v[148:149], s[76:77] op_sel_hi:[1,0]
	v_pk_mul_f32 v[146:147], v[146:147], s[76:77] op_sel_hi:[1,0]
	v_pk_fma_f32 v[142:143], v[22:23], 0.5, v[142:143] op_sel_hi:[1,0,1]
	v_pk_fma_f32 v[144:145], v[24:25], 0.5, v[144:145] op_sel_hi:[1,0,1]
	v_pk_fma_f32 v[146:147], v[26:27], 0.5, v[146:147] op_sel_hi:[1,0,1]
	v_pk_fma_f32 v[148:149], v[28:29], 0.5, v[148:149] op_sel_hi:[1,0,1]
	v_pk_add_f32 v[152:153], v[142:143], v[146:147]
	v_pk_add_f32 v[150:151], v[144:145], v[148:149]
	v_pk_mul_f32 v[154:155], v[146:147], v[146:147]
	v_pk_mov_b32 v[158:159], v[152:153], v[150:151] op_sel:[1,0]
	v_mov_b32_e32 v153, v151
	v_pk_mul_f32 v[156:157], v[148:149], v[148:149]
	v_pk_add_f32 v[150:151], v[158:159], v[152:153]
	v_pk_fma_f32 v[156:157], v[144:145], v[144:145], v[156:157]
	v_pk_fma_f32 v[154:155], v[142:143], v[142:143], v[154:155]
	v_add_f32_e32 v150, v150, v151
	v_add_f32_e32 v141, v150, v141
	v_pk_mov_b32 v[150:151], v[154:155], v[156:157] op_sel:[1,0]
	v_mov_b32_e32 v155, v157
	v_pk_add_f32 v[150:151], v[150:151], v[154:155]
	v_cvt_pk_bf16_f32 v142, v142, v143
	v_add_f32_e32 v150, v150, v151
	v_cvt_pk_bf16_f32 v143, v144, v145
	v_cvt_pk_bf16_f32 v144, v146, v147
	v_lshl_add_u64 v[146:147], s[18:19], 0, v[210:211]
	v_add_f32_e32 v137, v150, v137
	v_cvt_pk_bf16_f32 v145, v148, v149
	v_lshl_add_u64 v[146:147], v[178:179], 1, v[146:147]
	global_store_dwordx4 v[146:147], v[142:145], off nt

.LBB0_1078:
	s_waitcnt vmcnt(0)
	v_lshlrev_b32_e32 v2, 16, v158
	v_and_b32_e32 v4, 0xffff0000, v158
	v_lshlrev_b32_e32 v158, 16, v159
	v_and_b32_e32 v159, 0xffff0000, v159
	v_sub_f32_e32 v5, v4, v172
	v_sub_f32_e32 v4, v2, v172
	v_sub_f32_e32 v159, v159, v172
	v_sub_f32_e32 v158, v158, v172
	v_lshlrev_b32_e32 v162, 16, v160
	v_and_b32_e32 v160, 0xffff0000, v160
	v_lshlrev_b32_e32 v163, 16, v161
	v_and_b32_e32 v161, 0xffff0000, v161
	v_pk_mul_f32 v[158:159], v[170:171], v[158:159] op_sel_hi:[0,1]
	v_pk_mul_f32 v[4:5], v[170:171], v[4:5] op_sel_hi:[0,1]
	s_waitcnt lgkmcnt(1)
	v_pk_fma_f32 v[4:5], v[150:151], v[4:5], v[154:155]
	v_pk_fma_f32 v[150:151], v[152:153], v[158:159], v[156:157]
	v_sub_f32_e32 v153, v160, v172
	v_sub_f32_e32 v152, v162, v172
	v_sub_f32_e32 v155, v161, v172
	v_sub_f32_e32 v154, v163, v172
	v_pk_mul_f32 v[154:155], v[170:171], v[154:155] op_sel_hi:[0,1]
	v_pk_mul_f32 v[152:153], v[170:171], v[152:153] op_sel_hi:[0,1]
	s_waitcnt lgkmcnt(0)
	v_pk_fma_f32 v[142:143], v[142:143], v[152:153], v[146:147]
	v_pk_fma_f32 v[144:145], v[144:145], v[154:155], v[148:149]
	v_pk_mul_f32 v[150:151], v[150:151], s[76:77] op_sel_hi:[1,0]
	v_pk_mul_f32 v[4:5], v[4:5], s[76:77] op_sel_hi:[1,0]
	v_pk_mul_f32 v[144:145], v[144:145], s[76:77] op_sel_hi:[1,0]
	v_pk_mul_f32 v[142:143], v[142:143], s[76:77] op_sel_hi:[1,0]
	v_pk_fma_f32 v[4:5], v[58:59], 0.5, v[4:5] op_sel_hi:[1,0,1]
	v_pk_fma_f32 v[150:151], v[60:61], 0.5, v[150:151] op_sel_hi:[1,0,1]
	v_pk_fma_f32 v[146:147], v[66:67], 0.5, v[142:143] op_sel_hi:[1,0,1]
	v_pk_fma_f32 v[148:149], v[68:69], 0.5, v[144:145] op_sel_hi:[1,0,1]
	v_pk_add_f32 v[144:145], v[4:5], v[146:147]
	v_pk_add_f32 v[142:143], v[150:151], v[148:149]
	v_pk_mul_f32 v[152:153], v[146:147], v[146:147]
	v_pk_mul_f32 v[154:155], v[148:149], v[148:149]
	v_pk_mov_b32 v[156:157], v[144:145], v[142:143] op_sel:[1,0]
	v_mov_b32_e32 v145, v143
	v_pk_fma_f32 v[154:155], v[150:151], v[150:151], v[154:155]
	v_pk_fma_f32 v[152:153], v[4:5], v[4:5], v[152:153]
	v_pk_add_f32 v[142:143], v[156:157], v[144:145]
	v_cvt_pk_bf16_f32 v144, v146, v147
	v_add_f32_e32 v2, v142, v143
	v_pk_mov_b32 v[142:143], v[152:153], v[154:155] op_sel:[1,0]
	v_mov_b32_e32 v153, v155
	v_pk_add_f32 v[142:143], v[142:143], v[152:153]
	v_add_f32_e32 v141, v2, v141
	v_add_f32_e32 v2, v142, v143
	v_add_f32_e32 v137, v2, v137
	v_cvt_pk_bf16_f32 v142, v4, v5
	v_cvt_pk_bf16_f32 v143, v150, v151
	v_cvt_pk_bf16_f32 v145, v148, v149
	global_store_dwordx4 v[184:185], v[142:145], off offset:256 nt

.LBB0_1082:
	s_and_b64 vcc, exec, s[0:1]
	s_cbranch_vccz .LBB0_1106
	s_cmp_lt_i32 s4, 32
	s_cselect_b32 s0, 0, 0xffffe000
	s_waitcnt lgkmcnt(0)
	v_add_u32_e32 v4, s0, v180
	v_ashrrev_i32_e32 v5, 31, v4
	s_cselect_b32 s1, s56, s58
	s_cselect_b32 s0, s43, s57
	v_lshlrev_b64 v[4:5], 13, v[4:5]
	v_lshl_add_u64 v[4:5], s[0:1], 0, v[4:5]
	v_ashrrev_i32_e32 v179, 31, v178
	s_bitcmp0_b32 s84, 0
	v_lshl_add_u64 v[4:5], v[178:179], 2, v[4:5]
	s_cbranch_scc1 .LBB0_1088
	global_load_dwordx4 v[134:137], v[4:5], off offset:16
	global_load_dwordx4 v[138:141], v[4:5], off
	v_ashrrev_i32_e32 v181, 31, v180
	v_cmp_lt_i32_e32 vcc, v234, v230
	s_waitcnt vmcnt(0)
	v_pk_mul_f32 v[136:137], v[136:137], s[76:77] op_sel_hi:[1,0]
	v_pk_mul_f32 v[138:139], v[138:139], s[76:77] op_sel_hi:[1,0]
	v_pk_mul_f32 v[134:135], v[134:135], s[76:77] op_sel_hi:[1,0]
	v_pk_mul_f32 v[140:141], v[140:141], s[76:77] op_sel_hi:[1,0]
	v_pk_fma_f32 v[138:139], v[126:127], 0.5, v[138:139] op_sel_hi:[1,0,1]
	v_pk_fma_f32 v[144:145], v[132:133], 0.5, v[136:137] op_sel_hi:[1,0,1]
	v_pk_fma_f32 v[146:147], v[130:131], 0.5, v[134:135] op_sel_hi:[1,0,1]
	v_pk_fma_f32 v[140:141], v[128:129], 0.5, v[140:141] op_sel_hi:[1,0,1]
	v_mul_f32_e32 v134, v146, v146
	v_mul_f32_e32 v136, v147, v147
	v_mul_f32_e32 v148, v144, v144
	v_mul_f32_e32 v150, v145, v145
	v_pk_mul_f32 v[152:153], v[138:139], v[138:139]
	v_pk_add_f32 v[154:155], v[138:139], v[138:139] op_sel_hi:[0,1]
	v_mov_b32_e32 v135, v146
	v_mov_b32_e32 v137, v147
	v_mov_b32_e32 v151, v145
	v_mov_b32_e32 v149, v144
	v_mul_f32_e32 v2, v141, v141
	v_mov_b32_e32 v153, v155
	v_pk_mov_b32 v[154:155], v[138:139], v[140:141] op_sel:[1,0]
	v_pk_add_f32 v[134:135], v[134:135], v[136:137]
	v_pk_add_f32 v[136:137], v[150:151], v[148:149]
	v_pk_fma_f32 v[142:143], v[140:141], v[140:141], v[2:3] op_sel_hi:[1,1,0]
	v_pk_mul_f32 v[156:157], v[138:139], v[154:155] op_sel:[1,0] op_sel_hi:[0,1]
	v_pk_add_f32 v[154:155], v[140:141], v[154:155]
	v_pk_add_f32 v[134:135], v[134:135], v[136:137]
	v_cvt_pk_bf16_f32 v137, v140, v141
	v_lshlrev_b64 v[140:141], 12, v[180:181]
	v_mov_b32_e32 v157, v155
	v_lshl_add_u64 v[140:141], s[18:19], 0, v[140:141]
	v_pk_add_f32 v[152:153], v[152:153], v[156:157]
	v_mov_b32_e32 v143, v3
	v_cvt_pk_bf16_f32 v136, v138, v139
	v_cvt_pk_bf16_f32 v138, v146, v147
	v_cvt_pk_bf16_f32 v139, v144, v145
	v_lshl_add_u64 v[144:145], v[178:179], 1, v[140:141]
	v_pk_add_f32 v[142:143], v[152:153], v[142:143]
	global_store_dwordx4 v[144:145], v[136:139], off nt
	v_pk_add_f32 v[134:135], v[134:135], v[142:143]
	global_load_dwordx4 v[136:139], v[4:5], off offset:528
	global_load_dwordx4 v[140:143], v[4:5], off offset:512
	v_cndmask_b32_e32 v2, v228, v234, vcc
	v_lshlrev_b32_e32 v2, 2, v2
	v_cmp_lt_i32_e32 vcc, v195, v230
	s_waitcnt vmcnt(1)
	v_pk_mul_f32 v[136:137], v[136:137], s[76:77] op_sel_hi:[1,0]
	s_waitcnt vmcnt(0)
	v_pk_mul_f32 v[142:143], v[142:143], s[76:77] op_sel_hi:[1,0]
	v_pk_mul_f32 v[140:141], v[140:141], s[76:77] op_sel_hi:[1,0]
	v_pk_fma_f32 v[142:143], v[96:97], 0.5, v[142:143] op_sel_hi:[1,0,1]
	v_pk_fma_f32 v[140:141], v[94:95], 0.5, v[140:141] op_sel_hi:[1,0,1]
	v_mul_f32_e32 v150, v142, v142
	v_mul_f32_e32 v146, v140, v140
	v_mul_f32_e32 v148, v141, v141
	v_mul_f32_e32 v152, v143, v143
	v_mov_b32_e32 v147, v140
	v_mov_b32_e32 v149, v141
	v_mov_b32_e32 v153, v143
	v_mov_b32_e32 v151, v142
	v_pk_add_f32 v[146:147], v[146:147], v[148:149]
	v_pk_add_f32 v[148:149], v[152:153], v[150:151]
	v_pk_mul_f32 v[138:139], v[138:139], s[76:77] op_sel_hi:[1,0]
	v_pk_fma_f32 v[150:151], v[98:99], 0.5, v[136:137] op_sel_hi:[1,0,1]
	v_pk_add_f32 v[146:147], v[146:147], v[148:149]
	v_pk_fma_f32 v[148:149], v[100:101], 0.5, v[138:139] op_sel_hi:[1,0,1]
	v_mul_f32_e32 v136, v150, v150
	v_mul_f32_e32 v138, v151, v151
	v_mov_b32_e32 v137, v150
	v_mov_b32_e32 v139, v151
	v_pk_add_f32 v[136:137], v[136:137], v[138:139]
	v_mul_f32_e32 v138, v148, v148
	v_mul_f32_e32 v152, v149, v149
	v_mov_b32_e32 v153, v149
	v_mov_b32_e32 v139, v148
	v_pk_add_f32 v[138:139], v[152:153], v[138:139]
	v_pk_add_f32 v[134:135], v[134:135], v[146:147]
	v_pk_add_f32 v[136:137], v[136:137], v[138:139]
	v_cvt_pk_bf16_f32 v140, v140, v141
	v_pk_add_f32 v[134:135], v[134:135], v[136:137]
	ds_bpermute_b32 v137, v2, v135
	ds_bpermute_b32 v136, v2, v134
	v_cvt_pk_bf16_f32 v141, v142, v143
	v_cvt_pk_bf16_f32 v142, v150, v151
	v_cvt_pk_bf16_f32 v143, v148, v149
	global_store_dwordx4 v[144:145], v[140:143], off offset:256 nt
	s_waitcnt lgkmcnt(0)
	v_pk_add_f32 v[134:135], v[134:135], v[136:137]
	v_cndmask_b32_e32 v140, v228, v195, vcc
	v_lshlrev_b32_e32 v140, 2, v140
	ds_bpermute_b32 v137, v140, v135
	ds_bpermute_b32 v136, v140, v134
	v_cmp_eq_u32_e32 vcc, 0, v191
	s_waitcnt lgkmcnt(0)
	v_pk_add_f32 v[134:135], v[134:135], v[136:137]
	s_nop 0
	v_cndmask_b32_e32 v137, 0, v135, vcc
	v_cndmask_b32_e32 v136, 0, v134, vcc
	s_bitcmp0_b32 s84, 1
	s_cbranch_scc0 .LBB0_1089
	s_branch .LBB0_1090
.LBB0_1085:
	v_lshl_add_u64 v[174:175], v[182:183], 0, v[208:209]
	global_load_dwordx4 v[208:211], v[174:175], off offset:256
	s_waitcnt vmcnt(0)
	v_lshlrev_b32_e32 v173, 16, v208
	v_and_b32_e32 v179, 0xffff0000, v208
	v_lshlrev_b32_e32 v181, 16, v209
	v_and_b32_e32 v197, 0xffff0000, v209
	v_lshlrev_b32_e32 v199, 16, v210
	v_and_b32_e32 v207, 0xffff0000, v210
	v_lshlrev_b32_e32 v212, 16, v211
	v_and_b32_e32 v213, 0xffff0000, v211
	v_sub_f32_e32 v183, v179, v177
	v_sub_f32_e32 v182, v173, v177
	v_sub_f32_e32 v209, v197, v177
	v_sub_f32_e32 v208, v181, v177
	v_sub_f32_e32 v211, v207, v177
	v_sub_f32_e32 v210, v199, v177
	v_sub_f32_e32 v213, v213, v177
	v_sub_f32_e32 v212, v212, v177
	v_pk_mul_f32 v[208:209], v[206:207], v[208:209] op_sel_hi:[0,1]
	v_pk_mul_f32 v[182:183], v[206:207], v[182:183] op_sel_hi:[0,1]
	v_pk_mul_f32 v[212:213], v[206:207], v[212:213] op_sel_hi:[0,1]
	v_pk_mul_f32 v[206:207], v[206:207], v[210:211] op_sel_hi:[0,1]
	s_waitcnt lgkmcnt(1)
	v_pk_fma_f32 v[182:183], v[150:151], v[182:183], v[154:155]
	v_pk_fma_f32 v[208:209], v[152:153], v[208:209], v[156:157]
	s_waitcnt lgkmcnt(0)
	v_pk_fma_f32 v[206:207], v[142:143], v[206:207], v[146:147]
	v_pk_fma_f32 v[210:211], v[144:145], v[212:213], v[148:149]
	v_pk_mul_f32 v[208:209], v[208:209], s[76:77] op_sel_hi:[1,0]
	v_pk_mul_f32 v[182:183], v[182:183], s[76:77] op_sel_hi:[1,0]
	v_pk_mul_f32 v[210:211], v[210:211], s[76:77] op_sel_hi:[1,0]
	v_pk_mul_f32 v[206:207], v[206:207], s[76:77] op_sel_hi:[1,0]
	v_pk_fma_f32 v[182:183], v[14:15], 0.5, v[182:183] op_sel_hi:[1,0,1]
	v_pk_fma_f32 v[208:209], v[16:17], 0.5, v[208:209] op_sel_hi:[1,0,1]
	v_pk_fma_f32 v[212:213], v[18:19], 0.5, v[206:207] op_sel_hi:[1,0,1]
	v_pk_fma_f32 v[210:211], v[20:21], 0.5, v[210:211] op_sel_hi:[1,0,1]
	v_pk_add_f32 v[214:215], v[182:183], v[212:213]
	v_pk_add_f32 v[206:207], v[208:209], v[210:211]
	v_pk_mul_f32 v[216:217], v[212:213], v[212:213]
	v_pk_mul_f32 v[218:219], v[210:211], v[210:211]
	v_pk_mov_b32 v[222:223], v[214:215], v[206:207] op_sel:[1,0]
	v_mov_b32_e32 v215, v207
	v_pk_fma_f32 v[218:219], v[208:209], v[208:209], v[218:219]
	v_pk_fma_f32 v[216:217], v[182:183], v[182:183], v[216:217]
	v_pk_add_f32 v[206:207], v[222:223], v[214:215]
	s_nop 0
	v_add_f32_e32 v173, v206, v207
	v_pk_mov_b32 v[206:207], v[216:217], v[218:219] op_sel:[1,0]
	v_mov_b32_e32 v217, v219
	v_pk_add_f32 v[206:207], v[206:207], v[216:217]
	v_add_f32_e32 v138, v138, v173
	v_add_f32_e32 v173, v206, v207
	v_add_f32_e32 v134, v134, v173
	v_cvt_pk_bf16_f32 v206, v182, v183
	v_cvt_pk_bf16_f32 v207, v208, v209
	v_cvt_pk_bf16_f32 v208, v212, v213
	v_cvt_pk_bf16_f32 v209, v210, v211
	global_store_dwordx4 v[174:175], v[206:209], off offset:256 nt
	s_andn2_b64 vcc, exec, s[24:25]
	s_cbranch_vccnz .LBB0_1076
.LBB0_1086:
	s_waitcnt vmcnt(2)
	v_lshlrev_b32_e32 v173, 16, v166
	v_and_b32_e32 v166, 0xffff0000, v166
	v_lshlrev_b32_e32 v174, 16, v167
	v_and_b32_e32 v175, 0xffff0000, v167
	v_lshlrev_b32_e32 v177, 16, v168
	v_and_b32_e32 v179, 0xffff0000, v168
	v_lshlrev_b32_e32 v181, 16, v169
	v_and_b32_e32 v182, 0xffff0000, v169
	v_sub_f32_e32 v167, v166, v5
	v_sub_f32_e32 v166, v173, v5
	v_sub_f32_e32 v169, v175, v5
	v_sub_f32_e32 v168, v174, v5
	v_sub_f32_e32 v175, v179, v5
	v_sub_f32_e32 v174, v177, v5
	v_sub_f32_e32 v183, v182, v5
	v_sub_f32_e32 v182, v181, v5
	v_pk_mul_f32 v[168:169], v[2:3], v[168:169] op_sel_hi:[0,1]
	v_pk_mul_f32 v[166:167], v[2:3], v[166:167] op_sel_hi:[0,1]
	v_pk_mul_f32 v[182:183], v[2:3], v[182:183] op_sel_hi:[0,1]
	v_pk_mul_f32 v[174:175], v[2:3], v[174:175] op_sel_hi:[0,1]
	s_waitcnt lgkmcnt(1)
	v_pk_fma_f32 v[166:167], v[150:151], v[166:167], v[154:155]
	v_pk_fma_f32 v[168:169], v[152:153], v[168:169], v[156:157]
	s_waitcnt lgkmcnt(0)
	v_pk_fma_f32 v[174:175], v[142:143], v[174:175], v[146:147]
	v_pk_fma_f32 v[182:183], v[144:145], v[182:183], v[148:149]
	v_pk_mul_f32 v[168:169], v[168:169], s[76:77] op_sel_hi:[1,0]
	v_pk_mul_f32 v[166:167], v[166:167], s[76:77] op_sel_hi:[1,0]
	v_pk_mul_f32 v[182:183], v[182:183], s[76:77] op_sel_hi:[1,0]
	v_pk_mul_f32 v[174:175], v[174:175], s[76:77] op_sel_hi:[1,0]
	v_pk_fma_f32 v[166:167], v[6:7], 0.5, v[166:167] op_sel_hi:[1,0,1]
	v_pk_fma_f32 v[168:169], v[8:9], 0.5, v[168:169] op_sel_hi:[1,0,1]
	v_pk_fma_f32 v[174:175], v[10:11], 0.5, v[174:175] op_sel_hi:[1,0,1]
	v_pk_fma_f32 v[182:183], v[12:13], 0.5, v[182:183] op_sel_hi:[1,0,1]
	v_pk_add_f32 v[208:209], v[166:167], v[174:175]
	v_pk_add_f32 v[206:207], v[168:169], v[182:183]
	v_pk_mul_f32 v[210:211], v[174:175], v[174:175]
	v_pk_mul_f32 v[212:213], v[182:183], v[182:183]
	v_pk_mov_b32 v[214:215], v[208:209], v[206:207] op_sel:[1,0]
	v_mov_b32_e32 v209, v207
	v_pk_fma_f32 v[212:213], v[168:169], v[168:169], v[212:213]
	v_pk_fma_f32 v[210:211], v[166:167], v[166:167], v[210:211]
	v_pk_add_f32 v[206:207], v[214:215], v[208:209]
	v_cvt_pk_bf16_f32 v166, v166, v167
	v_add_f32_e32 v2, v206, v207
	v_pk_mov_b32 v[206:207], v[210:211], v[212:213] op_sel:[1,0]
	v_mov_b32_e32 v211, v213
	v_pk_add_f32 v[206:207], v[206:207], v[210:211]
	v_add_f32_e32 v139, v2, v139
	v_add_f32_e32 v2, v206, v207
	v_add_f32_e32 v135, v2, v135
	v_cvt_pk_bf16_f32 v167, v168, v169
	v_cvt_pk_bf16_f32 v168, v174, v175
	v_cvt_pk_bf16_f32 v169, v182, v183
	global_store_dwordx4 v[204:205], v[166:169], off offset:256 nt
	s_andn2_b64 vcc, exec, s[26:27]
	s_cbranch_vccnz .LBB0_1077
.LBB0_1087:
	s_waitcnt vmcnt(1)
	v_lshlrev_b32_e32 v2, 16, v162
	v_and_b32_e32 v5, 0xffff0000, v162
	v_lshlrev_b32_e32 v166, 16, v163
	v_and_b32_e32 v167, 0xffff0000, v163
	v_lshlrev_b32_e32 v168, 16, v164
	v_and_b32_e32 v169, 0xffff0000, v164
	v_lshlrev_b32_e32 v173, 16, v165
	v_and_b32_e32 v174, 0xffff0000, v165
	v_sub_f32_e32 v163, v5, v171
	v_sub_f32_e32 v162, v2, v171
	v_sub_f32_e32 v165, v167, v171
	v_sub_f32_e32 v164, v166, v171
	v_sub_f32_e32 v167, v169, v171
	v_sub_f32_e32 v166, v168, v171
	v_sub_f32_e32 v169, v174, v171
	v_sub_f32_e32 v168, v173, v171
	v_pk_mul_f32 v[164:165], v[4:5], v[164:165] op_sel_hi:[0,1]
	v_pk_mul_f32 v[162:163], v[4:5], v[162:163] op_sel_hi:[0,1]
	v_pk_mul_f32 v[168:169], v[4:5], v[168:169] op_sel_hi:[0,1]
	v_pk_mul_f32 v[4:5], v[4:5], v[166:167] op_sel_hi:[0,1]
	s_waitcnt lgkmcnt(1)
	v_pk_fma_f32 v[162:163], v[150:151], v[162:163], v[154:155]
	v_pk_fma_f32 v[164:165], v[152:153], v[164:165], v[156:157]
	s_waitcnt lgkmcnt(0)
	v_pk_fma_f32 v[4:5], v[142:143], v[4:5], v[146:147]
	v_pk_fma_f32 v[166:167], v[144:145], v[168:169], v[148:149]
	v_pk_mul_f32 v[164:165], v[164:165], s[76:77] op_sel_hi:[1,0]
	v_pk_mul_f32 v[162:163], v[162:163], s[76:77] op_sel_hi:[1,0]
	v_pk_mul_f32 v[166:167], v[166:167], s[76:77] op_sel_hi:[1,0]
	v_pk_mul_f32 v[4:5], v[4:5], s[76:77] op_sel_hi:[1,0]
	v_pk_fma_f32 v[162:163], v[54:55], 0.5, v[162:163] op_sel_hi:[1,0,1]
	v_pk_fma_f32 v[164:165], v[56:57], 0.5, v[164:165] op_sel_hi:[1,0,1]
	v_pk_fma_f32 v[4:5], v[62:63], 0.5, v[4:5] op_sel_hi:[1,0,1]
	v_pk_fma_f32 v[166:167], v[64:65], 0.5, v[166:167] op_sel_hi:[1,0,1]
	v_pk_add_f32 v[174:175], v[162:163], v[4:5]
	v_pk_add_f32 v[168:169], v[164:165], v[166:167]
	v_pk_mul_f32 v[182:183], v[4:5], v[4:5]
	v_pk_mul_f32 v[204:205], v[166:167], v[166:167]
	v_pk_mov_b32 v[206:207], v[174:175], v[168:169] op_sel:[1,0]
	v_mov_b32_e32 v175, v169
	v_pk_fma_f32 v[204:205], v[164:165], v[164:165], v[204:205]
	v_pk_fma_f32 v[182:183], v[162:163], v[162:163], v[182:183]
	v_pk_add_f32 v[168:169], v[206:207], v[174:175]
	v_cvt_pk_bf16_f32 v162, v162, v163
	v_add_f32_e32 v2, v168, v169
	v_pk_mov_b32 v[168:169], v[182:183], v[204:205] op_sel:[1,0]
	v_mov_b32_e32 v183, v205
	v_pk_add_f32 v[168:169], v[168:169], v[182:183]
	v_add_f32_e32 v140, v2, v140
	v_add_f32_e32 v2, v168, v169
	v_add_f32_e32 v136, v2, v136
	v_cvt_pk_bf16_f32 v163, v164, v165
	v_cvt_pk_bf16_f32 v164, v4, v5
	v_cvt_pk_bf16_f32 v165, v166, v167
	global_store_dwordx4 v[186:187], v[162:165], off offset:256 nt
	s_andn2_b64 vcc, exec, s[28:29]
	s_cbranch_vccz .LBB0_1078
	s_branch .LBB0_1079

.LBB0_1089:
	v_add_co_u32_e32 v134, vcc, 0x20000, v4
	s_mov_b64 s[0:1], 0x20000
	s_nop 0
	v_addc_co_u32_e32 v135, vcc, 0, v5, vcc
	v_lshl_add_u64 v[142:143], v[4:5], 0, s[0:1]
	global_load_dwordx4 v[138:141], v[134:135], off
	v_ashrrev_i32_e32 v181, 31, v180
	global_load_dwordx4 v[142:145], v[142:143], off offset:16
	v_lshlrev_b64 v[146:147], 12, v[180:181]
	v_lshl_add_u64 v[146:147], s[18:19], 0, v[146:147]
	v_lshl_add_u64 v[146:147], v[178:179], 1, v[146:147]
	s_mov_b32 s0, 0x10000
	v_add_co_u32_e32 v148, vcc, s0, v146
	s_mov_b64 s[0:1], 0x20200
	s_nop 0
	v_addc_co_u32_e32 v149, vcc, 0, v147, vcc
	v_cmp_lt_i32_e32 vcc, v234, v230
	s_waitcnt vmcnt(1)
	v_pk_mul_f32 v[140:141], v[140:141], s[76:77] op_sel_hi:[1,0]
	v_pk_mul_f32 v[138:139], v[138:139], s[76:77] op_sel_hi:[1,0]
	s_waitcnt vmcnt(0)
	v_pk_mul_f32 v[142:143], v[142:143], s[76:77] op_sel_hi:[1,0]
	v_pk_mul_f32 v[144:145], v[144:145], s[76:77] op_sel_hi:[1,0]
	v_pk_fma_f32 v[150:151], v[120:121], 0.5, v[140:141] op_sel_hi:[1,0,1]
	v_pk_fma_f32 v[152:153], v[118:119], 0.5, v[138:139] op_sel_hi:[1,0,1]
	v_pk_fma_f32 v[154:155], v[124:125], 0.5, v[144:145] op_sel_hi:[1,0,1]
	v_pk_fma_f32 v[156:157], v[122:123], 0.5, v[142:143] op_sel_hi:[1,0,1]
	v_cvt_pk_bf16_f32 v138, v152, v153
	v_cvt_pk_bf16_f32 v139, v150, v151
	v_cvt_pk_bf16_f32 v140, v156, v157
	v_cvt_pk_bf16_f32 v141, v154, v155
	global_store_dwordx4 v[148:149], v[138:141], off nt
	global_load_dwordx4 v[138:141], v[134:135], off offset:512
	v_lshl_add_u64 v[134:135], v[4:5], 0, s[0:1]
	global_load_dwordx4 v[142:145], v[134:135], off offset:16
	v_cndmask_b32_e32 v2, v228, v234, vcc
	v_mov_b32_e32 v134, v152
	v_mov_b32_e32 v135, v151
	v_pk_mov_b32 v[148:149], v[152:153], v[150:151] op_sel:[1,0]
	v_lshlrev_b32_e32 v164, 2, v2
	v_pk_mul_f32 v[152:153], v[152:153], v[152:153]
	v_mul_f32_e32 v2, v151, v151
	v_mul_f32_e32 v158, v156, v156
	v_mul_f32_e32 v160, v157, v157
	v_mov_b32_e32 v159, v156
	v_mov_b32_e32 v161, v157
	v_mul_f32_e32 v156, v154, v154
	v_mul_f32_e32 v162, v155, v155
	v_mov_b32_e32 v163, v155
	v_mov_b32_e32 v157, v154
	v_pk_add_f32 v[134:135], v[134:135], v[148:149]
	v_pk_fma_f32 v[148:149], v[150:151], v[150:151], v[2:3] op_sel_hi:[1,1,0]
	v_pk_add_f32 v[154:155], v[162:163], v[156:157]
	v_mov_b32_e32 v156, v152
	v_mov_b32_e32 v157, v134
	v_mov_b32_e32 v134, v153
	v_pk_add_f32 v[150:151], v[158:159], v[160:161]
	v_mov_b32_e32 v149, v3
	v_pk_add_f32 v[134:135], v[156:157], v[134:135]
	v_pk_add_f32 v[150:151], v[150:151], v[154:155]
	v_pk_add_f32 v[134:135], v[134:135], v[148:149]
	v_cmp_lt_i32_e32 vcc, v195, v230
	v_pk_add_f32 v[134:135], v[134:135], v[150:151]
	s_mov_b64 s[0:1], 0x10000
	v_cndmask_b32_e32 v2, v228, v195, vcc
	v_lshlrev_b32_e32 v2, 2, v2
	v_lshl_add_u64 v[146:147], v[146:147], 0, s[0:1]
	v_cmp_eq_u32_e32 vcc, 1, v191
	s_waitcnt vmcnt(1)
	v_pk_mul_f32 v[140:141], v[140:141], s[76:77] op_sel_hi:[1,0]
	v_pk_mul_f32 v[138:139], v[138:139], s[76:77] op_sel_hi:[1,0]
	s_waitcnt vmcnt(0)
	v_pk_mul_f32 v[142:143], v[142:143], s[76:77] op_sel_hi:[1,0]
	v_pk_mul_f32 v[144:145], v[144:145], s[76:77] op_sel_hi:[1,0]
	v_pk_fma_f32 v[140:141], v[88:89], 0.5, v[140:141] op_sel_hi:[1,0,1]
	v_pk_fma_f32 v[138:139], v[86:87], 0.5, v[138:139] op_sel_hi:[1,0,1]
	v_pk_fma_f32 v[144:145], v[92:93], 0.5, v[144:145] op_sel_hi:[1,0,1]
	v_pk_fma_f32 v[142:143], v[90:91], 0.5, v[142:143] op_sel_hi:[1,0,1]
	v_mul_f32_e32 v148, v138, v138
	v_mul_f32_e32 v150, v139, v139
	v_mul_f32_e32 v152, v140, v140
	v_mul_f32_e32 v154, v141, v141
	v_mov_b32_e32 v149, v138
	v_mov_b32_e32 v151, v139
	v_mov_b32_e32 v155, v141
	v_mov_b32_e32 v153, v140
	v_mul_f32_e32 v156, v142, v142
	v_mul_f32_e32 v158, v143, v143
	v_mul_f32_e32 v160, v144, v144
	v_mul_f32_e32 v162, v145, v145
	v_mov_b32_e32 v157, v142
	v_mov_b32_e32 v159, v143
	v_mov_b32_e32 v163, v145
	v_mov_b32_e32 v161, v144
	v_pk_add_f32 v[148:149], v[148:149], v[150:151]
	v_pk_add_f32 v[150:151], v[154:155], v[152:153]
	v_pk_add_f32 v[152:153], v[156:157], v[158:159]
	v_pk_add_f32 v[154:155], v[162:163], v[160:161]
	v_pk_add_f32 v[148:149], v[148:149], v[150:151]
	v_pk_add_f32 v[150:151], v[152:153], v[154:155]
	v_pk_add_f32 v[134:135], v[134:135], v[148:149]
	v_cvt_pk_bf16_f32 v138, v138, v139
	v_pk_add_f32 v[134:135], v[134:135], v[150:151]
	ds_bpermute_b32 v149, v164, v135
	ds_bpermute_b32 v148, v164, v134
	v_cvt_pk_bf16_f32 v139, v140, v141
	v_cvt_pk_bf16_f32 v140, v142, v143
	v_cvt_pk_bf16_f32 v141, v144, v145
	global_store_dwordx4 v[146:147], v[138:141], off offset:256 nt
	s_waitcnt lgkmcnt(0)
	v_pk_add_f32 v[134:135], v[134:135], v[148:149]
	ds_bpermute_b32 v149, v2, v135
	ds_bpermute_b32 v148, v2, v134
	s_waitcnt lgkmcnt(0)
	v_pk_add_f32 v[134:135], v[134:135], v[148:149]
	s_nop 0
	v_cndmask_b32_e32 v137, v137, v135, vcc
	v_cndmask_b32_e32 v136, v136, v134, vcc

.LBB0_1092:
	v_add_co_u32_e32 v134, vcc, 0x60000, v4
	s_mov_b64 s[0:1], 0x60000
	s_nop 0
	v_addc_co_u32_e32 v135, vcc, 0, v5, vcc
	v_lshl_add_u64 v[142:143], v[4:5], 0, s[0:1]
	global_load_dwordx4 v[138:141], v[134:135], off
	v_ashrrev_i32_e32 v181, 31, v180
	global_load_dwordx4 v[142:145], v[142:143], off offset:16
	v_lshlrev_b64 v[146:147], 12, v[180:181]
	v_lshl_add_u64 v[146:147], s[18:19], 0, v[146:147]
	v_lshl_add_u64 v[146:147], v[178:179], 1, v[146:147]
	s_mov_b32 s0, 0x30000
	v_add_co_u32_e32 v148, vcc, s0, v146
	s_mov_b64 s[0:1], 0x60200
	s_nop 0
	v_addc_co_u32_e32 v149, vcc, 0, v147, vcc
	v_cmp_lt_i32_e32 vcc, v234, v230
	s_waitcnt vmcnt(1)
	v_pk_mul_f32 v[140:141], v[140:141], s[76:77] op_sel_hi:[1,0]
	v_pk_mul_f32 v[138:139], v[138:139], s[76:77] op_sel_hi:[1,0]
	s_waitcnt vmcnt(0)
	v_pk_mul_f32 v[142:143], v[142:143], s[76:77] op_sel_hi:[1,0]
	v_pk_mul_f32 v[144:145], v[144:145], s[76:77] op_sel_hi:[1,0]
	v_pk_fma_f32 v[150:151], v[104:105], 0.5, v[140:141] op_sel_hi:[1,0,1]
	v_pk_fma_f32 v[152:153], v[102:103], 0.5, v[138:139] op_sel_hi:[1,0,1]
	v_pk_fma_f32 v[154:155], v[108:109], 0.5, v[144:145] op_sel_hi:[1,0,1]
	v_pk_fma_f32 v[156:157], v[106:107], 0.5, v[142:143] op_sel_hi:[1,0,1]
	v_cvt_pk_bf16_f32 v138, v152, v153
	v_cvt_pk_bf16_f32 v139, v150, v151
	v_cvt_pk_bf16_f32 v140, v156, v157
	v_cvt_pk_bf16_f32 v141, v154, v155
	global_store_dwordx4 v[148:149], v[138:141], off nt
	global_load_dwordx4 v[138:141], v[134:135], off offset:512
	v_lshl_add_u64 v[134:135], v[4:5], 0, s[0:1]
	global_load_dwordx4 v[142:145], v[134:135], off offset:16
	v_cndmask_b32_e32 v2, v228, v234, vcc
	v_lshlrev_b32_e32 v168, 2, v2
	v_mul_f32_e32 v2, v151, v151
	v_pk_mov_b32 v[166:167], v[152:153], v[150:151] op_sel:[1,0]
	v_mul_f32_e32 v134, v156, v156
	v_mul_f32_e32 v148, v157, v157
	v_mul_f32_e32 v158, v154, v154
	v_mul_f32_e32 v160, v155, v155
	v_pk_mul_f32 v[162:163], v[152:153], v[152:153]
	v_pk_add_f32 v[164:165], v[152:153], v[152:153] op_sel_hi:[0,1]
	v_mov_b32_e32 v135, v156
	v_mov_b32_e32 v149, v157
	v_mov_b32_e32 v161, v155
	v_mov_b32_e32 v159, v154
	v_pk_fma_f32 v[154:155], v[150:151], v[150:151], v[2:3] op_sel_hi:[1,1,0]
	v_pk_mul_f32 v[152:153], v[152:153], v[166:167] op_sel:[1,0] op_sel_hi:[0,1]
	v_pk_add_f32 v[150:151], v[150:151], v[166:167]
	v_mov_b32_e32 v163, v165
	v_pk_add_f32 v[134:135], v[134:135], v[148:149]
	v_pk_add_f32 v[148:149], v[160:161], v[158:159]
	v_mov_b32_e32 v153, v151
	v_mov_b32_e32 v155, v3
	v_pk_add_f32 v[134:135], v[134:135], v[148:149]
	v_pk_add_f32 v[148:149], v[162:163], v[152:153]
	v_cmp_lt_i32_e32 vcc, v195, v230
	v_pk_add_f32 v[148:149], v[148:149], v[154:155]
	s_mov_b64 s[0:1], 0x30000
	v_pk_add_f32 v[134:135], v[148:149], v[134:135]
	v_cndmask_b32_e32 v2, v228, v195, vcc
	v_lshlrev_b32_e32 v2, 2, v2
	v_lshl_add_u64 v[146:147], v[146:147], 0, s[0:1]
	v_cmp_eq_u32_e32 vcc, 3, v191
	s_waitcnt vmcnt(1)
	v_pk_mul_f32 v[140:141], v[140:141], s[76:77] op_sel_hi:[1,0]
	v_pk_mul_f32 v[138:139], v[138:139], s[76:77] op_sel_hi:[1,0]
	s_waitcnt vmcnt(0)
	v_pk_mul_f32 v[142:143], v[142:143], s[76:77] op_sel_hi:[1,0]
	v_pk_mul_f32 v[144:145], v[144:145], s[76:77] op_sel_hi:[1,0]
	v_pk_fma_f32 v[140:141], v[72:73], 0.5, v[140:141] op_sel_hi:[1,0,1]
	v_pk_fma_f32 v[138:139], v[70:71], 0.5, v[138:139] op_sel_hi:[1,0,1]
	v_pk_fma_f32 v[144:145], v[76:77], 0.5, v[144:145] op_sel_hi:[1,0,1]
	v_pk_fma_f32 v[142:143], v[74:75], 0.5, v[142:143] op_sel_hi:[1,0,1]
	v_mul_f32_e32 v148, v138, v138
	v_mul_f32_e32 v150, v139, v139
	v_mul_f32_e32 v152, v140, v140
	v_mul_f32_e32 v154, v141, v141
	v_mov_b32_e32 v149, v138
	v_mov_b32_e32 v151, v139
	v_mov_b32_e32 v155, v141
	v_mov_b32_e32 v153, v140
	v_mul_f32_e32 v156, v142, v142
	v_mul_f32_e32 v158, v143, v143
	v_mul_f32_e32 v160, v144, v144
	v_mul_f32_e32 v162, v145, v145
	v_mov_b32_e32 v157, v142
	v_mov_b32_e32 v159, v143
	v_mov_b32_e32 v163, v145
	v_mov_b32_e32 v161, v144
	v_pk_add_f32 v[148:149], v[148:149], v[150:151]
	v_pk_add_f32 v[150:151], v[154:155], v[152:153]
	v_pk_add_f32 v[152:153], v[156:157], v[158:159]
	v_pk_add_f32 v[154:155], v[162:163], v[160:161]
	v_pk_add_f32 v[148:149], v[148:149], v[150:151]
	v_pk_add_f32 v[150:151], v[152:153], v[154:155]
	v_pk_add_f32 v[134:135], v[134:135], v[148:149]
	v_cvt_pk_bf16_f32 v138, v138, v139
	v_pk_add_f32 v[134:135], v[134:135], v[150:151]
	ds_bpermute_b32 v149, v168, v135
	ds_bpermute_b32 v148, v168, v134
	v_cvt_pk_bf16_f32 v139, v140, v141
	v_cvt_pk_bf16_f32 v140, v142, v143
	v_cvt_pk_bf16_f32 v141, v144, v145
	global_store_dwordx4 v[146:147], v[138:141], off offset:256 nt
	s_waitcnt lgkmcnt(0)
	v_pk_add_f32 v[134:135], v[134:135], v[148:149]
	ds_bpermute_b32 v149, v2, v135
	ds_bpermute_b32 v148, v2, v134
	s_waitcnt lgkmcnt(0)
	v_pk_add_f32 v[134:135], v[134:135], v[148:149]
	s_nop 0
	v_cndmask_b32_e32 v137, v137, v135, vcc
	v_cndmask_b32_e32 v136, v136, v134, vcc

.LBB0_1095:
	s_or_b64 exec, exec, s[0:1]
	s_bitcmp0_b32 s84, 4
	s_cbranch_scc1 .LBB0_1098
	v_add_co_u32_e32 v138, vcc, 0x100000, v4
	s_mov_b64 s[0:1], 0x100000
	s_nop 0
	v_addc_co_u32_e32 v139, vcc, 0, v5, vcc
	v_lshl_add_u64 v[136:137], v[4:5], 0, s[0:1]
	global_load_dwordx4 v[140:143], v[138:139], off
	global_load_dwordx4 v[144:147], v[136:137], off offset:16
	v_ashrrev_i32_e32 v181, 31, v180
	v_lshlrev_b64 v[148:149], 12, v[180:181]
	s_mov_b64 s[0:1], 0x80000
	s_waitcnt vmcnt(1)
	v_pk_mul_f32 v[140:141], v[140:141], s[76:77] op_sel_hi:[1,0]
	v_pk_mul_f32 v[136:137], v[142:143], s[76:77] op_sel_hi:[1,0]
	v_pk_fma_f32 v[140:141], v[46:47], 0.5, v[140:141] op_sel_hi:[1,0,1]
	v_pk_fma_f32 v[142:143], v[48:49], 0.5, v[136:137] op_sel_hi:[1,0,1]
	s_waitcnt vmcnt(0)
	v_pk_mul_f32 v[144:145], v[144:145], s[76:77] op_sel_hi:[1,0]
	v_pk_mul_f32 v[158:159], v[140:141], v[140:141]
	v_pk_add_f32 v[160:161], v[140:141], v[140:141] op_sel_hi:[0,1]
	v_mul_f32_e32 v2, v143, v143
	v_pk_fma_f32 v[144:145], v[50:51], 0.5, v[144:145] op_sel_hi:[1,0,1]
	v_mov_b32_e32 v159, v161
	v_pk_mov_b32 v[160:161], v[140:141], v[142:143] op_sel:[1,0]
	v_pk_fma_f32 v[136:137], v[142:143], v[142:143], v[2:3] op_sel_hi:[1,1,0]
	v_pk_mul_f32 v[146:147], v[146:147], s[76:77] op_sel_hi:[1,0]
	v_mul_f32_e32 v150, v144, v144
	v_mul_f32_e32 v152, v145, v145
	v_pk_mul_f32 v[162:163], v[140:141], v[160:161] op_sel:[1,0] op_sel_hi:[0,1]
	v_pk_add_f32 v[160:161], v[142:143], v[160:161]
	v_mov_b32_e32 v151, v144
	v_mov_b32_e32 v153, v145
	v_cvt_pk_bf16_f32 v140, v140, v141
	v_cvt_pk_bf16_f32 v141, v142, v143
	v_cvt_pk_bf16_f32 v142, v144, v145
	v_lshl_add_u64 v[144:145], s[18:19], 0, v[148:149]
	v_pk_fma_f32 v[146:147], v[52:53], 0.5, v[146:147] op_sel_hi:[1,0,1]
	v_lshl_add_u64 v[144:145], v[178:179], 1, v[144:145]
	v_mul_f32_e32 v154, v146, v146
	v_mul_f32_e32 v156, v147, v147
	v_mov_b32_e32 v157, v147
	v_mov_b32_e32 v155, v146
	v_cvt_pk_bf16_f32 v143, v146, v147
	v_lshl_add_u64 v[146:147], v[144:145], 0, s[0:1]
	s_mov_b32 s0, 0x80000
	v_add_co_u32_e32 v144, vcc, s0, v144
	s_mov_b64 s[0:1], 0x100200
	s_nop 0
	v_addc_co_u32_e32 v145, vcc, 0, v145, vcc
	global_store_dwordx4 v[144:145], v[140:143], off nt
	v_mov_b32_e32 v163, v161
	v_pk_add_f32 v[158:159], v[158:159], v[162:163]
	v_lshl_add_u64 v[142:143], v[4:5], 0, s[0:1]
	global_load_dwordx4 v[138:141], v[138:139], off offset:512
	s_nop 0
	global_load_dwordx4 v[142:145], v[142:143], off offset:16
	v_mov_b32_e32 v137, v3
	v_pk_add_f32 v[150:151], v[150:151], v[152:153]
	v_pk_add_f32 v[152:153], v[156:157], v[154:155]
	v_pk_add_f32 v[136:137], v[158:159], v[136:137]
	v_pk_add_f32 v[150:151], v[150:151], v[152:153]
	v_cmp_lt_i32_e32 vcc, v234, v230
	v_pk_add_f32 v[136:137], v[136:137], v[150:151]
	s_waitcnt vmcnt(1)
	v_pk_mul_f32 v[140:141], v[140:141], s[76:77] op_sel_hi:[1,0]
	v_pk_mul_f32 v[138:139], v[138:139], s[76:77] op_sel_hi:[1,0]
	v_pk_fma_f32 v[148:149], v[16:17], 0.5, v[140:141] op_sel_hi:[1,0,1]
	v_pk_fma_f32 v[150:151], v[14:15], 0.5, v[138:139] op_sel_hi:[1,0,1]
	v_mul_f32_e32 v152, v148, v148
	v_mul_f32_e32 v138, v150, v150
	v_mul_f32_e32 v140, v151, v151
	v_mul_f32_e32 v154, v149, v149
	v_mov_b32_e32 v139, v150
	v_mov_b32_e32 v141, v151
	v_mov_b32_e32 v155, v149
	v_mov_b32_e32 v153, v148
	v_pk_add_f32 v[138:139], v[138:139], v[140:141]
	v_pk_add_f32 v[140:141], v[154:155], v[152:153]
	v_cndmask_b32_e32 v2, v228, v234, vcc
	v_pk_add_f32 v[152:153], v[138:139], v[140:141]
	s_waitcnt vmcnt(0)
	v_pk_mul_f32 v[138:139], v[142:143], s[76:77] op_sel_hi:[1,0]
	v_pk_mul_f32 v[140:141], v[144:145], s[76:77] op_sel_hi:[1,0]
	v_pk_fma_f32 v[144:145], v[18:19], 0.5, v[138:139] op_sel_hi:[1,0,1]
	v_pk_fma_f32 v[154:155], v[20:21], 0.5, v[140:141] op_sel_hi:[1,0,1]
	v_mul_f32_e32 v138, v144, v144
	v_mul_f32_e32 v140, v145, v145
	v_mov_b32_e32 v139, v144
	v_mov_b32_e32 v141, v145
	v_pk_add_f32 v[138:139], v[138:139], v[140:141]
	v_mul_f32_e32 v140, v154, v154
	v_mul_f32_e32 v142, v155, v155
	v_mov_b32_e32 v143, v155
	v_mov_b32_e32 v141, v154
	v_pk_add_f32 v[140:141], v[142:143], v[140:141]
	v_pk_add_f32 v[136:137], v[136:137], v[152:153]
	v_pk_add_f32 v[138:139], v[138:139], v[140:141]
	v_lshlrev_b32_e32 v2, 2, v2
	v_pk_add_f32 v[136:137], v[136:137], v[138:139]
	ds_bpermute_b32 v139, v2, v137
	ds_bpermute_b32 v138, v2, v136
	v_cmp_lt_i32_e32 vcc, v195, v230
	v_cvt_pk_bf16_f32 v142, v150, v151
	v_cvt_pk_bf16_f32 v143, v148, v149
	v_cndmask_b32_e32 v135, v228, v195, vcc
	v_lshlrev_b32_e32 v135, 2, v135
	s_waitcnt lgkmcnt(0)
	v_pk_add_f32 v[136:137], v[136:137], v[138:139]
	ds_bpermute_b32 v139, v135, v137
	ds_bpermute_b32 v138, v135, v136
	v_cvt_pk_bf16_f32 v144, v144, v145
	v_cvt_pk_bf16_f32 v145, v154, v155
	global_store_dwordx4 v[146:147], v[142:145], off offset:256 nt
	v_cmp_eq_u32_e32 vcc, 0, v191
	s_waitcnt lgkmcnt(0)
	v_pk_add_f32 v[136:137], v[136:137], v[138:139]
	s_nop 0
	v_cndmask_b32_e32 v137, 0, v137, vcc
	v_cndmask_b32_e32 v136, 0, v136, vcc
	s_bitcmp0_b32 s84, 5
	s_cbranch_scc0 .LBB0_1099
	s_branch .LBB0_1100
.LBB0_1097:
	v_add_co_u32_e32 v134, vcc, 0x40000, v4
	s_mov_b64 s[0:1], 0x40000
	s_nop 0
	v_addc_co_u32_e32 v135, vcc, 0, v5, vcc
	v_lshl_add_u64 v[142:143], v[4:5], 0, s[0:1]
	global_load_dwordx4 v[138:141], v[134:135], off
	v_ashrrev_i32_e32 v181, 31, v180
	global_load_dwordx4 v[142:145], v[142:143], off offset:16
	v_lshlrev_b64 v[146:147], 12, v[180:181]
	v_lshl_add_u64 v[146:147], s[18:19], 0, v[146:147]
	v_lshl_add_u64 v[146:147], v[178:179], 1, v[146:147]
	s_mov_b32 s0, 0x20000
	v_add_co_u32_e32 v148, vcc, s0, v146
	s_mov_b64 s[0:1], 0x40200
	s_nop 0
	v_addc_co_u32_e32 v149, vcc, 0, v147, vcc
	v_cmp_lt_i32_e32 vcc, v234, v230
	s_waitcnt vmcnt(1)
	v_pk_mul_f32 v[140:141], v[140:141], s[76:77] op_sel_hi:[1,0]
	v_pk_mul_f32 v[138:139], v[138:139], s[76:77] op_sel_hi:[1,0]
	s_waitcnt vmcnt(0)
	v_pk_mul_f32 v[142:143], v[142:143], s[76:77] op_sel_hi:[1,0]
	v_pk_mul_f32 v[144:145], v[144:145], s[76:77] op_sel_hi:[1,0]
	v_pk_fma_f32 v[150:151], v[112:113], 0.5, v[140:141] op_sel_hi:[1,0,1]
	v_pk_fma_f32 v[152:153], v[110:111], 0.5, v[138:139] op_sel_hi:[1,0,1]
	v_pk_fma_f32 v[154:155], v[116:117], 0.5, v[144:145] op_sel_hi:[1,0,1]
	v_pk_fma_f32 v[156:157], v[114:115], 0.5, v[142:143] op_sel_hi:[1,0,1]
	v_cvt_pk_bf16_f32 v138, v152, v153
	v_cvt_pk_bf16_f32 v139, v150, v151
	v_cvt_pk_bf16_f32 v140, v156, v157
	v_cvt_pk_bf16_f32 v141, v154, v155
	global_store_dwordx4 v[148:149], v[138:141], off nt
	global_load_dwordx4 v[138:141], v[134:135], off offset:512
	v_lshl_add_u64 v[134:135], v[4:5], 0, s[0:1]
	global_load_dwordx4 v[142:145], v[134:135], off offset:16
	v_cndmask_b32_e32 v2, v228, v234, vcc
	v_lshlrev_b32_e32 v164, 2, v2
	v_mul_f32_e32 v2, v151, v151
	v_add_f32_e32 v135, v152, v153
	v_add_f32_e32 v149, v151, v150
	v_mul_f32_e32 v134, v152, v152
	v_mul_f32_e32 v148, v153, v153
	v_mul_f32_e32 v152, v156, v156
	v_mul_f32_e32 v158, v157, v157
	v_mul_f32_e32 v160, v154, v154
	v_mul_f32_e32 v162, v155, v155
	v_mov_b32_e32 v153, v156
	v_mov_b32_e32 v159, v157
	v_mov_b32_e32 v163, v155
	v_mov_b32_e32 v161, v154
	v_pk_fma_f32 v[150:151], v[150:151], v[150:151], v[2:3] op_sel_hi:[1,1,0]
	v_pk_add_f32 v[134:135], v[134:135], v[148:149]
	v_pk_add_f32 v[148:149], v[152:153], v[158:159]
	v_pk_add_f32 v[152:153], v[162:163], v[160:161]
	v_mov_b32_e32 v151, v3
	v_pk_add_f32 v[148:149], v[148:149], v[152:153]
	v_pk_add_f32 v[134:135], v[134:135], v[150:151]
	v_cmp_lt_i32_e32 vcc, v195, v230
	v_pk_add_f32 v[134:135], v[134:135], v[148:149]
	s_mov_b64 s[0:1], 0x20000
	v_cndmask_b32_e32 v2, v228, v195, vcc
	v_lshlrev_b32_e32 v2, 2, v2
	v_lshl_add_u64 v[146:147], v[146:147], 0, s[0:1]
	v_cmp_eq_u32_e32 vcc, 2, v191
	s_waitcnt vmcnt(1)
	v_pk_mul_f32 v[140:141], v[140:141], s[76:77] op_sel_hi:[1,0]
	v_pk_mul_f32 v[138:139], v[138:139], s[76:77] op_sel_hi:[1,0]
	s_waitcnt vmcnt(0)
	v_pk_mul_f32 v[142:143], v[142:143], s[76:77] op_sel_hi:[1,0]
	v_pk_mul_f32 v[144:145], v[144:145], s[76:77] op_sel_hi:[1,0]
	v_pk_fma_f32 v[140:141], v[80:81], 0.5, v[140:141] op_sel_hi:[1,0,1]
	v_pk_fma_f32 v[138:139], v[78:79], 0.5, v[138:139] op_sel_hi:[1,0,1]
	v_pk_fma_f32 v[144:145], v[84:85], 0.5, v[144:145] op_sel_hi:[1,0,1]
	v_pk_fma_f32 v[142:143], v[82:83], 0.5, v[142:143] op_sel_hi:[1,0,1]
	v_mul_f32_e32 v148, v138, v138
	v_mul_f32_e32 v150, v139, v139
	v_mul_f32_e32 v152, v140, v140
	v_mul_f32_e32 v154, v141, v141
	v_mov_b32_e32 v149, v138
	v_mov_b32_e32 v151, v139
	v_mov_b32_e32 v155, v141
	v_mov_b32_e32 v153, v140
	v_mul_f32_e32 v156, v142, v142
	v_mul_f32_e32 v158, v143, v143
	v_mul_f32_e32 v160, v144, v144
	v_mul_f32_e32 v162, v145, v145
	v_mov_b32_e32 v157, v142
	v_mov_b32_e32 v159, v143
	v_mov_b32_e32 v163, v145
	v_mov_b32_e32 v161, v144
	v_pk_add_f32 v[148:149], v[148:149], v[150:151]
	v_pk_add_f32 v[150:151], v[154:155], v[152:153]
	v_pk_add_f32 v[152:153], v[156:157], v[158:159]
	v_pk_add_f32 v[154:155], v[162:163], v[160:161]
	v_pk_add_f32 v[148:149], v[148:149], v[150:151]
	v_pk_add_f32 v[150:151], v[152:153], v[154:155]
	v_pk_add_f32 v[134:135], v[134:135], v[148:149]
	v_cvt_pk_bf16_f32 v138, v138, v139
	v_pk_add_f32 v[134:135], v[134:135], v[150:151]
	ds_bpermute_b32 v149, v164, v135
	ds_bpermute_b32 v148, v164, v134
	v_cvt_pk_bf16_f32 v139, v140, v141
	v_cvt_pk_bf16_f32 v140, v142, v143
	v_cvt_pk_bf16_f32 v141, v144, v145
	global_store_dwordx4 v[146:147], v[138:141], off offset:256 nt
	s_waitcnt lgkmcnt(0)
	v_pk_add_f32 v[134:135], v[134:135], v[148:149]
	ds_bpermute_b32 v149, v2, v135
	ds_bpermute_b32 v148, v2, v134
	s_waitcnt lgkmcnt(0)
	v_pk_add_f32 v[134:135], v[134:135], v[148:149]
	s_nop 0
	v_cndmask_b32_e32 v137, v137, v135, vcc
	v_cndmask_b32_e32 v136, v136, v134, vcc
	s_bitcmp0_b32 s84, 3
	s_cbranch_scc0 .LBB0_1092
	s_branch .LBB0_1093

.LBB0_1099:
	v_add_co_u32_e32 v146, vcc, 0x120000, v4
	s_mov_b64 s[0:1], 0x120000
	s_nop 0
	v_addc_co_u32_e32 v147, vcc, 0, v5, vcc
	v_lshl_add_u64 v[142:143], v[4:5], 0, s[0:1]
	global_load_dwordx4 v[138:141], v[146:147], off
	v_ashrrev_i32_e32 v181, 31, v180
	global_load_dwordx4 v[142:145], v[142:143], off offset:16
	v_lshlrev_b64 v[148:149], 12, v[180:181]
	v_lshl_add_u64 v[148:149], s[18:19], 0, v[148:149]
	v_lshl_add_u64 v[148:149], v[178:179], 1, v[148:149]
	s_mov_b32 s0, 0x90000
	v_add_co_u32_e32 v150, vcc, s0, v148
	s_mov_b64 s[0:1], 0x120200
	s_nop 0
	v_addc_co_u32_e32 v151, vcc, 0, v149, vcc
	v_cmp_lt_i32_e32 vcc, v234, v230
	s_waitcnt vmcnt(1)
	v_pk_mul_f32 v[140:141], v[140:141], s[76:77] op_sel_hi:[1,0]
	v_pk_mul_f32 v[138:139], v[138:139], s[76:77] op_sel_hi:[1,0]
	s_waitcnt vmcnt(0)
	v_pk_mul_f32 v[142:143], v[142:143], s[76:77] op_sel_hi:[1,0]
	v_pk_mul_f32 v[144:145], v[144:145], s[76:77] op_sel_hi:[1,0]
	v_pk_fma_f32 v[152:153], v[40:41], 0.5, v[140:141] op_sel_hi:[1,0,1]
	v_pk_fma_f32 v[154:155], v[38:39], 0.5, v[138:139] op_sel_hi:[1,0,1]
	v_pk_fma_f32 v[156:157], v[44:45], 0.5, v[144:145] op_sel_hi:[1,0,1]
	v_pk_fma_f32 v[158:159], v[42:43], 0.5, v[142:143] op_sel_hi:[1,0,1]
	v_cvt_pk_bf16_f32 v138, v154, v155
	v_cvt_pk_bf16_f32 v139, v152, v153
	v_cvt_pk_bf16_f32 v140, v158, v159
	v_cvt_pk_bf16_f32 v141, v156, v157
	global_store_dwordx4 v[150:151], v[138:141], off nt
	global_load_dwordx4 v[138:141], v[146:147], off offset:512
	v_lshl_add_u64 v[142:143], v[4:5], 0, s[0:1]
	global_load_dwordx4 v[142:145], v[142:143], off offset:16
	v_cndmask_b32_e32 v2, v228, v234, vcc
	v_mov_b32_e32 v146, v154
	v_mov_b32_e32 v147, v153
	v_pk_mov_b32 v[150:151], v[154:155], v[152:153] op_sel:[1,0]
	v_lshlrev_b32_e32 v135, 2, v2
	v_pk_mul_f32 v[154:155], v[154:155], v[154:155]
	v_mul_f32_e32 v2, v153, v153
	v_mul_f32_e32 v160, v158, v158
	v_mul_f32_e32 v162, v159, v159
	v_mov_b32_e32 v161, v158
	v_mov_b32_e32 v163, v159
	v_mul_f32_e32 v158, v156, v156
	v_mul_f32_e32 v164, v157, v157
	v_mov_b32_e32 v165, v157
	v_mov_b32_e32 v159, v156
	v_pk_add_f32 v[146:147], v[146:147], v[150:151]
	v_pk_fma_f32 v[150:151], v[152:153], v[152:153], v[2:3] op_sel_hi:[1,1,0]
	v_pk_add_f32 v[156:157], v[164:165], v[158:159]
	v_mov_b32_e32 v158, v154
	v_mov_b32_e32 v159, v146
	v_mov_b32_e32 v146, v155
	v_pk_add_f32 v[152:153], v[160:161], v[162:163]
	v_mov_b32_e32 v151, v3
	v_pk_add_f32 v[146:147], v[158:159], v[146:147]
	v_pk_add_f32 v[152:153], v[152:153], v[156:157]
	v_pk_add_f32 v[146:147], v[146:147], v[150:151]
	v_cmp_lt_i32_e32 vcc, v195, v230
	v_pk_add_f32 v[146:147], v[146:147], v[152:153]
	s_mov_b64 s[0:1], 0x90000
	v_cndmask_b32_e32 v2, v228, v195, vcc
	v_lshlrev_b32_e32 v2, 2, v2
	v_lshl_add_u64 v[148:149], v[148:149], 0, s[0:1]
	v_cmp_eq_u32_e32 vcc, 1, v191
	s_waitcnt vmcnt(1)
	v_pk_mul_f32 v[140:141], v[140:141], s[76:77] op_sel_hi:[1,0]
	v_pk_mul_f32 v[138:139], v[138:139], s[76:77] op_sel_hi:[1,0]
	s_waitcnt vmcnt(0)
	v_pk_mul_f32 v[142:143], v[142:143], s[76:77] op_sel_hi:[1,0]
	v_pk_mul_f32 v[144:145], v[144:145], s[76:77] op_sel_hi:[1,0]
	v_pk_fma_f32 v[140:141], v[8:9], 0.5, v[140:141] op_sel_hi:[1,0,1]
	v_pk_fma_f32 v[138:139], v[6:7], 0.5, v[138:139] op_sel_hi:[1,0,1]
	v_pk_fma_f32 v[144:145], v[12:13], 0.5, v[144:145] op_sel_hi:[1,0,1]
	v_pk_fma_f32 v[142:143], v[10:11], 0.5, v[142:143] op_sel_hi:[1,0,1]
	v_mul_f32_e32 v150, v138, v138
	v_mul_f32_e32 v152, v139, v139
	v_mul_f32_e32 v154, v140, v140
	v_mul_f32_e32 v156, v141, v141
	v_mov_b32_e32 v151, v138
	v_mov_b32_e32 v153, v139
	v_mov_b32_e32 v157, v141
	v_mov_b32_e32 v155, v140
	v_mul_f32_e32 v158, v142, v142
	v_mul_f32_e32 v160, v143, v143
	v_mul_f32_e32 v162, v144, v144
	v_mul_f32_e32 v164, v145, v145
	v_mov_b32_e32 v159, v142
	v_mov_b32_e32 v161, v143
	v_mov_b32_e32 v165, v145
	v_mov_b32_e32 v163, v144
	v_pk_add_f32 v[150:151], v[150:151], v[152:153]
	v_pk_add_f32 v[152:153], v[156:157], v[154:155]
	v_pk_add_f32 v[154:155], v[158:159], v[160:161]
	v_pk_add_f32 v[156:157], v[164:165], v[162:163]
	v_pk_add_f32 v[150:151], v[150:151], v[152:153]
	v_pk_add_f32 v[152:153], v[154:155], v[156:157]
	v_pk_add_f32 v[146:147], v[146:147], v[150:151]
	v_cvt_pk_bf16_f32 v138, v138, v139
	v_pk_add_f32 v[146:147], v[146:147], v[152:153]
	ds_bpermute_b32 v151, v135, v147
	ds_bpermute_b32 v150, v135, v146
	v_cvt_pk_bf16_f32 v139, v140, v141
	v_cvt_pk_bf16_f32 v140, v142, v143
	v_cvt_pk_bf16_f32 v141, v144, v145
	global_store_dwordx4 v[148:149], v[138:141], off offset:256 nt
	s_waitcnt lgkmcnt(0)
	v_pk_add_f32 v[146:147], v[146:147], v[150:151]
	ds_bpermute_b32 v151, v2, v147
	ds_bpermute_b32 v150, v2, v146
	s_waitcnt lgkmcnt(0)
	v_pk_add_f32 v[138:139], v[146:147], v[150:151]
	s_nop 0
	v_cndmask_b32_e32 v137, v137, v139, vcc
	v_cndmask_b32_e32 v136, v136, v138, vcc

.LBB0_1102:
	s_mov_b64 s[0:1], 0x160000
	v_add_co_u32_e32 v146, vcc, 0x160000, v4
	v_lshl_add_u64 v[138:139], v[4:5], 0, s[0:1]
	global_load_dwordx4 v[138:141], v[138:139], off offset:16
	v_addc_co_u32_e32 v147, vcc, 0, v5, vcc
	global_load_dwordx4 v[142:145], v[146:147], off
	v_ashrrev_i32_e32 v181, 31, v180
	v_lshlrev_b64 v[148:149], 12, v[180:181]
	v_lshl_add_u64 v[148:149], s[18:19], 0, v[148:149]
	v_lshl_add_u64 v[148:149], v[178:179], 1, v[148:149]
	s_mov_b32 s0, 0xb0000
	v_add_co_u32_e32 v150, vcc, s0, v148
	s_mov_b64 s[0:1], 0x160200
	s_nop 0
	v_addc_co_u32_e32 v151, vcc, 0, v149, vcc
	v_lshl_add_u64 v[4:5], v[4:5], 0, s[0:1]
	v_cmp_lt_i32_e32 vcc, v234, v230
	s_mov_b64 s[0:1], 0xb0000
	v_lshl_add_u64 v[148:149], v[148:149], 0, s[0:1]
	v_cndmask_b32_e32 v2, v228, v234, vcc
	v_lshlrev_b32_e32 v135, 2, v2
	v_cmp_lt_i32_e32 vcc, v195, v230
	s_waitcnt vmcnt(1)
	v_pk_mul_f32 v[138:139], v[138:139], s[76:77] op_sel_hi:[1,0]
	v_pk_mul_f32 v[140:141], v[140:141], s[76:77] op_sel_hi:[1,0]
	v_pk_fma_f32 v[154:155], v[26:27], 0.5, v[138:139] op_sel_hi:[1,0,1]
	s_waitcnt vmcnt(0)
	v_pk_mul_f32 v[138:139], v[144:145], s[76:77] op_sel_hi:[1,0]
	v_pk_mul_f32 v[142:143], v[142:143], s[76:77] op_sel_hi:[1,0]
	v_pk_fma_f32 v[152:153], v[28:29], 0.5, v[140:141] op_sel_hi:[1,0,1]
	v_pk_fma_f32 v[156:157], v[24:25], 0.5, v[138:139] op_sel_hi:[1,0,1]
	v_pk_fma_f32 v[158:159], v[22:23], 0.5, v[142:143] op_sel_hi:[1,0,1]
	v_cvt_pk_bf16_f32 v140, v154, v155
	v_cvt_pk_bf16_f32 v141, v152, v153
	v_cvt_pk_bf16_f32 v138, v158, v159
	v_cvt_pk_bf16_f32 v139, v156, v157
	global_store_dwordx4 v[150:151], v[138:141], off nt
	global_load_dwordx4 v[138:141], v[146:147], off offset:512
	v_mul_f32_e32 v150, v152, v152
	global_load_dwordx4 v[142:145], v[4:5], off offset:16
	v_mul_f32_e32 v4, v154, v154
	v_mul_f32_e32 v146, v155, v155
	v_mul_f32_e32 v160, v153, v153
	v_mov_b32_e32 v5, v154
	v_mov_b32_e32 v147, v155
	v_mov_b32_e32 v161, v153
	v_mov_b32_e32 v151, v152
	v_pk_add_f32 v[4:5], v[4:5], v[146:147]
	v_pk_add_f32 v[146:147], v[160:161], v[150:151]
	v_pk_mul_f32 v[150:151], v[158:159], v[158:159]
	v_pk_add_f32 v[152:153], v[158:159], v[158:159] op_sel_hi:[0,1]
	v_pk_mov_b32 v[154:155], v[158:159], v[156:157] op_sel:[1,0]
	v_mul_f32_e32 v2, v157, v157
	v_mov_b32_e32 v151, v153
	v_pk_mul_f32 v[152:153], v[158:159], v[154:155] op_sel:[1,0] op_sel_hi:[0,1]
	v_pk_add_f32 v[154:155], v[156:157], v[154:155]
	v_pk_add_f32 v[4:5], v[4:5], v[146:147]
	v_pk_fma_f32 v[146:147], v[156:157], v[156:157], v[2:3] op_sel_hi:[1,1,0]
	v_mov_b32_e32 v153, v155
	v_mov_b32_e32 v147, v3
	v_pk_add_f32 v[150:151], v[150:151], v[152:153]
	v_cndmask_b32_e32 v2, v228, v195, vcc
	v_pk_add_f32 v[146:147], v[150:151], v[146:147]
	v_lshlrev_b32_e32 v2, 2, v2
	v_pk_add_f32 v[4:5], v[146:147], v[4:5]
	v_cmp_eq_u32_e32 vcc, 3, v191
	s_waitcnt vmcnt(1)
	v_pk_mul_f32 v[140:141], v[140:141], s[76:77] op_sel_hi:[1,0]
	v_pk_mul_f32 v[138:139], v[138:139], s[76:77] op_sel_hi:[1,0]
	s_waitcnt vmcnt(0)
	v_pk_mul_f32 v[142:143], v[142:143], s[76:77] op_sel_hi:[1,0]
	v_pk_mul_f32 v[144:145], v[144:145], s[76:77] op_sel_hi:[1,0]
	v_pk_fma_f32 v[140:141], v[60:61], 0.5, v[140:141] op_sel_hi:[1,0,1]
	v_pk_fma_f32 v[138:139], v[58:59], 0.5, v[138:139] op_sel_hi:[1,0,1]
	v_pk_fma_f32 v[144:145], v[68:69], 0.5, v[144:145] op_sel_hi:[1,0,1]
	v_pk_fma_f32 v[142:143], v[66:67], 0.5, v[142:143] op_sel_hi:[1,0,1]
	v_mul_f32_e32 v146, v138, v138
	v_mul_f32_e32 v150, v139, v139
	v_mul_f32_e32 v152, v140, v140
	v_mul_f32_e32 v154, v141, v141
	v_mov_b32_e32 v147, v138
	v_mov_b32_e32 v151, v139
	v_mov_b32_e32 v155, v141
	v_mov_b32_e32 v153, v140
	v_mul_f32_e32 v156, v142, v142
	v_mul_f32_e32 v158, v143, v143
	v_mul_f32_e32 v160, v144, v144
	v_mul_f32_e32 v162, v145, v145
	v_mov_b32_e32 v157, v142
	v_mov_b32_e32 v159, v143
	v_mov_b32_e32 v163, v145
	v_mov_b32_e32 v161, v144
	v_pk_add_f32 v[146:147], v[146:147], v[150:151]
	v_pk_add_f32 v[150:151], v[154:155], v[152:153]
	v_pk_add_f32 v[152:153], v[156:157], v[158:159]
	v_pk_add_f32 v[154:155], v[162:163], v[160:161]
	v_pk_add_f32 v[146:147], v[146:147], v[150:151]
	v_pk_add_f32 v[150:151], v[152:153], v[154:155]
	v_pk_add_f32 v[4:5], v[4:5], v[146:147]
	v_cvt_pk_bf16_f32 v138, v138, v139
	v_pk_add_f32 v[4:5], v[4:5], v[150:151]
	ds_bpermute_b32 v147, v135, v5
	ds_bpermute_b32 v146, v135, v4
	v_cvt_pk_bf16_f32 v139, v140, v141
	v_cvt_pk_bf16_f32 v140, v142, v143
	v_cvt_pk_bf16_f32 v141, v144, v145
	global_store_dwordx4 v[148:149], v[138:141], off offset:256 nt
	s_waitcnt lgkmcnt(0)
	v_pk_add_f32 v[4:5], v[4:5], v[146:147]
	ds_bpermute_b32 v147, v2, v5
	ds_bpermute_b32 v146, v2, v4
	s_waitcnt lgkmcnt(0)
	v_pk_add_f32 v[4:5], v[4:5], v[146:147]
	s_nop 0
	v_cndmask_b32_e32 v137, v137, v5, vcc
	v_cndmask_b32_e32 v136, v136, v4, vcc

.LBB0_1109:
	s_and_b64 vcc, exec, s[14:15]
	s_cbranch_vccz .LBB0_1172
	s_add_u32 s16, s12, 0x1aa00000
	s_mul_i32 s0, s36, 3
	s_mul_i32 s6, s36, 0x36000
	s_addc_u32 s17, s13, 0
	s_add_i32 s1, s0, 1
	s_add_i32 s7, s6, 0x12000
	s_mul_hi_i32 s1, s1, 0x12000
	s_add_u32 s7, s12, s7
	s_addc_u32 s1, s13, s1
	s_add_u32 s14, s7, 0x20000
	v_readlane_b32 s7, v254, 44
	s_addc_u32 s15, s1, 0
	s_mul_hi_i32 s0, s0, 0x12000
	v_mov_b32_e32 v2, s7
	ds_read_b32 v2, v2
	s_add_u32 s1, s12, s6
	v_readlane_b32 s7, v254, 45
	s_addc_u32 s6, s13, s0
	s_add_u32 s0, s1, 0x20000
	s_waitcnt lgkmcnt(0)
	v_mov_b32_e32 v4, s7
	v_readlane_b32 s7, v254, 46
	s_addc_u32 s1, s6, 0
	v_readlane_b32 s6, v254, 38
	v_mov_b32_e32 v5, s7
	v_readlane_b32 s7, v254, 47
	v_readfirstlane_b32 s28, v2
	v_mov_b32_e32 v2, s6
	s_waitcnt vmcnt(0)
	v_mov_b32_e32 v134, s7
	ds_read_b32 v4, v4
	ds_read_b32 v5, v5
	ds_read_b32 v134, v134
	ds_read_b32 v2, v2
	v_readlane_b32 s6, v254, 39
	s_waitcnt lgkmcnt(3)
	v_readfirstlane_b32 s29, v4
	s_waitcnt lgkmcnt(2)
	v_readfirstlane_b32 s42, v5
	s_waitcnt lgkmcnt(0)
	v_mov_b32_e32 v2, s6
	ds_read_b32 v2, v2
	v_readlane_b32 s6, v254, 40
	v_readfirstlane_b32 s43, v134
	s_cmp_eq_u64 s[0:1], 0
	s_waitcnt lgkmcnt(0)
	v_mov_b32_e32 v2, s6
	ds_read_b32 v2, v2
	v_readlane_b32 s6, v254, 41
	s_waitcnt lgkmcnt(0)
	s_nop 0
	v_mov_b32_e32 v2, s6
	ds_read_b32 v2, v2
	v_readlane_b32 s6, v255, 18
	s_waitcnt lgkmcnt(0)
	v_lshl_add_u32 v2, v191, 3, s70
	v_lshl_add_u32 v178, s3, 8, v2
	v_add_u32_e32 v4, s6, v189
	v_lshl_add_u32 v180, s4, 8, v4
	v_ashrrev_i32_e32 v179, 31, v178
	v_ashrrev_i32_e32 v181, 31, v180
	s_cbranch_scc1 .LBB0_1113
	s_cmp_eq_u32 s84, 0xff
	s_cbranch_scc1 .Lrfast_wo
	v_lshlrev_b64 v[138:139], 12, v[180:181]
	s_mov_b64 s[0:1], 0x10000
	v_lshl_add_u64 v[212:213], v[138:139], 0, s[0:1]
	s_mov_b64 s[0:1], 0x20000
	v_lshl_add_u64 v[210:211], v[138:139], 0, s[0:1]
	s_mov_b64 s[0:1], 0x30000
	v_lshl_add_u64 v[184:185], v[178:179], 1, s[16:17]
	v_lshl_add_u64 v[208:209], v[138:139], 0, s[0:1]
	v_lshl_add_u64 v[204:205], v[184:185], 0, v[212:213]
	v_lshl_add_u64 v[182:183], v[184:185], 0, v[208:209]
	v_lshl_add_u64 v[186:187], v[184:185], 0, v[210:211]
	global_load_dwordx4 v[170:173], v[204:205], off
	global_load_dwordx4 v[166:169], v[186:187], off
	global_load_dwordx4 v[158:161], v[182:183], off
	v_lshlrev_b32_e32 v4, 3, v4
	v_add_u32_e32 v216, 0, v4
	v_add_u32_e32 v4, 0x20000, v216
	ds_read2_b64 v[174:177], v4 offset1:16
	v_lshl_add_u32 v2, v2, 2, 0
	v_add_u32_e32 v197, 0x20800, v2
	v_add_u32_e32 v199, 0x20c00, v2
	ds_read2_b64 v[162:165], v4 offset0:32 offset1:48
	s_waitcnt lgkmcnt(1)
	v_mul_f32_e32 v201, 0x3a000000, v174
	v_mul_f32_e32 v5, v201, v201
	v_fma_f32 v5, v175, s72, -v5
	v_add_f32_e32 v5, 0x3727c5ac, v5
	ds_read_b128 v[150:153], v197
	ds_read_b128 v[142:145], v197 offset:16
	ds_read_b128 v[154:157], v199
	ds_read_b128 v[146:149], v199 offset:16
	v_rsq_f32_e32 v206, v5
	s_and_b32 s6, s84, 1
	s_bitcmp1_b32 s84, 0
	s_cselect_b64 s[0:1], -1, 0
	s_cmp_eq_u32 s6, 0
	v_lshl_add_u64 v[174:175], v[184:185], 0, v[138:139]
	s_cbranch_scc1 .LBB0_1114
	global_load_dwordx4 v[134:137], v[174:175], off
	v_lshl_add_u64 v[138:139], s[16:17], 0, v[138:139]
	v_lshl_add_u64 v[138:139], v[178:179], 1, v[138:139]
	s_waitcnt vmcnt(0)
	v_lshlrev_b32_e32 v2, 16, v134
	v_and_b32_e32 v134, 0xffff0000, v134
	v_lshlrev_b32_e32 v4, 16, v135
	v_and_b32_e32 v5, 0xffff0000, v135
	v_lshlrev_b32_e32 v207, 16, v137
	v_sub_f32_e32 v5, v5, v201
	v_sub_f32_e32 v4, v4, v201
	v_sub_f32_e32 v135, v134, v201
	v_sub_f32_e32 v134, v2, v201
	v_pk_mul_f32 v[134:135], v[206:207], v[134:135] op_sel_hi:[0,1]
	v_pk_mul_f32 v[4:5], v[206:207], v[4:5] op_sel_hi:[0,1]
	v_lshlrev_b32_e32 v203, 16, v136
	v_and_b32_e32 v136, 0xffff0000, v136
	v_and_b32_e32 v137, 0xffff0000, v137
	s_waitcnt lgkmcnt(1)
	v_pk_fma_f32 v[4:5], v[152:153], v[4:5], v[156:157]
	v_pk_fma_f32 v[134:135], v[150:151], v[134:135], v[154:155]
	v_pk_fma_f32 v[214:215], v[4:5], s[76:77], v[128:129] op_sel_hi:[1,0,1]
	v_pk_fma_f32 v[140:141], v[134:135], s[76:77], v[126:127] op_sel_hi:[1,0,1]
	v_sub_f32_e32 v5, v137, v201
	v_sub_f32_e32 v4, v207, v201
	v_sub_f32_e32 v135, v136, v201
	v_sub_f32_e32 v134, v203, v201
	v_pk_mul_f32 v[134:135], v[206:207], v[134:135] op_sel_hi:[0,1]
	v_pk_mul_f32 v[4:5], v[206:207], v[4:5] op_sel_hi:[0,1]
	s_waitcnt lgkmcnt(0)
	v_pk_fma_f32 v[4:5], v[144:145], v[4:5], v[148:149]
	v_pk_fma_f32 v[134:135], v[142:143], v[134:135], v[146:147]
	v_pk_fma_f32 v[222:223], v[4:5], s[76:77], v[132:133] op_sel_hi:[1,0,1]
	v_pk_fma_f32 v[218:219], v[134:135], s[76:77], v[130:131] op_sel_hi:[1,0,1]
	v_pk_add_f32 v[4:5], v[214:215], v[222:223]
	v_pk_add_f32 v[134:135], v[140:141], v[218:219]
	v_pk_mul_f32 v[136:137], v[218:219], v[218:219]
	v_pk_mul_f32 v[224:225], v[222:223], v[222:223]
	v_pk_fma_f32 v[136:137], v[140:141], v[140:141], v[136:137]
	v_pk_fma_f32 v[224:225], v[214:215], v[214:215], v[224:225]
	v_pk_mov_b32 v[226:227], v[134:135], v[4:5] op_sel:[1,0]
	v_mov_b32_e32 v135, v5
	v_pk_add_f32 v[4:5], v[226:227], v[134:135]
	v_pk_mov_b32 v[134:135], v[136:137], v[224:225] op_sel:[1,0]
	v_mov_b32_e32 v137, v225
	v_pk_add_f32 v[134:135], v[134:135], v[136:137]
	v_add_f32_e32 v2, v4, v5
	v_pk_add_f32 v[134:135], v[134:135], v[134:135] op_sel:[0,1] op_sel_hi:[1,0]
	v_add_f32_e32 v2, 0, v2
	v_mov_b32_e32 v4, v3
	v_mov_b32_e32 v5, v3
	v_mov_b32_e32 v135, v3
	v_mov_b32_e32 v136, v3
	v_mov_b32_e32 v137, v3
	v_cvt_pk_bf16_f32 v224, v140, v141
	v_cvt_pk_bf16_f32 v225, v214, v215
	v_cvt_pk_bf16_f32 v226, v218, v219
	v_cvt_pk_bf16_f32 v227, v222, v223
	global_store_dwordx4 v[138:139], v[224:227], off nt
	s_branch .LBB0_1115

.Lrfast_wo:
	v_lshlrev_b32_e32 v134, 12, v180
	v_lshl_add_u32 v134, v178, 1, v134
	v_add_u32_e32 v135, 0x80000, v134
	v_lshl_add_u32 v138, v191, 4, v180
	v_lshlrev_b32_e32 v138, 3, v138
	s_add_u32 s6, s16, 0x10000
	s_addc_u32 s7, s17, 0
	s_add_u32 s8, s16, 0x20000
	s_addc_u32 s9, s17, 0
	s_add_u32 s10, s16, 0x30000
	s_addc_u32 s11, s17, 0
	v_lshlrev_b32_e32 v136, 3, v4
	v_add_u32_e32 v136, 0x20000, v136
	v_lshlrev_b32_e32 v137, 2, v2
	v_add_u32_e32 v137, 0x20800, v137
	global_load_dwordx4 v[204:207], v134, s[16:17]
	global_load_dwordx4 v[208:211], v134, s[6:7]
	global_load_dwordx4 v[212:215], v134, s[8:9]
	global_load_dwordx4 v[216:219], v134, s[10:11]
	global_load_dwordx4 v[222:225], v134, s[16:17] offset:256
	global_load_dwordx4 v[182:185], v134, s[6:7] offset:256
	global_load_dwordx4 v[166:169], v134, s[8:9] offset:256
	global_load_dwordx4 v[170:173], v134, s[10:11] offset:256
	ds_read2_b64 v[142:145], v136 offset0:0 offset1:16
	ds_read2_b64 v[146:149], v136 offset0:32 offset1:48
	ds_read_b128 v[150:153], v137
	ds_read_b128 v[154:157], v137 offset:16
	ds_read_b128 v[158:161], v137 offset:1024
	ds_read_b128 v[162:165], v137 offset:1040
	v_cmp_lt_i32_e32 vcc, v234, v230
	s_nop 1
	v_cndmask_b32_e32 v201, v228, v234, vcc
	v_cmp_lt_i32_e32 vcc, v195, v230
	s_nop 1
	v_cndmask_b32_e32 v203, v228, v195, vcc
	v_lshlrev_b32_e32 v201, 2, v201
	v_lshlrev_b32_e32 v203, 2, v203
	s_waitcnt lgkmcnt(0)
	v_mul_f32_e32 v142, 0x3a000000, v142
	v_mul_f32_e32 v174, v142, v142
	v_fma_f32 v174, v143, s72, -v174
	v_add_f32_e32 v174, 0x3727c5ac, v174
	v_mul_f32_e32 v144, 0x3a000000, v144
	v_mul_f32_e32 v175, v144, v144
	v_fma_f32 v175, v145, s72, -v175
	v_add_f32_e32 v175, 0x3727c5ac, v175
	v_mul_f32_e32 v146, 0x3a000000, v146
	v_mul_f32_e32 v176, v146, v146
	v_fma_f32 v176, v147, s72, -v176
	v_add_f32_e32 v176, 0x3727c5ac, v176
	v_mul_f32_e32 v148, 0x3a000000, v148
	v_mul_f32_e32 v177, v148, v148
	v_fma_f32 v177, v149, s72, -v177
	v_add_f32_e32 v177, 0x3727c5ac, v177
	v_rsq_f32_e32 v143, v174
	v_rsq_f32_e32 v145, v175
	v_rsq_f32_e32 v147, v176
	v_rsq_f32_e32 v149, v177
	s_nop 0
	s_waitcnt vmcnt(4)
	v_lshlrev_b32_e32 v174, 16, v204
	v_and_b32_e32 v175, 0xffff0000, v204
	v_lshlrev_b32_e32 v176, 16, v205
	v_and_b32_e32 v177, 0xffff0000, v205
	v_lshlrev_b32_e32 v178, 16, v206
	v_and_b32_e32 v179, 0xffff0000, v206
	v_lshlrev_b32_e32 v180, 16, v207
	v_and_b32_e32 v181, 0xffff0000, v207
	v_pk_add_f32 v[174:175], v[174:175], v[142:143] op_sel_hi:[1,0] neg_lo:[0,1] neg_hi:[0,1]
	v_pk_add_f32 v[176:177], v[176:177], v[142:143] op_sel_hi:[1,0] neg_lo:[0,1] neg_hi:[0,1]
	v_pk_add_f32 v[178:179], v[178:179], v[142:143] op_sel_hi:[1,0] neg_lo:[0,1] neg_hi:[0,1]
	v_pk_add_f32 v[180:181], v[180:181], v[142:143] op_sel_hi:[1,0] neg_lo:[0,1] neg_hi:[0,1]
	v_pk_mul_f32 v[174:175], v[142:143], v[174:175] op_sel:[1,0] op_sel_hi:[1,1]
	v_pk_mul_f32 v[176:177], v[142:143], v[176:177] op_sel:[1,0] op_sel_hi:[1,1]
	v_pk_mul_f32 v[178:179], v[142:143], v[178:179] op_sel:[1,0] op_sel_hi:[1,1]
	v_pk_mul_f32 v[180:181], v[142:143], v[180:181] op_sel:[1,0] op_sel_hi:[1,1]
	v_pk_fma_f32 v[174:175], v[150:151], v[174:175], v[158:159]
	v_pk_fma_f32 v[176:177], v[152:153], v[176:177], v[160:161]
	v_pk_fma_f32 v[178:179], v[154:155], v[178:179], v[162:163]
	v_pk_fma_f32 v[180:181], v[156:157], v[180:181], v[164:165]
	v_pk_fma_f32 v[126:127], v[174:175], s[76:77], v[126:127] op_sel_hi:[1,0,1]
	v_pk_fma_f32 v[128:129], v[176:177], s[76:77], v[128:129] op_sel_hi:[1,0,1]
	v_pk_fma_f32 v[130:131], v[178:179], s[76:77], v[130:131] op_sel_hi:[1,0,1]
	v_pk_fma_f32 v[132:133], v[180:181], s[76:77], v[132:133] op_sel_hi:[1,0,1]
	v_pk_add_f32 v[174:175], v[126:127], v[130:131]
	v_pk_add_f32 v[176:177], v[128:129], v[132:133]
	v_pk_mul_f32 v[178:179], v[126:127], v[126:127]
	v_pk_mul_f32 v[180:181], v[128:129], v[128:129]
	v_pk_fma_f32 v[178:179], v[130:131], v[130:131], v[178:179]
	v_pk_fma_f32 v[180:181], v[132:133], v[132:133], v[180:181]
	v_pk_add_f32 v[174:175], v[174:175], v[176:177]
	v_pk_add_f32 v[178:179], v[178:179], v[180:181]
	v_cvt_pk_bf16_f32 v204, v126, v127
	v_cvt_pk_bf16_f32 v205, v128, v129
	v_cvt_pk_bf16_f32 v206, v130, v131
	v_cvt_pk_bf16_f32 v207, v132, v133
	v_add_f32_e32 v2, v174, v175
	v_add_f32_e32 v140, v178, v179
	v_lshlrev_b32_e32 v174, 16, v208
	v_and_b32_e32 v175, 0xffff0000, v208
	v_lshlrev_b32_e32 v176, 16, v209
	v_and_b32_e32 v177, 0xffff0000, v209
	v_lshlrev_b32_e32 v178, 16, v210
	v_and_b32_e32 v179, 0xffff0000, v210
	v_lshlrev_b32_e32 v180, 16, v211
	v_and_b32_e32 v181, 0xffff0000, v211
	v_pk_add_f32 v[174:175], v[174:175], v[144:145] op_sel_hi:[1,0] neg_lo:[0,1] neg_hi:[0,1]
	v_pk_add_f32 v[176:177], v[176:177], v[144:145] op_sel_hi:[1,0] neg_lo:[0,1] neg_hi:[0,1]
	v_pk_add_f32 v[178:179], v[178:179], v[144:145] op_sel_hi:[1,0] neg_lo:[0,1] neg_hi:[0,1]
	v_pk_add_f32 v[180:181], v[180:181], v[144:145] op_sel_hi:[1,0] neg_lo:[0,1] neg_hi:[0,1]
	v_pk_mul_f32 v[174:175], v[144:145], v[174:175] op_sel:[1,0] op_sel_hi:[1,1]
	v_pk_mul_f32 v[176:177], v[144:145], v[176:177] op_sel:[1,0] op_sel_hi:[1,1]
	v_pk_mul_f32 v[178:179], v[144:145], v[178:179] op_sel:[1,0] op_sel_hi:[1,1]
	v_pk_mul_f32 v[180:181], v[144:145], v[180:181] op_sel:[1,0] op_sel_hi:[1,1]
	v_pk_fma_f32 v[174:175], v[150:151], v[174:175], v[158:159]
	v_pk_fma_f32 v[176:177], v[152:153], v[176:177], v[160:161]
	v_pk_fma_f32 v[178:179], v[154:155], v[178:179], v[162:163]
	v_pk_fma_f32 v[180:181], v[156:157], v[180:181], v[164:165]
	v_pk_fma_f32 v[118:119], v[174:175], s[76:77], v[118:119] op_sel_hi:[1,0,1]
	v_pk_fma_f32 v[120:121], v[176:177], s[76:77], v[120:121] op_sel_hi:[1,0,1]
	v_pk_fma_f32 v[122:123], v[178:179], s[76:77], v[122:123] op_sel_hi:[1,0,1]
	v_pk_fma_f32 v[124:125], v[180:181], s[76:77], v[124:125] op_sel_hi:[1,0,1]
	v_pk_add_f32 v[174:175], v[118:119], v[122:123]
	v_pk_add_f32 v[176:177], v[120:121], v[124:125]
	v_pk_mul_f32 v[178:179], v[118:119], v[118:119]
	v_pk_mul_f32 v[180:181], v[120:121], v[120:121]
	v_pk_fma_f32 v[178:179], v[122:123], v[122:123], v[178:179]
	v_pk_fma_f32 v[180:181], v[124:125], v[124:125], v[180:181]
	v_pk_add_f32 v[174:175], v[174:175], v[176:177]
	v_pk_add_f32 v[178:179], v[178:179], v[180:181]
	v_cvt_pk_bf16_f32 v208, v118, v119
	v_cvt_pk_bf16_f32 v209, v120, v121
	v_cvt_pk_bf16_f32 v210, v122, v123
	v_cvt_pk_bf16_f32 v211, v124, v125
	v_add_f32_e32 v4, v174, v175
	v_add_f32_e32 v186, v178, v179
	v_lshlrev_b32_e32 v174, 16, v212
	v_and_b32_e32 v175, 0xffff0000, v212
	v_lshlrev_b32_e32 v176, 16, v213
	v_and_b32_e32 v177, 0xffff0000, v213
	v_lshlrev_b32_e32 v178, 16, v214
	v_and_b32_e32 v179, 0xffff0000, v214
	v_lshlrev_b32_e32 v180, 16, v215
	v_and_b32_e32 v181, 0xffff0000, v215
	v_pk_add_f32 v[174:175], v[174:175], v[146:147] op_sel_hi:[1,0] neg_lo:[0,1] neg_hi:[0,1]
	v_pk_add_f32 v[176:177], v[176:177], v[146:147] op_sel_hi:[1,0] neg_lo:[0,1] neg_hi:[0,1]
	v_pk_add_f32 v[178:179], v[178:179], v[146:147] op_sel_hi:[1,0] neg_lo:[0,1] neg_hi:[0,1]
	v_pk_add_f32 v[180:181], v[180:181], v[146:147] op_sel_hi:[1,0] neg_lo:[0,1] neg_hi:[0,1]
	v_pk_mul_f32 v[174:175], v[146:147], v[174:175] op_sel:[1,0] op_sel_hi:[1,1]
	v_pk_mul_f32 v[176:177], v[146:147], v[176:177] op_sel:[1,0] op_sel_hi:[1,1]
	v_pk_mul_f32 v[178:179], v[146:147], v[178:179] op_sel:[1,0] op_sel_hi:[1,1]
	v_pk_mul_f32 v[180:181], v[146:147], v[180:181] op_sel:[1,0] op_sel_hi:[1,1]
	v_pk_fma_f32 v[174:175], v[150:151], v[174:175], v[158:159]
	v_pk_fma_f32 v[176:177], v[152:153], v[176:177], v[160:161]
	v_pk_fma_f32 v[178:179], v[154:155], v[178:179], v[162:163]
	v_pk_fma_f32 v[180:181], v[156:157], v[180:181], v[164:165]
	v_pk_fma_f32 v[110:111], v[174:175], s[76:77], v[110:111] op_sel_hi:[1,0,1]
	v_pk_fma_f32 v[112:113], v[176:177], s[76:77], v[112:113] op_sel_hi:[1,0,1]
	v_pk_fma_f32 v[114:115], v[178:179], s[76:77], v[114:115] op_sel_hi:[1,0,1]
	v_pk_fma_f32 v[116:117], v[180:181], s[76:77], v[116:117] op_sel_hi:[1,0,1]
	v_pk_add_f32 v[174:175], v[110:111], v[114:115]
	v_pk_add_f32 v[176:177], v[112:113], v[116:117]
	v_pk_mul_f32 v[178:179], v[110:111], v[110:111]
	v_pk_mul_f32 v[180:181], v[112:113], v[112:113]
	v_pk_fma_f32 v[178:179], v[114:115], v[114:115], v[178:179]
	v_pk_fma_f32 v[180:181], v[116:117], v[116:117], v[180:181]
	v_pk_add_f32 v[174:175], v[174:175], v[176:177]
	v_pk_add_f32 v[178:179], v[178:179], v[180:181]
	v_cvt_pk_bf16_f32 v212, v110, v111
	v_cvt_pk_bf16_f32 v213, v112, v113
	v_cvt_pk_bf16_f32 v214, v114, v115
	v_cvt_pk_bf16_f32 v215, v116, v117
	v_add_f32_e32 v5, v174, v175
	v_add_f32_e32 v187, v178, v179
	v_lshlrev_b32_e32 v174, 16, v216
	v_and_b32_e32 v175, 0xffff0000, v216
	v_lshlrev_b32_e32 v176, 16, v217
	v_and_b32_e32 v177, 0xffff0000, v217
	v_lshlrev_b32_e32 v178, 16, v218
	v_and_b32_e32 v179, 0xffff0000, v218
	v_lshlrev_b32_e32 v180, 16, v219
	v_and_b32_e32 v181, 0xffff0000, v219
	v_pk_add_f32 v[174:175], v[174:175], v[148:149] op_sel_hi:[1,0] neg_lo:[0,1] neg_hi:[0,1]
	v_pk_add_f32 v[176:177], v[176:177], v[148:149] op_sel_hi:[1,0] neg_lo:[0,1] neg_hi:[0,1]
	v_pk_add_f32 v[178:179], v[178:179], v[148:149] op_sel_hi:[1,0] neg_lo:[0,1] neg_hi:[0,1]
	v_pk_add_f32 v[180:181], v[180:181], v[148:149] op_sel_hi:[1,0] neg_lo:[0,1] neg_hi:[0,1]
	v_pk_mul_f32 v[174:175], v[148:149], v[174:175] op_sel:[1,0] op_sel_hi:[1,1]
	v_pk_mul_f32 v[176:177], v[148:149], v[176:177] op_sel:[1,0] op_sel_hi:[1,1]
	v_pk_mul_f32 v[178:179], v[148:149], v[178:179] op_sel:[1,0] op_sel_hi:[1,1]
	v_pk_mul_f32 v[180:181], v[148:149], v[180:181] op_sel:[1,0] op_sel_hi:[1,1]
	v_pk_fma_f32 v[174:175], v[150:151], v[174:175], v[158:159]
	v_pk_fma_f32 v[176:177], v[152:153], v[176:177], v[160:161]
	v_pk_fma_f32 v[178:179], v[154:155], v[178:179], v[162:163]
	v_pk_fma_f32 v[180:181], v[156:157], v[180:181], v[164:165]
	v_pk_fma_f32 v[102:103], v[174:175], s[76:77], v[102:103] op_sel_hi:[1,0,1]
	v_pk_fma_f32 v[104:105], v[176:177], s[76:77], v[104:105] op_sel_hi:[1,0,1]
	v_pk_fma_f32 v[106:107], v[178:179], s[76:77], v[106:107] op_sel_hi:[1,0,1]
	v_pk_fma_f32 v[108:109], v[180:181], s[76:77], v[108:109] op_sel_hi:[1,0,1]
	v_pk_add_f32 v[174:175], v[102:103], v[106:107]
	v_pk_add_f32 v[176:177], v[104:105], v[108:109]
	v_pk_mul_f32 v[178:179], v[102:103], v[102:103]
	v_pk_mul_f32 v[180:181], v[104:105], v[104:105]
	v_pk_fma_f32 v[178:179], v[106:107], v[106:107], v[178:179]
	v_pk_fma_f32 v[180:181], v[108:109], v[108:109], v[180:181]
	v_pk_add_f32 v[174:175], v[174:175], v[176:177]
	v_pk_add_f32 v[178:179], v[178:179], v[180:181]
	v_cvt_pk_bf16_f32 v216, v102, v103
	v_cvt_pk_bf16_f32 v217, v104, v105
	v_cvt_pk_bf16_f32 v218, v106, v107
	v_cvt_pk_bf16_f32 v219, v108, v109
	v_add_f32_e32 v139, v174, v175
	v_add_f32_e32 v197, v178, v179
	global_load_dwordx4 v[102:105], v135, s[16:17]
	global_load_dwordx4 v[106:109], v135, s[6:7]
	global_load_dwordx4 v[110:113], v135, s[8:9]
	global_load_dwordx4 v[114:117], v135, s[10:11]
	global_load_dwordx4 v[118:121], v135, s[16:17] offset:256
	global_load_dwordx4 v[122:125], v135, s[6:7] offset:256
	global_load_dwordx4 v[126:129], v135, s[8:9] offset:256
	global_load_dwordx4 v[130:133], v135, s[10:11] offset:256
	global_store_dwordx4 v134, v[204:207], s[16:17] nt
	global_store_dwordx4 v134, v[208:211], s[6:7] nt
	global_store_dwordx4 v134, v[212:215], s[8:9] nt
	global_store_dwordx4 v134, v[216:219], s[10:11] nt
	ds_read_b128 v[150:153], v137 offset:512
	ds_read_b128 v[154:157], v137 offset:528
	ds_read_b128 v[158:161], v137 offset:1536
	ds_read_b128 v[162:165], v137 offset:1552
	s_waitcnt lgkmcnt(0)
	s_waitcnt vmcnt(12)
	v_lshlrev_b32_e32 v174, 16, v222
	v_and_b32_e32 v175, 0xffff0000, v222
	v_lshlrev_b32_e32 v176, 16, v223
	v_and_b32_e32 v177, 0xffff0000, v223
	v_lshlrev_b32_e32 v178, 16, v224
	v_and_b32_e32 v179, 0xffff0000, v224
	v_lshlrev_b32_e32 v180, 16, v225
	v_and_b32_e32 v181, 0xffff0000, v225
	v_pk_add_f32 v[174:175], v[174:175], v[142:143] op_sel_hi:[1,0] neg_lo:[0,1] neg_hi:[0,1]
	v_pk_add_f32 v[176:177], v[176:177], v[142:143] op_sel_hi:[1,0] neg_lo:[0,1] neg_hi:[0,1]
	v_pk_add_f32 v[178:179], v[178:179], v[142:143] op_sel_hi:[1,0] neg_lo:[0,1] neg_hi:[0,1]
	v_pk_add_f32 v[180:181], v[180:181], v[142:143] op_sel_hi:[1,0] neg_lo:[0,1] neg_hi:[0,1]
	v_pk_mul_f32 v[174:175], v[142:143], v[174:175] op_sel:[1,0] op_sel_hi:[1,1]
	v_pk_mul_f32 v[176:177], v[142:143], v[176:177] op_sel:[1,0] op_sel_hi:[1,1]
	v_pk_mul_f32 v[178:179], v[142:143], v[178:179] op_sel:[1,0] op_sel_hi:[1,1]
	v_pk_mul_f32 v[180:181], v[142:143], v[180:181] op_sel:[1,0] op_sel_hi:[1,1]
	v_pk_fma_f32 v[174:175], v[150:151], v[174:175], v[158:159]
	v_pk_fma_f32 v[176:177], v[152:153], v[176:177], v[160:161]
	v_pk_fma_f32 v[178:179], v[154:155], v[178:179], v[162:163]
	v_pk_fma_f32 v[180:181], v[156:157], v[180:181], v[164:165]
	v_pk_fma_f32 v[94:95], v[174:175], s[76:77], v[94:95] op_sel_hi:[1,0,1]
	v_pk_fma_f32 v[96:97], v[176:177], s[76:77], v[96:97] op_sel_hi:[1,0,1]
	v_pk_fma_f32 v[98:99], v[178:179], s[76:77], v[98:99] op_sel_hi:[1,0,1]
	v_pk_fma_f32 v[100:101], v[180:181], s[76:77], v[100:101] op_sel_hi:[1,0,1]
	v_pk_add_f32 v[174:175], v[94:95], v[98:99]
	v_pk_add_f32 v[176:177], v[96:97], v[100:101]
	v_pk_mul_f32 v[178:179], v[94:95], v[94:95]
	v_pk_mul_f32 v[180:181], v[96:97], v[96:97]
	v_pk_fma_f32 v[178:179], v[98:99], v[98:99], v[178:179]
	v_pk_fma_f32 v[180:181], v[100:101], v[100:101], v[180:181]
	v_pk_add_f32 v[174:175], v[174:175], v[176:177]
	v_pk_add_f32 v[178:179], v[178:179], v[180:181]
	v_cvt_pk_bf16_f32 v222, v94, v95
	v_cvt_pk_bf16_f32 v223, v96, v97
	v_cvt_pk_bf16_f32 v224, v98, v99
	v_cvt_pk_bf16_f32 v225, v100, v101
	v_add_f32_e32 v174, v174, v175
	v_add_f32_e32 v178, v178, v179
	v_add_f32_e32 v2, v2, v174
	v_add_f32_e32 v140, v140, v178
	v_lshlrev_b32_e32 v174, 16, v182
	v_and_b32_e32 v175, 0xffff0000, v182
	v_lshlrev_b32_e32 v176, 16, v183
	v_and_b32_e32 v177, 0xffff0000, v183
	v_lshlrev_b32_e32 v178, 16, v184
	v_and_b32_e32 v179, 0xffff0000, v184
	v_lshlrev_b32_e32 v180, 16, v185
	v_and_b32_e32 v181, 0xffff0000, v185
	v_pk_add_f32 v[174:175], v[174:175], v[144:145] op_sel_hi:[1,0] neg_lo:[0,1] neg_hi:[0,1]
	v_pk_add_f32 v[176:177], v[176:177], v[144:145] op_sel_hi:[1,0] neg_lo:[0,1] neg_hi:[0,1]
	v_pk_add_f32 v[178:179], v[178:179], v[144:145] op_sel_hi:[1,0] neg_lo:[0,1] neg_hi:[0,1]
	v_pk_add_f32 v[180:181], v[180:181], v[144:145] op_sel_hi:[1,0] neg_lo:[0,1] neg_hi:[0,1]
	v_pk_mul_f32 v[174:175], v[144:145], v[174:175] op_sel:[1,0] op_sel_hi:[1,1]
	v_pk_mul_f32 v[176:177], v[144:145], v[176:177] op_sel:[1,0] op_sel_hi:[1,1]
	v_pk_mul_f32 v[178:179], v[144:145], v[178:179] op_sel:[1,0] op_sel_hi:[1,1]
	v_pk_mul_f32 v[180:181], v[144:145], v[180:181] op_sel:[1,0] op_sel_hi:[1,1]
	v_pk_fma_f32 v[174:175], v[150:151], v[174:175], v[158:159]
	v_pk_fma_f32 v[176:177], v[152:153], v[176:177], v[160:161]
	v_pk_fma_f32 v[178:179], v[154:155], v[178:179], v[162:163]
	v_pk_fma_f32 v[180:181], v[156:157], v[180:181], v[164:165]
	v_pk_fma_f32 v[86:87], v[174:175], s[76:77], v[86:87] op_sel_hi:[1,0,1]
	v_pk_fma_f32 v[88:89], v[176:177], s[76:77], v[88:89] op_sel_hi:[1,0,1]
	v_pk_fma_f32 v[90:91], v[178:179], s[76:77], v[90:91] op_sel_hi:[1,0,1]
	v_pk_fma_f32 v[92:93], v[180:181], s[76:77], v[92:93] op_sel_hi:[1,0,1]
	v_pk_add_f32 v[174:175], v[86:87], v[90:91]
	v_pk_add_f32 v[176:177], v[88:89], v[92:93]
	v_pk_mul_f32 v[178:179], v[86:87], v[86:87]
	v_pk_mul_f32 v[180:181], v[88:89], v[88:89]
	v_pk_fma_f32 v[178:179], v[90:91], v[90:91], v[178:179]
	v_pk_fma_f32 v[180:181], v[92:93], v[92:93], v[180:181]
	v_pk_add_f32 v[174:175], v[174:175], v[176:177]
	v_pk_add_f32 v[178:179], v[178:179], v[180:181]
	v_cvt_pk_bf16_f32 v182, v86, v87
	v_cvt_pk_bf16_f32 v183, v88, v89
	v_cvt_pk_bf16_f32 v184, v90, v91
	v_cvt_pk_bf16_f32 v185, v92, v93
	v_add_f32_e32 v174, v174, v175
	v_add_f32_e32 v178, v178, v179
	v_add_f32_e32 v4, v4, v174
	v_add_f32_e32 v186, v186, v178
	v_lshlrev_b32_e32 v174, 16, v166
	v_and_b32_e32 v175, 0xffff0000, v166
	v_lshlrev_b32_e32 v176, 16, v167
	v_and_b32_e32 v177, 0xffff0000, v167
	v_lshlrev_b32_e32 v178, 16, v168
	v_and_b32_e32 v179, 0xffff0000, v168
	v_lshlrev_b32_e32 v180, 16, v169
	v_and_b32_e32 v181, 0xffff0000, v169
	v_pk_add_f32 v[174:175], v[174:175], v[146:147] op_sel_hi:[1,0] neg_lo:[0,1] neg_hi:[0,1]
	v_pk_add_f32 v[176:177], v[176:177], v[146:147] op_sel_hi:[1,0] neg_lo:[0,1] neg_hi:[0,1]
	v_pk_add_f32 v[178:179], v[178:179], v[146:147] op_sel_hi:[1,0] neg_lo:[0,1] neg_hi:[0,1]
	v_pk_add_f32 v[180:181], v[180:181], v[146:147] op_sel_hi:[1,0] neg_lo:[0,1] neg_hi:[0,1]
	v_pk_mul_f32 v[174:175], v[146:147], v[174:175] op_sel:[1,0] op_sel_hi:[1,1]
	v_pk_mul_f32 v[176:177], v[146:147], v[176:177] op_sel:[1,0] op_sel_hi:[1,1]
	v_pk_mul_f32 v[178:179], v[146:147], v[178:179] op_sel:[1,0] op_sel_hi:[1,1]
	v_pk_mul_f32 v[180:181], v[146:147], v[180:181] op_sel:[1,0] op_sel_hi:[1,1]
	v_pk_fma_f32 v[174:175], v[150:151], v[174:175], v[158:159]
	v_pk_fma_f32 v[176:177], v[152:153], v[176:177], v[160:161]
	v_pk_fma_f32 v[178:179], v[154:155], v[178:179], v[162:163]
	v_pk_fma_f32 v[180:181], v[156:157], v[180:181], v[164:165]
	v_pk_fma_f32 v[78:79], v[174:175], s[76:77], v[78:79] op_sel_hi:[1,0,1]
	v_pk_fma_f32 v[80:81], v[176:177], s[76:77], v[80:81] op_sel_hi:[1,0,1]
	v_pk_fma_f32 v[82:83], v[178:179], s[76:77], v[82:83] op_sel_hi:[1,0,1]
	v_pk_fma_f32 v[84:85], v[180:181], s[76:77], v[84:85] op_sel_hi:[1,0,1]
	v_pk_add_f32 v[174:175], v[78:79], v[82:83]
	v_pk_add_f32 v[176:177], v[80:81], v[84:85]
	v_pk_mul_f32 v[178:179], v[78:79], v[78:79]
	v_pk_mul_f32 v[180:181], v[80:81], v[80:81]
	v_pk_fma_f32 v[178:179], v[82:83], v[82:83], v[178:179]
	v_pk_fma_f32 v[180:181], v[84:85], v[84:85], v[180:181]
	v_pk_add_f32 v[174:175], v[174:175], v[176:177]
	v_pk_add_f32 v[178:179], v[178:179], v[180:181]
	v_cvt_pk_bf16_f32 v166, v78, v79
	v_cvt_pk_bf16_f32 v167, v80, v81
	v_cvt_pk_bf16_f32 v168, v82, v83
	v_cvt_pk_bf16_f32 v169, v84, v85
	v_add_f32_e32 v174, v174, v175
	v_add_f32_e32 v178, v178, v179
	v_add_f32_e32 v5, v5, v174
	v_add_f32_e32 v187, v187, v178
	v_lshlrev_b32_e32 v174, 16, v170
	v_and_b32_e32 v175, 0xffff0000, v170
	v_lshlrev_b32_e32 v176, 16, v171
	v_and_b32_e32 v177, 0xffff0000, v171
	v_lshlrev_b32_e32 v178, 16, v172
	v_and_b32_e32 v179, 0xffff0000, v172
	v_lshlrev_b32_e32 v180, 16, v173
	v_and_b32_e32 v181, 0xffff0000, v173
	v_pk_add_f32 v[174:175], v[174:175], v[148:149] op_sel_hi:[1,0] neg_lo:[0,1] neg_hi:[0,1]
	v_pk_add_f32 v[176:177], v[176:177], v[148:149] op_sel_hi:[1,0] neg_lo:[0,1] neg_hi:[0,1]
	v_pk_add_f32 v[178:179], v[178:179], v[148:149] op_sel_hi:[1,0] neg_lo:[0,1] neg_hi:[0,1]
	v_pk_add_f32 v[180:181], v[180:181], v[148:149] op_sel_hi:[1,0] neg_lo:[0,1] neg_hi:[0,1]
	v_pk_mul_f32 v[174:175], v[148:149], v[174:175] op_sel:[1,0] op_sel_hi:[1,1]
	v_pk_mul_f32 v[176:177], v[148:149], v[176:177] op_sel:[1,0] op_sel_hi:[1,1]
	v_pk_mul_f32 v[178:179], v[148:149], v[178:179] op_sel:[1,0] op_sel_hi:[1,1]
	v_pk_mul_f32 v[180:181], v[148:149], v[180:181] op_sel:[1,0] op_sel_hi:[1,1]
	v_pk_fma_f32 v[174:175], v[150:151], v[174:175], v[158:159]
	v_pk_fma_f32 v[176:177], v[152:153], v[176:177], v[160:161]
	v_pk_fma_f32 v[178:179], v[154:155], v[178:179], v[162:163]
	v_pk_fma_f32 v[180:181], v[156:157], v[180:181], v[164:165]
	v_pk_fma_f32 v[70:71], v[174:175], s[76:77], v[70:71] op_sel_hi:[1,0,1]
	v_pk_fma_f32 v[72:73], v[176:177], s[76:77], v[72:73] op_sel_hi:[1,0,1]
	v_pk_fma_f32 v[74:75], v[178:179], s[76:77], v[74:75] op_sel_hi:[1,0,1]
	v_pk_fma_f32 v[76:77], v[180:181], s[76:77], v[76:77] op_sel_hi:[1,0,1]
	v_pk_add_f32 v[174:175], v[70:71], v[74:75]
	v_pk_add_f32 v[176:177], v[72:73], v[76:77]
	v_pk_mul_f32 v[178:179], v[70:71], v[70:71]
	v_pk_mul_f32 v[180:181], v[72:73], v[72:73]
	v_pk_fma_f32 v[178:179], v[74:75], v[74:75], v[178:179]
	v_pk_fma_f32 v[180:181], v[76:77], v[76:77], v[180:181]
	v_pk_add_f32 v[174:175], v[174:175], v[176:177]
	v_pk_add_f32 v[178:179], v[178:179], v[180:181]
	v_cvt_pk_bf16_f32 v170, v70, v71
	v_cvt_pk_bf16_f32 v171, v72, v73
	v_cvt_pk_bf16_f32 v172, v74, v75
	v_cvt_pk_bf16_f32 v173, v76, v77
	v_add_f32_e32 v174, v174, v175
	v_add_f32_e32 v178, v178, v179
	v_add_f32_e32 v139, v139, v174
	v_add_f32_e32 v197, v197, v178
	global_store_dwordx4 v134, v[222:225], s[16:17] offset:256 nt
	global_store_dwordx4 v134, v[182:185], s[6:7] offset:256 nt
	global_store_dwordx4 v134, v[166:169], s[8:9] offset:256 nt
	global_store_dwordx4 v134, v[170:173], s[10:11] offset:256 nt
	ds_bpermute_b32 v174, v201, v2
	ds_bpermute_b32 v175, v201, v4
	ds_bpermute_b32 v176, v201, v5
	ds_bpermute_b32 v177, v201, v139
	ds_bpermute_b32 v178, v201, v140
	ds_bpermute_b32 v179, v201, v186
	ds_bpermute_b32 v180, v201, v187
	ds_bpermute_b32 v181, v201, v197
	s_waitcnt lgkmcnt(0)
	v_add_f32_e32 v2, v2, v174
	v_add_f32_e32 v4, v4, v175
	v_add_f32_e32 v5, v5, v176
	v_add_f32_e32 v139, v139, v177
	v_add_f32_e32 v140, v140, v178
	v_add_f32_e32 v186, v186, v179
	v_add_f32_e32 v187, v187, v180
	v_add_f32_e32 v197, v197, v181
	ds_bpermute_b32 v174, v203, v2
	ds_bpermute_b32 v175, v203, v4
	ds_bpermute_b32 v176, v203, v5
	ds_bpermute_b32 v177, v203, v139
	ds_bpermute_b32 v178, v203, v140
	ds_bpermute_b32 v179, v203, v186
	ds_bpermute_b32 v180, v203, v187
	ds_bpermute_b32 v181, v203, v197
	s_waitcnt lgkmcnt(0)
	v_add_f32_e32 v2, v2, v174
	v_add_f32_e32 v4, v4, v175
	v_add_f32_e32 v5, v5, v176
	v_add_f32_e32 v139, v139, v177
	v_add_f32_e32 v140, v140, v178
	v_add_f32_e32 v186, v186, v179
	v_add_f32_e32 v187, v187, v180
	v_add_f32_e32 v197, v197, v181
	v_cmp_eq_u32_e32 vcc, 1, v191
	s_nop 1
	v_cndmask_b32_e32 v2, v2, v4, vcc
	v_cndmask_b32_e32 v140, v140, v186, vcc
	v_cmp_eq_u32_e32 vcc, 2, v191
	s_nop 1
	v_cndmask_b32_e32 v2, v2, v5, vcc
	v_cndmask_b32_e32 v140, v140, v187, vcc
	v_cmp_eq_u32_e32 vcc, 3, v191
	s_nop 1
	v_cndmask_b32_e32 v2, v2, v139, vcc
	v_cndmask_b32_e32 v140, v140, v197, vcc
	global_atomic_add_f32 v138, v2, s[14:15]
	global_atomic_add_f32 v138, v140, s[14:15] offset:4
	ds_read2_b64 v[142:145], v136 offset0:128 offset1:144
	ds_read2_b64 v[146:149], v136 offset0:160 offset1:176
	ds_read_b128 v[150:153], v137
	ds_read_b128 v[154:157], v137 offset:16
	ds_read_b128 v[158:161], v137 offset:1024
	ds_read_b128 v[162:165], v137 offset:1040
	s_waitcnt lgkmcnt(0)
	v_mul_f32_e32 v142, 0x3a000000, v142
	v_mul_f32_e32 v174, v142, v142
	v_fma_f32 v174, v143, s72, -v174
	v_add_f32_e32 v174, 0x3727c5ac, v174
	v_mul_f32_e32 v144, 0x3a000000, v144
	v_mul_f32_e32 v175, v144, v144
	v_fma_f32 v175, v145, s72, -v175
	v_add_f32_e32 v175, 0x3727c5ac, v175
	v_mul_f32_e32 v146, 0x3a000000, v146
	v_mul_f32_e32 v176, v146, v146
	v_fma_f32 v176, v147, s72, -v176
	v_add_f32_e32 v176, 0x3727c5ac, v176
	v_mul_f32_e32 v148, 0x3a000000, v148
	v_mul_f32_e32 v177, v148, v148
	v_fma_f32 v177, v149, s72, -v177
	v_add_f32_e32 v177, 0x3727c5ac, v177
	v_rsq_f32_e32 v143, v174
	v_rsq_f32_e32 v145, v175
	v_rsq_f32_e32 v147, v176
	v_rsq_f32_e32 v149, v177
	s_nop 0
	s_waitcnt vmcnt(14)
	v_lshlrev_b32_e32 v174, 16, v102
	v_and_b32_e32 v175, 0xffff0000, v102
	v_lshlrev_b32_e32 v176, 16, v103
	v_and_b32_e32 v177, 0xffff0000, v103
	v_lshlrev_b32_e32 v178, 16, v104
	v_and_b32_e32 v179, 0xffff0000, v104
	v_lshlrev_b32_e32 v180, 16, v105
	v_and_b32_e32 v181, 0xffff0000, v105
	v_pk_add_f32 v[174:175], v[174:175], v[142:143] op_sel_hi:[1,0] neg_lo:[0,1] neg_hi:[0,1]
	v_pk_add_f32 v[176:177], v[176:177], v[142:143] op_sel_hi:[1,0] neg_lo:[0,1] neg_hi:[0,1]
	v_pk_add_f32 v[178:179], v[178:179], v[142:143] op_sel_hi:[1,0] neg_lo:[0,1] neg_hi:[0,1]
	v_pk_add_f32 v[180:181], v[180:181], v[142:143] op_sel_hi:[1,0] neg_lo:[0,1] neg_hi:[0,1]
	v_pk_mul_f32 v[174:175], v[142:143], v[174:175] op_sel:[1,0] op_sel_hi:[1,1]
	v_pk_mul_f32 v[176:177], v[142:143], v[176:177] op_sel:[1,0] op_sel_hi:[1,1]
	v_pk_mul_f32 v[178:179], v[142:143], v[178:179] op_sel:[1,0] op_sel_hi:[1,1]
	v_pk_mul_f32 v[180:181], v[142:143], v[180:181] op_sel:[1,0] op_sel_hi:[1,1]
	v_pk_fma_f32 v[174:175], v[150:151], v[174:175], v[158:159]
	v_pk_fma_f32 v[176:177], v[152:153], v[176:177], v[160:161]
	v_pk_fma_f32 v[178:179], v[154:155], v[178:179], v[162:163]
	v_pk_fma_f32 v[180:181], v[156:157], v[180:181], v[164:165]
	v_pk_fma_f32 v[46:47], v[174:175], s[76:77], v[46:47] op_sel_hi:[1,0,1]
	v_pk_fma_f32 v[48:49], v[176:177], s[76:77], v[48:49] op_sel_hi:[1,0,1]
	v_pk_fma_f32 v[50:51], v[178:179], s[76:77], v[50:51] op_sel_hi:[1,0,1]
	v_pk_fma_f32 v[52:53], v[180:181], s[76:77], v[52:53] op_sel_hi:[1,0,1]
	v_pk_add_f32 v[174:175], v[46:47], v[50:51]
	v_pk_add_f32 v[176:177], v[48:49], v[52:53]
	v_pk_mul_f32 v[178:179], v[46:47], v[46:47]
	v_pk_mul_f32 v[180:181], v[48:49], v[48:49]
	v_pk_fma_f32 v[178:179], v[50:51], v[50:51], v[178:179]
	v_pk_fma_f32 v[180:181], v[52:53], v[52:53], v[180:181]
	v_pk_add_f32 v[174:175], v[174:175], v[176:177]
	v_pk_add_f32 v[178:179], v[178:179], v[180:181]
	v_cvt_pk_bf16_f32 v102, v46, v47
	v_cvt_pk_bf16_f32 v103, v48, v49
	v_cvt_pk_bf16_f32 v104, v50, v51
	v_cvt_pk_bf16_f32 v105, v52, v53
	v_add_f32_e32 v2, v174, v175
	v_add_f32_e32 v140, v178, v179
	v_lshlrev_b32_e32 v174, 16, v106
	v_and_b32_e32 v175, 0xffff0000, v106
	v_lshlrev_b32_e32 v176, 16, v107
	v_and_b32_e32 v177, 0xffff0000, v107
	v_lshlrev_b32_e32 v178, 16, v108
	v_and_b32_e32 v179, 0xffff0000, v108
	v_lshlrev_b32_e32 v180, 16, v109
	v_and_b32_e32 v181, 0xffff0000, v109
	v_pk_add_f32 v[174:175], v[174:175], v[144:145] op_sel_hi:[1,0] neg_lo:[0,1] neg_hi:[0,1]
	v_pk_add_f32 v[176:177], v[176:177], v[144:145] op_sel_hi:[1,0] neg_lo:[0,1] neg_hi:[0,1]
	v_pk_add_f32 v[178:179], v[178:179], v[144:145] op_sel_hi:[1,0] neg_lo:[0,1] neg_hi:[0,1]
	v_pk_add_f32 v[180:181], v[180:181], v[144:145] op_sel_hi:[1,0] neg_lo:[0,1] neg_hi:[0,1]
	v_pk_mul_f32 v[174:175], v[144:145], v[174:175] op_sel:[1,0] op_sel_hi:[1,1]
	v_pk_mul_f32 v[176:177], v[144:145], v[176:177] op_sel:[1,0] op_sel_hi:[1,1]
	v_pk_mul_f32 v[178:179], v[144:145], v[178:179] op_sel:[1,0] op_sel_hi:[1,1]
	v_pk_mul_f32 v[180:181], v[144:145], v[180:181] op_sel:[1,0] op_sel_hi:[1,1]
	v_pk_fma_f32 v[174:175], v[150:151], v[174:175], v[158:159]
	v_pk_fma_f32 v[176:177], v[152:153], v[176:177], v[160:161]
	v_pk_fma_f32 v[178:179], v[154:155], v[178:179], v[162:163]
	v_pk_fma_f32 v[180:181], v[156:157], v[180:181], v[164:165]
	v_pk_fma_f32 v[38:39], v[174:175], s[76:77], v[38:39] op_sel_hi:[1,0,1]
	v_pk_fma_f32 v[40:41], v[176:177], s[76:77], v[40:41] op_sel_hi:[1,0,1]
	v_pk_fma_f32 v[42:43], v[178:179], s[76:77], v[42:43] op_sel_hi:[1,0,1]
	v_pk_fma_f32 v[44:45], v[180:181], s[76:77], v[44:45] op_sel_hi:[1,0,1]
	v_pk_add_f32 v[174:175], v[38:39], v[42:43]
	v_pk_add_f32 v[176:177], v[40:41], v[44:45]
	v_pk_mul_f32 v[178:179], v[38:39], v[38:39]
	v_pk_mul_f32 v[180:181], v[40:41], v[40:41]
	v_pk_fma_f32 v[178:179], v[42:43], v[42:43], v[178:179]
	v_pk_fma_f32 v[180:181], v[44:45], v[44:45], v[180:181]
	v_pk_add_f32 v[174:175], v[174:175], v[176:177]
	v_pk_add_f32 v[178:179], v[178:179], v[180:181]
	v_cvt_pk_bf16_f32 v106, v38, v39
	v_cvt_pk_bf16_f32 v107, v40, v41
	v_cvt_pk_bf16_f32 v108, v42, v43
	v_cvt_pk_bf16_f32 v109, v44, v45
	v_add_f32_e32 v4, v174, v175
	v_add_f32_e32 v186, v178, v179
	v_lshlrev_b32_e32 v174, 16, v110
	v_and_b32_e32 v175, 0xffff0000, v110
	v_lshlrev_b32_e32 v176, 16, v111
	v_and_b32_e32 v177, 0xffff0000, v111
	v_lshlrev_b32_e32 v178, 16, v112
	v_and_b32_e32 v179, 0xffff0000, v112
	v_lshlrev_b32_e32 v180, 16, v113
	v_and_b32_e32 v181, 0xffff0000, v113
	v_pk_add_f32 v[174:175], v[174:175], v[146:147] op_sel_hi:[1,0] neg_lo:[0,1] neg_hi:[0,1]
	v_pk_add_f32 v[176:177], v[176:177], v[146:147] op_sel_hi:[1,0] neg_lo:[0,1] neg_hi:[0,1]
	v_pk_add_f32 v[178:179], v[178:179], v[146:147] op_sel_hi:[1,0] neg_lo:[0,1] neg_hi:[0,1]
	v_pk_add_f32 v[180:181], v[180:181], v[146:147] op_sel_hi:[1,0] neg_lo:[0,1] neg_hi:[0,1]
	v_pk_mul_f32 v[174:175], v[146:147], v[174:175] op_sel:[1,0] op_sel_hi:[1,1]
	v_pk_mul_f32 v[176:177], v[146:147], v[176:177] op_sel:[1,0] op_sel_hi:[1,1]
	v_pk_mul_f32 v[178:179], v[146:147], v[178:179] op_sel:[1,0] op_sel_hi:[1,1]
	v_pk_mul_f32 v[180:181], v[146:147], v[180:181] op_sel:[1,0] op_sel_hi:[1,1]
	v_pk_fma_f32 v[174:175], v[150:151], v[174:175], v[158:159]
	v_pk_fma_f32 v[176:177], v[152:153], v[176:177], v[160:161]
	v_pk_fma_f32 v[178:179], v[154:155], v[178:179], v[162:163]
	v_pk_fma_f32 v[180:181], v[156:157], v[180:181], v[164:165]
	v_pk_fma_f32 v[30:31], v[174:175], s[76:77], v[30:31] op_sel_hi:[1,0,1]
	v_pk_fma_f32 v[32:33], v[176:177], s[76:77], v[32:33] op_sel_hi:[1,0,1]
	v_pk_fma_f32 v[34:35], v[178:179], s[76:77], v[34:35] op_sel_hi:[1,0,1]
	v_pk_fma_f32 v[36:37], v[180:181], s[76:77], v[36:37] op_sel_hi:[1,0,1]
	v_pk_add_f32 v[174:175], v[30:31], v[34:35]
	v_pk_add_f32 v[176:177], v[32:33], v[36:37]
	v_pk_mul_f32 v[178:179], v[30:31], v[30:31]
	v_pk_mul_f32 v[180:181], v[32:33], v[32:33]
	v_pk_fma_f32 v[178:179], v[34:35], v[34:35], v[178:179]
	v_pk_fma_f32 v[180:181], v[36:37], v[36:37], v[180:181]
	v_pk_add_f32 v[174:175], v[174:175], v[176:177]
	v_pk_add_f32 v[178:179], v[178:179], v[180:181]
	v_cvt_pk_bf16_f32 v110, v30, v31
	v_cvt_pk_bf16_f32 v111, v32, v33
	v_cvt_pk_bf16_f32 v112, v34, v35
	v_cvt_pk_bf16_f32 v113, v36, v37
	v_add_f32_e32 v5, v174, v175
	v_add_f32_e32 v187, v178, v179
	v_lshlrev_b32_e32 v174, 16, v114
	v_and_b32_e32 v175, 0xffff0000, v114
	v_lshlrev_b32_e32 v176, 16, v115
	v_and_b32_e32 v177, 0xffff0000, v115
	v_lshlrev_b32_e32 v178, 16, v116
	v_and_b32_e32 v179, 0xffff0000, v116
	v_lshlrev_b32_e32 v180, 16, v117
	v_and_b32_e32 v181, 0xffff0000, v117
	v_pk_add_f32 v[174:175], v[174:175], v[148:149] op_sel_hi:[1,0] neg_lo:[0,1] neg_hi:[0,1]
	v_pk_add_f32 v[176:177], v[176:177], v[148:149] op_sel_hi:[1,0] neg_lo:[0,1] neg_hi:[0,1]
	v_pk_add_f32 v[178:179], v[178:179], v[148:149] op_sel_hi:[1,0] neg_lo:[0,1] neg_hi:[0,1]
	v_pk_add_f32 v[180:181], v[180:181], v[148:149] op_sel_hi:[1,0] neg_lo:[0,1] neg_hi:[0,1]
	v_pk_mul_f32 v[174:175], v[148:149], v[174:175] op_sel:[1,0] op_sel_hi:[1,1]
	v_pk_mul_f32 v[176:177], v[148:149], v[176:177] op_sel:[1,0] op_sel_hi:[1,1]
	v_pk_mul_f32 v[178:179], v[148:149], v[178:179] op_sel:[1,0] op_sel_hi:[1,1]
	v_pk_mul_f32 v[180:181], v[148:149], v[180:181] op_sel:[1,0] op_sel_hi:[1,1]
	v_pk_fma_f32 v[174:175], v[150:151], v[174:175], v[158:159]
	v_pk_fma_f32 v[176:177], v[152:153], v[176:177], v[160:161]
	v_pk_fma_f32 v[178:179], v[154:155], v[178:179], v[162:163]
	v_pk_fma_f32 v[180:181], v[156:157], v[180:181], v[164:165]
	v_pk_fma_f32 v[22:23], v[174:175], s[76:77], v[22:23] op_sel_hi:[1,0,1]
	v_pk_fma_f32 v[24:25], v[176:177], s[76:77], v[24:25] op_sel_hi:[1,0,1]
	v_pk_fma_f32 v[26:27], v[178:179], s[76:77], v[26:27] op_sel_hi:[1,0,1]
	v_pk_fma_f32 v[28:29], v[180:181], s[76:77], v[28:29] op_sel_hi:[1,0,1]
	v_pk_add_f32 v[174:175], v[22:23], v[26:27]
	v_pk_add_f32 v[176:177], v[24:25], v[28:29]
	v_pk_mul_f32 v[178:179], v[22:23], v[22:23]
	v_pk_mul_f32 v[180:181], v[24:25], v[24:25]
	v_pk_fma_f32 v[178:179], v[26:27], v[26:27], v[178:179]
	v_pk_fma_f32 v[180:181], v[28:29], v[28:29], v[180:181]
	v_pk_add_f32 v[174:175], v[174:175], v[176:177]
	v_pk_add_f32 v[178:179], v[178:179], v[180:181]
	v_cvt_pk_bf16_f32 v114, v22, v23
	v_cvt_pk_bf16_f32 v115, v24, v25
	v_cvt_pk_bf16_f32 v116, v26, v27
	v_cvt_pk_bf16_f32 v117, v28, v29
	v_add_f32_e32 v139, v174, v175
	v_add_f32_e32 v197, v178, v179
	global_store_dwordx4 v135, v[102:105], s[16:17] nt
	global_store_dwordx4 v135, v[106:109], s[6:7] nt
	global_store_dwordx4 v135, v[110:113], s[8:9] nt
	global_store_dwordx4 v135, v[114:117], s[10:11] nt
	ds_read_b128 v[150:153], v137 offset:512
	ds_read_b128 v[154:157], v137 offset:528
	ds_read_b128 v[158:161], v137 offset:1536
	ds_read_b128 v[162:165], v137 offset:1552
	s_waitcnt lgkmcnt(0)
	s_waitcnt vmcnt(14)
	v_lshlrev_b32_e32 v174, 16, v118
	v_and_b32_e32 v175, 0xffff0000, v118
	v_lshlrev_b32_e32 v176, 16, v119
	v_and_b32_e32 v177, 0xffff0000, v119
	v_lshlrev_b32_e32 v178, 16, v120
	v_and_b32_e32 v179, 0xffff0000, v120
	v_lshlrev_b32_e32 v180, 16, v121
	v_and_b32_e32 v181, 0xffff0000, v121
	v_pk_add_f32 v[174:175], v[174:175], v[142:143] op_sel_hi:[1,0] neg_lo:[0,1] neg_hi:[0,1]
	v_pk_add_f32 v[176:177], v[176:177], v[142:143] op_sel_hi:[1,0] neg_lo:[0,1] neg_hi:[0,1]
	v_pk_add_f32 v[178:179], v[178:179], v[142:143] op_sel_hi:[1,0] neg_lo:[0,1] neg_hi:[0,1]
	v_pk_add_f32 v[180:181], v[180:181], v[142:143] op_sel_hi:[1,0] neg_lo:[0,1] neg_hi:[0,1]
	v_pk_mul_f32 v[174:175], v[142:143], v[174:175] op_sel:[1,0] op_sel_hi:[1,1]
	v_pk_mul_f32 v[176:177], v[142:143], v[176:177] op_sel:[1,0] op_sel_hi:[1,1]
	v_pk_mul_f32 v[178:179], v[142:143], v[178:179] op_sel:[1,0] op_sel_hi:[1,1]
	v_pk_mul_f32 v[180:181], v[142:143], v[180:181] op_sel:[1,0] op_sel_hi:[1,1]
	v_pk_fma_f32 v[174:175], v[150:151], v[174:175], v[158:159]
	v_pk_fma_f32 v[176:177], v[152:153], v[176:177], v[160:161]
	v_pk_fma_f32 v[178:179], v[154:155], v[178:179], v[162:163]
	v_pk_fma_f32 v[180:181], v[156:157], v[180:181], v[164:165]
	v_pk_fma_f32 v[14:15], v[174:175], s[76:77], v[14:15] op_sel_hi:[1,0,1]
	v_pk_fma_f32 v[16:17], v[176:177], s[76:77], v[16:17] op_sel_hi:[1,0,1]
	v_pk_fma_f32 v[18:19], v[178:179], s[76:77], v[18:19] op_sel_hi:[1,0,1]
	v_pk_fma_f32 v[20:21], v[180:181], s[76:77], v[20:21] op_sel_hi:[1,0,1]
	v_pk_add_f32 v[174:175], v[14:15], v[18:19]
	v_pk_add_f32 v[176:177], v[16:17], v[20:21]
	v_pk_mul_f32 v[178:179], v[14:15], v[14:15]
	v_pk_mul_f32 v[180:181], v[16:17], v[16:17]
	v_pk_fma_f32 v[178:179], v[18:19], v[18:19], v[178:179]
	v_pk_fma_f32 v[180:181], v[20:21], v[20:21], v[180:181]
	v_pk_add_f32 v[174:175], v[174:175], v[176:177]
	v_pk_add_f32 v[178:179], v[178:179], v[180:181]
	v_cvt_pk_bf16_f32 v118, v14, v15
	v_cvt_pk_bf16_f32 v119, v16, v17
	v_cvt_pk_bf16_f32 v120, v18, v19
	v_cvt_pk_bf16_f32 v121, v20, v21
	v_add_f32_e32 v174, v174, v175
	v_add_f32_e32 v178, v178, v179
	v_add_f32_e32 v2, v2, v174
	v_add_f32_e32 v140, v140, v178
	v_lshlrev_b32_e32 v174, 16, v122
	v_and_b32_e32 v175, 0xffff0000, v122
	v_lshlrev_b32_e32 v176, 16, v123
	v_and_b32_e32 v177, 0xffff0000, v123
	v_lshlrev_b32_e32 v178, 16, v124
	v_and_b32_e32 v179, 0xffff0000, v124
	v_lshlrev_b32_e32 v180, 16, v125
	v_and_b32_e32 v181, 0xffff0000, v125
	v_pk_add_f32 v[174:175], v[174:175], v[144:145] op_sel_hi:[1,0] neg_lo:[0,1] neg_hi:[0,1]
	v_pk_add_f32 v[176:177], v[176:177], v[144:145] op_sel_hi:[1,0] neg_lo:[0,1] neg_hi:[0,1]
	v_pk_add_f32 v[178:179], v[178:179], v[144:145] op_sel_hi:[1,0] neg_lo:[0,1] neg_hi:[0,1]
	v_pk_add_f32 v[180:181], v[180:181], v[144:145] op_sel_hi:[1,0] neg_lo:[0,1] neg_hi:[0,1]
	v_pk_mul_f32 v[174:175], v[144:145], v[174:175] op_sel:[1,0] op_sel_hi:[1,1]
	v_pk_mul_f32 v[176:177], v[144:145], v[176:177] op_sel:[1,0] op_sel_hi:[1,1]
	v_pk_mul_f32 v[178:179], v[144:145], v[178:179] op_sel:[1,0] op_sel_hi:[1,1]
	v_pk_mul_f32 v[180:181], v[144:145], v[180:181] op_sel:[1,0] op_sel_hi:[1,1]
	v_pk_fma_f32 v[174:175], v[150:151], v[174:175], v[158:159]
	v_pk_fma_f32 v[176:177], v[152:153], v[176:177], v[160:161]
	v_pk_fma_f32 v[178:179], v[154:155], v[178:179], v[162:163]
	v_pk_fma_f32 v[180:181], v[156:157], v[180:181], v[164:165]
	v_pk_fma_f32 v[6:7], v[174:175], s[76:77], v[6:7] op_sel_hi:[1,0,1]
	v_pk_fma_f32 v[8:9], v[176:177], s[76:77], v[8:9] op_sel_hi:[1,0,1]
	v_pk_fma_f32 v[10:11], v[178:179], s[76:77], v[10:11] op_sel_hi:[1,0,1]
	v_pk_fma_f32 v[12:13], v[180:181], s[76:77], v[12:13] op_sel_hi:[1,0,1]
	v_pk_add_f32 v[174:175], v[6:7], v[10:11]
	v_pk_add_f32 v[176:177], v[8:9], v[12:13]
	v_pk_mul_f32 v[178:179], v[6:7], v[6:7]
	v_pk_mul_f32 v[180:181], v[8:9], v[8:9]
	v_pk_fma_f32 v[178:179], v[10:11], v[10:11], v[178:179]
	v_pk_fma_f32 v[180:181], v[12:13], v[12:13], v[180:181]
	v_pk_add_f32 v[174:175], v[174:175], v[176:177]
	v_pk_add_f32 v[178:179], v[178:179], v[180:181]
	v_cvt_pk_bf16_f32 v122, v6, v7
	v_cvt_pk_bf16_f32 v123, v8, v9
	v_cvt_pk_bf16_f32 v124, v10, v11
	v_cvt_pk_bf16_f32 v125, v12, v13
	v_add_f32_e32 v174, v174, v175
	v_add_f32_e32 v178, v178, v179
	v_add_f32_e32 v4, v4, v174
	v_add_f32_e32 v186, v186, v178
	v_lshlrev_b32_e32 v174, 16, v126
	v_and_b32_e32 v175, 0xffff0000, v126
	v_lshlrev_b32_e32 v176, 16, v127
	v_and_b32_e32 v177, 0xffff0000, v127
	v_lshlrev_b32_e32 v178, 16, v128
	v_and_b32_e32 v179, 0xffff0000, v128
	v_lshlrev_b32_e32 v180, 16, v129
	v_and_b32_e32 v181, 0xffff0000, v129
	v_pk_add_f32 v[174:175], v[174:175], v[146:147] op_sel_hi:[1,0] neg_lo:[0,1] neg_hi:[0,1]
	v_pk_add_f32 v[176:177], v[176:177], v[146:147] op_sel_hi:[1,0] neg_lo:[0,1] neg_hi:[0,1]
	v_pk_add_f32 v[178:179], v[178:179], v[146:147] op_sel_hi:[1,0] neg_lo:[0,1] neg_hi:[0,1]
	v_pk_add_f32 v[180:181], v[180:181], v[146:147] op_sel_hi:[1,0] neg_lo:[0,1] neg_hi:[0,1]
	v_pk_mul_f32 v[174:175], v[146:147], v[174:175] op_sel:[1,0] op_sel_hi:[1,1]
	v_pk_mul_f32 v[176:177], v[146:147], v[176:177] op_sel:[1,0] op_sel_hi:[1,1]
	v_pk_mul_f32 v[178:179], v[146:147], v[178:179] op_sel:[1,0] op_sel_hi:[1,1]
	v_pk_mul_f32 v[180:181], v[146:147], v[180:181] op_sel:[1,0] op_sel_hi:[1,1]
	v_pk_fma_f32 v[174:175], v[150:151], v[174:175], v[158:159]
	v_pk_fma_f32 v[176:177], v[152:153], v[176:177], v[160:161]
	v_pk_fma_f32 v[178:179], v[154:155], v[178:179], v[162:163]
	v_pk_fma_f32 v[180:181], v[156:157], v[180:181], v[164:165]
	v_pk_fma_f32 v[54:55], v[174:175], s[76:77], v[54:55] op_sel_hi:[1,0,1]
	v_pk_fma_f32 v[56:57], v[176:177], s[76:77], v[56:57] op_sel_hi:[1,0,1]
	v_pk_fma_f32 v[62:63], v[178:179], s[76:77], v[62:63] op_sel_hi:[1,0,1]
	v_pk_fma_f32 v[64:65], v[180:181], s[76:77], v[64:65] op_sel_hi:[1,0,1]
	v_pk_add_f32 v[174:175], v[54:55], v[62:63]
	v_pk_add_f32 v[176:177], v[56:57], v[64:65]
	v_pk_mul_f32 v[178:179], v[54:55], v[54:55]
	v_pk_mul_f32 v[180:181], v[56:57], v[56:57]
	v_pk_fma_f32 v[178:179], v[62:63], v[62:63], v[178:179]
	v_pk_fma_f32 v[180:181], v[64:65], v[64:65], v[180:181]
	v_pk_add_f32 v[174:175], v[174:175], v[176:177]
	v_pk_add_f32 v[178:179], v[178:179], v[180:181]
	v_cvt_pk_bf16_f32 v126, v54, v55
	v_cvt_pk_bf16_f32 v127, v56, v57
	v_cvt_pk_bf16_f32 v128, v62, v63
	v_cvt_pk_bf16_f32 v129, v64, v65
	v_add_f32_e32 v174, v174, v175
	v_add_f32_e32 v178, v178, v179
	v_add_f32_e32 v5, v5, v174
	v_add_f32_e32 v187, v187, v178
	v_lshlrev_b32_e32 v174, 16, v130
	v_and_b32_e32 v175, 0xffff0000, v130
	v_lshlrev_b32_e32 v176, 16, v131
	v_and_b32_e32 v177, 0xffff0000, v131
	v_lshlrev_b32_e32 v178, 16, v132
	v_and_b32_e32 v179, 0xffff0000, v132
	v_lshlrev_b32_e32 v180, 16, v133
	v_and_b32_e32 v181, 0xffff0000, v133
	v_pk_add_f32 v[174:175], v[174:175], v[148:149] op_sel_hi:[1,0] neg_lo:[0,1] neg_hi:[0,1]
	v_pk_add_f32 v[176:177], v[176:177], v[148:149] op_sel_hi:[1,0] neg_lo:[0,1] neg_hi:[0,1]
	v_pk_add_f32 v[178:179], v[178:179], v[148:149] op_sel_hi:[1,0] neg_lo:[0,1] neg_hi:[0,1]
	v_pk_add_f32 v[180:181], v[180:181], v[148:149] op_sel_hi:[1,0] neg_lo:[0,1] neg_hi:[0,1]
	v_pk_mul_f32 v[174:175], v[148:149], v[174:175] op_sel:[1,0] op_sel_hi:[1,1]
	v_pk_mul_f32 v[176:177], v[148:149], v[176:177] op_sel:[1,0] op_sel_hi:[1,1]
	v_pk_mul_f32 v[178:179], v[148:149], v[178:179] op_sel:[1,0] op_sel_hi:[1,1]
	v_pk_mul_f32 v[180:181], v[148:149], v[180:181] op_sel:[1,0] op_sel_hi:[1,1]
	v_pk_fma_f32 v[174:175], v[150:151], v[174:175], v[158:159]
	v_pk_fma_f32 v[176:177], v[152:153], v[176:177], v[160:161]
	v_pk_fma_f32 v[178:179], v[154:155], v[178:179], v[162:163]
	v_pk_fma_f32 v[180:181], v[156:157], v[180:181], v[164:165]
	v_pk_fma_f32 v[58:59], v[174:175], s[76:77], v[58:59] op_sel_hi:[1,0,1]
	v_pk_fma_f32 v[60:61], v[176:177], s[76:77], v[60:61] op_sel_hi:[1,0,1]
	v_pk_fma_f32 v[66:67], v[178:179], s[76:77], v[66:67] op_sel_hi:[1,0,1]
	v_pk_fma_f32 v[68:69], v[180:181], s[76:77], v[68:69] op_sel_hi:[1,0,1]
	v_pk_add_f32 v[174:175], v[58:59], v[66:67]
	v_pk_add_f32 v[176:177], v[60:61], v[68:69]
	v_pk_mul_f32 v[178:179], v[58:59], v[58:59]
	v_pk_mul_f32 v[180:181], v[60:61], v[60:61]
	v_pk_fma_f32 v[178:179], v[66:67], v[66:67], v[178:179]
	v_pk_fma_f32 v[180:181], v[68:69], v[68:69], v[180:181]
	v_pk_add_f32 v[174:175], v[174:175], v[176:177]
	v_pk_add_f32 v[178:179], v[178:179], v[180:181]
	v_cvt_pk_bf16_f32 v130, v58, v59
	v_cvt_pk_bf16_f32 v131, v60, v61
	v_cvt_pk_bf16_f32 v132, v66, v67
	v_cvt_pk_bf16_f32 v133, v68, v69
	v_add_f32_e32 v174, v174, v175
	v_add_f32_e32 v178, v178, v179
	v_add_f32_e32 v139, v139, v174
	v_add_f32_e32 v197, v197, v178
	global_store_dwordx4 v135, v[118:121], s[16:17] offset:256 nt
	global_store_dwordx4 v135, v[122:125], s[6:7] offset:256 nt
	global_store_dwordx4 v135, v[126:129], s[8:9] offset:256 nt
	global_store_dwordx4 v135, v[130:133], s[10:11] offset:256 nt
	ds_bpermute_b32 v174, v201, v2
	ds_bpermute_b32 v175, v201, v4
	ds_bpermute_b32 v176, v201, v5
	ds_bpermute_b32 v177, v201, v139
	ds_bpermute_b32 v178, v201, v140
	ds_bpermute_b32 v179, v201, v186
	ds_bpermute_b32 v180, v201, v187
	ds_bpermute_b32 v181, v201, v197
	s_waitcnt lgkmcnt(0)
	v_add_f32_e32 v2, v2, v174
	v_add_f32_e32 v4, v4, v175
	v_add_f32_e32 v5, v5, v176
	v_add_f32_e32 v139, v139, v177
	v_add_f32_e32 v140, v140, v178
	v_add_f32_e32 v186, v186, v179
	v_add_f32_e32 v187, v187, v180
	v_add_f32_e32 v197, v197, v181
	ds_bpermute_b32 v174, v203, v2
	ds_bpermute_b32 v175, v203, v4
	ds_bpermute_b32 v176, v203, v5
	ds_bpermute_b32 v177, v203, v139
	ds_bpermute_b32 v178, v203, v140
	ds_bpermute_b32 v179, v203, v186
	ds_bpermute_b32 v180, v203, v187
	ds_bpermute_b32 v181, v203, v197
	s_waitcnt lgkmcnt(0)
	v_add_f32_e32 v2, v2, v174
	v_add_f32_e32 v4, v4, v175
	v_add_f32_e32 v5, v5, v176
	v_add_f32_e32 v139, v139, v177
	v_add_f32_e32 v140, v140, v178
	v_add_f32_e32 v186, v186, v179
	v_add_f32_e32 v187, v187, v180
	v_add_f32_e32 v197, v197, v181
	v_cmp_eq_u32_e32 vcc, 1, v191
	s_nop 1
	v_cndmask_b32_e32 v2, v2, v4, vcc
	v_cndmask_b32_e32 v140, v140, v186, vcc
	v_cmp_eq_u32_e32 vcc, 2, v191
	s_nop 1
	v_cndmask_b32_e32 v2, v2, v5, vcc
	v_cndmask_b32_e32 v140, v140, v187, vcc
	v_cmp_eq_u32_e32 vcc, 3, v191
	s_nop 1
	v_cndmask_b32_e32 v2, v2, v139, vcc
	v_cndmask_b32_e32 v140, v140, v197, vcc
	global_atomic_add_f32 v138, v2, s[14:15] offset:1024
	global_atomic_add_f32 v138, v140, s[14:15] offset:1028
	s_branch .LBB0_1171

.LBB0_1115:
	v_mov_b64_e32 v[140:141], v[4:5]
	v_mov_b64_e32 v[138:139], v[2:3]
	v_mul_f32_e32 v5, 0x3a000000, v176
	v_mul_f32_e32 v2, v5, v5
	v_fma_f32 v2, v177, s72, -v2
	v_add_f32_e32 v2, 0x3727c5ac, v2
	v_rsq_f32_e32 v2, v2
	s_and_b32 s8, s84, 2
	s_bitcmp1_b32 s84, 1
	s_cselect_b64 s[6:7], -1, 0
	s_cmp_eq_u32 s8, 0
	s_cbranch_scc1 .LBB0_1117
	s_waitcnt vmcnt(2)
	v_lshlrev_b32_e32 v4, 16, v170
	v_and_b32_e32 v176, 0xffff0000, v170
	v_lshlrev_b32_e32 v170, 16, v171
	v_and_b32_e32 v171, 0xffff0000, v171
	v_sub_f32_e32 v171, v171, v5
	v_sub_f32_e32 v170, v170, v5
	v_pk_mul_f32 v[170:171], v[2:3], v[170:171] op_sel_hi:[0,1]
	v_lshlrev_b32_e32 v203, 16, v172
	v_and_b32_e32 v207, 0xffff0000, v172
	v_lshlrev_b32_e32 v214, 16, v173
	v_and_b32_e32 v215, 0xffff0000, v173
	s_waitcnt lgkmcnt(1)
	v_pk_fma_f32 v[170:171], v[152:153], v[170:171], v[156:157]
	v_sub_f32_e32 v173, v176, v5
	v_sub_f32_e32 v172, v4, v5
	v_pk_fma_f32 v[176:177], v[170:171], s[76:77], v[120:121] op_sel_hi:[1,0,1]
	v_sub_f32_e32 v171, v215, v5
	v_sub_f32_e32 v170, v214, v5
	v_sub_f32_e32 v215, v207, v5
	v_sub_f32_e32 v214, v203, v5
	v_pk_mul_f32 v[172:173], v[2:3], v[172:173] op_sel_hi:[0,1]
	v_pk_mul_f32 v[214:215], v[2:3], v[214:215] op_sel_hi:[0,1]
	v_pk_mul_f32 v[170:171], v[2:3], v[170:171] op_sel_hi:[0,1]
	v_pk_fma_f32 v[172:173], v[150:151], v[172:173], v[154:155]
	s_waitcnt lgkmcnt(0)
	v_pk_fma_f32 v[170:171], v[144:145], v[170:171], v[148:149]
	v_pk_fma_f32 v[214:215], v[142:143], v[214:215], v[146:147]
	v_pk_fma_f32 v[172:173], v[172:173], s[76:77], v[118:119] op_sel_hi:[1,0,1]
	v_pk_fma_f32 v[214:215], v[214:215], s[76:77], v[122:123] op_sel_hi:[1,0,1]
	v_pk_fma_f32 v[218:219], v[170:171], s[76:77], v[124:125] op_sel_hi:[1,0,1]
	v_pk_add_f32 v[222:223], v[172:173], v[214:215]
	v_pk_add_f32 v[170:171], v[176:177], v[218:219]
	v_pk_mul_f32 v[224:225], v[214:215], v[214:215]
	v_pk_mul_f32 v[226:227], v[218:219], v[218:219]
	v_pk_mov_b32 v[232:233], v[222:223], v[170:171] op_sel:[1,0]
	v_mov_b32_e32 v223, v171
	v_pk_fma_f32 v[226:227], v[176:177], v[176:177], v[226:227]
	v_pk_fma_f32 v[224:225], v[172:173], v[172:173], v[224:225]
	v_pk_add_f32 v[170:171], v[232:233], v[222:223]
	s_nop 0
	v_add_f32_e32 v4, v170, v171
	v_pk_mov_b32 v[170:171], v[224:225], v[226:227] op_sel:[1,0]
	v_mov_b32_e32 v225, v227
	v_pk_add_f32 v[170:171], v[170:171], v[224:225]
	v_add_f32_e32 v139, v4, v139
	v_add_f32_e32 v4, v170, v171
	v_cvt_pk_bf16_f32 v171, v176, v177
	v_lshl_add_u64 v[176:177], s[16:17], 0, v[212:213]
	v_add_f32_e32 v135, v4, v135
	v_cvt_pk_bf16_f32 v170, v172, v173
	v_cvt_pk_bf16_f32 v172, v214, v215
	v_cvt_pk_bf16_f32 v173, v218, v219
	v_lshl_add_u64 v[176:177], v[178:179], 1, v[176:177]
	global_store_dwordx4 v[176:177], v[170:173], off nt
.LBB0_1117:
	s_waitcnt vmcnt(2) lgkmcnt(4)
	s_nop 0
	v_mul_f32_e32 v171, 0x3a000000, v162
	v_mul_f32_e32 v4, v171, v171
	v_fma_f32 v4, v163, s72, -v4
	v_add_f32_e32 v4, 0x3727c5ac, v4
	v_rsq_f32_e32 v4, v4
	s_and_b32 s10, s84, 4
	s_bitcmp1_b32 s84, 2
	s_cselect_b64 s[8:9], -1, 0
	s_cmp_eq_u32 s10, 0
	s_cbranch_scc1 .LBB0_1119
	s_waitcnt vmcnt(1)
	v_lshlrev_b32_e32 v170, 16, v166
	v_and_b32_e32 v166, 0xffff0000, v166
	v_lshlrev_b32_e32 v162, 16, v167
	v_and_b32_e32 v163, 0xffff0000, v167
	v_lshlrev_b32_e32 v172, 16, v168
	v_and_b32_e32 v173, 0xffff0000, v168
	v_lshlrev_b32_e32 v168, 16, v169
	v_and_b32_e32 v169, 0xffff0000, v169
	v_sub_f32_e32 v163, v163, v171
	v_sub_f32_e32 v162, v162, v171
	v_sub_f32_e32 v167, v166, v171
	v_sub_f32_e32 v166, v170, v171
	v_sub_f32_e32 v169, v169, v171
	v_sub_f32_e32 v168, v168, v171
	v_sub_f32_e32 v173, v173, v171
	v_sub_f32_e32 v172, v172, v171
	v_pk_mul_f32 v[166:167], v[4:5], v[166:167] op_sel_hi:[0,1]
	v_pk_mul_f32 v[162:163], v[4:5], v[162:163] op_sel_hi:[0,1]
	v_pk_mul_f32 v[172:173], v[4:5], v[172:173] op_sel_hi:[0,1]
	v_pk_mul_f32 v[168:169], v[4:5], v[168:169] op_sel_hi:[0,1]
	s_waitcnt lgkmcnt(1)
	v_pk_fma_f32 v[162:163], v[152:153], v[162:163], v[156:157]
	v_pk_fma_f32 v[166:167], v[150:151], v[166:167], v[154:155]
	s_waitcnt lgkmcnt(0)
	v_pk_fma_f32 v[168:169], v[144:145], v[168:169], v[148:149]
	v_pk_fma_f32 v[172:173], v[142:143], v[172:173], v[146:147]
	v_pk_fma_f32 v[166:167], v[166:167], s[76:77], v[110:111] op_sel_hi:[1,0,1]
	v_pk_fma_f32 v[162:163], v[162:163], s[76:77], v[112:113] op_sel_hi:[1,0,1]
	v_pk_fma_f32 v[172:173], v[172:173], s[76:77], v[114:115] op_sel_hi:[1,0,1]
	v_pk_fma_f32 v[176:177], v[168:169], s[76:77], v[116:117] op_sel_hi:[1,0,1]
	v_pk_add_f32 v[212:213], v[166:167], v[172:173]
	v_pk_add_f32 v[168:169], v[162:163], v[176:177]
	v_pk_mul_f32 v[214:215], v[172:173], v[172:173]
	v_pk_mov_b32 v[222:223], v[212:213], v[168:169] op_sel:[1,0]
	v_mov_b32_e32 v213, v169
	v_pk_mul_f32 v[218:219], v[176:177], v[176:177]
	v_pk_add_f32 v[168:169], v[222:223], v[212:213]
	v_pk_fma_f32 v[218:219], v[162:163], v[162:163], v[218:219]
	v_pk_fma_f32 v[214:215], v[166:167], v[166:167], v[214:215]
	v_add_f32_e32 v168, v168, v169
	v_add_f32_e32 v140, v168, v140
	v_pk_mov_b32 v[168:169], v[214:215], v[218:219] op_sel:[1,0]
	v_mov_b32_e32 v215, v219
	v_pk_add_f32 v[168:169], v[168:169], v[214:215]
	v_cvt_pk_bf16_f32 v166, v166, v167
	v_add_f32_e32 v168, v168, v169
	v_cvt_pk_bf16_f32 v167, v162, v163
	v_lshl_add_u64 v[162:163], s[16:17], 0, v[210:211]
	v_add_f32_e32 v136, v168, v136
	v_cvt_pk_bf16_f32 v168, v172, v173
	v_cvt_pk_bf16_f32 v169, v176, v177
	v_lshl_add_u64 v[162:163], v[178:179], 1, v[162:163]
	global_store_dwordx4 v[162:163], v[166:169], off nt
.LBB0_1119:
	v_mul_f32_e32 v172, 0x3a000000, v164
	v_mul_f32_e32 v162, v172, v172
	v_fma_f32 v162, v165, s72, -v162
	v_add_f32_e32 v162, 0x3727c5ac, v162
	v_rsq_f32_e32 v170, v162
	s_and_b32 s18, s84, 8
	s_bitcmp1_b32 s84, 3
	s_cselect_b64 s[10:11], -1, 0
	s_cmp_eq_u32 s18, 0
	s_cbranch_scc1 .LBB0_1121
	s_waitcnt vmcnt(0)
	v_lshlrev_b32_e32 v162, 16, v158
	v_and_b32_e32 v163, 0xffff0000, v158
	v_lshlrev_b32_e32 v158, 16, v159
	v_and_b32_e32 v159, 0xffff0000, v159
	v_lshlrev_b32_e32 v164, 16, v160
	v_and_b32_e32 v165, 0xffff0000, v160
	v_lshlrev_b32_e32 v166, 16, v161
	v_and_b32_e32 v167, 0xffff0000, v161
	v_sub_f32_e32 v159, v159, v172
	v_sub_f32_e32 v158, v158, v172
	v_sub_f32_e32 v161, v163, v172
	v_sub_f32_e32 v160, v162, v172
	v_pk_mul_f32 v[160:161], v[170:171], v[160:161] op_sel_hi:[0,1]
	v_pk_mul_f32 v[158:159], v[170:171], v[158:159] op_sel_hi:[0,1]
	s_waitcnt lgkmcnt(1)
	v_pk_fma_f32 v[152:153], v[152:153], v[158:159], v[156:157]
	v_pk_fma_f32 v[150:151], v[150:151], v[160:161], v[154:155]
	v_sub_f32_e32 v155, v167, v172
	v_sub_f32_e32 v154, v166, v172
	v_sub_f32_e32 v157, v165, v172
	v_sub_f32_e32 v156, v164, v172
	v_pk_mul_f32 v[156:157], v[170:171], v[156:157] op_sel_hi:[0,1]
	v_pk_mul_f32 v[154:155], v[170:171], v[154:155] op_sel_hi:[0,1]
	s_waitcnt lgkmcnt(0)
	v_pk_fma_f32 v[144:145], v[144:145], v[154:155], v[148:149]
	v_pk_fma_f32 v[142:143], v[142:143], v[156:157], v[146:147]
	v_pk_fma_f32 v[150:151], v[150:151], s[76:77], v[102:103] op_sel_hi:[1,0,1]
	v_pk_fma_f32 v[152:153], v[152:153], s[76:77], v[104:105] op_sel_hi:[1,0,1]
	v_pk_fma_f32 v[146:147], v[142:143], s[76:77], v[106:107] op_sel_hi:[1,0,1]
	v_pk_fma_f32 v[148:149], v[144:145], s[76:77], v[108:109] op_sel_hi:[1,0,1]
	v_pk_add_f32 v[144:145], v[150:151], v[146:147]
	v_pk_add_f32 v[142:143], v[152:153], v[148:149]
	v_pk_mul_f32 v[154:155], v[146:147], v[146:147]
	v_pk_mov_b32 v[158:159], v[144:145], v[142:143] op_sel:[1,0]
	v_mov_b32_e32 v145, v143
	v_pk_mul_f32 v[156:157], v[148:149], v[148:149]
	v_pk_add_f32 v[142:143], v[158:159], v[144:145]
	v_pk_fma_f32 v[156:157], v[152:153], v[152:153], v[156:157]
	v_pk_fma_f32 v[154:155], v[150:151], v[150:151], v[154:155]
	v_add_f32_e32 v142, v142, v143
	v_add_f32_e32 v141, v142, v141
	v_pk_mov_b32 v[142:143], v[154:155], v[156:157] op_sel:[1,0]
	v_mov_b32_e32 v155, v157
	v_pk_add_f32 v[142:143], v[142:143], v[154:155]
	v_cvt_pk_bf16_f32 v144, v146, v147
	v_add_f32_e32 v142, v142, v143
	v_lshl_add_u64 v[146:147], s[16:17], 0, v[208:209]
	v_add_f32_e32 v137, v142, v137
	v_cvt_pk_bf16_f32 v142, v150, v151
	v_cvt_pk_bf16_f32 v143, v152, v153
	v_cvt_pk_bf16_f32 v145, v148, v149
	v_lshl_add_u64 v[146:147], v[178:179], 1, v[146:147]
	global_store_dwordx4 v[146:147], v[142:145], off nt

.LBB0_1125:
	s_waitcnt vmcnt(0)
	v_lshlrev_b32_e32 v2, 16, v158
	v_and_b32_e32 v158, 0xffff0000, v158
	v_lshlrev_b32_e32 v4, 16, v159
	v_and_b32_e32 v5, 0xffff0000, v159
	v_sub_f32_e32 v5, v5, v172
	v_sub_f32_e32 v4, v4, v172
	v_sub_f32_e32 v159, v158, v172
	v_sub_f32_e32 v158, v2, v172
	v_lshlrev_b32_e32 v162, 16, v160
	v_and_b32_e32 v160, 0xffff0000, v160
	v_lshlrev_b32_e32 v163, 16, v161
	v_and_b32_e32 v161, 0xffff0000, v161
	v_pk_mul_f32 v[158:159], v[170:171], v[158:159] op_sel_hi:[0,1]
	v_pk_mul_f32 v[4:5], v[170:171], v[4:5] op_sel_hi:[0,1]
	s_waitcnt lgkmcnt(1)
	v_pk_fma_f32 v[4:5], v[152:153], v[4:5], v[156:157]
	v_pk_fma_f32 v[150:151], v[150:151], v[158:159], v[154:155]
	v_sub_f32_e32 v153, v161, v172
	v_sub_f32_e32 v152, v163, v172
	v_sub_f32_e32 v155, v160, v172
	v_sub_f32_e32 v154, v162, v172
	v_pk_mul_f32 v[154:155], v[170:171], v[154:155] op_sel_hi:[0,1]
	v_pk_mul_f32 v[152:153], v[170:171], v[152:153] op_sel_hi:[0,1]
	s_waitcnt lgkmcnt(0)
	v_pk_fma_f32 v[144:145], v[144:145], v[152:153], v[148:149]
	v_pk_fma_f32 v[142:143], v[142:143], v[154:155], v[146:147]
	v_pk_fma_f32 v[150:151], v[150:151], s[76:77], v[70:71] op_sel_hi:[1,0,1]
	v_pk_fma_f32 v[4:5], v[4:5], s[76:77], v[72:73] op_sel_hi:[1,0,1]
	v_pk_fma_f32 v[146:147], v[142:143], s[76:77], v[74:75] op_sel_hi:[1,0,1]
	v_pk_fma_f32 v[148:149], v[144:145], s[76:77], v[76:77] op_sel_hi:[1,0,1]
	v_pk_add_f32 v[144:145], v[150:151], v[146:147]
	v_pk_add_f32 v[142:143], v[4:5], v[148:149]
	v_pk_mul_f32 v[152:153], v[146:147], v[146:147]
	v_pk_mul_f32 v[154:155], v[148:149], v[148:149]
	v_pk_mov_b32 v[156:157], v[144:145], v[142:143] op_sel:[1,0]
	v_mov_b32_e32 v145, v143
	v_pk_fma_f32 v[154:155], v[4:5], v[4:5], v[154:155]
	v_pk_fma_f32 v[152:153], v[150:151], v[150:151], v[152:153]
	v_pk_add_f32 v[142:143], v[156:157], v[144:145]
	v_cvt_pk_bf16_f32 v144, v146, v147
	v_add_f32_e32 v2, v142, v143
	v_pk_mov_b32 v[142:143], v[152:153], v[154:155] op_sel:[1,0]
	v_mov_b32_e32 v153, v155
	v_pk_add_f32 v[142:143], v[142:143], v[152:153]
	v_add_f32_e32 v141, v2, v141
	v_add_f32_e32 v2, v142, v143
	v_add_f32_e32 v137, v2, v137
	v_cvt_pk_bf16_f32 v142, v150, v151
	v_cvt_pk_bf16_f32 v143, v4, v5
	v_cvt_pk_bf16_f32 v145, v148, v149
	global_store_dwordx4 v[182:183], v[142:145], off offset:256 nt

.LBB0_1128:
	s_or_b64 exec, exec, s[18:19]
	s_waitcnt lgkmcnt(6)
	v_lshlrev_b64 v[4:5], 12, v[180:181]
	s_mov_b64 s[18:19], 0x90000
	v_lshl_add_u64 v[214:215], v[4:5], 0, s[18:19]
	s_mov_b64 s[18:19], 0xa0000
	v_lshl_add_u64 v[212:213], v[4:5], 0, s[18:19]
	s_mov_b64 s[18:19], 0xb0000
	v_lshl_add_u64 v[210:211], v[4:5], 0, s[18:19]
	v_lshl_add_u64 v[206:207], v[184:185], 0, v[214:215]
	v_lshl_add_u64 v[186:187], v[184:185], 0, v[210:211]
	v_lshl_add_u64 v[204:205], v[184:185], 0, v[212:213]
	global_load_dwordx4 v[170:173], v[206:207], off
	global_load_dwordx4 v[166:169], v[204:205], off
	global_load_dwordx4 v[158:161], v[186:187], off
	v_add_u32_e32 v2, 0x20400, v216
	ds_read2_b64 v[174:177], v2 offset1:16
	s_waitcnt vmcnt(4)
	ds_read2_b64 v[162:165], v2 offset0:32 offset1:48
	ds_read_b128 v[150:153], v197
	s_waitcnt lgkmcnt(5)
	ds_read_b128 v[142:145], v197 offset:16
	ds_read_b128 v[154:157], v199
	s_waitcnt lgkmcnt(6)
	ds_read_b128 v[146:149], v199 offset:16
	s_mov_b64 s[18:19], 0x80000
	s_and_b32 s20, s84, 16
	s_waitcnt lgkmcnt(5)
	v_mul_f32_e32 v183, 0x3a000000, v174
	v_mul_f32_e32 v134, v183, v183
	v_fma_f32 v134, v175, s72, -v134
	v_add_f32_e32 v134, 0x3727c5ac, v134
	v_rsq_f32_e32 v208, v134
	v_lshl_add_u64 v[138:139], v[4:5], 0, s[18:19]
	s_bitcmp1_b32 s84, 4
	s_cselect_b64 s[18:19], -1, 0
	s_cmp_eq_u32 s20, 0
	v_lshl_add_u64 v[174:175], v[184:185], 0, v[138:139]
	s_cbranch_scc1 .LBB0_1133
	global_load_dwordx4 v[134:137], v[174:175], off
	v_lshl_add_u64 v[138:139], s[16:17], 0, v[138:139]
	v_lshl_add_u64 v[138:139], v[178:179], 1, v[138:139]
	s_waitcnt vmcnt(0)
	v_lshlrev_b32_e32 v2, 16, v134
	v_and_b32_e32 v134, 0xffff0000, v134
	v_lshlrev_b32_e32 v4, 16, v135
	v_and_b32_e32 v5, 0xffff0000, v135
	v_lshlrev_b32_e32 v209, 16, v136
	v_sub_f32_e32 v5, v5, v183
	v_sub_f32_e32 v4, v4, v183
	v_sub_f32_e32 v135, v134, v183
	v_sub_f32_e32 v134, v2, v183
	v_pk_mul_f32 v[134:135], v[208:209], v[134:135] op_sel_hi:[0,1]
	v_pk_mul_f32 v[4:5], v[208:209], v[4:5] op_sel_hi:[0,1]
	v_and_b32_e32 v136, 0xffff0000, v136
	v_lshlrev_b32_e32 v216, 16, v137
	v_and_b32_e32 v137, 0xffff0000, v137
	s_waitcnt lgkmcnt(1)
	v_pk_fma_f32 v[4:5], v[152:153], v[4:5], v[156:157]
	v_pk_fma_f32 v[134:135], v[150:151], v[134:135], v[154:155]
	v_pk_fma_f32 v[184:185], v[4:5], s[76:77], v[48:49] op_sel_hi:[1,0,1]
	v_pk_fma_f32 v[140:141], v[134:135], s[76:77], v[46:47] op_sel_hi:[1,0,1]
	v_sub_f32_e32 v5, v137, v183
	v_sub_f32_e32 v4, v216, v183
	v_sub_f32_e32 v135, v136, v183
	v_sub_f32_e32 v134, v209, v183
	v_pk_mul_f32 v[134:135], v[208:209], v[134:135] op_sel_hi:[0,1]
	v_pk_mul_f32 v[4:5], v[208:209], v[4:5] op_sel_hi:[0,1]
	s_waitcnt lgkmcnt(0)
	v_pk_fma_f32 v[4:5], v[144:145], v[4:5], v[148:149]
	v_pk_fma_f32 v[134:135], v[142:143], v[134:135], v[146:147]
	v_pk_fma_f32 v[222:223], v[4:5], s[76:77], v[52:53] op_sel_hi:[1,0,1]
	v_pk_fma_f32 v[218:219], v[134:135], s[76:77], v[50:51] op_sel_hi:[1,0,1]
	v_pk_add_f32 v[4:5], v[184:185], v[222:223]
	v_pk_add_f32 v[134:135], v[140:141], v[218:219]
	v_pk_mul_f32 v[136:137], v[218:219], v[218:219]
	v_pk_mul_f32 v[216:217], v[222:223], v[222:223]
	v_pk_fma_f32 v[136:137], v[140:141], v[140:141], v[136:137]
	v_pk_fma_f32 v[216:217], v[184:185], v[184:185], v[216:217]
	v_pk_mov_b32 v[224:225], v[134:135], v[4:5] op_sel:[1,0]
	v_mov_b32_e32 v135, v5
	v_pk_add_f32 v[4:5], v[224:225], v[134:135]
	v_pk_mov_b32 v[134:135], v[136:137], v[216:217] op_sel:[1,0]
	v_mov_b32_e32 v137, v217
	v_pk_add_f32 v[134:135], v[134:135], v[136:137]
	v_add_f32_e32 v2, v4, v5
	v_pk_add_f32 v[134:135], v[134:135], v[134:135] op_sel:[0,1] op_sel_hi:[1,0]
	v_add_f32_e32 v2, 0, v2
	v_mov_b32_e32 v4, v3
	v_mov_b32_e32 v5, v3
	v_mov_b32_e32 v135, v3
	v_mov_b32_e32 v136, v3
	v_mov_b32_e32 v137, v3
	v_cvt_pk_bf16_f32 v216, v140, v141
	v_cvt_pk_bf16_f32 v217, v184, v185
	v_cvt_pk_bf16_f32 v218, v218, v219
	v_cvt_pk_bf16_f32 v219, v222, v223
	global_store_dwordx4 v[138:139], v[216:219], off nt
	s_branch .LBB0_1134
.LBB0_1130:
	global_load_dwordx4 v[208:211], v[174:175], off offset:256
	s_waitcnt vmcnt(0)
	v_lshlrev_b32_e32 v173, 16, v208
	v_and_b32_e32 v203, 0xffff0000, v208
	v_lshlrev_b32_e32 v176, 16, v209
	v_and_b32_e32 v177, 0xffff0000, v209
	v_lshlrev_b32_e32 v207, 16, v210
	v_and_b32_e32 v212, 0xffff0000, v210
	v_lshlrev_b32_e32 v210, 16, v211
	v_and_b32_e32 v211, 0xffff0000, v211
	v_sub_f32_e32 v177, v177, v201
	v_sub_f32_e32 v176, v176, v201
	v_sub_f32_e32 v209, v203, v201
	v_sub_f32_e32 v208, v173, v201
	v_sub_f32_e32 v211, v211, v201
	v_sub_f32_e32 v210, v210, v201
	v_sub_f32_e32 v213, v212, v201
	v_sub_f32_e32 v212, v207, v201
	v_pk_mul_f32 v[208:209], v[206:207], v[208:209] op_sel_hi:[0,1]
	v_pk_mul_f32 v[176:177], v[206:207], v[176:177] op_sel_hi:[0,1]
	v_pk_mul_f32 v[212:213], v[206:207], v[212:213] op_sel_hi:[0,1]
	v_pk_mul_f32 v[206:207], v[206:207], v[210:211] op_sel_hi:[0,1]
	s_waitcnt lgkmcnt(1)
	v_pk_fma_f32 v[176:177], v[152:153], v[176:177], v[156:157]
	v_pk_fma_f32 v[208:209], v[150:151], v[208:209], v[154:155]
	s_waitcnt lgkmcnt(0)
	v_pk_fma_f32 v[206:207], v[144:145], v[206:207], v[148:149]
	v_pk_fma_f32 v[210:211], v[142:143], v[212:213], v[146:147]
	v_pk_fma_f32 v[208:209], v[208:209], s[76:77], v[94:95] op_sel_hi:[1,0,1]
	v_pk_fma_f32 v[176:177], v[176:177], s[76:77], v[96:97] op_sel_hi:[1,0,1]
	v_pk_fma_f32 v[210:211], v[210:211], s[76:77], v[98:99] op_sel_hi:[1,0,1]
	v_pk_fma_f32 v[212:213], v[206:207], s[76:77], v[100:101] op_sel_hi:[1,0,1]
	v_pk_add_f32 v[214:215], v[208:209], v[210:211]
	v_pk_add_f32 v[206:207], v[176:177], v[212:213]
	v_pk_mul_f32 v[218:219], v[210:211], v[210:211]
	v_pk_mul_f32 v[222:223], v[212:213], v[212:213]
	v_pk_mov_b32 v[224:225], v[214:215], v[206:207] op_sel:[1,0]
	v_mov_b32_e32 v215, v207
	v_pk_fma_f32 v[222:223], v[176:177], v[176:177], v[222:223]
	v_pk_fma_f32 v[218:219], v[208:209], v[208:209], v[218:219]
	v_pk_add_f32 v[206:207], v[224:225], v[214:215]
	s_nop 0
	v_add_f32_e32 v173, v206, v207
	v_pk_mov_b32 v[206:207], v[218:219], v[222:223] op_sel:[1,0]
	v_mov_b32_e32 v219, v223
	v_pk_add_f32 v[206:207], v[206:207], v[218:219]
	v_add_f32_e32 v138, v138, v173
	v_add_f32_e32 v173, v206, v207
	v_add_f32_e32 v134, v134, v173
	v_cvt_pk_bf16_f32 v206, v208, v209
	v_cvt_pk_bf16_f32 v207, v176, v177
	v_cvt_pk_bf16_f32 v208, v210, v211
	v_cvt_pk_bf16_f32 v209, v212, v213
	global_store_dwordx4 v[174:175], v[206:209], off offset:256 nt
	s_andn2_b64 vcc, exec, s[6:7]
	s_cbranch_vccnz .LBB0_1123
.LBB0_1131:
	s_waitcnt vmcnt(2)
	v_lshlrev_b32_e32 v173, 16, v166
	v_and_b32_e32 v174, 0xffff0000, v166
	v_lshlrev_b32_e32 v166, 16, v167
	v_and_b32_e32 v167, 0xffff0000, v167
	v_sub_f32_e32 v167, v167, v5
	v_sub_f32_e32 v166, v166, v5
	v_pk_mul_f32 v[166:167], v[2:3], v[166:167] op_sel_hi:[0,1]
	v_lshlrev_b32_e32 v176, 16, v168
	v_and_b32_e32 v177, 0xffff0000, v168
	v_lshlrev_b32_e32 v201, 16, v169
	v_and_b32_e32 v203, 0xffff0000, v169
	s_waitcnt lgkmcnt(1)
	v_pk_fma_f32 v[166:167], v[152:153], v[166:167], v[156:157]
	v_sub_f32_e32 v169, v174, v5
	v_sub_f32_e32 v168, v173, v5
	v_pk_fma_f32 v[174:175], v[166:167], s[76:77], v[88:89] op_sel_hi:[1,0,1]
	v_sub_f32_e32 v167, v203, v5
	v_sub_f32_e32 v166, v201, v5
	v_sub_f32_e32 v177, v177, v5
	v_sub_f32_e32 v176, v176, v5
	v_pk_mul_f32 v[168:169], v[2:3], v[168:169] op_sel_hi:[0,1]
	v_pk_mul_f32 v[176:177], v[2:3], v[176:177] op_sel_hi:[0,1]
	v_pk_mul_f32 v[166:167], v[2:3], v[166:167] op_sel_hi:[0,1]
	v_pk_fma_f32 v[168:169], v[150:151], v[168:169], v[154:155]
	s_waitcnt lgkmcnt(0)
	v_pk_fma_f32 v[166:167], v[144:145], v[166:167], v[148:149]
	v_pk_fma_f32 v[176:177], v[142:143], v[176:177], v[146:147]
	v_pk_fma_f32 v[168:169], v[168:169], s[76:77], v[86:87] op_sel_hi:[1,0,1]
	v_pk_fma_f32 v[176:177], v[176:177], s[76:77], v[90:91] op_sel_hi:[1,0,1]
	v_pk_fma_f32 v[206:207], v[166:167], s[76:77], v[92:93] op_sel_hi:[1,0,1]
	v_pk_add_f32 v[208:209], v[168:169], v[176:177]
	v_pk_add_f32 v[166:167], v[174:175], v[206:207]
	v_pk_mul_f32 v[210:211], v[176:177], v[176:177]
	v_pk_mul_f32 v[212:213], v[206:207], v[206:207]
	v_pk_mov_b32 v[214:215], v[208:209], v[166:167] op_sel:[1,0]
	v_mov_b32_e32 v209, v167
	v_pk_fma_f32 v[212:213], v[174:175], v[174:175], v[212:213]
	v_pk_fma_f32 v[210:211], v[168:169], v[168:169], v[210:211]
	v_pk_add_f32 v[166:167], v[214:215], v[208:209]
	s_nop 0
	v_add_f32_e32 v2, v166, v167
	v_pk_mov_b32 v[166:167], v[210:211], v[212:213] op_sel:[1,0]
	v_mov_b32_e32 v211, v213
	v_pk_add_f32 v[166:167], v[166:167], v[210:211]
	v_add_f32_e32 v139, v2, v139
	v_add_f32_e32 v2, v166, v167
	v_add_f32_e32 v135, v2, v135
	v_cvt_pk_bf16_f32 v166, v168, v169
	v_cvt_pk_bf16_f32 v167, v174, v175
	v_cvt_pk_bf16_f32 v168, v176, v177
	v_cvt_pk_bf16_f32 v169, v206, v207
	global_store_dwordx4 v[204:205], v[166:169], off offset:256 nt
	s_andn2_b64 vcc, exec, s[8:9]
	s_cbranch_vccnz .LBB0_1124
.LBB0_1132:
	s_waitcnt vmcnt(1)
	v_lshlrev_b32_e32 v2, 16, v162
	v_and_b32_e32 v5, 0xffff0000, v162
	v_lshlrev_b32_e32 v162, 16, v163
	v_and_b32_e32 v163, 0xffff0000, v163
	v_sub_f32_e32 v163, v163, v171
	v_sub_f32_e32 v162, v162, v171
	v_pk_mul_f32 v[162:163], v[4:5], v[162:163] op_sel_hi:[0,1]
	v_lshlrev_b32_e32 v168, 16, v164
	v_and_b32_e32 v169, 0xffff0000, v164
	v_lshlrev_b32_e32 v173, 16, v165
	v_and_b32_e32 v174, 0xffff0000, v165
	s_waitcnt lgkmcnt(1)
	v_pk_fma_f32 v[162:163], v[152:153], v[162:163], v[156:157]
	v_sub_f32_e32 v165, v5, v171
	v_sub_f32_e32 v164, v2, v171
	v_pk_fma_f32 v[166:167], v[162:163], s[76:77], v[80:81] op_sel_hi:[1,0,1]
	v_sub_f32_e32 v163, v174, v171
	v_sub_f32_e32 v162, v173, v171
	v_sub_f32_e32 v169, v169, v171
	v_sub_f32_e32 v168, v168, v171
	v_pk_mul_f32 v[164:165], v[4:5], v[164:165] op_sel_hi:[0,1]
	v_pk_mul_f32 v[168:169], v[4:5], v[168:169] op_sel_hi:[0,1]
	v_pk_mul_f32 v[4:5], v[4:5], v[162:163] op_sel_hi:[0,1]
	v_pk_fma_f32 v[164:165], v[150:151], v[164:165], v[154:155]
	s_waitcnt lgkmcnt(0)
	v_pk_fma_f32 v[4:5], v[144:145], v[4:5], v[148:149]
	v_pk_fma_f32 v[162:163], v[142:143], v[168:169], v[146:147]
	v_pk_fma_f32 v[164:165], v[164:165], s[76:77], v[78:79] op_sel_hi:[1,0,1]
	v_pk_fma_f32 v[168:169], v[162:163], s[76:77], v[82:83] op_sel_hi:[1,0,1]
	v_pk_fma_f32 v[4:5], v[4:5], s[76:77], v[84:85] op_sel_hi:[1,0,1]
	v_pk_add_f32 v[174:175], v[164:165], v[168:169]
	v_pk_add_f32 v[162:163], v[166:167], v[4:5]
	v_pk_mul_f32 v[176:177], v[168:169], v[168:169]
	v_pk_mul_f32 v[204:205], v[4:5], v[4:5]
	v_pk_mov_b32 v[206:207], v[174:175], v[162:163] op_sel:[1,0]
	v_mov_b32_e32 v175, v163
	v_pk_fma_f32 v[204:205], v[166:167], v[166:167], v[204:205]
	v_pk_fma_f32 v[176:177], v[164:165], v[164:165], v[176:177]
	v_pk_add_f32 v[162:163], v[206:207], v[174:175]
	s_nop 0
	v_add_f32_e32 v2, v162, v163
	v_pk_mov_b32 v[162:163], v[176:177], v[204:205] op_sel:[1,0]
	v_mov_b32_e32 v177, v205
	v_pk_add_f32 v[162:163], v[162:163], v[176:177]
	v_add_f32_e32 v140, v2, v140
	v_add_f32_e32 v2, v162, v163
	v_add_f32_e32 v136, v2, v136
	v_cvt_pk_bf16_f32 v162, v164, v165
	v_cvt_pk_bf16_f32 v163, v166, v167
	v_cvt_pk_bf16_f32 v164, v168, v169
	v_cvt_pk_bf16_f32 v165, v4, v5
	global_store_dwordx4 v[186:187], v[162:165], off offset:256 nt
	s_andn2_b64 vcc, exec, s[10:11]
	s_cbranch_vccz .LBB0_1125
	s_branch .LBB0_1126

.LBB0_1134:
	v_mov_b64_e32 v[140:141], v[4:5]
	v_mov_b64_e32 v[138:139], v[2:3]
	v_mul_f32_e32 v5, 0x3a000000, v176
	v_mul_f32_e32 v2, v5, v5
	v_fma_f32 v2, v177, s72, -v2
	v_add_f32_e32 v2, 0x3727c5ac, v2
	v_rsq_f32_e32 v2, v2
	s_and_b32 s24, s84, 32
	s_bitcmp1_b32 s84, 5
	s_cselect_b64 s[20:21], -1, 0
	s_cmp_eq_u32 s24, 0
	s_cbranch_scc1 .LBB0_1136
	s_waitcnt vmcnt(2)
	v_lshlrev_b32_e32 v4, 16, v170
	v_and_b32_e32 v176, 0xffff0000, v170
	v_lshlrev_b32_e32 v170, 16, v171
	v_and_b32_e32 v171, 0xffff0000, v171
	v_sub_f32_e32 v171, v171, v5
	v_sub_f32_e32 v170, v170, v5
	v_pk_mul_f32 v[170:171], v[2:3], v[170:171] op_sel_hi:[0,1]
	v_lshlrev_b32_e32 v184, 16, v172
	v_and_b32_e32 v185, 0xffff0000, v172
	v_lshlrev_b32_e32 v209, 16, v173
	v_and_b32_e32 v216, 0xffff0000, v173
	s_waitcnt lgkmcnt(1)
	v_pk_fma_f32 v[170:171], v[152:153], v[170:171], v[156:157]
	v_sub_f32_e32 v173, v176, v5
	v_sub_f32_e32 v172, v4, v5
	v_pk_fma_f32 v[176:177], v[170:171], s[76:77], v[40:41] op_sel_hi:[1,0,1]
	v_sub_f32_e32 v171, v216, v5
	v_sub_f32_e32 v170, v209, v5
	v_sub_f32_e32 v185, v185, v5
	v_sub_f32_e32 v184, v184, v5
	v_pk_mul_f32 v[172:173], v[2:3], v[172:173] op_sel_hi:[0,1]
	v_pk_mul_f32 v[184:185], v[2:3], v[184:185] op_sel_hi:[0,1]
	v_pk_mul_f32 v[170:171], v[2:3], v[170:171] op_sel_hi:[0,1]
	v_pk_fma_f32 v[172:173], v[150:151], v[172:173], v[154:155]
	s_waitcnt lgkmcnt(0)
	v_pk_fma_f32 v[170:171], v[144:145], v[170:171], v[148:149]
	v_pk_fma_f32 v[184:185], v[142:143], v[184:185], v[146:147]
	v_pk_fma_f32 v[172:173], v[172:173], s[76:77], v[38:39] op_sel_hi:[1,0,1]
	v_pk_fma_f32 v[184:185], v[184:185], s[76:77], v[42:43] op_sel_hi:[1,0,1]
	v_pk_fma_f32 v[216:217], v[170:171], s[76:77], v[44:45] op_sel_hi:[1,0,1]
	v_pk_add_f32 v[218:219], v[172:173], v[184:185]
	v_pk_add_f32 v[170:171], v[176:177], v[216:217]
	v_pk_mul_f32 v[222:223], v[184:185], v[184:185]
	v_pk_mul_f32 v[224:225], v[216:217], v[216:217]
	v_pk_mov_b32 v[226:227], v[218:219], v[170:171] op_sel:[1,0]
	v_mov_b32_e32 v219, v171
	v_pk_fma_f32 v[224:225], v[176:177], v[176:177], v[224:225]
	v_pk_fma_f32 v[222:223], v[172:173], v[172:173], v[222:223]
	v_pk_add_f32 v[170:171], v[226:227], v[218:219]
	s_nop 0
	v_add_f32_e32 v4, v170, v171
	v_pk_mov_b32 v[170:171], v[222:223], v[224:225] op_sel:[1,0]
	v_mov_b32_e32 v223, v225
	v_pk_add_f32 v[170:171], v[170:171], v[222:223]
	v_add_f32_e32 v139, v4, v139
	v_add_f32_e32 v4, v170, v171
	v_cvt_pk_bf16_f32 v171, v176, v177
	v_lshl_add_u64 v[176:177], s[16:17], 0, v[214:215]
	v_add_f32_e32 v135, v4, v135
	v_cvt_pk_bf16_f32 v170, v172, v173
	v_cvt_pk_bf16_f32 v172, v184, v185
	v_cvt_pk_bf16_f32 v173, v216, v217
	v_lshl_add_u64 v[176:177], v[178:179], 1, v[176:177]
	global_store_dwordx4 v[176:177], v[170:173], off nt
.LBB0_1136:
	s_waitcnt vmcnt(2) lgkmcnt(4)
	s_nop 0
	v_mul_f32_e32 v171, 0x3a000000, v162
	v_mul_f32_e32 v4, v171, v171
	v_fma_f32 v4, v163, s72, -v4
	v_add_f32_e32 v4, 0x3727c5ac, v4
	v_rsq_f32_e32 v4, v4
	s_and_b32 s26, s84, 64
	s_bitcmp1_b32 s84, 6
	s_cselect_b64 s[24:25], -1, 0
	s_cmp_eq_u32 s26, 0
	s_cbranch_scc1 .LBB0_1138
	s_waitcnt vmcnt(1)
	v_lshlrev_b32_e32 v170, 16, v166
	v_and_b32_e32 v166, 0xffff0000, v166
	v_lshlrev_b32_e32 v162, 16, v167
	v_and_b32_e32 v163, 0xffff0000, v167
	v_lshlrev_b32_e32 v172, 16, v168
	v_and_b32_e32 v173, 0xffff0000, v168
	v_lshlrev_b32_e32 v168, 16, v169
	v_and_b32_e32 v169, 0xffff0000, v169
	v_sub_f32_e32 v163, v163, v171
	v_sub_f32_e32 v162, v162, v171
	v_sub_f32_e32 v167, v166, v171
	v_sub_f32_e32 v166, v170, v171
	v_sub_f32_e32 v169, v169, v171
	v_sub_f32_e32 v168, v168, v171
	v_sub_f32_e32 v173, v173, v171
	v_sub_f32_e32 v172, v172, v171
	v_pk_mul_f32 v[166:167], v[4:5], v[166:167] op_sel_hi:[0,1]
	v_pk_mul_f32 v[162:163], v[4:5], v[162:163] op_sel_hi:[0,1]
	v_pk_mul_f32 v[172:173], v[4:5], v[172:173] op_sel_hi:[0,1]
	v_pk_mul_f32 v[168:169], v[4:5], v[168:169] op_sel_hi:[0,1]
	s_waitcnt lgkmcnt(1)
	v_pk_fma_f32 v[162:163], v[152:153], v[162:163], v[156:157]
	v_pk_fma_f32 v[166:167], v[150:151], v[166:167], v[154:155]
	s_waitcnt lgkmcnt(0)
	v_pk_fma_f32 v[168:169], v[144:145], v[168:169], v[148:149]
	v_pk_fma_f32 v[172:173], v[142:143], v[172:173], v[146:147]
	v_pk_fma_f32 v[166:167], v[166:167], s[76:77], v[30:31] op_sel_hi:[1,0,1]
	v_pk_fma_f32 v[162:163], v[162:163], s[76:77], v[32:33] op_sel_hi:[1,0,1]
	v_pk_fma_f32 v[172:173], v[172:173], s[76:77], v[34:35] op_sel_hi:[1,0,1]
	v_pk_fma_f32 v[176:177], v[168:169], s[76:77], v[36:37] op_sel_hi:[1,0,1]
	v_pk_add_f32 v[184:185], v[166:167], v[172:173]
	v_pk_add_f32 v[168:169], v[162:163], v[176:177]
	v_pk_mul_f32 v[214:215], v[172:173], v[172:173]
	v_pk_mov_b32 v[218:219], v[184:185], v[168:169] op_sel:[1,0]
	v_mov_b32_e32 v185, v169
	v_pk_mul_f32 v[216:217], v[176:177], v[176:177]
	v_pk_add_f32 v[168:169], v[218:219], v[184:185]
	v_pk_fma_f32 v[216:217], v[162:163], v[162:163], v[216:217]
	v_pk_fma_f32 v[214:215], v[166:167], v[166:167], v[214:215]
	v_add_f32_e32 v168, v168, v169
	v_add_f32_e32 v140, v168, v140
	v_pk_mov_b32 v[168:169], v[214:215], v[216:217] op_sel:[1,0]
	v_mov_b32_e32 v215, v217
	v_pk_add_f32 v[168:169], v[168:169], v[214:215]
	v_cvt_pk_bf16_f32 v166, v166, v167
	v_add_f32_e32 v168, v168, v169
	v_cvt_pk_bf16_f32 v167, v162, v163
	v_lshl_add_u64 v[162:163], s[16:17], 0, v[212:213]
	v_add_f32_e32 v136, v168, v136
	v_cvt_pk_bf16_f32 v168, v172, v173
	v_cvt_pk_bf16_f32 v169, v176, v177
	v_lshl_add_u64 v[162:163], v[178:179], 1, v[162:163]
	global_store_dwordx4 v[162:163], v[166:169], off nt
.LBB0_1138:
	v_mul_f32_e32 v172, 0x3a000000, v164
	v_mul_f32_e32 v162, v172, v172
	v_fma_f32 v162, v165, s72, -v162
	v_add_f32_e32 v162, 0x3727c5ac, v162
	v_rsq_f32_e32 v170, v162
	s_and_b32 s56, s84, 0x80
	s_bitcmp1_b32 s84, 7
	s_cselect_b64 s[26:27], -1, 0
	s_cmp_eq_u32 s56, 0
	s_cbranch_scc1 .LBB0_1140
	s_waitcnt vmcnt(0)
	v_lshlrev_b32_e32 v162, 16, v158
	v_and_b32_e32 v163, 0xffff0000, v158
	v_lshlrev_b32_e32 v158, 16, v159
	v_and_b32_e32 v159, 0xffff0000, v159
	v_lshlrev_b32_e32 v164, 16, v160
	v_and_b32_e32 v165, 0xffff0000, v160
	v_lshlrev_b32_e32 v166, 16, v161
	v_and_b32_e32 v167, 0xffff0000, v161
	v_sub_f32_e32 v159, v159, v172
	v_sub_f32_e32 v158, v158, v172
	v_sub_f32_e32 v161, v163, v172
	v_sub_f32_e32 v160, v162, v172
	v_pk_mul_f32 v[160:161], v[170:171], v[160:161] op_sel_hi:[0,1]
	v_pk_mul_f32 v[158:159], v[170:171], v[158:159] op_sel_hi:[0,1]
	s_waitcnt lgkmcnt(1)
	v_pk_fma_f32 v[152:153], v[152:153], v[158:159], v[156:157]
	v_pk_fma_f32 v[150:151], v[150:151], v[160:161], v[154:155]
	v_sub_f32_e32 v155, v167, v172
	v_sub_f32_e32 v154, v166, v172
	v_sub_f32_e32 v157, v165, v172
	v_sub_f32_e32 v156, v164, v172
	v_pk_mul_f32 v[156:157], v[170:171], v[156:157] op_sel_hi:[0,1]
	v_pk_mul_f32 v[154:155], v[170:171], v[154:155] op_sel_hi:[0,1]
	s_waitcnt lgkmcnt(0)
	v_pk_fma_f32 v[144:145], v[144:145], v[154:155], v[148:149]
	v_pk_fma_f32 v[142:143], v[142:143], v[156:157], v[146:147]
	v_pk_fma_f32 v[150:151], v[150:151], s[76:77], v[22:23] op_sel_hi:[1,0,1]
	v_pk_fma_f32 v[152:153], v[152:153], s[76:77], v[24:25] op_sel_hi:[1,0,1]
	v_pk_fma_f32 v[146:147], v[142:143], s[76:77], v[26:27] op_sel_hi:[1,0,1]
	v_pk_fma_f32 v[148:149], v[144:145], s[76:77], v[28:29] op_sel_hi:[1,0,1]
	v_pk_add_f32 v[144:145], v[150:151], v[146:147]
	v_pk_add_f32 v[142:143], v[152:153], v[148:149]
	v_pk_mul_f32 v[154:155], v[146:147], v[146:147]
	v_pk_mov_b32 v[158:159], v[144:145], v[142:143] op_sel:[1,0]
	v_mov_b32_e32 v145, v143
	v_pk_mul_f32 v[156:157], v[148:149], v[148:149]
	v_pk_add_f32 v[142:143], v[158:159], v[144:145]
	v_pk_fma_f32 v[156:157], v[152:153], v[152:153], v[156:157]
	v_pk_fma_f32 v[154:155], v[150:151], v[150:151], v[154:155]
	v_add_f32_e32 v142, v142, v143
	v_add_f32_e32 v141, v142, v141
	v_pk_mov_b32 v[142:143], v[154:155], v[156:157] op_sel:[1,0]
	v_mov_b32_e32 v155, v157
	v_pk_add_f32 v[142:143], v[142:143], v[154:155]
	v_cvt_pk_bf16_f32 v144, v146, v147
	v_add_f32_e32 v142, v142, v143
	v_lshl_add_u64 v[146:147], s[16:17], 0, v[210:211]
	v_add_f32_e32 v137, v142, v137
	v_cvt_pk_bf16_f32 v142, v150, v151
	v_cvt_pk_bf16_f32 v143, v152, v153
	v_cvt_pk_bf16_f32 v145, v148, v149
	v_lshl_add_u64 v[146:147], v[178:179], 1, v[146:147]
	global_store_dwordx4 v[146:147], v[142:145], off nt

.LBB0_1144:
	s_waitcnt vmcnt(0)
	v_lshlrev_b32_e32 v2, 16, v158
	v_and_b32_e32 v158, 0xffff0000, v158
	v_lshlrev_b32_e32 v4, 16, v159
	v_and_b32_e32 v5, 0xffff0000, v159
	v_sub_f32_e32 v5, v5, v172
	v_sub_f32_e32 v4, v4, v172
	v_sub_f32_e32 v159, v158, v172
	v_sub_f32_e32 v158, v2, v172
	v_lshlrev_b32_e32 v162, 16, v160
	v_and_b32_e32 v160, 0xffff0000, v160
	v_lshlrev_b32_e32 v163, 16, v161
	v_and_b32_e32 v161, 0xffff0000, v161
	v_pk_mul_f32 v[158:159], v[170:171], v[158:159] op_sel_hi:[0,1]
	v_pk_mul_f32 v[4:5], v[170:171], v[4:5] op_sel_hi:[0,1]
	s_waitcnt lgkmcnt(1)
	v_pk_fma_f32 v[4:5], v[152:153], v[4:5], v[156:157]
	v_pk_fma_f32 v[150:151], v[150:151], v[158:159], v[154:155]
	v_sub_f32_e32 v153, v161, v172
	v_sub_f32_e32 v152, v163, v172
	v_sub_f32_e32 v155, v160, v172
	v_sub_f32_e32 v154, v162, v172
	v_pk_mul_f32 v[154:155], v[170:171], v[154:155] op_sel_hi:[0,1]
	v_pk_mul_f32 v[152:153], v[170:171], v[152:153] op_sel_hi:[0,1]
	s_waitcnt lgkmcnt(0)
	v_pk_fma_f32 v[144:145], v[144:145], v[152:153], v[148:149]
	v_pk_fma_f32 v[142:143], v[142:143], v[154:155], v[146:147]
	v_pk_fma_f32 v[150:151], v[150:151], s[76:77], v[58:59] op_sel_hi:[1,0,1]
	v_pk_fma_f32 v[4:5], v[4:5], s[76:77], v[60:61] op_sel_hi:[1,0,1]
	v_pk_fma_f32 v[146:147], v[142:143], s[76:77], v[66:67] op_sel_hi:[1,0,1]
	v_pk_fma_f32 v[148:149], v[144:145], s[76:77], v[68:69] op_sel_hi:[1,0,1]
	v_pk_add_f32 v[144:145], v[150:151], v[146:147]
	v_pk_add_f32 v[142:143], v[4:5], v[148:149]
	v_pk_mul_f32 v[152:153], v[146:147], v[146:147]
	v_pk_mul_f32 v[154:155], v[148:149], v[148:149]
	v_pk_mov_b32 v[156:157], v[144:145], v[142:143] op_sel:[1,0]
	v_mov_b32_e32 v145, v143
	v_pk_fma_f32 v[154:155], v[4:5], v[4:5], v[154:155]
	v_pk_fma_f32 v[152:153], v[150:151], v[150:151], v[152:153]
	v_pk_add_f32 v[142:143], v[156:157], v[144:145]
	v_cvt_pk_bf16_f32 v144, v146, v147
	v_add_f32_e32 v2, v142, v143
	v_pk_mov_b32 v[142:143], v[152:153], v[154:155] op_sel:[1,0]
	v_mov_b32_e32 v153, v155
	v_pk_add_f32 v[142:143], v[142:143], v[152:153]
	v_add_f32_e32 v141, v2, v141
	v_add_f32_e32 v2, v142, v143
	v_add_f32_e32 v137, v2, v137
	v_cvt_pk_bf16_f32 v142, v150, v151
	v_cvt_pk_bf16_f32 v143, v4, v5
	v_cvt_pk_bf16_f32 v145, v148, v149
	global_store_dwordx4 v[186:187], v[142:145], off offset:256 nt

.LBB0_1148:
	s_cmp_lt_i32 s4, 32
	s_cselect_b32 s0, 0, 0xffffe000
	s_waitcnt lgkmcnt(6)
	v_add_u32_e32 v4, s0, v180
	v_ashrrev_i32_e32 v5, 31, v4
	s_cselect_b32 s1, s29, s43
	s_cselect_b32 s0, s28, s42
	v_lshlrev_b64 v[4:5], 13, v[4:5]
	v_lshl_add_u64 v[4:5], s[0:1], 0, v[4:5]
	s_bitcmp0_b32 s84, 0
	v_lshl_add_u64 v[4:5], v[178:179], 2, v[4:5]
	s_cbranch_scc1 .LBB0_1153
	global_load_dwordx4 v[134:137], v[4:5], off offset:16
	s_waitcnt lgkmcnt(0)
	global_load_dwordx4 v[138:141], v[4:5], off
	v_cmp_lt_i32_e32 vcc, v234, v230
	s_waitcnt vmcnt(1)
	v_pk_fma_f32 v[144:145], v[136:137], s[76:77], v[132:133] op_sel_hi:[1,0,1]
	s_waitcnt vmcnt(0)
	v_pk_fma_f32 v[138:139], v[138:139], s[76:77], v[126:127] op_sel_hi:[1,0,1]
	v_pk_fma_f32 v[146:147], v[134:135], s[76:77], v[130:131] op_sel_hi:[1,0,1]
	v_pk_fma_f32 v[140:141], v[140:141], s[76:77], v[128:129] op_sel_hi:[1,0,1]
	v_mul_f32_e32 v134, v146, v146
	v_mul_f32_e32 v136, v147, v147
	v_mul_f32_e32 v148, v144, v144
	v_mul_f32_e32 v150, v145, v145
	v_pk_mul_f32 v[152:153], v[138:139], v[138:139]
	v_pk_add_f32 v[154:155], v[138:139], v[138:139] op_sel_hi:[0,1]
	v_mov_b32_e32 v135, v146
	v_mov_b32_e32 v137, v147
	v_mov_b32_e32 v151, v145
	v_mov_b32_e32 v149, v144
	v_mul_f32_e32 v2, v141, v141
	v_mov_b32_e32 v153, v155
	v_pk_mov_b32 v[154:155], v[138:139], v[140:141] op_sel:[1,0]
	v_pk_add_f32 v[134:135], v[134:135], v[136:137]
	v_pk_add_f32 v[136:137], v[150:151], v[148:149]
	v_pk_fma_f32 v[142:143], v[140:141], v[140:141], v[2:3] op_sel_hi:[1,1,0]
	v_pk_mul_f32 v[156:157], v[138:139], v[154:155] op_sel:[1,0] op_sel_hi:[0,1]
	v_pk_add_f32 v[154:155], v[140:141], v[154:155]
	v_pk_add_f32 v[134:135], v[134:135], v[136:137]
	v_cvt_pk_bf16_f32 v137, v140, v141
	v_lshlrev_b64 v[140:141], 12, v[180:181]
	v_mov_b32_e32 v157, v155
	v_lshl_add_u64 v[140:141], s[16:17], 0, v[140:141]
	v_pk_add_f32 v[152:153], v[152:153], v[156:157]
	v_mov_b32_e32 v143, v3
	v_cvt_pk_bf16_f32 v136, v138, v139
	v_cvt_pk_bf16_f32 v138, v146, v147
	v_cvt_pk_bf16_f32 v139, v144, v145
	v_lshl_add_u64 v[144:145], v[178:179], 1, v[140:141]
	v_pk_add_f32 v[142:143], v[152:153], v[142:143]
	global_store_dwordx4 v[144:145], v[136:139], off nt
	v_pk_add_f32 v[134:135], v[134:135], v[142:143]
	global_load_dwordx4 v[136:139], v[4:5], off offset:528
	global_load_dwordx4 v[140:143], v[4:5], off offset:512
	v_cndmask_b32_e32 v2, v228, v234, vcc
	v_lshlrev_b32_e32 v2, 2, v2
	v_cmp_lt_i32_e32 vcc, v195, v230
	s_waitcnt vmcnt(0)
	v_pk_fma_f32 v[142:143], v[142:143], s[76:77], v[96:97] op_sel_hi:[1,0,1]
	v_pk_fma_f32 v[140:141], v[140:141], s[76:77], v[94:95] op_sel_hi:[1,0,1]
	v_mul_f32_e32 v150, v142, v142
	v_mul_f32_e32 v146, v140, v140
	v_mul_f32_e32 v148, v141, v141
	v_mul_f32_e32 v152, v143, v143
	v_mov_b32_e32 v147, v140
	v_mov_b32_e32 v149, v141
	v_mov_b32_e32 v153, v143
	v_mov_b32_e32 v151, v142
	v_pk_add_f32 v[146:147], v[146:147], v[148:149]
	v_pk_add_f32 v[148:149], v[152:153], v[150:151]
	v_pk_fma_f32 v[150:151], v[136:137], s[76:77], v[98:99] op_sel_hi:[1,0,1]
	v_pk_add_f32 v[146:147], v[146:147], v[148:149]
	v_pk_fma_f32 v[148:149], v[138:139], s[76:77], v[100:101] op_sel_hi:[1,0,1]
	v_mul_f32_e32 v136, v150, v150
	v_mul_f32_e32 v138, v151, v151
	v_mov_b32_e32 v137, v150
	v_mov_b32_e32 v139, v151
	v_pk_add_f32 v[136:137], v[136:137], v[138:139]
	v_mul_f32_e32 v138, v148, v148
	v_mul_f32_e32 v152, v149, v149
	v_mov_b32_e32 v153, v149
	v_mov_b32_e32 v139, v148
	v_pk_add_f32 v[138:139], v[152:153], v[138:139]
	v_pk_add_f32 v[134:135], v[134:135], v[146:147]
	v_pk_add_f32 v[136:137], v[136:137], v[138:139]
	v_cvt_pk_bf16_f32 v140, v140, v141
	v_pk_add_f32 v[134:135], v[134:135], v[136:137]
	ds_bpermute_b32 v137, v2, v135
	ds_bpermute_b32 v136, v2, v134
	v_cvt_pk_bf16_f32 v141, v142, v143
	v_cvt_pk_bf16_f32 v142, v150, v151
	v_cvt_pk_bf16_f32 v143, v148, v149
	global_store_dwordx4 v[144:145], v[140:143], off offset:256 nt
	s_waitcnt lgkmcnt(0)
	v_pk_add_f32 v[134:135], v[134:135], v[136:137]
	v_cndmask_b32_e32 v140, v228, v195, vcc
	v_lshlrev_b32_e32 v140, 2, v140
	ds_bpermute_b32 v137, v140, v135
	ds_bpermute_b32 v136, v140, v134
	v_cmp_eq_u32_e32 vcc, 0, v191
	s_waitcnt lgkmcnt(0)
	v_pk_add_f32 v[134:135], v[134:135], v[136:137]
	s_nop 0
	v_cndmask_b32_e32 v137, 0, v135, vcc
	v_cndmask_b32_e32 v136, 0, v134, vcc
	s_bitcmp0_b32 s84, 1
	s_cbranch_scc0 .LBB0_1154
	s_branch .LBB0_1155
.LBB0_1150:
	global_load_dwordx4 v[210:213], v[174:175], off offset:256
	s_waitcnt vmcnt(0)
	v_lshlrev_b32_e32 v173, 16, v210
	v_and_b32_e32 v184, 0xffff0000, v210
	v_lshlrev_b32_e32 v176, 16, v211
	v_and_b32_e32 v177, 0xffff0000, v211
	v_lshlrev_b32_e32 v197, 16, v212
	v_and_b32_e32 v199, 0xffff0000, v212
	v_lshlrev_b32_e32 v209, 16, v213
	v_and_b32_e32 v210, 0xffff0000, v213
	v_sub_f32_e32 v177, v177, v183
	v_sub_f32_e32 v176, v176, v183
	v_sub_f32_e32 v185, v184, v183
	v_sub_f32_e32 v184, v173, v183
	v_sub_f32_e32 v211, v210, v183
	v_sub_f32_e32 v210, v209, v183
	v_sub_f32_e32 v213, v199, v183
	v_sub_f32_e32 v212, v197, v183
	v_pk_mul_f32 v[184:185], v[208:209], v[184:185] op_sel_hi:[0,1]
	v_pk_mul_f32 v[176:177], v[208:209], v[176:177] op_sel_hi:[0,1]
	v_pk_mul_f32 v[212:213], v[208:209], v[212:213] op_sel_hi:[0,1]
	v_pk_mul_f32 v[208:209], v[208:209], v[210:211] op_sel_hi:[0,1]
	s_waitcnt lgkmcnt(1)
	v_pk_fma_f32 v[176:177], v[152:153], v[176:177], v[156:157]
	v_pk_fma_f32 v[184:185], v[150:151], v[184:185], v[154:155]
	s_waitcnt lgkmcnt(0)
	v_pk_fma_f32 v[208:209], v[144:145], v[208:209], v[148:149]
	v_pk_fma_f32 v[210:211], v[142:143], v[212:213], v[146:147]
	v_pk_fma_f32 v[184:185], v[184:185], s[76:77], v[14:15] op_sel_hi:[1,0,1]
	v_pk_fma_f32 v[176:177], v[176:177], s[76:77], v[16:17] op_sel_hi:[1,0,1]
	v_pk_fma_f32 v[210:211], v[210:211], s[76:77], v[18:19] op_sel_hi:[1,0,1]
	v_pk_fma_f32 v[212:213], v[208:209], s[76:77], v[20:21] op_sel_hi:[1,0,1]
	v_pk_add_f32 v[214:215], v[184:185], v[210:211]
	v_pk_add_f32 v[208:209], v[176:177], v[212:213]
	v_pk_mul_f32 v[216:217], v[210:211], v[210:211]
	v_pk_mul_f32 v[218:219], v[212:213], v[212:213]
	v_pk_mov_b32 v[222:223], v[214:215], v[208:209] op_sel:[1,0]
	v_mov_b32_e32 v215, v209
	v_pk_fma_f32 v[218:219], v[176:177], v[176:177], v[218:219]
	v_pk_fma_f32 v[216:217], v[184:185], v[184:185], v[216:217]
	v_pk_add_f32 v[208:209], v[222:223], v[214:215]
	v_cvt_pk_bf16_f32 v210, v210, v211
	v_add_f32_e32 v173, v208, v209
	v_pk_mov_b32 v[208:209], v[216:217], v[218:219] op_sel:[1,0]
	v_mov_b32_e32 v217, v219
	v_pk_add_f32 v[208:209], v[208:209], v[216:217]
	v_add_f32_e32 v138, v138, v173
	v_add_f32_e32 v173, v208, v209
	v_add_f32_e32 v134, v134, v173
	v_cvt_pk_bf16_f32 v208, v184, v185
	v_cvt_pk_bf16_f32 v209, v176, v177
	v_cvt_pk_bf16_f32 v211, v212, v213
	global_store_dwordx4 v[174:175], v[208:211], off offset:256 nt
	s_andn2_b64 vcc, exec, s[20:21]
	s_cbranch_vccnz .LBB0_1142
.LBB0_1151:
	s_waitcnt vmcnt(2)
	v_lshlrev_b32_e32 v173, 16, v166
	v_and_b32_e32 v174, 0xffff0000, v166
	v_lshlrev_b32_e32 v166, 16, v167
	v_and_b32_e32 v167, 0xffff0000, v167
	v_sub_f32_e32 v167, v167, v5
	v_sub_f32_e32 v166, v166, v5
	v_pk_mul_f32 v[166:167], v[2:3], v[166:167] op_sel_hi:[0,1]
	v_lshlrev_b32_e32 v176, 16, v168
	v_and_b32_e32 v177, 0xffff0000, v168
	v_lshlrev_b32_e32 v183, 16, v169
	v_and_b32_e32 v184, 0xffff0000, v169
	s_waitcnt lgkmcnt(1)
	v_pk_fma_f32 v[166:167], v[152:153], v[166:167], v[156:157]
	v_sub_f32_e32 v169, v174, v5
	v_sub_f32_e32 v168, v173, v5
	v_pk_fma_f32 v[174:175], v[166:167], s[76:77], v[8:9] op_sel_hi:[1,0,1]
	v_sub_f32_e32 v167, v184, v5
	v_sub_f32_e32 v166, v183, v5
	v_sub_f32_e32 v177, v177, v5
	v_sub_f32_e32 v176, v176, v5
	v_pk_mul_f32 v[168:169], v[2:3], v[168:169] op_sel_hi:[0,1]
	v_pk_mul_f32 v[176:177], v[2:3], v[176:177] op_sel_hi:[0,1]
	v_pk_mul_f32 v[166:167], v[2:3], v[166:167] op_sel_hi:[0,1]
	v_pk_fma_f32 v[168:169], v[150:151], v[168:169], v[154:155]
	s_waitcnt lgkmcnt(0)
	v_pk_fma_f32 v[166:167], v[144:145], v[166:167], v[148:149]
	v_pk_fma_f32 v[176:177], v[142:143], v[176:177], v[146:147]
	v_pk_fma_f32 v[168:169], v[168:169], s[76:77], v[6:7] op_sel_hi:[1,0,1]
	v_pk_fma_f32 v[176:177], v[176:177], s[76:77], v[10:11] op_sel_hi:[1,0,1]
	v_pk_fma_f32 v[184:185], v[166:167], s[76:77], v[12:13] op_sel_hi:[1,0,1]
	v_pk_add_f32 v[208:209], v[168:169], v[176:177]
	v_pk_add_f32 v[166:167], v[174:175], v[184:185]
	v_pk_mul_f32 v[210:211], v[176:177], v[176:177]
	v_pk_mul_f32 v[212:213], v[184:185], v[184:185]
	v_pk_mov_b32 v[214:215], v[208:209], v[166:167] op_sel:[1,0]
	v_mov_b32_e32 v209, v167
	v_pk_fma_f32 v[212:213], v[174:175], v[174:175], v[212:213]
	v_pk_fma_f32 v[210:211], v[168:169], v[168:169], v[210:211]
	v_pk_add_f32 v[166:167], v[214:215], v[208:209]
	s_nop 0
	v_add_f32_e32 v2, v166, v167
	v_pk_mov_b32 v[166:167], v[210:211], v[212:213] op_sel:[1,0]
	v_mov_b32_e32 v211, v213
	v_pk_add_f32 v[166:167], v[166:167], v[210:211]
	v_add_f32_e32 v139, v2, v139
	v_add_f32_e32 v2, v166, v167
	v_add_f32_e32 v135, v2, v135
	v_cvt_pk_bf16_f32 v166, v168, v169
	v_cvt_pk_bf16_f32 v167, v174, v175
	v_cvt_pk_bf16_f32 v168, v176, v177
	v_cvt_pk_bf16_f32 v169, v184, v185
	global_store_dwordx4 v[206:207], v[166:169], off offset:256 nt
	s_andn2_b64 vcc, exec, s[24:25]
	s_cbranch_vccnz .LBB0_1143
.LBB0_1152:
	s_waitcnt vmcnt(1)
	v_lshlrev_b32_e32 v2, 16, v162
	v_and_b32_e32 v5, 0xffff0000, v162
	v_lshlrev_b32_e32 v162, 16, v163
	v_and_b32_e32 v163, 0xffff0000, v163
	v_sub_f32_e32 v163, v163, v171
	v_sub_f32_e32 v162, v162, v171
	v_pk_mul_f32 v[162:163], v[4:5], v[162:163] op_sel_hi:[0,1]
	v_lshlrev_b32_e32 v168, 16, v164
	v_and_b32_e32 v169, 0xffff0000, v164
	v_lshlrev_b32_e32 v173, 16, v165
	v_and_b32_e32 v174, 0xffff0000, v165
	s_waitcnt lgkmcnt(1)
	v_pk_fma_f32 v[162:163], v[152:153], v[162:163], v[156:157]
	v_sub_f32_e32 v165, v5, v171
	v_sub_f32_e32 v164, v2, v171
	v_pk_fma_f32 v[166:167], v[162:163], s[76:77], v[56:57] op_sel_hi:[1,0,1]
	v_sub_f32_e32 v163, v174, v171
	v_sub_f32_e32 v162, v173, v171
	v_sub_f32_e32 v169, v169, v171
	v_sub_f32_e32 v168, v168, v171
	v_pk_mul_f32 v[164:165], v[4:5], v[164:165] op_sel_hi:[0,1]
	v_pk_mul_f32 v[168:169], v[4:5], v[168:169] op_sel_hi:[0,1]
	v_pk_mul_f32 v[4:5], v[4:5], v[162:163] op_sel_hi:[0,1]
	v_pk_fma_f32 v[164:165], v[150:151], v[164:165], v[154:155]
	s_waitcnt lgkmcnt(0)
	v_pk_fma_f32 v[4:5], v[144:145], v[4:5], v[148:149]
	v_pk_fma_f32 v[162:163], v[142:143], v[168:169], v[146:147]
	v_pk_fma_f32 v[164:165], v[164:165], s[76:77], v[54:55] op_sel_hi:[1,0,1]
	v_pk_fma_f32 v[168:169], v[162:163], s[76:77], v[62:63] op_sel_hi:[1,0,1]
	v_pk_fma_f32 v[4:5], v[4:5], s[76:77], v[64:65] op_sel_hi:[1,0,1]
	v_pk_add_f32 v[174:175], v[164:165], v[168:169]
	v_pk_add_f32 v[162:163], v[166:167], v[4:5]
	v_pk_mul_f32 v[176:177], v[168:169], v[168:169]
	v_pk_mul_f32 v[184:185], v[4:5], v[4:5]
	v_pk_mov_b32 v[206:207], v[174:175], v[162:163] op_sel:[1,0]
	v_mov_b32_e32 v175, v163
	v_pk_fma_f32 v[184:185], v[166:167], v[166:167], v[184:185]
	v_pk_fma_f32 v[176:177], v[164:165], v[164:165], v[176:177]
	v_pk_add_f32 v[162:163], v[206:207], v[174:175]
	s_nop 0
	v_add_f32_e32 v2, v162, v163
	v_pk_mov_b32 v[162:163], v[176:177], v[184:185] op_sel:[1,0]
	v_mov_b32_e32 v177, v185
	v_pk_add_f32 v[162:163], v[162:163], v[176:177]
	v_add_f32_e32 v140, v2, v140
	v_add_f32_e32 v2, v162, v163
	v_add_f32_e32 v136, v2, v136
	v_cvt_pk_bf16_f32 v162, v164, v165
	v_cvt_pk_bf16_f32 v163, v166, v167
	v_cvt_pk_bf16_f32 v164, v168, v169
	v_cvt_pk_bf16_f32 v165, v4, v5
	global_store_dwordx4 v[204:205], v[162:165], off offset:256 nt
	s_andn2_b64 vcc, exec, s[26:27]
	s_cbranch_vccz .LBB0_1144
	s_branch .LBB0_1145

.LBB0_1154:
	v_add_co_u32_e32 v134, vcc, 0x20000, v4
	s_mov_b64 s[0:1], 0x20000
	s_nop 0
	v_addc_co_u32_e32 v135, vcc, 0, v5, vcc
	s_waitcnt lgkmcnt(2)
	v_lshl_add_u64 v[142:143], v[4:5], 0, s[0:1]
	s_waitcnt lgkmcnt(0)
	global_load_dwordx4 v[138:141], v[134:135], off
	v_lshlrev_b64 v[146:147], 12, v[180:181]
	global_load_dwordx4 v[142:145], v[142:143], off offset:16
	v_lshl_add_u64 v[146:147], s[16:17], 0, v[146:147]
	v_lshl_add_u64 v[146:147], v[178:179], 1, v[146:147]
	s_mov_b32 s0, 0x10000
	v_add_co_u32_e32 v148, vcc, s0, v146
	s_mov_b64 s[0:1], 0x20200
	s_nop 0
	v_addc_co_u32_e32 v149, vcc, 0, v147, vcc
	v_cmp_lt_i32_e32 vcc, v234, v230
	s_waitcnt vmcnt(1)
	v_pk_fma_f32 v[150:151], v[140:141], s[76:77], v[120:121] op_sel_hi:[1,0,1]
	v_pk_fma_f32 v[152:153], v[138:139], s[76:77], v[118:119] op_sel_hi:[1,0,1]
	s_waitcnt vmcnt(0)
	v_pk_fma_f32 v[154:155], v[144:145], s[76:77], v[124:125] op_sel_hi:[1,0,1]
	v_pk_fma_f32 v[156:157], v[142:143], s[76:77], v[122:123] op_sel_hi:[1,0,1]
	v_cvt_pk_bf16_f32 v138, v152, v153
	v_cvt_pk_bf16_f32 v139, v150, v151
	v_cvt_pk_bf16_f32 v140, v156, v157
	v_cvt_pk_bf16_f32 v141, v154, v155
	global_store_dwordx4 v[148:149], v[138:141], off nt
	global_load_dwordx4 v[138:141], v[134:135], off offset:512
	v_lshl_add_u64 v[134:135], v[4:5], 0, s[0:1]
	global_load_dwordx4 v[142:145], v[134:135], off offset:16
	v_cndmask_b32_e32 v2, v228, v234, vcc
	v_mov_b32_e32 v134, v152
	v_mov_b32_e32 v135, v151
	v_pk_mov_b32 v[148:149], v[152:153], v[150:151] op_sel:[1,0]
	v_lshlrev_b32_e32 v164, 2, v2
	v_pk_mul_f32 v[152:153], v[152:153], v[152:153]
	v_mul_f32_e32 v2, v151, v151
	v_mul_f32_e32 v158, v156, v156
	v_mul_f32_e32 v160, v157, v157
	v_mov_b32_e32 v159, v156
	v_mov_b32_e32 v161, v157
	v_mul_f32_e32 v156, v154, v154
	v_mul_f32_e32 v162, v155, v155
	v_mov_b32_e32 v163, v155
	v_mov_b32_e32 v157, v154
	v_pk_add_f32 v[134:135], v[134:135], v[148:149]
	v_pk_fma_f32 v[148:149], v[150:151], v[150:151], v[2:3] op_sel_hi:[1,1,0]
	v_pk_add_f32 v[154:155], v[162:163], v[156:157]
	v_mov_b32_e32 v156, v152
	v_mov_b32_e32 v157, v134
	v_mov_b32_e32 v134, v153
	v_pk_add_f32 v[150:151], v[158:159], v[160:161]
	v_mov_b32_e32 v149, v3
	v_pk_add_f32 v[134:135], v[156:157], v[134:135]
	v_pk_add_f32 v[150:151], v[150:151], v[154:155]
	v_pk_add_f32 v[134:135], v[134:135], v[148:149]
	v_cmp_lt_i32_e32 vcc, v195, v230
	v_pk_add_f32 v[134:135], v[134:135], v[150:151]
	s_mov_b64 s[0:1], 0x10000
	v_cndmask_b32_e32 v2, v228, v195, vcc
	v_lshlrev_b32_e32 v2, 2, v2
	v_lshl_add_u64 v[146:147], v[146:147], 0, s[0:1]
	v_cmp_eq_u32_e32 vcc, 1, v191
	s_waitcnt vmcnt(1)
	v_pk_fma_f32 v[140:141], v[140:141], s[76:77], v[88:89] op_sel_hi:[1,0,1]
	v_pk_fma_f32 v[138:139], v[138:139], s[76:77], v[86:87] op_sel_hi:[1,0,1]
	s_waitcnt vmcnt(0)
	v_pk_fma_f32 v[144:145], v[144:145], s[76:77], v[92:93] op_sel_hi:[1,0,1]
	v_pk_fma_f32 v[142:143], v[142:143], s[76:77], v[90:91] op_sel_hi:[1,0,1]
	v_mul_f32_e32 v148, v138, v138
	v_mul_f32_e32 v150, v139, v139
	v_mul_f32_e32 v152, v140, v140
	v_mul_f32_e32 v154, v141, v141
	v_mov_b32_e32 v149, v138
	v_mov_b32_e32 v151, v139
	v_mov_b32_e32 v155, v141
	v_mov_b32_e32 v153, v140
	v_mul_f32_e32 v156, v142, v142
	v_mul_f32_e32 v158, v143, v143
	v_mul_f32_e32 v160, v144, v144
	v_mul_f32_e32 v162, v145, v145
	v_mov_b32_e32 v157, v142
	v_mov_b32_e32 v159, v143
	v_mov_b32_e32 v163, v145
	v_mov_b32_e32 v161, v144
	v_pk_add_f32 v[148:149], v[148:149], v[150:151]
	v_pk_add_f32 v[150:151], v[154:155], v[152:153]
	v_pk_add_f32 v[152:153], v[156:157], v[158:159]
	v_pk_add_f32 v[154:155], v[162:163], v[160:161]
	v_pk_add_f32 v[148:149], v[148:149], v[150:151]
	v_pk_add_f32 v[150:151], v[152:153], v[154:155]
	v_pk_add_f32 v[134:135], v[134:135], v[148:149]
	v_cvt_pk_bf16_f32 v138, v138, v139
	v_pk_add_f32 v[134:135], v[134:135], v[150:151]
	ds_bpermute_b32 v149, v164, v135
	ds_bpermute_b32 v148, v164, v134
	v_cvt_pk_bf16_f32 v139, v140, v141
	v_cvt_pk_bf16_f32 v140, v142, v143
	v_cvt_pk_bf16_f32 v141, v144, v145
	global_store_dwordx4 v[146:147], v[138:141], off offset:256 nt
	s_waitcnt lgkmcnt(0)
	v_pk_add_f32 v[134:135], v[134:135], v[148:149]
	ds_bpermute_b32 v149, v2, v135
	ds_bpermute_b32 v148, v2, v134
	s_waitcnt lgkmcnt(0)
	v_pk_add_f32 v[134:135], v[134:135], v[148:149]
	s_nop 0
	v_cndmask_b32_e32 v137, v137, v135, vcc
	v_cndmask_b32_e32 v136, v136, v134, vcc

.LBB0_1157:
	v_add_co_u32_e32 v134, vcc, 0x60000, v4
	s_mov_b64 s[0:1], 0x60000
	s_nop 0
	v_addc_co_u32_e32 v135, vcc, 0, v5, vcc
	s_waitcnt lgkmcnt(2)
	v_lshl_add_u64 v[142:143], v[4:5], 0, s[0:1]
	s_waitcnt lgkmcnt(0)
	global_load_dwordx4 v[138:141], v[134:135], off
	v_lshlrev_b64 v[146:147], 12, v[180:181]
	global_load_dwordx4 v[142:145], v[142:143], off offset:16
	v_lshl_add_u64 v[146:147], s[16:17], 0, v[146:147]
	v_lshl_add_u64 v[146:147], v[178:179], 1, v[146:147]
	s_mov_b32 s0, 0x30000
	v_add_co_u32_e32 v148, vcc, s0, v146
	s_mov_b64 s[0:1], 0x60200
	s_nop 0
	v_addc_co_u32_e32 v149, vcc, 0, v147, vcc
	v_cmp_lt_i32_e32 vcc, v234, v230
	s_waitcnt vmcnt(1)
	v_pk_fma_f32 v[150:151], v[140:141], s[76:77], v[104:105] op_sel_hi:[1,0,1]
	v_pk_fma_f32 v[152:153], v[138:139], s[76:77], v[102:103] op_sel_hi:[1,0,1]
	s_waitcnt vmcnt(0)
	v_pk_fma_f32 v[154:155], v[144:145], s[76:77], v[108:109] op_sel_hi:[1,0,1]
	v_pk_fma_f32 v[156:157], v[142:143], s[76:77], v[106:107] op_sel_hi:[1,0,1]
	v_cvt_pk_bf16_f32 v138, v152, v153
	v_cvt_pk_bf16_f32 v139, v150, v151
	v_cvt_pk_bf16_f32 v140, v156, v157
	v_cvt_pk_bf16_f32 v141, v154, v155
	global_store_dwordx4 v[148:149], v[138:141], off nt
	global_load_dwordx4 v[138:141], v[134:135], off offset:512
	v_lshl_add_u64 v[134:135], v[4:5], 0, s[0:1]
	global_load_dwordx4 v[142:145], v[134:135], off offset:16
	v_cndmask_b32_e32 v2, v228, v234, vcc
	v_lshlrev_b32_e32 v168, 2, v2
	v_mul_f32_e32 v2, v151, v151
	v_pk_mov_b32 v[166:167], v[152:153], v[150:151] op_sel:[1,0]
	v_mul_f32_e32 v134, v156, v156
	v_mul_f32_e32 v148, v157, v157
	v_mul_f32_e32 v158, v154, v154
	v_mul_f32_e32 v160, v155, v155
	v_pk_mul_f32 v[162:163], v[152:153], v[152:153]
	v_pk_add_f32 v[164:165], v[152:153], v[152:153] op_sel_hi:[0,1]
	v_mov_b32_e32 v135, v156
	v_mov_b32_e32 v149, v157
	v_mov_b32_e32 v161, v155
	v_mov_b32_e32 v159, v154
	v_pk_fma_f32 v[154:155], v[150:151], v[150:151], v[2:3] op_sel_hi:[1,1,0]
	v_pk_mul_f32 v[152:153], v[152:153], v[166:167] op_sel:[1,0] op_sel_hi:[0,1]
	v_pk_add_f32 v[150:151], v[150:151], v[166:167]
	v_mov_b32_e32 v163, v165
	v_pk_add_f32 v[134:135], v[134:135], v[148:149]
	v_pk_add_f32 v[148:149], v[160:161], v[158:159]
	v_mov_b32_e32 v153, v151
	v_mov_b32_e32 v155, v3
	v_pk_add_f32 v[134:135], v[134:135], v[148:149]
	v_pk_add_f32 v[148:149], v[162:163], v[152:153]
	v_cmp_lt_i32_e32 vcc, v195, v230
	v_pk_add_f32 v[148:149], v[148:149], v[154:155]
	s_mov_b64 s[0:1], 0x30000
	v_pk_add_f32 v[134:135], v[148:149], v[134:135]
	v_cndmask_b32_e32 v2, v228, v195, vcc
	v_lshlrev_b32_e32 v2, 2, v2
	v_lshl_add_u64 v[146:147], v[146:147], 0, s[0:1]
	v_cmp_eq_u32_e32 vcc, 3, v191
	s_waitcnt vmcnt(1)
	v_pk_fma_f32 v[140:141], v[140:141], s[76:77], v[72:73] op_sel_hi:[1,0,1]
	v_pk_fma_f32 v[138:139], v[138:139], s[76:77], v[70:71] op_sel_hi:[1,0,1]
	s_waitcnt vmcnt(0)
	v_pk_fma_f32 v[144:145], v[144:145], s[76:77], v[76:77] op_sel_hi:[1,0,1]
	v_pk_fma_f32 v[142:143], v[142:143], s[76:77], v[74:75] op_sel_hi:[1,0,1]
	v_mul_f32_e32 v148, v138, v138
	v_mul_f32_e32 v150, v139, v139
	v_mul_f32_e32 v152, v140, v140
	v_mul_f32_e32 v154, v141, v141
	v_mov_b32_e32 v149, v138
	v_mov_b32_e32 v151, v139
	v_mov_b32_e32 v155, v141
	v_mov_b32_e32 v153, v140
	v_mul_f32_e32 v156, v142, v142
	v_mul_f32_e32 v158, v143, v143
	v_mul_f32_e32 v160, v144, v144
	v_mul_f32_e32 v162, v145, v145
	v_mov_b32_e32 v157, v142
	v_mov_b32_e32 v159, v143
	v_mov_b32_e32 v163, v145
	v_mov_b32_e32 v161, v144
	v_pk_add_f32 v[148:149], v[148:149], v[150:151]
	v_pk_add_f32 v[150:151], v[154:155], v[152:153]
	v_pk_add_f32 v[152:153], v[156:157], v[158:159]
	v_pk_add_f32 v[154:155], v[162:163], v[160:161]
	v_pk_add_f32 v[148:149], v[148:149], v[150:151]
	v_pk_add_f32 v[150:151], v[152:153], v[154:155]
	v_pk_add_f32 v[134:135], v[134:135], v[148:149]
	v_cvt_pk_bf16_f32 v138, v138, v139
	v_pk_add_f32 v[134:135], v[134:135], v[150:151]
	ds_bpermute_b32 v149, v168, v135
	ds_bpermute_b32 v148, v168, v134
	v_cvt_pk_bf16_f32 v139, v140, v141
	v_cvt_pk_bf16_f32 v140, v142, v143
	v_cvt_pk_bf16_f32 v141, v144, v145
	global_store_dwordx4 v[146:147], v[138:141], off offset:256 nt
	s_waitcnt lgkmcnt(0)
	v_pk_add_f32 v[134:135], v[134:135], v[148:149]
	ds_bpermute_b32 v149, v2, v135
	ds_bpermute_b32 v148, v2, v134
	s_waitcnt lgkmcnt(0)
	v_pk_add_f32 v[134:135], v[134:135], v[148:149]
	s_nop 0
	v_cndmask_b32_e32 v137, v137, v135, vcc
	v_cndmask_b32_e32 v136, v136, v134, vcc

.LBB0_1160:
	s_or_b64 exec, exec, s[0:1]
	s_bitcmp0_b32 s84, 4
	s_cbranch_scc1 .LBB0_1163
	s_waitcnt lgkmcnt(4)
	v_add_co_u32_e32 v138, vcc, 0x100000, v4
	s_mov_b64 s[0:1], 0x100000
	s_nop 0
	v_addc_co_u32_e32 v139, vcc, 0, v5, vcc
	v_lshl_add_u64 v[136:137], v[4:5], 0, s[0:1]
	s_waitcnt lgkmcnt(0)
	global_load_dwordx4 v[140:143], v[138:139], off
	global_load_dwordx4 v[144:147], v[136:137], off offset:16
	v_lshlrev_b64 v[148:149], 12, v[180:181]
	s_mov_b64 s[0:1], 0x80000
	s_waitcnt vmcnt(1)
	v_pk_fma_f32 v[140:141], v[140:141], s[76:77], v[46:47] op_sel_hi:[1,0,1]
	v_pk_fma_f32 v[142:143], v[142:143], s[76:77], v[48:49] op_sel_hi:[1,0,1]
	v_pk_mul_f32 v[158:159], v[140:141], v[140:141]
	v_pk_add_f32 v[160:161], v[140:141], v[140:141] op_sel_hi:[0,1]
	v_mul_f32_e32 v2, v143, v143
	s_waitcnt vmcnt(0)
	v_pk_fma_f32 v[144:145], v[144:145], s[76:77], v[50:51] op_sel_hi:[1,0,1]
	v_mov_b32_e32 v159, v161
	v_pk_mov_b32 v[160:161], v[140:141], v[142:143] op_sel:[1,0]
	v_pk_fma_f32 v[136:137], v[142:143], v[142:143], v[2:3] op_sel_hi:[1,1,0]
	v_mul_f32_e32 v150, v144, v144
	v_mul_f32_e32 v152, v145, v145
	v_pk_mul_f32 v[162:163], v[140:141], v[160:161] op_sel:[1,0] op_sel_hi:[0,1]
	v_pk_add_f32 v[160:161], v[142:143], v[160:161]
	v_mov_b32_e32 v151, v144
	v_mov_b32_e32 v153, v145
	v_cvt_pk_bf16_f32 v140, v140, v141
	v_cvt_pk_bf16_f32 v141, v142, v143
	v_cvt_pk_bf16_f32 v142, v144, v145
	v_lshl_add_u64 v[144:145], s[16:17], 0, v[148:149]
	v_pk_fma_f32 v[146:147], v[146:147], s[76:77], v[52:53] op_sel_hi:[1,0,1]
	v_lshl_add_u64 v[144:145], v[178:179], 1, v[144:145]
	v_mul_f32_e32 v154, v146, v146
	v_mul_f32_e32 v156, v147, v147
	v_mov_b32_e32 v157, v147
	v_mov_b32_e32 v155, v146
	v_cvt_pk_bf16_f32 v143, v146, v147
	v_lshl_add_u64 v[146:147], v[144:145], 0, s[0:1]
	s_mov_b32 s0, 0x80000
	v_add_co_u32_e32 v144, vcc, s0, v144
	s_mov_b64 s[0:1], 0x100200
	s_nop 0
	v_addc_co_u32_e32 v145, vcc, 0, v145, vcc
	global_store_dwordx4 v[144:145], v[140:143], off nt
	v_mov_b32_e32 v163, v161
	v_pk_add_f32 v[158:159], v[158:159], v[162:163]
	v_lshl_add_u64 v[142:143], v[4:5], 0, s[0:1]
	global_load_dwordx4 v[138:141], v[138:139], off offset:512
	s_nop 0
	global_load_dwordx4 v[142:145], v[142:143], off offset:16
	v_mov_b32_e32 v137, v3
	v_pk_add_f32 v[150:151], v[150:151], v[152:153]
	v_pk_add_f32 v[152:153], v[156:157], v[154:155]
	v_pk_add_f32 v[136:137], v[158:159], v[136:137]
	v_pk_add_f32 v[150:151], v[150:151], v[152:153]
	v_cmp_lt_i32_e32 vcc, v234, v230
	v_pk_add_f32 v[136:137], v[136:137], v[150:151]
	s_waitcnt vmcnt(1)
	v_pk_fma_f32 v[148:149], v[140:141], s[76:77], v[16:17] op_sel_hi:[1,0,1]
	v_pk_fma_f32 v[150:151], v[138:139], s[76:77], v[14:15] op_sel_hi:[1,0,1]
	v_mul_f32_e32 v152, v148, v148
	v_mul_f32_e32 v138, v150, v150
	v_mul_f32_e32 v140, v151, v151
	v_mul_f32_e32 v154, v149, v149
	v_mov_b32_e32 v139, v150
	v_mov_b32_e32 v141, v151
	v_mov_b32_e32 v155, v149
	v_mov_b32_e32 v153, v148
	v_pk_add_f32 v[138:139], v[138:139], v[140:141]
	v_pk_add_f32 v[140:141], v[154:155], v[152:153]
	s_waitcnt vmcnt(0)
	v_pk_fma_f32 v[154:155], v[144:145], s[76:77], v[20:21] op_sel_hi:[1,0,1]
	v_pk_fma_f32 v[144:145], v[142:143], s[76:77], v[18:19] op_sel_hi:[1,0,1]
	v_pk_add_f32 v[152:153], v[138:139], v[140:141]
	v_mul_f32_e32 v138, v144, v144
	v_mul_f32_e32 v140, v145, v145
	v_mov_b32_e32 v139, v144
	v_mov_b32_e32 v141, v145
	v_pk_add_f32 v[138:139], v[138:139], v[140:141]
	v_mul_f32_e32 v140, v154, v154
	v_mul_f32_e32 v142, v155, v155
	v_mov_b32_e32 v143, v155
	v_mov_b32_e32 v141, v154
	v_pk_add_f32 v[140:141], v[142:143], v[140:141]
	v_cndmask_b32_e32 v2, v228, v234, vcc
	v_pk_add_f32 v[136:137], v[136:137], v[152:153]
	v_pk_add_f32 v[138:139], v[138:139], v[140:141]
	v_lshlrev_b32_e32 v2, 2, v2
	v_pk_add_f32 v[136:137], v[136:137], v[138:139]
	ds_bpermute_b32 v139, v2, v137
	ds_bpermute_b32 v138, v2, v136
	v_cmp_lt_i32_e32 vcc, v195, v230
	v_cvt_pk_bf16_f32 v142, v150, v151
	v_cvt_pk_bf16_f32 v143, v148, v149
	v_cndmask_b32_e32 v135, v228, v195, vcc
	v_lshlrev_b32_e32 v135, 2, v135
	s_waitcnt lgkmcnt(0)
	v_pk_add_f32 v[136:137], v[136:137], v[138:139]
	ds_bpermute_b32 v139, v135, v137
	ds_bpermute_b32 v138, v135, v136
	v_cvt_pk_bf16_f32 v144, v144, v145
	v_cvt_pk_bf16_f32 v145, v154, v155
	global_store_dwordx4 v[146:147], v[142:145], off offset:256 nt
	v_cmp_eq_u32_e32 vcc, 0, v191
	s_waitcnt lgkmcnt(0)
	v_pk_add_f32 v[136:137], v[136:137], v[138:139]
	s_nop 0
	v_cndmask_b32_e32 v137, 0, v137, vcc
	v_cndmask_b32_e32 v136, 0, v136, vcc
	s_bitcmp0_b32 s84, 5
	s_cbranch_scc0 .LBB0_1164
	s_branch .LBB0_1165
.LBB0_1162:
	v_add_co_u32_e32 v134, vcc, 0x40000, v4
	s_mov_b64 s[0:1], 0x40000
	s_nop 0
	v_addc_co_u32_e32 v135, vcc, 0, v5, vcc
	s_waitcnt lgkmcnt(2)
	v_lshl_add_u64 v[142:143], v[4:5], 0, s[0:1]
	s_waitcnt lgkmcnt(0)
	global_load_dwordx4 v[138:141], v[134:135], off
	v_lshlrev_b64 v[146:147], 12, v[180:181]
	global_load_dwordx4 v[142:145], v[142:143], off offset:16
	v_lshl_add_u64 v[146:147], s[16:17], 0, v[146:147]
	v_lshl_add_u64 v[146:147], v[178:179], 1, v[146:147]
	s_mov_b32 s0, 0x20000
	v_add_co_u32_e32 v148, vcc, s0, v146
	s_mov_b64 s[0:1], 0x40200
	s_nop 0
	v_addc_co_u32_e32 v149, vcc, 0, v147, vcc
	v_cmp_lt_i32_e32 vcc, v234, v230
	s_waitcnt vmcnt(1)
	v_pk_fma_f32 v[150:151], v[140:141], s[76:77], v[112:113] op_sel_hi:[1,0,1]
	v_pk_fma_f32 v[152:153], v[138:139], s[76:77], v[110:111] op_sel_hi:[1,0,1]
	s_waitcnt vmcnt(0)
	v_pk_fma_f32 v[154:155], v[144:145], s[76:77], v[116:117] op_sel_hi:[1,0,1]
	v_pk_fma_f32 v[156:157], v[142:143], s[76:77], v[114:115] op_sel_hi:[1,0,1]
	v_cvt_pk_bf16_f32 v138, v152, v153
	v_cvt_pk_bf16_f32 v139, v150, v151
	v_cvt_pk_bf16_f32 v140, v156, v157
	v_cvt_pk_bf16_f32 v141, v154, v155
	global_store_dwordx4 v[148:149], v[138:141], off nt
	global_load_dwordx4 v[138:141], v[134:135], off offset:512
	v_lshl_add_u64 v[134:135], v[4:5], 0, s[0:1]
	global_load_dwordx4 v[142:145], v[134:135], off offset:16
	v_cndmask_b32_e32 v2, v228, v234, vcc
	v_lshlrev_b32_e32 v164, 2, v2
	v_mul_f32_e32 v2, v151, v151
	v_add_f32_e32 v135, v152, v153
	v_add_f32_e32 v149, v151, v150
	v_mul_f32_e32 v134, v152, v152
	v_mul_f32_e32 v148, v153, v153
	v_mul_f32_e32 v152, v156, v156
	v_mul_f32_e32 v158, v157, v157
	v_mul_f32_e32 v160, v154, v154
	v_mul_f32_e32 v162, v155, v155
	v_mov_b32_e32 v153, v156
	v_mov_b32_e32 v159, v157
	v_mov_b32_e32 v163, v155
	v_mov_b32_e32 v161, v154
	v_pk_fma_f32 v[150:151], v[150:151], v[150:151], v[2:3] op_sel_hi:[1,1,0]
	v_pk_add_f32 v[134:135], v[134:135], v[148:149]
	v_pk_add_f32 v[148:149], v[152:153], v[158:159]
	v_pk_add_f32 v[152:153], v[162:163], v[160:161]
	v_mov_b32_e32 v151, v3
	v_pk_add_f32 v[148:149], v[148:149], v[152:153]
	v_pk_add_f32 v[134:135], v[134:135], v[150:151]
	v_cmp_lt_i32_e32 vcc, v195, v230
	v_pk_add_f32 v[134:135], v[134:135], v[148:149]
	s_mov_b64 s[0:1], 0x20000
	v_cndmask_b32_e32 v2, v228, v195, vcc
	v_lshlrev_b32_e32 v2, 2, v2
	v_lshl_add_u64 v[146:147], v[146:147], 0, s[0:1]
	v_cmp_eq_u32_e32 vcc, 2, v191
	s_waitcnt vmcnt(1)
	v_pk_fma_f32 v[140:141], v[140:141], s[76:77], v[80:81] op_sel_hi:[1,0,1]
	v_pk_fma_f32 v[138:139], v[138:139], s[76:77], v[78:79] op_sel_hi:[1,0,1]
	s_waitcnt vmcnt(0)
	v_pk_fma_f32 v[144:145], v[144:145], s[76:77], v[84:85] op_sel_hi:[1,0,1]
	v_pk_fma_f32 v[142:143], v[142:143], s[76:77], v[82:83] op_sel_hi:[1,0,1]
	v_mul_f32_e32 v148, v138, v138
	v_mul_f32_e32 v150, v139, v139
	v_mul_f32_e32 v152, v140, v140
	v_mul_f32_e32 v154, v141, v141
	v_mov_b32_e32 v149, v138
	v_mov_b32_e32 v151, v139
	v_mov_b32_e32 v155, v141
	v_mov_b32_e32 v153, v140
	v_mul_f32_e32 v156, v142, v142
	v_mul_f32_e32 v158, v143, v143
	v_mul_f32_e32 v160, v144, v144
	v_mul_f32_e32 v162, v145, v145
	v_mov_b32_e32 v157, v142
	v_mov_b32_e32 v159, v143
	v_mov_b32_e32 v163, v145
	v_mov_b32_e32 v161, v144
	v_pk_add_f32 v[148:149], v[148:149], v[150:151]
	v_pk_add_f32 v[150:151], v[154:155], v[152:153]
	v_pk_add_f32 v[152:153], v[156:157], v[158:159]
	v_pk_add_f32 v[154:155], v[162:163], v[160:161]
	v_pk_add_f32 v[148:149], v[148:149], v[150:151]
	v_pk_add_f32 v[150:151], v[152:153], v[154:155]
	v_pk_add_f32 v[134:135], v[134:135], v[148:149]
	v_cvt_pk_bf16_f32 v138, v138, v139
	v_pk_add_f32 v[134:135], v[134:135], v[150:151]
	ds_bpermute_b32 v149, v164, v135
	ds_bpermute_b32 v148, v164, v134
	v_cvt_pk_bf16_f32 v139, v140, v141
	v_cvt_pk_bf16_f32 v140, v142, v143
	v_cvt_pk_bf16_f32 v141, v144, v145
	global_store_dwordx4 v[146:147], v[138:141], off offset:256 nt
	s_waitcnt lgkmcnt(0)
	v_pk_add_f32 v[134:135], v[134:135], v[148:149]
	ds_bpermute_b32 v149, v2, v135
	ds_bpermute_b32 v148, v2, v134
	s_waitcnt lgkmcnt(0)
	v_pk_add_f32 v[134:135], v[134:135], v[148:149]
	s_nop 0
	v_cndmask_b32_e32 v137, v137, v135, vcc
	v_cndmask_b32_e32 v136, v136, v134, vcc
	s_bitcmp0_b32 s84, 3
	s_cbranch_scc0 .LBB0_1157
	s_branch .LBB0_1158

.LBB0_1164:
	s_waitcnt lgkmcnt(1)
	v_add_co_u32_e32 v146, vcc, 0x120000, v4
	s_mov_b64 s[0:1], 0x120000
	s_nop 0
	v_addc_co_u32_e32 v147, vcc, 0, v5, vcc
	v_lshl_add_u64 v[142:143], v[4:5], 0, s[0:1]
	s_waitcnt lgkmcnt(0)
	global_load_dwordx4 v[138:141], v[146:147], off
	v_lshlrev_b64 v[148:149], 12, v[180:181]
	global_load_dwordx4 v[142:145], v[142:143], off offset:16
	v_lshl_add_u64 v[148:149], s[16:17], 0, v[148:149]
	v_lshl_add_u64 v[148:149], v[178:179], 1, v[148:149]
	s_mov_b32 s0, 0x90000
	v_add_co_u32_e32 v150, vcc, s0, v148
	s_mov_b64 s[0:1], 0x120200
	s_nop 0
	v_addc_co_u32_e32 v151, vcc, 0, v149, vcc
	v_cmp_lt_i32_e32 vcc, v234, v230
	s_waitcnt vmcnt(1)
	v_pk_fma_f32 v[152:153], v[140:141], s[76:77], v[40:41] op_sel_hi:[1,0,1]
	v_pk_fma_f32 v[154:155], v[138:139], s[76:77], v[38:39] op_sel_hi:[1,0,1]
	s_waitcnt vmcnt(0)
	v_pk_fma_f32 v[156:157], v[144:145], s[76:77], v[44:45] op_sel_hi:[1,0,1]
	v_pk_fma_f32 v[158:159], v[142:143], s[76:77], v[42:43] op_sel_hi:[1,0,1]
	v_cvt_pk_bf16_f32 v138, v154, v155
	v_cvt_pk_bf16_f32 v139, v152, v153
	v_cvt_pk_bf16_f32 v140, v158, v159
	v_cvt_pk_bf16_f32 v141, v156, v157
	global_store_dwordx4 v[150:151], v[138:141], off nt
	global_load_dwordx4 v[138:141], v[146:147], off offset:512
	v_lshl_add_u64 v[142:143], v[4:5], 0, s[0:1]
	global_load_dwordx4 v[142:145], v[142:143], off offset:16
	v_cndmask_b32_e32 v2, v228, v234, vcc
	v_mov_b32_e32 v146, v154
	v_mov_b32_e32 v147, v153
	v_pk_mov_b32 v[150:151], v[154:155], v[152:153] op_sel:[1,0]
	v_lshlrev_b32_e32 v135, 2, v2
	v_pk_mul_f32 v[154:155], v[154:155], v[154:155]
	v_mul_f32_e32 v2, v153, v153
	v_mul_f32_e32 v160, v158, v158
	v_mul_f32_e32 v162, v159, v159
	v_mov_b32_e32 v161, v158
	v_mov_b32_e32 v163, v159
	v_mul_f32_e32 v158, v156, v156
	v_mul_f32_e32 v164, v157, v157
	v_mov_b32_e32 v165, v157
	v_mov_b32_e32 v159, v156
	v_pk_add_f32 v[146:147], v[146:147], v[150:151]
	v_pk_fma_f32 v[150:151], v[152:153], v[152:153], v[2:3] op_sel_hi:[1,1,0]
	v_pk_add_f32 v[156:157], v[164:165], v[158:159]
	v_mov_b32_e32 v158, v154
	v_mov_b32_e32 v159, v146
	v_mov_b32_e32 v146, v155
	v_pk_add_f32 v[152:153], v[160:161], v[162:163]
	v_mov_b32_e32 v151, v3
	v_pk_add_f32 v[146:147], v[158:159], v[146:147]
	v_pk_add_f32 v[152:153], v[152:153], v[156:157]
	v_pk_add_f32 v[146:147], v[146:147], v[150:151]
	v_cmp_lt_i32_e32 vcc, v195, v230
	v_pk_add_f32 v[146:147], v[146:147], v[152:153]
	s_mov_b64 s[0:1], 0x90000
	v_cndmask_b32_e32 v2, v228, v195, vcc
	v_lshlrev_b32_e32 v2, 2, v2
	v_lshl_add_u64 v[148:149], v[148:149], 0, s[0:1]
	v_cmp_eq_u32_e32 vcc, 1, v191
	s_waitcnt vmcnt(1)
	v_pk_fma_f32 v[140:141], v[140:141], s[76:77], v[8:9] op_sel_hi:[1,0,1]
	v_pk_fma_f32 v[138:139], v[138:139], s[76:77], v[6:7] op_sel_hi:[1,0,1]
	s_waitcnt vmcnt(0)
	v_pk_fma_f32 v[144:145], v[144:145], s[76:77], v[12:13] op_sel_hi:[1,0,1]
	v_pk_fma_f32 v[142:143], v[142:143], s[76:77], v[10:11] op_sel_hi:[1,0,1]
	v_mul_f32_e32 v150, v138, v138
	v_mul_f32_e32 v152, v139, v139
	v_mul_f32_e32 v154, v140, v140
	v_mul_f32_e32 v156, v141, v141
	v_mov_b32_e32 v151, v138
	v_mov_b32_e32 v153, v139
	v_mov_b32_e32 v157, v141
	v_mov_b32_e32 v155, v140
	v_mul_f32_e32 v158, v142, v142
	v_mul_f32_e32 v160, v143, v143
	v_mul_f32_e32 v162, v144, v144
	v_mul_f32_e32 v164, v145, v145
	v_mov_b32_e32 v159, v142
	v_mov_b32_e32 v161, v143
	v_mov_b32_e32 v165, v145
	v_mov_b32_e32 v163, v144
	v_pk_add_f32 v[150:151], v[150:151], v[152:153]
	v_pk_add_f32 v[152:153], v[156:157], v[154:155]
	v_pk_add_f32 v[154:155], v[158:159], v[160:161]
	v_pk_add_f32 v[156:157], v[164:165], v[162:163]
	v_pk_add_f32 v[150:151], v[150:151], v[152:153]
	v_pk_add_f32 v[152:153], v[154:155], v[156:157]
	v_pk_add_f32 v[146:147], v[146:147], v[150:151]
	v_cvt_pk_bf16_f32 v138, v138, v139
	v_pk_add_f32 v[146:147], v[146:147], v[152:153]
	ds_bpermute_b32 v151, v135, v147
	ds_bpermute_b32 v150, v135, v146
	v_cvt_pk_bf16_f32 v139, v140, v141
	v_cvt_pk_bf16_f32 v140, v142, v143
	v_cvt_pk_bf16_f32 v141, v144, v145
	global_store_dwordx4 v[148:149], v[138:141], off offset:256 nt
	s_waitcnt lgkmcnt(0)
	v_pk_add_f32 v[146:147], v[146:147], v[150:151]
	ds_bpermute_b32 v151, v2, v147
	ds_bpermute_b32 v150, v2, v146
	s_waitcnt lgkmcnt(0)
	v_pk_add_f32 v[138:139], v[146:147], v[150:151]
	s_nop 0
	v_cndmask_b32_e32 v137, v137, v139, vcc
	v_cndmask_b32_e32 v136, v136, v138, vcc

.LBB0_1167:
	s_waitcnt lgkmcnt(1)
	v_add_co_u32_e32 v146, vcc, 0x160000, v4
	s_mov_b64 s[0:1], 0x160000
	v_lshl_add_u64 v[138:139], v[4:5], 0, s[0:1]
	v_addc_co_u32_e32 v147, vcc, 0, v5, vcc
	s_waitcnt lgkmcnt(0)
	global_load_dwordx4 v[138:141], v[138:139], off offset:16
	v_lshlrev_b64 v[148:149], 12, v[180:181]
	global_load_dwordx4 v[142:145], v[146:147], off
	v_lshl_add_u64 v[148:149], s[16:17], 0, v[148:149]
	v_lshl_add_u64 v[148:149], v[178:179], 1, v[148:149]
	s_mov_b32 s0, 0xb0000
	v_add_co_u32_e32 v150, vcc, s0, v148
	s_mov_b64 s[0:1], 0x160200
	s_nop 0
	v_addc_co_u32_e32 v151, vcc, 0, v149, vcc
	v_lshl_add_u64 v[4:5], v[4:5], 0, s[0:1]
	v_cmp_lt_i32_e32 vcc, v234, v230
	s_mov_b64 s[0:1], 0xb0000
	v_lshl_add_u64 v[148:149], v[148:149], 0, s[0:1]
	v_cndmask_b32_e32 v2, v228, v234, vcc
	v_lshlrev_b32_e32 v135, 2, v2
	v_cmp_lt_i32_e32 vcc, v195, v230
	s_waitcnt vmcnt(1)
	v_pk_fma_f32 v[152:153], v[140:141], s[76:77], v[28:29] op_sel_hi:[1,0,1]
	v_pk_fma_f32 v[154:155], v[138:139], s[76:77], v[26:27] op_sel_hi:[1,0,1]
	s_waitcnt vmcnt(0)
	v_pk_fma_f32 v[156:157], v[144:145], s[76:77], v[24:25] op_sel_hi:[1,0,1]
	v_pk_fma_f32 v[158:159], v[142:143], s[76:77], v[22:23] op_sel_hi:[1,0,1]
	v_cvt_pk_bf16_f32 v140, v154, v155
	v_cvt_pk_bf16_f32 v141, v152, v153
	v_cvt_pk_bf16_f32 v138, v158, v159
	v_cvt_pk_bf16_f32 v139, v156, v157
	global_store_dwordx4 v[150:151], v[138:141], off nt
	global_load_dwordx4 v[138:141], v[146:147], off offset:512
	v_mul_f32_e32 v150, v152, v152
	global_load_dwordx4 v[142:145], v[4:5], off offset:16
	v_mul_f32_e32 v4, v154, v154
	v_mul_f32_e32 v146, v155, v155
	v_mul_f32_e32 v160, v153, v153
	v_mov_b32_e32 v5, v154
	v_mov_b32_e32 v147, v155
	v_mov_b32_e32 v161, v153
	v_mov_b32_e32 v151, v152
	v_pk_add_f32 v[4:5], v[4:5], v[146:147]
	v_pk_add_f32 v[146:147], v[160:161], v[150:151]
	v_pk_mul_f32 v[150:151], v[158:159], v[158:159]
	v_pk_add_f32 v[152:153], v[158:159], v[158:159] op_sel_hi:[0,1]
	v_pk_mov_b32 v[154:155], v[158:159], v[156:157] op_sel:[1,0]
	v_mul_f32_e32 v2, v157, v157
	v_mov_b32_e32 v151, v153
	v_pk_mul_f32 v[152:153], v[158:159], v[154:155] op_sel:[1,0] op_sel_hi:[0,1]
	v_pk_add_f32 v[154:155], v[156:157], v[154:155]
	v_pk_add_f32 v[4:5], v[4:5], v[146:147]
	v_pk_fma_f32 v[146:147], v[156:157], v[156:157], v[2:3] op_sel_hi:[1,1,0]
	v_mov_b32_e32 v153, v155
	v_mov_b32_e32 v147, v3
	v_pk_add_f32 v[150:151], v[150:151], v[152:153]
	v_cndmask_b32_e32 v2, v228, v195, vcc
	v_pk_add_f32 v[146:147], v[150:151], v[146:147]
	v_lshlrev_b32_e32 v2, 2, v2
	v_pk_add_f32 v[4:5], v[146:147], v[4:5]
	v_cmp_eq_u32_e32 vcc, 3, v191
	s_waitcnt vmcnt(1)
	v_pk_fma_f32 v[140:141], v[140:141], s[76:77], v[60:61] op_sel_hi:[1,0,1]
	v_pk_fma_f32 v[138:139], v[138:139], s[76:77], v[58:59] op_sel_hi:[1,0,1]
	s_waitcnt vmcnt(0)
	v_pk_fma_f32 v[144:145], v[144:145], s[76:77], v[68:69] op_sel_hi:[1,0,1]
	v_pk_fma_f32 v[142:143], v[142:143], s[76:77], v[66:67] op_sel_hi:[1,0,1]
	v_mul_f32_e32 v146, v138, v138
	v_mul_f32_e32 v150, v139, v139
	v_mul_f32_e32 v152, v140, v140
	v_mul_f32_e32 v154, v141, v141
	v_mov_b32_e32 v147, v138
	v_mov_b32_e32 v151, v139
	v_mov_b32_e32 v155, v141
	v_mov_b32_e32 v153, v140
	v_mul_f32_e32 v156, v142, v142
	v_mul_f32_e32 v158, v143, v143
	v_mul_f32_e32 v160, v144, v144
	v_mul_f32_e32 v162, v145, v145
	v_mov_b32_e32 v157, v142
	v_mov_b32_e32 v159, v143
	v_mov_b32_e32 v163, v145
	v_mov_b32_e32 v161, v144
	v_pk_add_f32 v[146:147], v[146:147], v[150:151]
	v_pk_add_f32 v[150:151], v[154:155], v[152:153]
	v_pk_add_f32 v[152:153], v[156:157], v[158:159]
	v_pk_add_f32 v[154:155], v[162:163], v[160:161]
	v_pk_add_f32 v[146:147], v[146:147], v[150:151]
	v_pk_add_f32 v[150:151], v[152:153], v[154:155]
	v_pk_add_f32 v[4:5], v[4:5], v[146:147]
	v_cvt_pk_bf16_f32 v138, v138, v139
	v_pk_add_f32 v[4:5], v[4:5], v[150:151]
	ds_bpermute_b32 v147, v135, v5
	ds_bpermute_b32 v146, v135, v4
	v_cvt_pk_bf16_f32 v139, v140, v141
	v_cvt_pk_bf16_f32 v140, v142, v143
	v_cvt_pk_bf16_f32 v141, v144, v145
	global_store_dwordx4 v[148:149], v[138:141], off offset:256 nt
	s_waitcnt lgkmcnt(0)
	v_pk_add_f32 v[4:5], v[4:5], v[146:147]
	ds_bpermute_b32 v147, v2, v5
	ds_bpermute_b32 v146, v2, v4
	s_waitcnt lgkmcnt(0)
	v_pk_add_f32 v[4:5], v[4:5], v[146:147]
	s_nop 0
	v_cndmask_b32_e32 v137, v137, v5, vcc
	v_cndmask_b32_e32 v136, v136, v4, vcc

.LBB0_1181:
	s_waitcnt lgkmcnt(0)
	v_mul_f32_e32 v166, 0x3a000000, v178
	v_mul_f32_e32 v167, v166, v166
	v_fma_f32 v167, v179, s72, -v167
	v_add_f32_e32 v167, 0x3727c5ac, v167
	v_rsq_f32_e32 v167, v167
	v_cndmask_b32_e64 v166, v166, 0, s[6:7]
	v_add_u32_e32 v2, 0xb0, v2
	v_cndmask_b32_e64 v168, v167, 1.0, s[6:7]
	v_pk_fma_f32 v[146:147], v[146:147], v[166:167], v[58:59] op_sel_hi:[1,0,1] neg_lo:[1,0,0] neg_hi:[1,0,0]
	v_pk_fma_f32 v[154:155], v[154:155], v[166:167], v[26:27] op_sel_hi:[1,0,1] neg_lo:[1,0,0] neg_hi:[1,0,0]
	v_pk_fma_f32 v[142:143], v[146:147], v[168:169], v[142:143] op_sel_hi:[1,0,1]
	v_pk_fma_f32 v[146:147], v[156:157], v[166:167], v[28:29] op_sel_hi:[1,0,1]
	v_pk_fma_f32 v[150:151], v[154:155], v[168:169], v[150:151] op_sel_hi:[1,0,1]
	v_pk_fma_f32 v[164:165], v[164:165], v[166:167], v[24:25] op_sel_hi:[1,0,1]
	v_pk_fma_f32 v[162:163], v[162:163], v[166:167], v[22:23] op_sel_hi:[1,0,1] neg_lo:[1,0,0] neg_hi:[1,0,0]
	v_pk_fma_f32 v[146:147], v[146:147], v[168:169], v[152:153] op_sel_hi:[1,0,1]
	v_mul_f32_e32 v152, 0xbfb8aa3b, v150
	v_mul_f32_e32 v153, 0xbfb8aa3b, v151
	v_pk_fma_f32 v[160:161], v[164:165], v[168:169], v[160:161] op_sel_hi:[1,0,1]
	v_pk_fma_f32 v[158:159], v[162:163], v[168:169], v[158:159] op_sel_hi:[1,0,1]
	v_exp_f32_e32 v152, v152
	v_exp_f32_e32 v153, v153
	v_mul_f32_e32 v162, 0xbfb8aa3b, v158
	v_mul_f32_e32 v163, 0xbfb8aa3b, v159
	v_mul_f32_e32 v164, 0xbfb8aa3b, v160
	v_mul_f32_e32 v165, 0xbfb8aa3b, v161
	v_mul_f32_e32 v154, 0xbfb8aa3b, v146
	v_mul_f32_e32 v155, 0xbfb8aa3b, v147
	v_exp_f32_e32 v162, v162
	v_exp_f32_e32 v164, v164
	v_exp_f32_e32 v165, v165
	v_exp_f32_e32 v163, v163
	v_exp_f32_e32 v154, v154
	v_exp_f32_e32 v155, v155
	v_pk_add_f32 v[152:153], v[152:153], 1.0 op_sel_hi:[1,0]
	v_pk_add_f32 v[164:165], v[164:165], 1.0 op_sel_hi:[1,0]
	v_rcp_f32_e32 v152, v152
	v_rcp_f32_e32 v153, v153
	v_pk_add_f32 v[162:163], v[162:163], 1.0 op_sel_hi:[1,0]
	v_pk_add_f32 v[154:155], v[154:155], 1.0 op_sel_hi:[1,0]
	v_rcp_f32_e32 v162, v162
	v_rcp_f32_e32 v164, v164
	v_rcp_f32_e32 v165, v165
	v_rcp_f32_e32 v163, v163
	v_rcp_f32_e32 v154, v154
	v_rcp_f32_e32 v155, v155
	v_pk_fma_f32 v[148:149], v[148:149], v[166:167], v[60:61] op_sel_hi:[1,0,1] neg_lo:[1,0,0] neg_hi:[1,0,0]
	v_pk_fma_f32 v[138:139], v[138:139], v[166:167], v[66:67] op_sel_hi:[1,0,1] neg_lo:[1,0,0] neg_hi:[1,0,0]
	v_pk_fma_f32 v[144:145], v[148:149], v[168:169], v[144:145] op_sel_hi:[1,0,1]
	v_pk_mul_f32 v[148:149], v[150:151], v[152:153]
	v_pk_fma_f32 v[134:135], v[138:139], v[168:169], v[134:135] op_sel_hi:[1,0,1]
	v_pk_mul_f32 v[160:161], v[160:161], v[164:165]
	v_pk_mul_f32 v[138:139], v[134:135], v[148:149]
	v_pk_fma_f32 v[134:135], v[140:141], v[166:167], v[68:69] op_sel_hi:[1,0,1] neg_lo:[1,0,0] neg_hi:[1,0,0]
	v_pk_mul_f32 v[158:159], v[158:159], v[162:163]
	v_pk_mul_f32 v[146:147], v[146:147], v[154:155]
	v_pk_fma_f32 v[134:135], v[134:135], v[168:169], v[136:137] op_sel_hi:[1,0,1]
	v_cvt_pk_bf16_f32 v136, v138, v139
	v_mov_b64_e32 v[138:139], s[0:1]
	s_movk_i32 s0, 0x2c00
	v_pk_mul_f32 v[142:143], v[142:143], v[158:159]
	v_pk_mul_f32 v[144:145], v[144:145], v[160:161]
	v_pk_mul_f32 v[140:141], v[134:135], v[146:147]
	v_mad_i64_i32 v[138:139], s[0:1], v2, s0, v[138:139]
	v_cvt_pk_bf16_f32 v134, v142, v143
	v_cvt_pk_bf16_f32 v135, v144, v145
	v_cvt_pk_bf16_f32 v137, v140, v141
	v_lshl_add_u64 v[4:5], v[4:5], 1, v[138:139]
	global_store_dwordx4 v[4:5], v[134:137], off nt
